# all four GEMM k-loops on v_mfma_f32_16x16x32_bf16 (same bf16 operands, f32 accumulate), results put back into the 32x32 accumulator layout by v_permlane16_swap
# speedup vs baseline: 1.0254x; 1.0222x over previous
.LBB0_152:
	s_or_saveexec_b64 s[0:1], s[0:1]
	v_mov_b32_e32 v176, 0
	v_mov_b32_e32 v94, 0
	v_mov_b32_e32 v182, 0
	v_mov_b32_e32 v92, 0
	v_mov_b32_e32 v184, 0
	v_mov_b32_e32 v90, 0
	v_mov_b32_e32 v186, 0
	v_mov_b32_e32 v88, 0
	v_mov_b32_e32 v188, 0
	v_mov_b32_e32 v86, 0
	v_mov_b32_e32 v190, 0
	v_mov_b32_e32 v84, 0
	v_mov_b32_e32 v192, 0
	v_mov_b32_e32 v82, 0
	v_mov_b32_e32 v194, 0
	v_mov_b32_e32 v80, 0
	v_mov_b32_e32 v128, 0
	v_mov_b32_e32 v46, 0
	v_mov_b32_e32 v130, 0
	v_mov_b32_e32 v44, 0
	v_mov_b32_e32 v132, 0
	v_mov_b32_e32 v42, 0
	v_mov_b32_e32 v134, 0
	v_mov_b32_e32 v40, 0
	v_mov_b32_e32 v136, 0
	v_mov_b32_e32 v38, 0
	v_mov_b32_e32 v138, 0
	v_mov_b32_e32 v36, 0
	v_mov_b32_e32 v172, 0
	v_mov_b32_e32 v34, 0
	v_mov_b32_e32 v174, 0
	v_mov_b32_e32 v32, 0
	v_mov_b32_e32 v177, 0
	v_mov_b32_e32 v95, 0
	v_mov_b32_e32 v183, 0
	v_mov_b32_e32 v93, 0
	v_mov_b32_e32 v185, 0
	v_mov_b32_e32 v91, 0
	v_mov_b32_e32 v187, 0
	v_mov_b32_e32 v89, 0
	v_mov_b32_e32 v189, 0
	v_mov_b32_e32 v87, 0
	v_mov_b32_e32 v191, 0
	v_mov_b32_e32 v85, 0
	v_mov_b32_e32 v193, 0
	v_mov_b32_e32 v83, 0
	v_mov_b32_e32 v195, 0
	v_mov_b32_e32 v81, 0
	v_mov_b32_e32 v129, 0
	v_mov_b32_e32 v47, 0
	v_mov_b32_e32 v131, 0
	v_mov_b32_e32 v45, 0
	v_mov_b32_e32 v133, 0
	v_mov_b32_e32 v43, 0
	v_mov_b32_e32 v135, 0
	v_mov_b32_e32 v41, 0
	v_mov_b32_e32 v137, 0
	v_mov_b32_e32 v39, 0
	v_mov_b32_e32 v139, 0
	v_mov_b32_e32 v37, 0
	v_mov_b32_e32 v173, 0
	v_mov_b32_e32 v35, 0
	v_mov_b32_e32 v175, 0
	v_mov_b32_e32 v33, 0
	s_xor_b64 exec, exec, s[0:1]
	s_cbranch_execz .LBB0_156
	v_readfirstlane_b32 s78, v170
	v_readfirstlane_b32 s79, v168
	v_readfirstlane_b32 s76, v204
	v_mbcnt_lo_u32_b32 v136, -1, 0
	v_mbcnt_hi_u32_b32 v136, -1, v136
	s_nop 3
	s_lshl_b32 s78, s78, 14
	s_lshl_b32 s79, s79, 13
	s_add_u32 s72, s90, s78
	s_addc_u32 s73, s91, 0
	s_add_u32 s74, s90, s79
	s_addc_u32 s75, s91, 0
	s_add_u32 s74, s74, 0x1ab88000
	s_addc_u32 s75, s75, 0
	v_lshrrev_b32_e32 v137, 2, v136
	v_lshrrev_b32_e32 v138, 4, v136
	v_xor_b32_e32 v138, v138, v136
	v_and_b32_e32 v138, 3, v138
	v_lshlrev_b32_e32 v138, 4, v138
	v_lshl_or_b32 v137, v137, 6, v138
	v_or_b32_e32 v132, v137, v204
	v_add_u32_e32 v133, 0x1000, v132
	v_add_u32_e32 v134, 0x2000, v132
	v_add_u32_e32 v135, 0x3000, v132
	v_and_b32_e32 v137, 15, v136
	v_lshrrev_b32_e32 v138, 4, v136
	v_bfe_u32 v139, v136, 2, 2
	v_xor_b32_e32 v139, v139, v138
	v_lshlrev_b32_e32 v139, 4, v139
	v_lshl_or_b32 v128, v137, 6, v139
	v_lshrrev_b32_e32 v139, 10, v204
	v_lshrrev_b32_e32 v139, 1, v139
	v_lshl_or_b32 v128, v139, 11, v128
	v_and_b32_e32 v139, 3, v136
	v_bfe_u32 v137, v136, 2, 1
	v_lshl_or_b32 v139, v137, 3, v139
	v_bfe_u32 v137, v136, 3, 1
	v_lshl_or_b32 v139, v137, 2, v139
	v_lshrrev_b32_e32 v137, 2, v139
	v_xor_b32_e32 v137, v137, v138
	v_lshlrev_b32_e32 v137, 4, v137
	v_lshl_or_b32 v130, v139, 6, v137
	v_lshrrev_b32_e32 v139, 10, v204
	v_and_b32_e32 v139, 1, v139
	v_lshl_or_b32 v130, v139, 12, v130
	v_or_b32_e32 v130, 0x4000, v130
	s_add_u32 m0, s76, 0x2000
	s_nop 0
	global_load_lds_dwordx4 v134, s[72:73]
	s_add_u32 m0, s76, 0x3000
	s_nop 0
	global_load_lds_dwordx4 v135, s[72:73]
	s_add_u32 m0, s76, 0x4000
	s_nop 0
	global_load_lds_dwordx4 v132, s[74:75]
	s_add_u32 m0, s76, 0x5000
	s_nop 0
	global_load_lds_dwordx4 v133, s[74:75]
	s_add_u32 s72, s72, 0x202000
	s_addc_u32 s73, s73, 0
	s_add_u32 s74, s74, 0x2c000
	s_addc_u32 s75, s75, 0
	s_add_u32 m0, s76, 0x6000
	s_nop 0
	global_load_lds_dwordx4 v132, s[72:73]
	s_add_u32 m0, s76, 0x7000
	s_nop 0
	global_load_lds_dwordx4 v133, s[72:73]
	s_add_u32 m0, s76, 0x8000
	s_nop 0
	global_load_lds_dwordx4 v134, s[72:73]
	s_add_u32 m0, s76, 0x9000
	s_nop 0
	global_load_lds_dwordx4 v135, s[72:73]
	s_add_u32 m0, s76, 0xa000
	s_nop 0
	global_load_lds_dwordx4 v132, s[74:75]
	s_add_u32 m0, s76, 0xb000
	s_nop 0
	global_load_lds_dwordx4 v133, s[74:75]
	s_add_u32 s72, s72, 0x202000
	s_addc_u32 s73, s73, 0
	s_add_u32 s74, s74, 0x2c000
	s_addc_u32 s75, s75, 0
	s_add_u32 m0, s76, 0xc000
	s_nop 0
	global_load_lds_dwordx4 v132, s[72:73]
	s_add_u32 m0, s76, 0xd000
	s_nop 0
	global_load_lds_dwordx4 v133, s[72:73]
	s_add_u32 m0, s76, 0xe000
	s_nop 0
	global_load_lds_dwordx4 v134, s[72:73]
	s_add_u32 m0, s76, 0xf000
	s_nop 0
	global_load_lds_dwordx4 v135, s[72:73]
	s_add_u32 m0, s76, 0x10000
	s_nop 0
	global_load_lds_dwordx4 v132, s[74:75]
	s_add_u32 m0, s76, 0x11000
	s_nop 0
	global_load_lds_dwordx4 v133, s[74:75]
	s_add_u32 s72, s72, 0x202000
	s_addc_u32 s73, s73, 0
	s_add_u32 s74, s74, 0x2c000
	s_addc_u32 s75, s75, 0
	s_waitcnt vmcnt(12)
	s_barrier
	ds_read_b128 v[172:175], v130
	ds_read_b128 v[176:179], v130 offset:1024
	ds_read_b128 v[180:183], v130 offset:2048
	ds_read_b128 v[184:187], v130 offset:3072
	ds_read_b128 v[228:231], v128
	ds_read_b128 v[232:235], v128 offset:1024
	ds_read_b128 v[236:239], v128 offset:4096
	ds_read_b128 v[240:243], v128 offset:5120
	s_waitcnt lgkmcnt(0)
	v_mfma_f32_16x16x32_bf16 v[64:67], v[172:175], v[228:231], 0
	ds_read_b128 v[244:247], v128 offset:8192
	v_mfma_f32_16x16x32_bf16 v[68:71], v[172:175], v[232:235], 0
	ds_read_b128 v[248:251], v128 offset:9216
	v_mfma_f32_16x16x32_bf16 v[72:75], v[176:179], v[228:231], 0
	v_mfma_f32_16x16x32_bf16 v[76:79], v[176:179], v[232:235], 0
	v_mfma_f32_16x16x32_bf16 v[48:51], v[180:183], v[228:231], 0
	v_mfma_f32_16x16x32_bf16 v[52:55], v[180:183], v[232:235], 0
	v_mfma_f32_16x16x32_bf16 v[56:59], v[184:187], v[228:231], 0
	v_mfma_f32_16x16x32_bf16 v[60:63], v[184:187], v[232:235], 0
	s_waitcnt lgkmcnt(2)
	v_mfma_f32_16x16x32_bf16 v[16:19], v[172:175], v[236:239], 0
	ds_read_b128 v[228:231], v128 offset:12288
	v_mfma_f32_16x16x32_bf16 v[20:23], v[172:175], v[240:243], 0
	ds_read_b128 v[232:235], v128 offset:13312
	v_mfma_f32_16x16x32_bf16 v[24:27], v[176:179], v[236:239], 0
	v_mfma_f32_16x16x32_bf16 v[28:31], v[176:179], v[240:243], 0
	v_mfma_f32_16x16x32_bf16 v[0:3], v[180:183], v[236:239], 0
	v_mfma_f32_16x16x32_bf16 v[4:7], v[180:183], v[240:243], 0
	v_mfma_f32_16x16x32_bf16 v[8:11], v[184:187], v[236:239], 0
	v_mfma_f32_16x16x32_bf16 v[12:15], v[184:187], v[240:243], 0
	s_waitcnt lgkmcnt(0)
	s_waitcnt vmcnt(6)
	s_barrier
	ds_read_b128 v[188:191], v130 offset:24576
	ds_read_b128 v[192:195], v130 offset:25600
	v_mfma_f32_16x16x32_bf16 v[80:83], v[172:175], v[244:247], 0
	ds_read_b128 v[220:223], v130 offset:26624
	ds_read_b128 v[224:227], v130 offset:27648
	v_mfma_f32_16x16x32_bf16 v[84:87], v[172:175], v[248:251], 0
	ds_read_b128 v[236:239], v128 offset:24576
	ds_read_b128 v[240:243], v128 offset:25600
	s_add_u32 m0, s76, 0x0
	v_mfma_f32_16x16x32_bf16 v[88:91], v[176:179], v[244:247], 0
	global_load_lds_dwordx4 v132, s[72:73]
	s_add_u32 m0, s76, 0x1000
	v_mfma_f32_16x16x32_bf16 v[92:95], v[176:179], v[248:251], 0
	global_load_lds_dwordx4 v133, s[72:73]
	s_add_u32 m0, s76, 0x2000
	v_mfma_f32_16x16x32_bf16 v[112:115], v[180:183], v[244:247], 0
	global_load_lds_dwordx4 v134, s[72:73]
	v_mfma_f32_16x16x32_bf16 v[116:119], v[180:183], v[248:251], 0
	v_mfma_f32_16x16x32_bf16 v[120:123], v[184:187], v[244:247], 0
	v_mfma_f32_16x16x32_bf16 v[124:127], v[184:187], v[248:251], 0
	ds_read_b128 v[244:247], v128 offset:28672
	ds_read_b128 v[248:251], v128 offset:29696
	v_mfma_f32_16x16x32_bf16 v[32:35], v[172:175], v[228:231], 0
	s_add_u32 m0, s76, 0x3000
	v_mfma_f32_16x16x32_bf16 v[36:39], v[172:175], v[232:235], 0
	global_load_lds_dwordx4 v135, s[72:73]
	s_add_u32 m0, s76, 0x4000
	v_mfma_f32_16x16x32_bf16 v[40:43], v[176:179], v[228:231], 0
	global_load_lds_dwordx4 v132, s[74:75]
	s_add_u32 m0, s76, 0x5000
	v_mfma_f32_16x16x32_bf16 v[44:47], v[176:179], v[232:235], 0
	global_load_lds_dwordx4 v133, s[74:75]
	s_add_u32 s72, s72, 0x202000
	s_addc_u32 s73, s73, 0
	v_mfma_f32_16x16x32_bf16 v[96:99], v[180:183], v[228:231], 0
	s_add_u32 s74, s74, 0x2c000
	s_addc_u32 s75, s75, 0
	v_mfma_f32_16x16x32_bf16 v[100:103], v[180:183], v[232:235], 0
	v_mfma_f32_16x16x32_bf16 v[104:107], v[184:187], v[228:231], 0
	v_mfma_f32_16x16x32_bf16 v[108:111], v[184:187], v[232:235], 0
	s_waitcnt lgkmcnt(2)
	v_mfma_f32_16x16x32_bf16 v[64:67], v[188:191], v[236:239], v[64:67]
	ds_read_b128 v[228:231], v128 offset:32768
	v_mfma_f32_16x16x32_bf16 v[68:71], v[188:191], v[240:243], v[68:71]
	ds_read_b128 v[232:235], v128 offset:33792
	v_mfma_f32_16x16x32_bf16 v[72:75], v[192:195], v[236:239], v[72:75]
	v_mfma_f32_16x16x32_bf16 v[76:79], v[192:195], v[240:243], v[76:79]
	v_mfma_f32_16x16x32_bf16 v[48:51], v[220:223], v[236:239], v[48:51]
	v_mfma_f32_16x16x32_bf16 v[52:55], v[220:223], v[240:243], v[52:55]
	v_mfma_f32_16x16x32_bf16 v[56:59], v[224:227], v[236:239], v[56:59]
	v_mfma_f32_16x16x32_bf16 v[60:63], v[224:227], v[240:243], v[60:63]
	s_waitcnt lgkmcnt(2)
	v_mfma_f32_16x16x32_bf16 v[16:19], v[188:191], v[244:247], v[16:19]
	ds_read_b128 v[236:239], v128 offset:36864
	v_mfma_f32_16x16x32_bf16 v[20:23], v[188:191], v[248:251], v[20:23]
	ds_read_b128 v[240:243], v128 offset:37888
	v_mfma_f32_16x16x32_bf16 v[24:27], v[192:195], v[244:247], v[24:27]
	v_mfma_f32_16x16x32_bf16 v[28:31], v[192:195], v[248:251], v[28:31]
	v_mfma_f32_16x16x32_bf16 v[0:3], v[220:223], v[244:247], v[0:3]
	v_mfma_f32_16x16x32_bf16 v[4:7], v[220:223], v[248:251], v[4:7]
	v_mfma_f32_16x16x32_bf16 v[8:11], v[224:227], v[244:247], v[8:11]
	v_mfma_f32_16x16x32_bf16 v[12:15], v[224:227], v[248:251], v[12:15]
	s_waitcnt lgkmcnt(0)
	s_waitcnt vmcnt(6)
	s_barrier
	ds_read_b128 v[172:175], v130 offset:49152
	ds_read_b128 v[176:179], v130 offset:50176
	v_mfma_f32_16x16x32_bf16 v[80:83], v[188:191], v[228:231], v[80:83]
	ds_read_b128 v[180:183], v130 offset:51200
	ds_read_b128 v[184:187], v130 offset:52224
	v_mfma_f32_16x16x32_bf16 v[84:87], v[188:191], v[232:235], v[84:87]
	ds_read_b128 v[244:247], v128 offset:49152
	ds_read_b128 v[248:251], v128 offset:50176
	s_add_u32 m0, s76, 0x6000
	v_mfma_f32_16x16x32_bf16 v[88:91], v[192:195], v[228:231], v[88:91]
	global_load_lds_dwordx4 v132, s[72:73]
	s_add_u32 m0, s76, 0x7000
	v_mfma_f32_16x16x32_bf16 v[92:95], v[192:195], v[232:235], v[92:95]
	global_load_lds_dwordx4 v133, s[72:73]
	s_add_u32 m0, s76, 0x8000
	v_mfma_f32_16x16x32_bf16 v[112:115], v[220:223], v[228:231], v[112:115]
	global_load_lds_dwordx4 v134, s[72:73]
	v_mfma_f32_16x16x32_bf16 v[116:119], v[220:223], v[232:235], v[116:119]
	v_mfma_f32_16x16x32_bf16 v[120:123], v[224:227], v[228:231], v[120:123]
	v_mfma_f32_16x16x32_bf16 v[124:127], v[224:227], v[232:235], v[124:127]
	ds_read_b128 v[228:231], v128 offset:53248
	ds_read_b128 v[232:235], v128 offset:54272
	v_mfma_f32_16x16x32_bf16 v[32:35], v[188:191], v[236:239], v[32:35]
	s_add_u32 m0, s76, 0x9000
	v_mfma_f32_16x16x32_bf16 v[36:39], v[188:191], v[240:243], v[36:39]
	global_load_lds_dwordx4 v135, s[72:73]
	s_add_u32 m0, s76, 0xa000
	v_mfma_f32_16x16x32_bf16 v[40:43], v[192:195], v[236:239], v[40:43]
	global_load_lds_dwordx4 v132, s[74:75]
	s_add_u32 m0, s76, 0xb000
	v_mfma_f32_16x16x32_bf16 v[44:47], v[192:195], v[240:243], v[44:47]
	global_load_lds_dwordx4 v133, s[74:75]
	s_add_u32 s72, s72, 0x202000
	s_addc_u32 s73, s73, 0
	v_mfma_f32_16x16x32_bf16 v[96:99], v[220:223], v[236:239], v[96:99]
	s_add_u32 s74, s74, 0x2c000
	s_addc_u32 s75, s75, 0
	v_mfma_f32_16x16x32_bf16 v[100:103], v[220:223], v[240:243], v[100:103]
	v_mfma_f32_16x16x32_bf16 v[104:107], v[224:227], v[236:239], v[104:107]
	v_mfma_f32_16x16x32_bf16 v[108:111], v[224:227], v[240:243], v[108:111]
	s_waitcnt lgkmcnt(2)
	v_mfma_f32_16x16x32_bf16 v[64:67], v[172:175], v[244:247], v[64:67]
	ds_read_b128 v[236:239], v128 offset:57344
	v_mfma_f32_16x16x32_bf16 v[68:71], v[172:175], v[248:251], v[68:71]
	ds_read_b128 v[240:243], v128 offset:58368
	v_mfma_f32_16x16x32_bf16 v[72:75], v[176:179], v[244:247], v[72:75]
	v_mfma_f32_16x16x32_bf16 v[76:79], v[176:179], v[248:251], v[76:79]
	v_mfma_f32_16x16x32_bf16 v[48:51], v[180:183], v[244:247], v[48:51]
	v_mfma_f32_16x16x32_bf16 v[52:55], v[180:183], v[248:251], v[52:55]
	v_mfma_f32_16x16x32_bf16 v[56:59], v[184:187], v[244:247], v[56:59]
	v_mfma_f32_16x16x32_bf16 v[60:63], v[184:187], v[248:251], v[60:63]
	s_waitcnt lgkmcnt(2)
	v_mfma_f32_16x16x32_bf16 v[16:19], v[172:175], v[228:231], v[16:19]
	ds_read_b128 v[244:247], v128 offset:61440
	v_mfma_f32_16x16x32_bf16 v[20:23], v[172:175], v[232:235], v[20:23]
	ds_read_b128 v[248:251], v128 offset:62464
	v_mfma_f32_16x16x32_bf16 v[24:27], v[176:179], v[228:231], v[24:27]
	v_mfma_f32_16x16x32_bf16 v[28:31], v[176:179], v[232:235], v[28:31]
	v_mfma_f32_16x16x32_bf16 v[0:3], v[180:183], v[228:231], v[0:3]
	v_mfma_f32_16x16x32_bf16 v[4:7], v[180:183], v[232:235], v[4:7]
	v_mfma_f32_16x16x32_bf16 v[8:11], v[184:187], v[228:231], v[8:11]
	v_mfma_f32_16x16x32_bf16 v[12:15], v[184:187], v[232:235], v[12:15]
	s_waitcnt lgkmcnt(0)
	s_waitcnt vmcnt(6)
	s_barrier
	ds_read_b128 v[188:191], v130
	ds_read_b128 v[192:195], v130 offset:1024
	v_mfma_f32_16x16x32_bf16 v[80:83], v[172:175], v[236:239], v[80:83]
	ds_read_b128 v[220:223], v130 offset:2048
	ds_read_b128 v[224:227], v130 offset:3072
	v_mfma_f32_16x16x32_bf16 v[84:87], v[172:175], v[240:243], v[84:87]
	ds_read_b128 v[228:231], v128
	ds_read_b128 v[232:235], v128 offset:1024
	s_add_u32 m0, s76, 0xc000
	v_mfma_f32_16x16x32_bf16 v[88:91], v[176:179], v[236:239], v[88:91]
	global_load_lds_dwordx4 v132, s[72:73]
	s_add_u32 m0, s76, 0xd000
	v_mfma_f32_16x16x32_bf16 v[92:95], v[176:179], v[240:243], v[92:95]
	global_load_lds_dwordx4 v133, s[72:73]
	s_add_u32 m0, s76, 0xe000
	v_mfma_f32_16x16x32_bf16 v[112:115], v[180:183], v[236:239], v[112:115]
	global_load_lds_dwordx4 v134, s[72:73]
	v_mfma_f32_16x16x32_bf16 v[116:119], v[180:183], v[240:243], v[116:119]
	v_mfma_f32_16x16x32_bf16 v[120:123], v[184:187], v[236:239], v[120:123]
	v_mfma_f32_16x16x32_bf16 v[124:127], v[184:187], v[240:243], v[124:127]
	ds_read_b128 v[236:239], v128 offset:4096
	ds_read_b128 v[240:243], v128 offset:5120
	v_mfma_f32_16x16x32_bf16 v[32:35], v[172:175], v[244:247], v[32:35]
	s_add_u32 m0, s76, 0xf000
	v_mfma_f32_16x16x32_bf16 v[36:39], v[172:175], v[248:251], v[36:39]
	global_load_lds_dwordx4 v135, s[72:73]
	s_add_u32 m0, s76, 0x10000
	v_mfma_f32_16x16x32_bf16 v[40:43], v[176:179], v[244:247], v[40:43]
	global_load_lds_dwordx4 v132, s[74:75]
	s_add_u32 m0, s76, 0x11000
	v_mfma_f32_16x16x32_bf16 v[44:47], v[176:179], v[248:251], v[44:47]
	global_load_lds_dwordx4 v133, s[74:75]
	s_add_u32 s72, s72, 0x202000
	s_addc_u32 s73, s73, 0
	v_mfma_f32_16x16x32_bf16 v[96:99], v[180:183], v[244:247], v[96:99]
	s_add_u32 s74, s74, 0x2c000
	s_addc_u32 s75, s75, 0
	v_mfma_f32_16x16x32_bf16 v[100:103], v[180:183], v[248:251], v[100:103]
	v_mfma_f32_16x16x32_bf16 v[104:107], v[184:187], v[244:247], v[104:107]
	v_mfma_f32_16x16x32_bf16 v[108:111], v[184:187], v[248:251], v[108:111]
	s_waitcnt lgkmcnt(2)
	v_mfma_f32_16x16x32_bf16 v[64:67], v[188:191], v[228:231], v[64:67]
	ds_read_b128 v[244:247], v128 offset:8192
	v_mfma_f32_16x16x32_bf16 v[68:71], v[188:191], v[232:235], v[68:71]
	ds_read_b128 v[248:251], v128 offset:9216
	v_mfma_f32_16x16x32_bf16 v[72:75], v[192:195], v[228:231], v[72:75]
	v_mfma_f32_16x16x32_bf16 v[76:79], v[192:195], v[232:235], v[76:79]
	v_mfma_f32_16x16x32_bf16 v[48:51], v[220:223], v[228:231], v[48:51]
	v_mfma_f32_16x16x32_bf16 v[52:55], v[220:223], v[232:235], v[52:55]
	v_mfma_f32_16x16x32_bf16 v[56:59], v[224:227], v[228:231], v[56:59]
	v_mfma_f32_16x16x32_bf16 v[60:63], v[224:227], v[232:235], v[60:63]
	s_waitcnt lgkmcnt(2)
	v_mfma_f32_16x16x32_bf16 v[16:19], v[188:191], v[236:239], v[16:19]
	ds_read_b128 v[228:231], v128 offset:12288
	v_mfma_f32_16x16x32_bf16 v[20:23], v[188:191], v[240:243], v[20:23]
	ds_read_b128 v[232:235], v128 offset:13312
	v_mfma_f32_16x16x32_bf16 v[24:27], v[192:195], v[236:239], v[24:27]
	v_mfma_f32_16x16x32_bf16 v[28:31], v[192:195], v[240:243], v[28:31]
	v_mfma_f32_16x16x32_bf16 v[0:3], v[220:223], v[236:239], v[0:3]
	v_mfma_f32_16x16x32_bf16 v[4:7], v[220:223], v[240:243], v[4:7]
	v_mfma_f32_16x16x32_bf16 v[8:11], v[224:227], v[236:239], v[8:11]
	v_mfma_f32_16x16x32_bf16 v[12:15], v[224:227], v[240:243], v[12:15]
	s_waitcnt lgkmcnt(0)
	s_waitcnt vmcnt(6)
	s_barrier
	ds_read_b128 v[172:175], v130 offset:24576
	ds_read_b128 v[176:179], v130 offset:25600
	v_mfma_f32_16x16x32_bf16 v[80:83], v[188:191], v[244:247], v[80:83]
	ds_read_b128 v[180:183], v130 offset:26624
	ds_read_b128 v[184:187], v130 offset:27648
	v_mfma_f32_16x16x32_bf16 v[84:87], v[188:191], v[248:251], v[84:87]
	ds_read_b128 v[236:239], v128 offset:24576
	ds_read_b128 v[240:243], v128 offset:25600
	s_add_u32 m0, s76, 0x0
	v_mfma_f32_16x16x32_bf16 v[88:91], v[192:195], v[244:247], v[88:91]
	global_load_lds_dwordx4 v132, s[72:73]
	s_add_u32 m0, s76, 0x1000
	v_mfma_f32_16x16x32_bf16 v[92:95], v[192:195], v[248:251], v[92:95]
	global_load_lds_dwordx4 v133, s[72:73]
	s_add_u32 m0, s76, 0x2000
	v_mfma_f32_16x16x32_bf16 v[112:115], v[220:223], v[244:247], v[112:115]
	global_load_lds_dwordx4 v134, s[72:73]
	v_mfma_f32_16x16x32_bf16 v[116:119], v[220:223], v[248:251], v[116:119]
	v_mfma_f32_16x16x32_bf16 v[120:123], v[224:227], v[244:247], v[120:123]
	v_mfma_f32_16x16x32_bf16 v[124:127], v[224:227], v[248:251], v[124:127]
	ds_read_b128 v[244:247], v128 offset:28672
	ds_read_b128 v[248:251], v128 offset:29696
	v_mfma_f32_16x16x32_bf16 v[32:35], v[188:191], v[228:231], v[32:35]
	s_add_u32 m0, s76, 0x3000
	v_mfma_f32_16x16x32_bf16 v[36:39], v[188:191], v[232:235], v[36:39]
	global_load_lds_dwordx4 v135, s[72:73]
	s_add_u32 m0, s76, 0x4000
	v_mfma_f32_16x16x32_bf16 v[40:43], v[192:195], v[228:231], v[40:43]
	global_load_lds_dwordx4 v132, s[74:75]
	s_add_u32 m0, s76, 0x5000
	v_mfma_f32_16x16x32_bf16 v[44:47], v[192:195], v[232:235], v[44:47]
	global_load_lds_dwordx4 v133, s[74:75]
	s_add_u32 s72, s72, 0x202000
	s_addc_u32 s73, s73, 0
	v_mfma_f32_16x16x32_bf16 v[96:99], v[220:223], v[228:231], v[96:99]
	s_add_u32 s74, s74, 0x2c000
	s_addc_u32 s75, s75, 0
	v_mfma_f32_16x16x32_bf16 v[100:103], v[220:223], v[232:235], v[100:103]
	v_mfma_f32_16x16x32_bf16 v[104:107], v[224:227], v[228:231], v[104:107]
	v_mfma_f32_16x16x32_bf16 v[108:111], v[224:227], v[232:235], v[108:111]
	s_waitcnt lgkmcnt(2)
	v_mfma_f32_16x16x32_bf16 v[64:67], v[172:175], v[236:239], v[64:67]
	ds_read_b128 v[228:231], v128 offset:32768
	v_mfma_f32_16x16x32_bf16 v[68:71], v[172:175], v[240:243], v[68:71]
	ds_read_b128 v[232:235], v128 offset:33792
	v_mfma_f32_16x16x32_bf16 v[72:75], v[176:179], v[236:239], v[72:75]
	v_mfma_f32_16x16x32_bf16 v[76:79], v[176:179], v[240:243], v[76:79]
	v_mfma_f32_16x16x32_bf16 v[48:51], v[180:183], v[236:239], v[48:51]
	v_mfma_f32_16x16x32_bf16 v[52:55], v[180:183], v[240:243], v[52:55]
	v_mfma_f32_16x16x32_bf16 v[56:59], v[184:187], v[236:239], v[56:59]
	v_mfma_f32_16x16x32_bf16 v[60:63], v[184:187], v[240:243], v[60:63]
	s_waitcnt lgkmcnt(2)
	v_mfma_f32_16x16x32_bf16 v[16:19], v[172:175], v[244:247], v[16:19]
	ds_read_b128 v[236:239], v128 offset:36864
	v_mfma_f32_16x16x32_bf16 v[20:23], v[172:175], v[248:251], v[20:23]
	ds_read_b128 v[240:243], v128 offset:37888
	v_mfma_f32_16x16x32_bf16 v[24:27], v[176:179], v[244:247], v[24:27]
	v_mfma_f32_16x16x32_bf16 v[28:31], v[176:179], v[248:251], v[28:31]
	v_mfma_f32_16x16x32_bf16 v[0:3], v[180:183], v[244:247], v[0:3]
	v_mfma_f32_16x16x32_bf16 v[4:7], v[180:183], v[248:251], v[4:7]
	v_mfma_f32_16x16x32_bf16 v[8:11], v[184:187], v[244:247], v[8:11]
	v_mfma_f32_16x16x32_bf16 v[12:15], v[184:187], v[248:251], v[12:15]
	s_waitcnt lgkmcnt(0)
	s_waitcnt vmcnt(6)
	s_barrier
	ds_read_b128 v[188:191], v130 offset:49152
	ds_read_b128 v[192:195], v130 offset:50176
	v_mfma_f32_16x16x32_bf16 v[80:83], v[172:175], v[228:231], v[80:83]
	ds_read_b128 v[220:223], v130 offset:51200
	ds_read_b128 v[224:227], v130 offset:52224
	v_mfma_f32_16x16x32_bf16 v[84:87], v[172:175], v[232:235], v[84:87]
	ds_read_b128 v[244:247], v128 offset:49152
	ds_read_b128 v[248:251], v128 offset:50176
	s_add_u32 m0, s76, 0x6000
	v_mfma_f32_16x16x32_bf16 v[88:91], v[176:179], v[228:231], v[88:91]
	global_load_lds_dwordx4 v132, s[72:73]
	s_add_u32 m0, s76, 0x7000
	v_mfma_f32_16x16x32_bf16 v[92:95], v[176:179], v[232:235], v[92:95]
	global_load_lds_dwordx4 v133, s[72:73]
	s_add_u32 m0, s76, 0x8000
	v_mfma_f32_16x16x32_bf16 v[112:115], v[180:183], v[228:231], v[112:115]
	global_load_lds_dwordx4 v134, s[72:73]
	v_mfma_f32_16x16x32_bf16 v[116:119], v[180:183], v[232:235], v[116:119]
	v_mfma_f32_16x16x32_bf16 v[120:123], v[184:187], v[228:231], v[120:123]
	v_mfma_f32_16x16x32_bf16 v[124:127], v[184:187], v[232:235], v[124:127]
	ds_read_b128 v[228:231], v128 offset:53248
	ds_read_b128 v[232:235], v128 offset:54272
	v_mfma_f32_16x16x32_bf16 v[32:35], v[172:175], v[236:239], v[32:35]
	s_add_u32 m0, s76, 0x9000
	v_mfma_f32_16x16x32_bf16 v[36:39], v[172:175], v[240:243], v[36:39]
	global_load_lds_dwordx4 v135, s[72:73]
	s_add_u32 m0, s76, 0xa000
	v_mfma_f32_16x16x32_bf16 v[40:43], v[176:179], v[236:239], v[40:43]
	global_load_lds_dwordx4 v132, s[74:75]
	s_add_u32 m0, s76, 0xb000
	v_mfma_f32_16x16x32_bf16 v[44:47], v[176:179], v[240:243], v[44:47]
	global_load_lds_dwordx4 v133, s[74:75]
	s_add_u32 s72, s72, 0x202000
	s_addc_u32 s73, s73, 0
	v_mfma_f32_16x16x32_bf16 v[96:99], v[180:183], v[236:239], v[96:99]
	s_add_u32 s74, s74, 0x2c000
	s_addc_u32 s75, s75, 0
	v_mfma_f32_16x16x32_bf16 v[100:103], v[180:183], v[240:243], v[100:103]
	v_mfma_f32_16x16x32_bf16 v[104:107], v[184:187], v[236:239], v[104:107]
	v_mfma_f32_16x16x32_bf16 v[108:111], v[184:187], v[240:243], v[108:111]
	s_waitcnt lgkmcnt(2)
	v_mfma_f32_16x16x32_bf16 v[64:67], v[188:191], v[244:247], v[64:67]
	ds_read_b128 v[236:239], v128 offset:57344
	v_mfma_f32_16x16x32_bf16 v[68:71], v[188:191], v[248:251], v[68:71]
	ds_read_b128 v[240:243], v128 offset:58368
	v_mfma_f32_16x16x32_bf16 v[72:75], v[192:195], v[244:247], v[72:75]
	v_mfma_f32_16x16x32_bf16 v[76:79], v[192:195], v[248:251], v[76:79]
	v_mfma_f32_16x16x32_bf16 v[48:51], v[220:223], v[244:247], v[48:51]
	v_mfma_f32_16x16x32_bf16 v[52:55], v[220:223], v[248:251], v[52:55]
	v_mfma_f32_16x16x32_bf16 v[56:59], v[224:227], v[244:247], v[56:59]
	v_mfma_f32_16x16x32_bf16 v[60:63], v[224:227], v[248:251], v[60:63]
	s_waitcnt lgkmcnt(2)
	v_mfma_f32_16x16x32_bf16 v[16:19], v[188:191], v[228:231], v[16:19]
	ds_read_b128 v[244:247], v128 offset:61440
	v_mfma_f32_16x16x32_bf16 v[20:23], v[188:191], v[232:235], v[20:23]
	ds_read_b128 v[248:251], v128 offset:62464
	v_mfma_f32_16x16x32_bf16 v[24:27], v[192:195], v[228:231], v[24:27]
	v_mfma_f32_16x16x32_bf16 v[28:31], v[192:195], v[232:235], v[28:31]
	v_mfma_f32_16x16x32_bf16 v[0:3], v[220:223], v[228:231], v[0:3]
	v_mfma_f32_16x16x32_bf16 v[4:7], v[220:223], v[232:235], v[4:7]
	v_mfma_f32_16x16x32_bf16 v[8:11], v[224:227], v[228:231], v[8:11]
	v_mfma_f32_16x16x32_bf16 v[12:15], v[224:227], v[232:235], v[12:15]
	s_waitcnt lgkmcnt(0)
	s_waitcnt vmcnt(6)
	s_barrier
	ds_read_b128 v[172:175], v130
	ds_read_b128 v[176:179], v130 offset:1024
	v_mfma_f32_16x16x32_bf16 v[80:83], v[188:191], v[236:239], v[80:83]
	ds_read_b128 v[180:183], v130 offset:2048
	ds_read_b128 v[184:187], v130 offset:3072
	v_mfma_f32_16x16x32_bf16 v[84:87], v[188:191], v[240:243], v[84:87]
	ds_read_b128 v[228:231], v128
	ds_read_b128 v[232:235], v128 offset:1024
	s_add_u32 m0, s76, 0xc000
	v_mfma_f32_16x16x32_bf16 v[88:91], v[192:195], v[236:239], v[88:91]
	global_load_lds_dwordx4 v132, s[72:73]
	s_add_u32 m0, s76, 0xd000
	v_mfma_f32_16x16x32_bf16 v[92:95], v[192:195], v[240:243], v[92:95]
	global_load_lds_dwordx4 v133, s[72:73]
	s_add_u32 m0, s76, 0xe000
	v_mfma_f32_16x16x32_bf16 v[112:115], v[220:223], v[236:239], v[112:115]
	global_load_lds_dwordx4 v134, s[72:73]
	v_mfma_f32_16x16x32_bf16 v[116:119], v[220:223], v[240:243], v[116:119]
	v_mfma_f32_16x16x32_bf16 v[120:123], v[224:227], v[236:239], v[120:123]
	v_mfma_f32_16x16x32_bf16 v[124:127], v[224:227], v[240:243], v[124:127]
	ds_read_b128 v[236:239], v128 offset:4096
	ds_read_b128 v[240:243], v128 offset:5120
	v_mfma_f32_16x16x32_bf16 v[32:35], v[188:191], v[244:247], v[32:35]
	s_add_u32 m0, s76, 0xf000
	v_mfma_f32_16x16x32_bf16 v[36:39], v[188:191], v[248:251], v[36:39]
	global_load_lds_dwordx4 v135, s[72:73]
	s_add_u32 m0, s76, 0x10000
	v_mfma_f32_16x16x32_bf16 v[40:43], v[192:195], v[244:247], v[40:43]
	global_load_lds_dwordx4 v132, s[74:75]
	s_add_u32 m0, s76, 0x11000
	v_mfma_f32_16x16x32_bf16 v[44:47], v[192:195], v[248:251], v[44:47]
	global_load_lds_dwordx4 v133, s[74:75]
	s_add_u32 s72, s72, 0x202000
	s_addc_u32 s73, s73, 0
	v_mfma_f32_16x16x32_bf16 v[96:99], v[220:223], v[244:247], v[96:99]
	s_add_u32 s74, s74, 0x2c000
	s_addc_u32 s75, s75, 0
	v_mfma_f32_16x16x32_bf16 v[100:103], v[220:223], v[248:251], v[100:103]
	v_mfma_f32_16x16x32_bf16 v[104:107], v[224:227], v[244:247], v[104:107]
	v_mfma_f32_16x16x32_bf16 v[108:111], v[224:227], v[248:251], v[108:111]
	s_mov_b32 s77, 3
.Lgemm_p1_loop:
	s_waitcnt lgkmcnt(2)
	v_mfma_f32_16x16x32_bf16 v[64:67], v[172:175], v[228:231], v[64:67]
	ds_read_b128 v[244:247], v128 offset:8192
	v_mfma_f32_16x16x32_bf16 v[68:71], v[172:175], v[232:235], v[68:71]
	ds_read_b128 v[248:251], v128 offset:9216
	v_mfma_f32_16x16x32_bf16 v[72:75], v[176:179], v[228:231], v[72:75]
	v_mfma_f32_16x16x32_bf16 v[76:79], v[176:179], v[232:235], v[76:79]
	v_mfma_f32_16x16x32_bf16 v[48:51], v[180:183], v[228:231], v[48:51]
	v_mfma_f32_16x16x32_bf16 v[52:55], v[180:183], v[232:235], v[52:55]
	v_mfma_f32_16x16x32_bf16 v[56:59], v[184:187], v[228:231], v[56:59]
	v_mfma_f32_16x16x32_bf16 v[60:63], v[184:187], v[232:235], v[60:63]
	s_waitcnt lgkmcnt(2)
	v_mfma_f32_16x16x32_bf16 v[16:19], v[172:175], v[236:239], v[16:19]
	ds_read_b128 v[228:231], v128 offset:12288
	v_mfma_f32_16x16x32_bf16 v[20:23], v[172:175], v[240:243], v[20:23]
	ds_read_b128 v[232:235], v128 offset:13312
	v_mfma_f32_16x16x32_bf16 v[24:27], v[176:179], v[236:239], v[24:27]
	v_mfma_f32_16x16x32_bf16 v[28:31], v[176:179], v[240:243], v[28:31]
	v_mfma_f32_16x16x32_bf16 v[0:3], v[180:183], v[236:239], v[0:3]
	v_mfma_f32_16x16x32_bf16 v[4:7], v[180:183], v[240:243], v[4:7]
	v_mfma_f32_16x16x32_bf16 v[8:11], v[184:187], v[236:239], v[8:11]
	v_mfma_f32_16x16x32_bf16 v[12:15], v[184:187], v[240:243], v[12:15]
	s_waitcnt lgkmcnt(0)
	s_waitcnt vmcnt(6)
	s_barrier
	ds_read_b128 v[188:191], v130 offset:24576
	ds_read_b128 v[192:195], v130 offset:25600
	v_mfma_f32_16x16x32_bf16 v[80:83], v[172:175], v[244:247], v[80:83]
	ds_read_b128 v[220:223], v130 offset:26624
	ds_read_b128 v[224:227], v130 offset:27648
	v_mfma_f32_16x16x32_bf16 v[84:87], v[172:175], v[248:251], v[84:87]
	ds_read_b128 v[236:239], v128 offset:24576
	ds_read_b128 v[240:243], v128 offset:25600
	s_add_u32 m0, s76, 0x0
	v_mfma_f32_16x16x32_bf16 v[88:91], v[176:179], v[244:247], v[88:91]
	global_load_lds_dwordx4 v132, s[72:73]
	s_add_u32 m0, s76, 0x1000
	v_mfma_f32_16x16x32_bf16 v[92:95], v[176:179], v[248:251], v[92:95]
	global_load_lds_dwordx4 v133, s[72:73]
	s_add_u32 m0, s76, 0x2000
	v_mfma_f32_16x16x32_bf16 v[112:115], v[180:183], v[244:247], v[112:115]
	global_load_lds_dwordx4 v134, s[72:73]
	v_mfma_f32_16x16x32_bf16 v[116:119], v[180:183], v[248:251], v[116:119]
	v_mfma_f32_16x16x32_bf16 v[120:123], v[184:187], v[244:247], v[120:123]
	v_mfma_f32_16x16x32_bf16 v[124:127], v[184:187], v[248:251], v[124:127]
	ds_read_b128 v[244:247], v128 offset:28672
	ds_read_b128 v[248:251], v128 offset:29696
	v_mfma_f32_16x16x32_bf16 v[32:35], v[172:175], v[228:231], v[32:35]
	s_add_u32 m0, s76, 0x3000
	v_mfma_f32_16x16x32_bf16 v[36:39], v[172:175], v[232:235], v[36:39]
	global_load_lds_dwordx4 v135, s[72:73]
	s_add_u32 m0, s76, 0x4000
	v_mfma_f32_16x16x32_bf16 v[40:43], v[176:179], v[228:231], v[40:43]
	global_load_lds_dwordx4 v132, s[74:75]
	s_add_u32 m0, s76, 0x5000
	v_mfma_f32_16x16x32_bf16 v[44:47], v[176:179], v[232:235], v[44:47]
	global_load_lds_dwordx4 v133, s[74:75]
	s_add_u32 s72, s72, 0x202000
	s_addc_u32 s73, s73, 0
	v_mfma_f32_16x16x32_bf16 v[96:99], v[180:183], v[228:231], v[96:99]
	s_add_u32 s74, s74, 0x2c000
	s_addc_u32 s75, s75, 0
	v_mfma_f32_16x16x32_bf16 v[100:103], v[180:183], v[232:235], v[100:103]
	v_mfma_f32_16x16x32_bf16 v[104:107], v[184:187], v[228:231], v[104:107]
	v_mfma_f32_16x16x32_bf16 v[108:111], v[184:187], v[232:235], v[108:111]
	s_waitcnt lgkmcnt(2)
	v_mfma_f32_16x16x32_bf16 v[64:67], v[188:191], v[236:239], v[64:67]
	ds_read_b128 v[228:231], v128 offset:32768
	v_mfma_f32_16x16x32_bf16 v[68:71], v[188:191], v[240:243], v[68:71]
	ds_read_b128 v[232:235], v128 offset:33792
	v_mfma_f32_16x16x32_bf16 v[72:75], v[192:195], v[236:239], v[72:75]
	v_mfma_f32_16x16x32_bf16 v[76:79], v[192:195], v[240:243], v[76:79]
	v_mfma_f32_16x16x32_bf16 v[48:51], v[220:223], v[236:239], v[48:51]
	v_mfma_f32_16x16x32_bf16 v[52:55], v[220:223], v[240:243], v[52:55]
	v_mfma_f32_16x16x32_bf16 v[56:59], v[224:227], v[236:239], v[56:59]
	v_mfma_f32_16x16x32_bf16 v[60:63], v[224:227], v[240:243], v[60:63]
	s_waitcnt lgkmcnt(2)
	v_mfma_f32_16x16x32_bf16 v[16:19], v[188:191], v[244:247], v[16:19]
	ds_read_b128 v[236:239], v128 offset:36864
	v_mfma_f32_16x16x32_bf16 v[20:23], v[188:191], v[248:251], v[20:23]
	ds_read_b128 v[240:243], v128 offset:37888
	v_mfma_f32_16x16x32_bf16 v[24:27], v[192:195], v[244:247], v[24:27]
	v_mfma_f32_16x16x32_bf16 v[28:31], v[192:195], v[248:251], v[28:31]
	v_mfma_f32_16x16x32_bf16 v[0:3], v[220:223], v[244:247], v[0:3]
	v_mfma_f32_16x16x32_bf16 v[4:7], v[220:223], v[248:251], v[4:7]
	v_mfma_f32_16x16x32_bf16 v[8:11], v[224:227], v[244:247], v[8:11]
	v_mfma_f32_16x16x32_bf16 v[12:15], v[224:227], v[248:251], v[12:15]
	s_waitcnt lgkmcnt(0)
	s_waitcnt vmcnt(6)
	s_barrier
	ds_read_b128 v[172:175], v130 offset:49152
	ds_read_b128 v[176:179], v130 offset:50176
	v_mfma_f32_16x16x32_bf16 v[80:83], v[188:191], v[228:231], v[80:83]
	ds_read_b128 v[180:183], v130 offset:51200
	ds_read_b128 v[184:187], v130 offset:52224
	v_mfma_f32_16x16x32_bf16 v[84:87], v[188:191], v[232:235], v[84:87]
	ds_read_b128 v[244:247], v128 offset:49152
	ds_read_b128 v[248:251], v128 offset:50176
	s_add_u32 m0, s76, 0x6000
	v_mfma_f32_16x16x32_bf16 v[88:91], v[192:195], v[228:231], v[88:91]
	global_load_lds_dwordx4 v132, s[72:73]
	s_add_u32 m0, s76, 0x7000
	v_mfma_f32_16x16x32_bf16 v[92:95], v[192:195], v[232:235], v[92:95]
	global_load_lds_dwordx4 v133, s[72:73]
	s_add_u32 m0, s76, 0x8000
	v_mfma_f32_16x16x32_bf16 v[112:115], v[220:223], v[228:231], v[112:115]
	global_load_lds_dwordx4 v134, s[72:73]
	v_mfma_f32_16x16x32_bf16 v[116:119], v[220:223], v[232:235], v[116:119]
	v_mfma_f32_16x16x32_bf16 v[120:123], v[224:227], v[228:231], v[120:123]
	v_mfma_f32_16x16x32_bf16 v[124:127], v[224:227], v[232:235], v[124:127]
	ds_read_b128 v[228:231], v128 offset:53248
	ds_read_b128 v[232:235], v128 offset:54272
	v_mfma_f32_16x16x32_bf16 v[32:35], v[188:191], v[236:239], v[32:35]
	s_add_u32 m0, s76, 0x9000
	v_mfma_f32_16x16x32_bf16 v[36:39], v[188:191], v[240:243], v[36:39]
	global_load_lds_dwordx4 v135, s[72:73]
	s_add_u32 m0, s76, 0xa000
	v_mfma_f32_16x16x32_bf16 v[40:43], v[192:195], v[236:239], v[40:43]
	global_load_lds_dwordx4 v132, s[74:75]
	s_add_u32 m0, s76, 0xb000
	v_mfma_f32_16x16x32_bf16 v[44:47], v[192:195], v[240:243], v[44:47]
	global_load_lds_dwordx4 v133, s[74:75]
	s_add_u32 s72, s72, 0x202000
	s_addc_u32 s73, s73, 0
	v_mfma_f32_16x16x32_bf16 v[96:99], v[220:223], v[236:239], v[96:99]
	s_add_u32 s74, s74, 0x2c000
	s_addc_u32 s75, s75, 0
	v_mfma_f32_16x16x32_bf16 v[100:103], v[220:223], v[240:243], v[100:103]
	v_mfma_f32_16x16x32_bf16 v[104:107], v[224:227], v[236:239], v[104:107]
	v_mfma_f32_16x16x32_bf16 v[108:111], v[224:227], v[240:243], v[108:111]
	s_waitcnt lgkmcnt(2)
	v_mfma_f32_16x16x32_bf16 v[64:67], v[172:175], v[244:247], v[64:67]
	ds_read_b128 v[236:239], v128 offset:57344
	v_mfma_f32_16x16x32_bf16 v[68:71], v[172:175], v[248:251], v[68:71]
	ds_read_b128 v[240:243], v128 offset:58368
	v_mfma_f32_16x16x32_bf16 v[72:75], v[176:179], v[244:247], v[72:75]
	v_mfma_f32_16x16x32_bf16 v[76:79], v[176:179], v[248:251], v[76:79]
	v_mfma_f32_16x16x32_bf16 v[48:51], v[180:183], v[244:247], v[48:51]
	v_mfma_f32_16x16x32_bf16 v[52:55], v[180:183], v[248:251], v[52:55]
	v_mfma_f32_16x16x32_bf16 v[56:59], v[184:187], v[244:247], v[56:59]
	v_mfma_f32_16x16x32_bf16 v[60:63], v[184:187], v[248:251], v[60:63]
	s_waitcnt lgkmcnt(2)
	v_mfma_f32_16x16x32_bf16 v[16:19], v[172:175], v[228:231], v[16:19]
	ds_read_b128 v[244:247], v128 offset:61440
	v_mfma_f32_16x16x32_bf16 v[20:23], v[172:175], v[232:235], v[20:23]
	ds_read_b128 v[248:251], v128 offset:62464
	v_mfma_f32_16x16x32_bf16 v[24:27], v[176:179], v[228:231], v[24:27]
	v_mfma_f32_16x16x32_bf16 v[28:31], v[176:179], v[232:235], v[28:31]
	v_mfma_f32_16x16x32_bf16 v[0:3], v[180:183], v[228:231], v[0:3]
	v_mfma_f32_16x16x32_bf16 v[4:7], v[180:183], v[232:235], v[4:7]
	v_mfma_f32_16x16x32_bf16 v[8:11], v[184:187], v[228:231], v[8:11]
	v_mfma_f32_16x16x32_bf16 v[12:15], v[184:187], v[232:235], v[12:15]
	s_waitcnt lgkmcnt(0)
	s_waitcnt vmcnt(6)
	s_barrier
	ds_read_b128 v[188:191], v130
	ds_read_b128 v[192:195], v130 offset:1024
	v_mfma_f32_16x16x32_bf16 v[80:83], v[172:175], v[236:239], v[80:83]
	ds_read_b128 v[220:223], v130 offset:2048
	ds_read_b128 v[224:227], v130 offset:3072
	v_mfma_f32_16x16x32_bf16 v[84:87], v[172:175], v[240:243], v[84:87]
	ds_read_b128 v[228:231], v128
	ds_read_b128 v[232:235], v128 offset:1024
	s_add_u32 m0, s76, 0xc000
	v_mfma_f32_16x16x32_bf16 v[88:91], v[176:179], v[236:239], v[88:91]
	global_load_lds_dwordx4 v132, s[72:73]
	s_add_u32 m0, s76, 0xd000
	v_mfma_f32_16x16x32_bf16 v[92:95], v[176:179], v[240:243], v[92:95]
	global_load_lds_dwordx4 v133, s[72:73]
	s_add_u32 m0, s76, 0xe000
	v_mfma_f32_16x16x32_bf16 v[112:115], v[180:183], v[236:239], v[112:115]
	global_load_lds_dwordx4 v134, s[72:73]
	v_mfma_f32_16x16x32_bf16 v[116:119], v[180:183], v[240:243], v[116:119]
	v_mfma_f32_16x16x32_bf16 v[120:123], v[184:187], v[236:239], v[120:123]
	v_mfma_f32_16x16x32_bf16 v[124:127], v[184:187], v[240:243], v[124:127]
	ds_read_b128 v[236:239], v128 offset:4096
	ds_read_b128 v[240:243], v128 offset:5120
	v_mfma_f32_16x16x32_bf16 v[32:35], v[172:175], v[244:247], v[32:35]
	s_add_u32 m0, s76, 0xf000
	v_mfma_f32_16x16x32_bf16 v[36:39], v[172:175], v[248:251], v[36:39]
	global_load_lds_dwordx4 v135, s[72:73]
	s_add_u32 m0, s76, 0x10000
	v_mfma_f32_16x16x32_bf16 v[40:43], v[176:179], v[244:247], v[40:43]
	global_load_lds_dwordx4 v132, s[74:75]
	s_add_u32 m0, s76, 0x11000
	v_mfma_f32_16x16x32_bf16 v[44:47], v[176:179], v[248:251], v[44:47]
	global_load_lds_dwordx4 v133, s[74:75]
	s_add_u32 s72, s72, 0x202000
	s_addc_u32 s73, s73, 0
	v_mfma_f32_16x16x32_bf16 v[96:99], v[180:183], v[244:247], v[96:99]
	s_add_u32 s74, s74, 0x2c000
	s_addc_u32 s75, s75, 0
	v_mfma_f32_16x16x32_bf16 v[100:103], v[180:183], v[248:251], v[100:103]
	v_mfma_f32_16x16x32_bf16 v[104:107], v[184:187], v[244:247], v[104:107]
	v_mfma_f32_16x16x32_bf16 v[108:111], v[184:187], v[248:251], v[108:111]
	s_waitcnt lgkmcnt(2)
	v_mfma_f32_16x16x32_bf16 v[64:67], v[188:191], v[228:231], v[64:67]
	ds_read_b128 v[244:247], v128 offset:8192
	v_mfma_f32_16x16x32_bf16 v[68:71], v[188:191], v[232:235], v[68:71]
	ds_read_b128 v[248:251], v128 offset:9216
	v_mfma_f32_16x16x32_bf16 v[72:75], v[192:195], v[228:231], v[72:75]
	v_mfma_f32_16x16x32_bf16 v[76:79], v[192:195], v[232:235], v[76:79]
	v_mfma_f32_16x16x32_bf16 v[48:51], v[220:223], v[228:231], v[48:51]
	v_mfma_f32_16x16x32_bf16 v[52:55], v[220:223], v[232:235], v[52:55]
	v_mfma_f32_16x16x32_bf16 v[56:59], v[224:227], v[228:231], v[56:59]
	v_mfma_f32_16x16x32_bf16 v[60:63], v[224:227], v[232:235], v[60:63]
	s_waitcnt lgkmcnt(2)
	v_mfma_f32_16x16x32_bf16 v[16:19], v[188:191], v[236:239], v[16:19]
	ds_read_b128 v[228:231], v128 offset:12288
	v_mfma_f32_16x16x32_bf16 v[20:23], v[188:191], v[240:243], v[20:23]
	ds_read_b128 v[232:235], v128 offset:13312
	v_mfma_f32_16x16x32_bf16 v[24:27], v[192:195], v[236:239], v[24:27]
	v_mfma_f32_16x16x32_bf16 v[28:31], v[192:195], v[240:243], v[28:31]
	v_mfma_f32_16x16x32_bf16 v[0:3], v[220:223], v[236:239], v[0:3]
	v_mfma_f32_16x16x32_bf16 v[4:7], v[220:223], v[240:243], v[4:7]
	v_mfma_f32_16x16x32_bf16 v[8:11], v[224:227], v[236:239], v[8:11]
	v_mfma_f32_16x16x32_bf16 v[12:15], v[224:227], v[240:243], v[12:15]
	s_waitcnt lgkmcnt(0)
	s_waitcnt vmcnt(6)
	s_barrier
	ds_read_b128 v[172:175], v130 offset:24576
	ds_read_b128 v[176:179], v130 offset:25600
	v_mfma_f32_16x16x32_bf16 v[80:83], v[188:191], v[244:247], v[80:83]
	ds_read_b128 v[180:183], v130 offset:26624
	ds_read_b128 v[184:187], v130 offset:27648
	v_mfma_f32_16x16x32_bf16 v[84:87], v[188:191], v[248:251], v[84:87]
	ds_read_b128 v[236:239], v128 offset:24576
	ds_read_b128 v[240:243], v128 offset:25600
	s_add_u32 m0, s76, 0x0
	v_mfma_f32_16x16x32_bf16 v[88:91], v[192:195], v[244:247], v[88:91]
	global_load_lds_dwordx4 v132, s[72:73]
	s_add_u32 m0, s76, 0x1000
	v_mfma_f32_16x16x32_bf16 v[92:95], v[192:195], v[248:251], v[92:95]
	global_load_lds_dwordx4 v133, s[72:73]
	s_add_u32 m0, s76, 0x2000
	v_mfma_f32_16x16x32_bf16 v[112:115], v[220:223], v[244:247], v[112:115]
	global_load_lds_dwordx4 v134, s[72:73]
	v_mfma_f32_16x16x32_bf16 v[116:119], v[220:223], v[248:251], v[116:119]
	v_mfma_f32_16x16x32_bf16 v[120:123], v[224:227], v[244:247], v[120:123]
	v_mfma_f32_16x16x32_bf16 v[124:127], v[224:227], v[248:251], v[124:127]
	ds_read_b128 v[244:247], v128 offset:28672
	ds_read_b128 v[248:251], v128 offset:29696
	v_mfma_f32_16x16x32_bf16 v[32:35], v[188:191], v[228:231], v[32:35]
	s_add_u32 m0, s76, 0x3000
	v_mfma_f32_16x16x32_bf16 v[36:39], v[188:191], v[232:235], v[36:39]
	global_load_lds_dwordx4 v135, s[72:73]
	s_add_u32 m0, s76, 0x4000
	v_mfma_f32_16x16x32_bf16 v[40:43], v[192:195], v[228:231], v[40:43]
	global_load_lds_dwordx4 v132, s[74:75]
	s_add_u32 m0, s76, 0x5000
	v_mfma_f32_16x16x32_bf16 v[44:47], v[192:195], v[232:235], v[44:47]
	global_load_lds_dwordx4 v133, s[74:75]
	s_add_u32 s72, s72, 0x202000
	s_addc_u32 s73, s73, 0
	v_mfma_f32_16x16x32_bf16 v[96:99], v[220:223], v[228:231], v[96:99]
	s_add_u32 s74, s74, 0x2c000
	s_addc_u32 s75, s75, 0
	v_mfma_f32_16x16x32_bf16 v[100:103], v[220:223], v[232:235], v[100:103]
	v_mfma_f32_16x16x32_bf16 v[104:107], v[224:227], v[228:231], v[104:107]
	v_mfma_f32_16x16x32_bf16 v[108:111], v[224:227], v[232:235], v[108:111]
	s_waitcnt lgkmcnt(2)
	v_mfma_f32_16x16x32_bf16 v[64:67], v[172:175], v[236:239], v[64:67]
	ds_read_b128 v[228:231], v128 offset:32768
	v_mfma_f32_16x16x32_bf16 v[68:71], v[172:175], v[240:243], v[68:71]
	ds_read_b128 v[232:235], v128 offset:33792
	v_mfma_f32_16x16x32_bf16 v[72:75], v[176:179], v[236:239], v[72:75]
	v_mfma_f32_16x16x32_bf16 v[76:79], v[176:179], v[240:243], v[76:79]
	v_mfma_f32_16x16x32_bf16 v[48:51], v[180:183], v[236:239], v[48:51]
	v_mfma_f32_16x16x32_bf16 v[52:55], v[180:183], v[240:243], v[52:55]
	v_mfma_f32_16x16x32_bf16 v[56:59], v[184:187], v[236:239], v[56:59]
	v_mfma_f32_16x16x32_bf16 v[60:63], v[184:187], v[240:243], v[60:63]
	s_waitcnt lgkmcnt(2)
	v_mfma_f32_16x16x32_bf16 v[16:19], v[172:175], v[244:247], v[16:19]
	ds_read_b128 v[236:239], v128 offset:36864
	v_mfma_f32_16x16x32_bf16 v[20:23], v[172:175], v[248:251], v[20:23]
	ds_read_b128 v[240:243], v128 offset:37888
	v_mfma_f32_16x16x32_bf16 v[24:27], v[176:179], v[244:247], v[24:27]
	v_mfma_f32_16x16x32_bf16 v[28:31], v[176:179], v[248:251], v[28:31]
	v_mfma_f32_16x16x32_bf16 v[0:3], v[180:183], v[244:247], v[0:3]
	v_mfma_f32_16x16x32_bf16 v[4:7], v[180:183], v[248:251], v[4:7]
	v_mfma_f32_16x16x32_bf16 v[8:11], v[184:187], v[244:247], v[8:11]
	v_mfma_f32_16x16x32_bf16 v[12:15], v[184:187], v[248:251], v[12:15]
	s_waitcnt lgkmcnt(0)
	s_waitcnt vmcnt(6)
	s_barrier
	ds_read_b128 v[188:191], v130 offset:49152
	ds_read_b128 v[192:195], v130 offset:50176
	v_mfma_f32_16x16x32_bf16 v[80:83], v[172:175], v[228:231], v[80:83]
	ds_read_b128 v[220:223], v130 offset:51200
	ds_read_b128 v[224:227], v130 offset:52224
	v_mfma_f32_16x16x32_bf16 v[84:87], v[172:175], v[232:235], v[84:87]
	ds_read_b128 v[244:247], v128 offset:49152
	ds_read_b128 v[248:251], v128 offset:50176
	s_add_u32 m0, s76, 0x6000
	v_mfma_f32_16x16x32_bf16 v[88:91], v[176:179], v[228:231], v[88:91]
	global_load_lds_dwordx4 v132, s[72:73]
	s_add_u32 m0, s76, 0x7000
	v_mfma_f32_16x16x32_bf16 v[92:95], v[176:179], v[232:235], v[92:95]
	global_load_lds_dwordx4 v133, s[72:73]
	s_add_u32 m0, s76, 0x8000
	v_mfma_f32_16x16x32_bf16 v[112:115], v[180:183], v[228:231], v[112:115]
	global_load_lds_dwordx4 v134, s[72:73]
	v_mfma_f32_16x16x32_bf16 v[116:119], v[180:183], v[232:235], v[116:119]
	v_mfma_f32_16x16x32_bf16 v[120:123], v[184:187], v[228:231], v[120:123]
	v_mfma_f32_16x16x32_bf16 v[124:127], v[184:187], v[232:235], v[124:127]
	ds_read_b128 v[228:231], v128 offset:53248
	ds_read_b128 v[232:235], v128 offset:54272
	v_mfma_f32_16x16x32_bf16 v[32:35], v[172:175], v[236:239], v[32:35]
	s_add_u32 m0, s76, 0x9000
	v_mfma_f32_16x16x32_bf16 v[36:39], v[172:175], v[240:243], v[36:39]
	global_load_lds_dwordx4 v135, s[72:73]
	s_add_u32 m0, s76, 0xa000
	v_mfma_f32_16x16x32_bf16 v[40:43], v[176:179], v[236:239], v[40:43]
	global_load_lds_dwordx4 v132, s[74:75]
	s_add_u32 m0, s76, 0xb000
	v_mfma_f32_16x16x32_bf16 v[44:47], v[176:179], v[240:243], v[44:47]
	global_load_lds_dwordx4 v133, s[74:75]
	s_add_u32 s72, s72, 0x202000
	s_addc_u32 s73, s73, 0
	v_mfma_f32_16x16x32_bf16 v[96:99], v[180:183], v[236:239], v[96:99]
	s_add_u32 s74, s74, 0x2c000
	s_addc_u32 s75, s75, 0
	v_mfma_f32_16x16x32_bf16 v[100:103], v[180:183], v[240:243], v[100:103]
	v_mfma_f32_16x16x32_bf16 v[104:107], v[184:187], v[236:239], v[104:107]
	v_mfma_f32_16x16x32_bf16 v[108:111], v[184:187], v[240:243], v[108:111]
	s_waitcnt lgkmcnt(2)
	v_mfma_f32_16x16x32_bf16 v[64:67], v[188:191], v[244:247], v[64:67]
	ds_read_b128 v[236:239], v128 offset:57344
	v_mfma_f32_16x16x32_bf16 v[68:71], v[188:191], v[248:251], v[68:71]
	ds_read_b128 v[240:243], v128 offset:58368
	v_mfma_f32_16x16x32_bf16 v[72:75], v[192:195], v[244:247], v[72:75]
	v_mfma_f32_16x16x32_bf16 v[76:79], v[192:195], v[248:251], v[76:79]
	v_mfma_f32_16x16x32_bf16 v[48:51], v[220:223], v[244:247], v[48:51]
	v_mfma_f32_16x16x32_bf16 v[52:55], v[220:223], v[248:251], v[52:55]
	v_mfma_f32_16x16x32_bf16 v[56:59], v[224:227], v[244:247], v[56:59]
	v_mfma_f32_16x16x32_bf16 v[60:63], v[224:227], v[248:251], v[60:63]
	s_waitcnt lgkmcnt(2)
	v_mfma_f32_16x16x32_bf16 v[16:19], v[188:191], v[228:231], v[16:19]
	ds_read_b128 v[244:247], v128 offset:61440
	v_mfma_f32_16x16x32_bf16 v[20:23], v[188:191], v[232:235], v[20:23]
	ds_read_b128 v[248:251], v128 offset:62464
	v_mfma_f32_16x16x32_bf16 v[24:27], v[192:195], v[228:231], v[24:27]
	v_mfma_f32_16x16x32_bf16 v[28:31], v[192:195], v[232:235], v[28:31]
	v_mfma_f32_16x16x32_bf16 v[0:3], v[220:223], v[228:231], v[0:3]
	v_mfma_f32_16x16x32_bf16 v[4:7], v[220:223], v[232:235], v[4:7]
	v_mfma_f32_16x16x32_bf16 v[8:11], v[224:227], v[228:231], v[8:11]
	v_mfma_f32_16x16x32_bf16 v[12:15], v[224:227], v[232:235], v[12:15]
	s_waitcnt lgkmcnt(0)
	s_waitcnt vmcnt(6)
	s_barrier
	ds_read_b128 v[172:175], v130
	ds_read_b128 v[176:179], v130 offset:1024
	v_mfma_f32_16x16x32_bf16 v[80:83], v[188:191], v[236:239], v[80:83]
	ds_read_b128 v[180:183], v130 offset:2048
	ds_read_b128 v[184:187], v130 offset:3072
	v_mfma_f32_16x16x32_bf16 v[84:87], v[188:191], v[240:243], v[84:87]
	ds_read_b128 v[228:231], v128
	ds_read_b128 v[232:235], v128 offset:1024
	s_add_u32 m0, s76, 0xc000
	v_mfma_f32_16x16x32_bf16 v[88:91], v[192:195], v[236:239], v[88:91]
	global_load_lds_dwordx4 v132, s[72:73]
	s_add_u32 m0, s76, 0xd000
	v_mfma_f32_16x16x32_bf16 v[92:95], v[192:195], v[240:243], v[92:95]
	global_load_lds_dwordx4 v133, s[72:73]
	s_add_u32 m0, s76, 0xe000
	v_mfma_f32_16x16x32_bf16 v[112:115], v[220:223], v[236:239], v[112:115]
	global_load_lds_dwordx4 v134, s[72:73]
	v_mfma_f32_16x16x32_bf16 v[116:119], v[220:223], v[240:243], v[116:119]
	v_mfma_f32_16x16x32_bf16 v[120:123], v[224:227], v[236:239], v[120:123]
	v_mfma_f32_16x16x32_bf16 v[124:127], v[224:227], v[240:243], v[124:127]
	ds_read_b128 v[236:239], v128 offset:4096
	ds_read_b128 v[240:243], v128 offset:5120
	v_mfma_f32_16x16x32_bf16 v[32:35], v[188:191], v[244:247], v[32:35]
	s_add_u32 m0, s76, 0xf000
	v_mfma_f32_16x16x32_bf16 v[36:39], v[188:191], v[248:251], v[36:39]
	global_load_lds_dwordx4 v135, s[72:73]
	s_add_u32 m0, s76, 0x10000
	v_mfma_f32_16x16x32_bf16 v[40:43], v[192:195], v[244:247], v[40:43]
	global_load_lds_dwordx4 v132, s[74:75]
	s_add_u32 m0, s76, 0x11000
	v_mfma_f32_16x16x32_bf16 v[44:47], v[192:195], v[248:251], v[44:47]
	global_load_lds_dwordx4 v133, s[74:75]
	s_add_u32 s72, s72, 0x202000
	s_addc_u32 s73, s73, 0
	v_mfma_f32_16x16x32_bf16 v[96:99], v[220:223], v[244:247], v[96:99]
	s_add_u32 s74, s74, 0x2c000
	s_addc_u32 s75, s75, 0
	v_mfma_f32_16x16x32_bf16 v[100:103], v[220:223], v[248:251], v[100:103]
	v_mfma_f32_16x16x32_bf16 v[104:107], v[224:227], v[244:247], v[104:107]
	v_mfma_f32_16x16x32_bf16 v[108:111], v[224:227], v[248:251], v[108:111]
	s_sub_i32 s77, s77, 1
	s_cmp_lg_u32 s77, 0
	s_cbranch_scc1 .Lgemm_p1_loop
	s_waitcnt lgkmcnt(2)
	v_mfma_f32_16x16x32_bf16 v[64:67], v[172:175], v[228:231], v[64:67]
	ds_read_b128 v[244:247], v128 offset:8192
	v_mfma_f32_16x16x32_bf16 v[68:71], v[172:175], v[232:235], v[68:71]
	ds_read_b128 v[248:251], v128 offset:9216
	v_mfma_f32_16x16x32_bf16 v[72:75], v[176:179], v[228:231], v[72:75]
	v_mfma_f32_16x16x32_bf16 v[76:79], v[176:179], v[232:235], v[76:79]
	v_mfma_f32_16x16x32_bf16 v[48:51], v[180:183], v[228:231], v[48:51]
	v_mfma_f32_16x16x32_bf16 v[52:55], v[180:183], v[232:235], v[52:55]
	v_mfma_f32_16x16x32_bf16 v[56:59], v[184:187], v[228:231], v[56:59]
	v_mfma_f32_16x16x32_bf16 v[60:63], v[184:187], v[232:235], v[60:63]
	s_waitcnt lgkmcnt(2)
	v_mfma_f32_16x16x32_bf16 v[16:19], v[172:175], v[236:239], v[16:19]
	ds_read_b128 v[228:231], v128 offset:12288
	v_mfma_f32_16x16x32_bf16 v[20:23], v[172:175], v[240:243], v[20:23]
	ds_read_b128 v[232:235], v128 offset:13312
	v_mfma_f32_16x16x32_bf16 v[24:27], v[176:179], v[236:239], v[24:27]
	v_mfma_f32_16x16x32_bf16 v[28:31], v[176:179], v[240:243], v[28:31]
	v_mfma_f32_16x16x32_bf16 v[0:3], v[180:183], v[236:239], v[0:3]
	v_mfma_f32_16x16x32_bf16 v[4:7], v[180:183], v[240:243], v[4:7]
	v_mfma_f32_16x16x32_bf16 v[8:11], v[184:187], v[236:239], v[8:11]
	v_mfma_f32_16x16x32_bf16 v[12:15], v[184:187], v[240:243], v[12:15]
	s_waitcnt lgkmcnt(0)
	s_waitcnt vmcnt(6)
	s_barrier
	ds_read_b128 v[188:191], v130 offset:24576
	ds_read_b128 v[192:195], v130 offset:25600
	v_mfma_f32_16x16x32_bf16 v[80:83], v[172:175], v[244:247], v[80:83]
	ds_read_b128 v[220:223], v130 offset:26624
	ds_read_b128 v[224:227], v130 offset:27648
	v_mfma_f32_16x16x32_bf16 v[84:87], v[172:175], v[248:251], v[84:87]
	ds_read_b128 v[236:239], v128 offset:24576
	ds_read_b128 v[240:243], v128 offset:25600
	s_add_u32 m0, s76, 0x0
	v_mfma_f32_16x16x32_bf16 v[88:91], v[176:179], v[244:247], v[88:91]
	global_load_lds_dwordx4 v132, s[72:73]
	s_add_u32 m0, s76, 0x1000
	v_mfma_f32_16x16x32_bf16 v[92:95], v[176:179], v[248:251], v[92:95]
	global_load_lds_dwordx4 v133, s[72:73]
	s_add_u32 m0, s76, 0x2000
	v_mfma_f32_16x16x32_bf16 v[112:115], v[180:183], v[244:247], v[112:115]
	global_load_lds_dwordx4 v134, s[72:73]
	v_mfma_f32_16x16x32_bf16 v[116:119], v[180:183], v[248:251], v[116:119]
	v_mfma_f32_16x16x32_bf16 v[120:123], v[184:187], v[244:247], v[120:123]
	v_mfma_f32_16x16x32_bf16 v[124:127], v[184:187], v[248:251], v[124:127]
	ds_read_b128 v[244:247], v128 offset:28672
	ds_read_b128 v[248:251], v128 offset:29696
	v_mfma_f32_16x16x32_bf16 v[32:35], v[172:175], v[228:231], v[32:35]
	s_add_u32 m0, s76, 0x3000
	v_mfma_f32_16x16x32_bf16 v[36:39], v[172:175], v[232:235], v[36:39]
	global_load_lds_dwordx4 v135, s[72:73]
	s_add_u32 m0, s76, 0x4000
	v_mfma_f32_16x16x32_bf16 v[40:43], v[176:179], v[228:231], v[40:43]
	global_load_lds_dwordx4 v132, s[74:75]
	s_add_u32 m0, s76, 0x5000
	v_mfma_f32_16x16x32_bf16 v[44:47], v[176:179], v[232:235], v[44:47]
	global_load_lds_dwordx4 v133, s[74:75]
	s_add_u32 s72, s72, 0x202000
	s_addc_u32 s73, s73, 0
	v_mfma_f32_16x16x32_bf16 v[96:99], v[180:183], v[228:231], v[96:99]
	s_add_u32 s74, s74, 0x2c000
	s_addc_u32 s75, s75, 0
	v_mfma_f32_16x16x32_bf16 v[100:103], v[180:183], v[232:235], v[100:103]
	v_mfma_f32_16x16x32_bf16 v[104:107], v[184:187], v[228:231], v[104:107]
	v_mfma_f32_16x16x32_bf16 v[108:111], v[184:187], v[232:235], v[108:111]
	s_waitcnt lgkmcnt(2)
	v_mfma_f32_16x16x32_bf16 v[64:67], v[188:191], v[236:239], v[64:67]
	ds_read_b128 v[228:231], v128 offset:32768
	v_mfma_f32_16x16x32_bf16 v[68:71], v[188:191], v[240:243], v[68:71]
	ds_read_b128 v[232:235], v128 offset:33792
	v_mfma_f32_16x16x32_bf16 v[72:75], v[192:195], v[236:239], v[72:75]
	v_mfma_f32_16x16x32_bf16 v[76:79], v[192:195], v[240:243], v[76:79]
	v_mfma_f32_16x16x32_bf16 v[48:51], v[220:223], v[236:239], v[48:51]
	v_mfma_f32_16x16x32_bf16 v[52:55], v[220:223], v[240:243], v[52:55]
	v_mfma_f32_16x16x32_bf16 v[56:59], v[224:227], v[236:239], v[56:59]
	v_mfma_f32_16x16x32_bf16 v[60:63], v[224:227], v[240:243], v[60:63]
	s_waitcnt lgkmcnt(2)
	v_mfma_f32_16x16x32_bf16 v[16:19], v[188:191], v[244:247], v[16:19]
	ds_read_b128 v[236:239], v128 offset:36864
	v_mfma_f32_16x16x32_bf16 v[20:23], v[188:191], v[248:251], v[20:23]
	ds_read_b128 v[240:243], v128 offset:37888
	v_mfma_f32_16x16x32_bf16 v[24:27], v[192:195], v[244:247], v[24:27]
	v_mfma_f32_16x16x32_bf16 v[28:31], v[192:195], v[248:251], v[28:31]
	v_mfma_f32_16x16x32_bf16 v[0:3], v[220:223], v[244:247], v[0:3]
	v_mfma_f32_16x16x32_bf16 v[4:7], v[220:223], v[248:251], v[4:7]
	v_mfma_f32_16x16x32_bf16 v[8:11], v[224:227], v[244:247], v[8:11]
	v_mfma_f32_16x16x32_bf16 v[12:15], v[224:227], v[248:251], v[12:15]
	s_waitcnt lgkmcnt(0)
	s_waitcnt vmcnt(6)
	s_barrier
	ds_read_b128 v[172:175], v130 offset:49152
	ds_read_b128 v[176:179], v130 offset:50176
	v_mfma_f32_16x16x32_bf16 v[80:83], v[188:191], v[228:231], v[80:83]
	ds_read_b128 v[180:183], v130 offset:51200
	ds_read_b128 v[184:187], v130 offset:52224
	v_mfma_f32_16x16x32_bf16 v[84:87], v[188:191], v[232:235], v[84:87]
	ds_read_b128 v[244:247], v128 offset:49152
	ds_read_b128 v[248:251], v128 offset:50176
	s_add_u32 m0, s76, 0x6000
	v_mfma_f32_16x16x32_bf16 v[88:91], v[192:195], v[228:231], v[88:91]
	global_load_lds_dwordx4 v132, s[72:73]
	s_add_u32 m0, s76, 0x7000
	v_mfma_f32_16x16x32_bf16 v[92:95], v[192:195], v[232:235], v[92:95]
	global_load_lds_dwordx4 v133, s[72:73]
	s_add_u32 m0, s76, 0x8000
	v_mfma_f32_16x16x32_bf16 v[112:115], v[220:223], v[228:231], v[112:115]
	global_load_lds_dwordx4 v134, s[72:73]
	v_mfma_f32_16x16x32_bf16 v[116:119], v[220:223], v[232:235], v[116:119]
	v_mfma_f32_16x16x32_bf16 v[120:123], v[224:227], v[228:231], v[120:123]
	v_mfma_f32_16x16x32_bf16 v[124:127], v[224:227], v[232:235], v[124:127]
	ds_read_b128 v[228:231], v128 offset:53248
	ds_read_b128 v[232:235], v128 offset:54272
	v_mfma_f32_16x16x32_bf16 v[32:35], v[188:191], v[236:239], v[32:35]
	s_add_u32 m0, s76, 0x9000
	v_mfma_f32_16x16x32_bf16 v[36:39], v[188:191], v[240:243], v[36:39]
	global_load_lds_dwordx4 v135, s[72:73]
	s_add_u32 m0, s76, 0xa000
	v_mfma_f32_16x16x32_bf16 v[40:43], v[192:195], v[236:239], v[40:43]
	global_load_lds_dwordx4 v132, s[74:75]
	s_add_u32 m0, s76, 0xb000
	v_mfma_f32_16x16x32_bf16 v[44:47], v[192:195], v[240:243], v[44:47]
	global_load_lds_dwordx4 v133, s[74:75]
	s_add_u32 s72, s72, 0x202000
	s_addc_u32 s73, s73, 0
	v_mfma_f32_16x16x32_bf16 v[96:99], v[220:223], v[236:239], v[96:99]
	s_add_u32 s74, s74, 0x2c000
	s_addc_u32 s75, s75, 0
	v_mfma_f32_16x16x32_bf16 v[100:103], v[220:223], v[240:243], v[100:103]
	v_mfma_f32_16x16x32_bf16 v[104:107], v[224:227], v[236:239], v[104:107]
	v_mfma_f32_16x16x32_bf16 v[108:111], v[224:227], v[240:243], v[108:111]
	s_waitcnt lgkmcnt(2)
	v_mfma_f32_16x16x32_bf16 v[64:67], v[172:175], v[244:247], v[64:67]
	ds_read_b128 v[236:239], v128 offset:57344
	v_mfma_f32_16x16x32_bf16 v[68:71], v[172:175], v[248:251], v[68:71]
	ds_read_b128 v[240:243], v128 offset:58368
	v_mfma_f32_16x16x32_bf16 v[72:75], v[176:179], v[244:247], v[72:75]
	v_mfma_f32_16x16x32_bf16 v[76:79], v[176:179], v[248:251], v[76:79]
	v_mfma_f32_16x16x32_bf16 v[48:51], v[180:183], v[244:247], v[48:51]
	v_mfma_f32_16x16x32_bf16 v[52:55], v[180:183], v[248:251], v[52:55]
	v_mfma_f32_16x16x32_bf16 v[56:59], v[184:187], v[244:247], v[56:59]
	v_mfma_f32_16x16x32_bf16 v[60:63], v[184:187], v[248:251], v[60:63]
	s_waitcnt lgkmcnt(2)
	v_mfma_f32_16x16x32_bf16 v[16:19], v[172:175], v[228:231], v[16:19]
	ds_read_b128 v[244:247], v128 offset:61440
	v_mfma_f32_16x16x32_bf16 v[20:23], v[172:175], v[232:235], v[20:23]
	ds_read_b128 v[248:251], v128 offset:62464
	v_mfma_f32_16x16x32_bf16 v[24:27], v[176:179], v[228:231], v[24:27]
	v_mfma_f32_16x16x32_bf16 v[28:31], v[176:179], v[232:235], v[28:31]
	v_mfma_f32_16x16x32_bf16 v[0:3], v[180:183], v[228:231], v[0:3]
	v_mfma_f32_16x16x32_bf16 v[4:7], v[180:183], v[232:235], v[4:7]
	v_mfma_f32_16x16x32_bf16 v[8:11], v[184:187], v[228:231], v[8:11]
	v_mfma_f32_16x16x32_bf16 v[12:15], v[184:187], v[232:235], v[12:15]
	s_waitcnt lgkmcnt(0)
	s_waitcnt vmcnt(6)
	s_barrier
	ds_read_b128 v[188:191], v130
	ds_read_b128 v[192:195], v130 offset:1024
	v_mfma_f32_16x16x32_bf16 v[80:83], v[172:175], v[236:239], v[80:83]
	ds_read_b128 v[220:223], v130 offset:2048
	ds_read_b128 v[224:227], v130 offset:3072
	v_mfma_f32_16x16x32_bf16 v[84:87], v[172:175], v[240:243], v[84:87]
	ds_read_b128 v[228:231], v128
	ds_read_b128 v[232:235], v128 offset:1024
	s_add_u32 m0, s76, 0xc000
	v_mfma_f32_16x16x32_bf16 v[88:91], v[176:179], v[236:239], v[88:91]
	global_load_lds_dwordx4 v132, s[72:73]
	s_add_u32 m0, s76, 0xd000
	v_mfma_f32_16x16x32_bf16 v[92:95], v[176:179], v[240:243], v[92:95]
	global_load_lds_dwordx4 v133, s[72:73]
	s_add_u32 m0, s76, 0xe000
	v_mfma_f32_16x16x32_bf16 v[112:115], v[180:183], v[236:239], v[112:115]
	global_load_lds_dwordx4 v134, s[72:73]
	v_mfma_f32_16x16x32_bf16 v[116:119], v[180:183], v[240:243], v[116:119]
	v_mfma_f32_16x16x32_bf16 v[120:123], v[184:187], v[236:239], v[120:123]
	v_mfma_f32_16x16x32_bf16 v[124:127], v[184:187], v[240:243], v[124:127]
	ds_read_b128 v[236:239], v128 offset:4096
	ds_read_b128 v[240:243], v128 offset:5120
	v_mfma_f32_16x16x32_bf16 v[32:35], v[172:175], v[244:247], v[32:35]
	s_add_u32 m0, s76, 0xf000
	v_mfma_f32_16x16x32_bf16 v[36:39], v[172:175], v[248:251], v[36:39]
	global_load_lds_dwordx4 v135, s[72:73]
	s_add_u32 m0, s76, 0x10000
	v_mfma_f32_16x16x32_bf16 v[40:43], v[176:179], v[244:247], v[40:43]
	global_load_lds_dwordx4 v132, s[74:75]
	s_add_u32 m0, s76, 0x11000
	v_mfma_f32_16x16x32_bf16 v[44:47], v[176:179], v[248:251], v[44:47]
	global_load_lds_dwordx4 v133, s[74:75]
	s_add_u32 s72, s72, 0x202000
	s_addc_u32 s73, s73, 0
	v_mfma_f32_16x16x32_bf16 v[96:99], v[180:183], v[244:247], v[96:99]
	s_add_u32 s74, s74, 0x2c000
	s_addc_u32 s75, s75, 0
	v_mfma_f32_16x16x32_bf16 v[100:103], v[180:183], v[248:251], v[100:103]
	v_mfma_f32_16x16x32_bf16 v[104:107], v[184:187], v[244:247], v[104:107]
	v_mfma_f32_16x16x32_bf16 v[108:111], v[184:187], v[248:251], v[108:111]
	s_waitcnt lgkmcnt(2)
	v_mfma_f32_16x16x32_bf16 v[64:67], v[188:191], v[228:231], v[64:67]
	ds_read_b128 v[244:247], v128 offset:8192
	v_mfma_f32_16x16x32_bf16 v[68:71], v[188:191], v[232:235], v[68:71]
	ds_read_b128 v[248:251], v128 offset:9216
	v_mfma_f32_16x16x32_bf16 v[72:75], v[192:195], v[228:231], v[72:75]
	v_mfma_f32_16x16x32_bf16 v[76:79], v[192:195], v[232:235], v[76:79]
	v_mfma_f32_16x16x32_bf16 v[48:51], v[220:223], v[228:231], v[48:51]
	v_mfma_f32_16x16x32_bf16 v[52:55], v[220:223], v[232:235], v[52:55]
	v_mfma_f32_16x16x32_bf16 v[56:59], v[224:227], v[228:231], v[56:59]
	v_mfma_f32_16x16x32_bf16 v[60:63], v[224:227], v[232:235], v[60:63]
	s_waitcnt lgkmcnt(2)
	v_mfma_f32_16x16x32_bf16 v[16:19], v[188:191], v[236:239], v[16:19]
	ds_read_b128 v[228:231], v128 offset:12288
	v_mfma_f32_16x16x32_bf16 v[20:23], v[188:191], v[240:243], v[20:23]
	ds_read_b128 v[232:235], v128 offset:13312
	v_mfma_f32_16x16x32_bf16 v[24:27], v[192:195], v[236:239], v[24:27]
	v_mfma_f32_16x16x32_bf16 v[28:31], v[192:195], v[240:243], v[28:31]
	v_mfma_f32_16x16x32_bf16 v[0:3], v[220:223], v[236:239], v[0:3]
	v_mfma_f32_16x16x32_bf16 v[4:7], v[220:223], v[240:243], v[4:7]
	v_mfma_f32_16x16x32_bf16 v[8:11], v[224:227], v[236:239], v[8:11]
	v_mfma_f32_16x16x32_bf16 v[12:15], v[224:227], v[240:243], v[12:15]
	s_waitcnt lgkmcnt(0)
	s_waitcnt vmcnt(6)
	s_barrier
	ds_read_b128 v[172:175], v130 offset:24576
	ds_read_b128 v[176:179], v130 offset:25600
	v_mfma_f32_16x16x32_bf16 v[80:83], v[188:191], v[244:247], v[80:83]
	ds_read_b128 v[180:183], v130 offset:26624
	ds_read_b128 v[184:187], v130 offset:27648
	v_mfma_f32_16x16x32_bf16 v[84:87], v[188:191], v[248:251], v[84:87]
	ds_read_b128 v[236:239], v128 offset:24576
	ds_read_b128 v[240:243], v128 offset:25600
	s_add_u32 m0, s76, 0x0
	v_mfma_f32_16x16x32_bf16 v[88:91], v[192:195], v[244:247], v[88:91]
	global_load_lds_dwordx4 v132, s[72:73]
	s_add_u32 m0, s76, 0x1000
	v_mfma_f32_16x16x32_bf16 v[92:95], v[192:195], v[248:251], v[92:95]
	global_load_lds_dwordx4 v133, s[72:73]
	s_add_u32 m0, s76, 0x2000
	v_mfma_f32_16x16x32_bf16 v[112:115], v[220:223], v[244:247], v[112:115]
	global_load_lds_dwordx4 v134, s[72:73]
	v_mfma_f32_16x16x32_bf16 v[116:119], v[220:223], v[248:251], v[116:119]
	v_mfma_f32_16x16x32_bf16 v[120:123], v[224:227], v[244:247], v[120:123]
	v_mfma_f32_16x16x32_bf16 v[124:127], v[224:227], v[248:251], v[124:127]
	ds_read_b128 v[244:247], v128 offset:28672
	ds_read_b128 v[248:251], v128 offset:29696
	v_mfma_f32_16x16x32_bf16 v[32:35], v[188:191], v[228:231], v[32:35]
	s_add_u32 m0, s76, 0x3000
	v_mfma_f32_16x16x32_bf16 v[36:39], v[188:191], v[232:235], v[36:39]
	global_load_lds_dwordx4 v135, s[72:73]
	s_add_u32 m0, s76, 0x4000
	v_mfma_f32_16x16x32_bf16 v[40:43], v[192:195], v[228:231], v[40:43]
	global_load_lds_dwordx4 v132, s[74:75]
	s_add_u32 m0, s76, 0x5000
	v_mfma_f32_16x16x32_bf16 v[44:47], v[192:195], v[232:235], v[44:47]
	global_load_lds_dwordx4 v133, s[74:75]
	s_add_u32 s72, s72, 0x202000
	s_addc_u32 s73, s73, 0
	v_mfma_f32_16x16x32_bf16 v[96:99], v[220:223], v[228:231], v[96:99]
	s_add_u32 s74, s74, 0x2c000
	s_addc_u32 s75, s75, 0
	v_mfma_f32_16x16x32_bf16 v[100:103], v[220:223], v[232:235], v[100:103]
	v_mfma_f32_16x16x32_bf16 v[104:107], v[224:227], v[228:231], v[104:107]
	v_mfma_f32_16x16x32_bf16 v[108:111], v[224:227], v[232:235], v[108:111]
	s_waitcnt lgkmcnt(2)
	v_mfma_f32_16x16x32_bf16 v[64:67], v[172:175], v[236:239], v[64:67]
	ds_read_b128 v[228:231], v128 offset:32768
	v_mfma_f32_16x16x32_bf16 v[68:71], v[172:175], v[240:243], v[68:71]
	ds_read_b128 v[232:235], v128 offset:33792
	v_mfma_f32_16x16x32_bf16 v[72:75], v[176:179], v[236:239], v[72:75]
	v_mfma_f32_16x16x32_bf16 v[76:79], v[176:179], v[240:243], v[76:79]
	v_mfma_f32_16x16x32_bf16 v[48:51], v[180:183], v[236:239], v[48:51]
	v_mfma_f32_16x16x32_bf16 v[52:55], v[180:183], v[240:243], v[52:55]
	v_mfma_f32_16x16x32_bf16 v[56:59], v[184:187], v[236:239], v[56:59]
	v_mfma_f32_16x16x32_bf16 v[60:63], v[184:187], v[240:243], v[60:63]
	s_waitcnt lgkmcnt(2)
	v_mfma_f32_16x16x32_bf16 v[16:19], v[172:175], v[244:247], v[16:19]
	ds_read_b128 v[236:239], v128 offset:36864
	v_mfma_f32_16x16x32_bf16 v[20:23], v[172:175], v[248:251], v[20:23]
	ds_read_b128 v[240:243], v128 offset:37888
	v_mfma_f32_16x16x32_bf16 v[24:27], v[176:179], v[244:247], v[24:27]
	v_mfma_f32_16x16x32_bf16 v[28:31], v[176:179], v[248:251], v[28:31]
	v_mfma_f32_16x16x32_bf16 v[0:3], v[180:183], v[244:247], v[0:3]
	v_mfma_f32_16x16x32_bf16 v[4:7], v[180:183], v[248:251], v[4:7]
	v_mfma_f32_16x16x32_bf16 v[8:11], v[184:187], v[244:247], v[8:11]
	v_mfma_f32_16x16x32_bf16 v[12:15], v[184:187], v[248:251], v[12:15]
	s_waitcnt lgkmcnt(0)
	s_waitcnt vmcnt(6)
	s_barrier
	ds_read_b128 v[188:191], v130 offset:49152
	ds_read_b128 v[192:195], v130 offset:50176
	v_mfma_f32_16x16x32_bf16 v[80:83], v[172:175], v[228:231], v[80:83]
	ds_read_b128 v[220:223], v130 offset:51200
	ds_read_b128 v[224:227], v130 offset:52224
	v_mfma_f32_16x16x32_bf16 v[84:87], v[172:175], v[232:235], v[84:87]
	ds_read_b128 v[244:247], v128 offset:49152
	ds_read_b128 v[248:251], v128 offset:50176
	s_add_u32 m0, s76, 0x6000
	v_mfma_f32_16x16x32_bf16 v[88:91], v[176:179], v[228:231], v[88:91]
	global_load_lds_dwordx4 v132, s[72:73]
	s_add_u32 m0, s76, 0x7000
	v_mfma_f32_16x16x32_bf16 v[92:95], v[176:179], v[232:235], v[92:95]
	global_load_lds_dwordx4 v133, s[72:73]
	s_add_u32 m0, s76, 0x8000
	v_mfma_f32_16x16x32_bf16 v[112:115], v[180:183], v[228:231], v[112:115]
	global_load_lds_dwordx4 v134, s[72:73]
	v_mfma_f32_16x16x32_bf16 v[116:119], v[180:183], v[232:235], v[116:119]
	v_mfma_f32_16x16x32_bf16 v[120:123], v[184:187], v[228:231], v[120:123]
	v_mfma_f32_16x16x32_bf16 v[124:127], v[184:187], v[232:235], v[124:127]
	ds_read_b128 v[228:231], v128 offset:53248
	ds_read_b128 v[232:235], v128 offset:54272
	v_mfma_f32_16x16x32_bf16 v[32:35], v[172:175], v[236:239], v[32:35]
	s_add_u32 m0, s76, 0x9000
	v_mfma_f32_16x16x32_bf16 v[36:39], v[172:175], v[240:243], v[36:39]
	global_load_lds_dwordx4 v135, s[72:73]
	s_add_u32 m0, s76, 0xa000
	v_mfma_f32_16x16x32_bf16 v[40:43], v[176:179], v[236:239], v[40:43]
	global_load_lds_dwordx4 v132, s[74:75]
	s_add_u32 m0, s76, 0xb000
	v_mfma_f32_16x16x32_bf16 v[44:47], v[176:179], v[240:243], v[44:47]
	global_load_lds_dwordx4 v133, s[74:75]
	s_add_u32 s72, s72, 0x202000
	s_addc_u32 s73, s73, 0
	v_mfma_f32_16x16x32_bf16 v[96:99], v[180:183], v[236:239], v[96:99]
	s_add_u32 s74, s74, 0x2c000
	s_addc_u32 s75, s75, 0
	v_mfma_f32_16x16x32_bf16 v[100:103], v[180:183], v[240:243], v[100:103]
	v_mfma_f32_16x16x32_bf16 v[104:107], v[184:187], v[236:239], v[104:107]
	v_mfma_f32_16x16x32_bf16 v[108:111], v[184:187], v[240:243], v[108:111]
	s_waitcnt lgkmcnt(2)
	v_mfma_f32_16x16x32_bf16 v[64:67], v[188:191], v[244:247], v[64:67]
	ds_read_b128 v[236:239], v128 offset:57344
	v_mfma_f32_16x16x32_bf16 v[68:71], v[188:191], v[248:251], v[68:71]
	ds_read_b128 v[240:243], v128 offset:58368
	v_mfma_f32_16x16x32_bf16 v[72:75], v[192:195], v[244:247], v[72:75]
	v_mfma_f32_16x16x32_bf16 v[76:79], v[192:195], v[248:251], v[76:79]
	v_mfma_f32_16x16x32_bf16 v[48:51], v[220:223], v[244:247], v[48:51]
	v_mfma_f32_16x16x32_bf16 v[52:55], v[220:223], v[248:251], v[52:55]
	v_mfma_f32_16x16x32_bf16 v[56:59], v[224:227], v[244:247], v[56:59]
	v_mfma_f32_16x16x32_bf16 v[60:63], v[224:227], v[248:251], v[60:63]
	s_waitcnt lgkmcnt(2)
	v_mfma_f32_16x16x32_bf16 v[16:19], v[188:191], v[228:231], v[16:19]
	ds_read_b128 v[244:247], v128 offset:61440
	v_mfma_f32_16x16x32_bf16 v[20:23], v[188:191], v[232:235], v[20:23]
	ds_read_b128 v[248:251], v128 offset:62464
	v_mfma_f32_16x16x32_bf16 v[24:27], v[192:195], v[228:231], v[24:27]
	v_mfma_f32_16x16x32_bf16 v[28:31], v[192:195], v[232:235], v[28:31]
	v_mfma_f32_16x16x32_bf16 v[0:3], v[220:223], v[228:231], v[0:3]
	v_mfma_f32_16x16x32_bf16 v[4:7], v[220:223], v[232:235], v[4:7]
	v_mfma_f32_16x16x32_bf16 v[8:11], v[224:227], v[228:231], v[8:11]
	v_mfma_f32_16x16x32_bf16 v[12:15], v[224:227], v[232:235], v[12:15]
	s_waitcnt lgkmcnt(0)
	s_waitcnt vmcnt(6)
	s_barrier
	ds_read_b128 v[172:175], v130
	ds_read_b128 v[176:179], v130 offset:1024
	v_mfma_f32_16x16x32_bf16 v[80:83], v[188:191], v[236:239], v[80:83]
	ds_read_b128 v[180:183], v130 offset:2048
	ds_read_b128 v[184:187], v130 offset:3072
	v_mfma_f32_16x16x32_bf16 v[84:87], v[188:191], v[240:243], v[84:87]
	ds_read_b128 v[228:231], v128
	ds_read_b128 v[232:235], v128 offset:1024
	v_mfma_f32_16x16x32_bf16 v[88:91], v[192:195], v[236:239], v[88:91]
	v_mfma_f32_16x16x32_bf16 v[92:95], v[192:195], v[240:243], v[92:95]
	v_mfma_f32_16x16x32_bf16 v[112:115], v[220:223], v[236:239], v[112:115]
	v_mfma_f32_16x16x32_bf16 v[116:119], v[220:223], v[240:243], v[116:119]
	v_mfma_f32_16x16x32_bf16 v[120:123], v[224:227], v[236:239], v[120:123]
	v_mfma_f32_16x16x32_bf16 v[124:127], v[224:227], v[240:243], v[124:127]
	ds_read_b128 v[236:239], v128 offset:4096
	ds_read_b128 v[240:243], v128 offset:5120
	v_mfma_f32_16x16x32_bf16 v[32:35], v[188:191], v[244:247], v[32:35]
	v_mfma_f32_16x16x32_bf16 v[36:39], v[188:191], v[248:251], v[36:39]
	v_mfma_f32_16x16x32_bf16 v[40:43], v[192:195], v[244:247], v[40:43]
	v_mfma_f32_16x16x32_bf16 v[44:47], v[192:195], v[248:251], v[44:47]
	v_mfma_f32_16x16x32_bf16 v[96:99], v[220:223], v[244:247], v[96:99]
	v_mfma_f32_16x16x32_bf16 v[100:103], v[220:223], v[248:251], v[100:103]
	v_mfma_f32_16x16x32_bf16 v[104:107], v[224:227], v[244:247], v[104:107]
	v_mfma_f32_16x16x32_bf16 v[108:111], v[224:227], v[248:251], v[108:111]
	s_waitcnt lgkmcnt(2)
	v_mfma_f32_16x16x32_bf16 v[64:67], v[172:175], v[228:231], v[64:67]
	ds_read_b128 v[244:247], v128 offset:8192
	v_mfma_f32_16x16x32_bf16 v[68:71], v[172:175], v[232:235], v[68:71]
	ds_read_b128 v[248:251], v128 offset:9216
	v_mfma_f32_16x16x32_bf16 v[72:75], v[176:179], v[228:231], v[72:75]
	v_mfma_f32_16x16x32_bf16 v[76:79], v[176:179], v[232:235], v[76:79]
	v_mfma_f32_16x16x32_bf16 v[48:51], v[180:183], v[228:231], v[48:51]
	v_mfma_f32_16x16x32_bf16 v[52:55], v[180:183], v[232:235], v[52:55]
	v_mfma_f32_16x16x32_bf16 v[56:59], v[184:187], v[228:231], v[56:59]
	v_mfma_f32_16x16x32_bf16 v[60:63], v[184:187], v[232:235], v[60:63]
	s_waitcnt lgkmcnt(2)
	v_mfma_f32_16x16x32_bf16 v[16:19], v[172:175], v[236:239], v[16:19]
	ds_read_b128 v[228:231], v128 offset:12288
	v_mfma_f32_16x16x32_bf16 v[20:23], v[172:175], v[240:243], v[20:23]
	ds_read_b128 v[232:235], v128 offset:13312
	v_mfma_f32_16x16x32_bf16 v[24:27], v[176:179], v[236:239], v[24:27]
	v_mfma_f32_16x16x32_bf16 v[28:31], v[176:179], v[240:243], v[28:31]
	v_mfma_f32_16x16x32_bf16 v[0:3], v[180:183], v[236:239], v[0:3]
	v_mfma_f32_16x16x32_bf16 v[4:7], v[180:183], v[240:243], v[4:7]
	v_mfma_f32_16x16x32_bf16 v[8:11], v[184:187], v[236:239], v[8:11]
	v_mfma_f32_16x16x32_bf16 v[12:15], v[184:187], v[240:243], v[12:15]
	s_waitcnt lgkmcnt(0)
	s_waitcnt vmcnt(0)
	s_barrier
	ds_read_b128 v[188:191], v130 offset:24576
	ds_read_b128 v[192:195], v130 offset:25600
	v_mfma_f32_16x16x32_bf16 v[80:83], v[172:175], v[244:247], v[80:83]
	ds_read_b128 v[220:223], v130 offset:26624
	ds_read_b128 v[224:227], v130 offset:27648
	v_mfma_f32_16x16x32_bf16 v[84:87], v[172:175], v[248:251], v[84:87]
	ds_read_b128 v[236:239], v128 offset:24576
	ds_read_b128 v[240:243], v128 offset:25600
	v_mfma_f32_16x16x32_bf16 v[88:91], v[176:179], v[244:247], v[88:91]
	v_mfma_f32_16x16x32_bf16 v[92:95], v[176:179], v[248:251], v[92:95]
	v_mfma_f32_16x16x32_bf16 v[112:115], v[180:183], v[244:247], v[112:115]
	v_mfma_f32_16x16x32_bf16 v[116:119], v[180:183], v[248:251], v[116:119]
	v_mfma_f32_16x16x32_bf16 v[120:123], v[184:187], v[244:247], v[120:123]
	v_mfma_f32_16x16x32_bf16 v[124:127], v[184:187], v[248:251], v[124:127]
	ds_read_b128 v[244:247], v128 offset:28672
	ds_read_b128 v[248:251], v128 offset:29696
	v_mfma_f32_16x16x32_bf16 v[32:35], v[172:175], v[228:231], v[32:35]
	v_mfma_f32_16x16x32_bf16 v[36:39], v[172:175], v[232:235], v[36:39]
	v_mfma_f32_16x16x32_bf16 v[40:43], v[176:179], v[228:231], v[40:43]
	v_mfma_f32_16x16x32_bf16 v[44:47], v[176:179], v[232:235], v[44:47]
	v_mfma_f32_16x16x32_bf16 v[96:99], v[180:183], v[228:231], v[96:99]
	v_mfma_f32_16x16x32_bf16 v[100:103], v[180:183], v[232:235], v[100:103]
	v_mfma_f32_16x16x32_bf16 v[104:107], v[184:187], v[228:231], v[104:107]
	v_mfma_f32_16x16x32_bf16 v[108:111], v[184:187], v[232:235], v[108:111]
	s_waitcnt lgkmcnt(2)
	v_mfma_f32_16x16x32_bf16 v[64:67], v[188:191], v[236:239], v[64:67]
	ds_read_b128 v[228:231], v128 offset:32768
	v_mfma_f32_16x16x32_bf16 v[68:71], v[188:191], v[240:243], v[68:71]
	ds_read_b128 v[232:235], v128 offset:33792
	v_mfma_f32_16x16x32_bf16 v[72:75], v[192:195], v[236:239], v[72:75]
	v_mfma_f32_16x16x32_bf16 v[76:79], v[192:195], v[240:243], v[76:79]
	v_mfma_f32_16x16x32_bf16 v[48:51], v[220:223], v[236:239], v[48:51]
	v_mfma_f32_16x16x32_bf16 v[52:55], v[220:223], v[240:243], v[52:55]
	v_mfma_f32_16x16x32_bf16 v[56:59], v[224:227], v[236:239], v[56:59]
	v_mfma_f32_16x16x32_bf16 v[60:63], v[224:227], v[240:243], v[60:63]
	s_waitcnt lgkmcnt(2)
	v_mfma_f32_16x16x32_bf16 v[16:19], v[188:191], v[244:247], v[16:19]
	ds_read_b128 v[236:239], v128 offset:36864
	v_mfma_f32_16x16x32_bf16 v[20:23], v[188:191], v[248:251], v[20:23]
	ds_read_b128 v[240:243], v128 offset:37888
	v_mfma_f32_16x16x32_bf16 v[24:27], v[192:195], v[244:247], v[24:27]
	v_mfma_f32_16x16x32_bf16 v[28:31], v[192:195], v[248:251], v[28:31]
	v_mfma_f32_16x16x32_bf16 v[0:3], v[220:223], v[244:247], v[0:3]
	v_mfma_f32_16x16x32_bf16 v[4:7], v[220:223], v[248:251], v[4:7]
	v_mfma_f32_16x16x32_bf16 v[8:11], v[224:227], v[244:247], v[8:11]
	v_mfma_f32_16x16x32_bf16 v[12:15], v[224:227], v[248:251], v[12:15]
	s_waitcnt lgkmcnt(0)
	v_mfma_f32_16x16x32_bf16 v[80:83], v[188:191], v[228:231], v[80:83]
	v_mfma_f32_16x16x32_bf16 v[84:87], v[188:191], v[232:235], v[84:87]
	v_mfma_f32_16x16x32_bf16 v[88:91], v[192:195], v[228:231], v[88:91]
	v_mfma_f32_16x16x32_bf16 v[92:95], v[192:195], v[232:235], v[92:95]
	v_mfma_f32_16x16x32_bf16 v[112:115], v[220:223], v[228:231], v[112:115]
	v_mfma_f32_16x16x32_bf16 v[116:119], v[220:223], v[232:235], v[116:119]
	v_mfma_f32_16x16x32_bf16 v[120:123], v[224:227], v[228:231], v[120:123]
	v_mfma_f32_16x16x32_bf16 v[124:127], v[224:227], v[232:235], v[124:127]
	v_mfma_f32_16x16x32_bf16 v[32:35], v[188:191], v[236:239], v[32:35]
	v_mfma_f32_16x16x32_bf16 v[36:39], v[188:191], v[240:243], v[36:39]
	v_mfma_f32_16x16x32_bf16 v[40:43], v[192:195], v[236:239], v[40:43]
	v_mfma_f32_16x16x32_bf16 v[44:47], v[192:195], v[240:243], v[44:47]
	v_mfma_f32_16x16x32_bf16 v[96:99], v[220:223], v[236:239], v[96:99]
	v_mfma_f32_16x16x32_bf16 v[100:103], v[220:223], v[240:243], v[100:103]
	v_mfma_f32_16x16x32_bf16 v[104:107], v[224:227], v[236:239], v[104:107]
	v_mfma_f32_16x16x32_bf16 v[108:111], v[224:227], v[240:243], v[108:111]
	s_nop 15
	s_nop 15
	v_permlane16_swap_b32_e32 v64, v68
	v_permlane16_swap_b32_e32 v65, v69
	v_permlane16_swap_b32_e32 v66, v70
	v_permlane16_swap_b32_e32 v67, v71
	v_permlane16_swap_b32_e32 v72, v76
	v_permlane16_swap_b32_e32 v73, v77
	v_permlane16_swap_b32_e32 v74, v78
	v_permlane16_swap_b32_e32 v75, v79
	v_permlane16_swap_b32_e32 v16, v20
	v_permlane16_swap_b32_e32 v17, v21
	v_permlane16_swap_b32_e32 v18, v22
	v_permlane16_swap_b32_e32 v19, v23
	v_permlane16_swap_b32_e32 v24, v28
	v_permlane16_swap_b32_e32 v25, v29
	v_permlane16_swap_b32_e32 v26, v30
	v_permlane16_swap_b32_e32 v27, v31
	v_permlane16_swap_b32_e32 v80, v84
	v_permlane16_swap_b32_e32 v81, v85
	v_permlane16_swap_b32_e32 v82, v86
	v_permlane16_swap_b32_e32 v83, v87
	v_permlane16_swap_b32_e32 v88, v92
	v_permlane16_swap_b32_e32 v89, v93
	v_permlane16_swap_b32_e32 v90, v94
	v_permlane16_swap_b32_e32 v91, v95
	v_permlane16_swap_b32_e32 v32, v36
	v_permlane16_swap_b32_e32 v33, v37
	v_permlane16_swap_b32_e32 v34, v38
	v_permlane16_swap_b32_e32 v35, v39
	v_permlane16_swap_b32_e32 v40, v44
	v_permlane16_swap_b32_e32 v41, v45
	v_permlane16_swap_b32_e32 v42, v46
	v_permlane16_swap_b32_e32 v43, v47
	v_permlane16_swap_b32_e32 v48, v52
	v_permlane16_swap_b32_e32 v49, v53
	v_permlane16_swap_b32_e32 v50, v54
	v_permlane16_swap_b32_e32 v51, v55
	v_permlane16_swap_b32_e32 v56, v60
	v_permlane16_swap_b32_e32 v57, v61
	v_permlane16_swap_b32_e32 v58, v62
	v_permlane16_swap_b32_e32 v59, v63
	v_permlane16_swap_b32_e32 v0, v4
	v_permlane16_swap_b32_e32 v1, v5
	v_permlane16_swap_b32_e32 v2, v6
	v_permlane16_swap_b32_e32 v3, v7
	v_permlane16_swap_b32_e32 v8, v12
	v_permlane16_swap_b32_e32 v9, v13
	v_permlane16_swap_b32_e32 v10, v14
	v_permlane16_swap_b32_e32 v11, v15
	v_permlane16_swap_b32_e32 v112, v116
	v_permlane16_swap_b32_e32 v113, v117
	v_permlane16_swap_b32_e32 v114, v118
	v_permlane16_swap_b32_e32 v115, v119
	v_permlane16_swap_b32_e32 v120, v124
	v_permlane16_swap_b32_e32 v121, v125
	v_permlane16_swap_b32_e32 v122, v126
	v_permlane16_swap_b32_e32 v123, v127
	v_permlane16_swap_b32_e32 v96, v100
	v_permlane16_swap_b32_e32 v97, v101
	v_permlane16_swap_b32_e32 v98, v102
	v_permlane16_swap_b32_e32 v99, v103
	v_permlane16_swap_b32_e32 v104, v108
	v_permlane16_swap_b32_e32 v105, v109
	v_permlane16_swap_b32_e32 v106, v110
	v_permlane16_swap_b32_e32 v107, v111
	s_nop 1
	v_mov_b32_e32 v176, v95
	v_mov_b32_e32 v184, v91
	v_mov_b32_e32 v186, v89
	v_mov_b32_e32 v192, v83
	v_mov_b32_e32 v194, v81
	v_mov_b32_e32 v177, v127
	v_mov_b32_e32 v95, v126
	v_mov_b32_e32 v185, v123
	v_mov_b32_e32 v91, v122
	v_mov_b32_e32 v187, v121
	v_mov_b32_e32 v89, v120
	v_mov_b32_e32 v193, v115
	v_mov_b32_e32 v83, v114
	v_mov_b32_e32 v128, v47
	v_mov_b32_e32 v130, v45
	v_mov_b32_e32 v136, v39
	v_mov_b32_e32 v138, v37
	v_mov_b32_e32 v195, v113
	v_mov_b32_e32 v81, v112
	v_mov_b32_e32 v129, v111
	v_mov_b32_e32 v47, v110
	v_mov_b32_e32 v131, v109
	v_mov_b32_e32 v45, v108
	v_mov_b32_e32 v137, v103
	v_mov_b32_e32 v39, v102
	v_mov_b32_e32 v139, v101
	v_mov_b32_e32 v37, v100
	v_mov_b32_e32 v182, v93
	v_mov_b32_e32 v183, v125
	v_mov_b32_e32 v93, v124
	v_mov_b32_e32 v132, v43
	v_mov_b32_e32 v134, v41
	v_mov_b32_e32 v133, v107
	v_mov_b32_e32 v43, v106
	v_mov_b32_e32 v135, v105
	v_mov_b32_e32 v41, v104
	v_mov_b32_e32 v188, v87
	v_mov_b32_e32 v190, v85
	v_mov_b32_e32 v172, v35
	v_mov_b32_e32 v174, v33
	v_mov_b32_e32 v189, v119
	v_mov_b32_e32 v87, v118
	v_mov_b32_e32 v191, v117
	v_mov_b32_e32 v85, v116
	v_mov_b32_e32 v173, v99
	v_mov_b32_e32 v35, v98
	v_mov_b32_e32 v175, v97
	v_mov_b32_e32 v33, v96

.LBB0_535:
	s_or_saveexec_b64 s[0:1], s[0:1]
	v_mov_b32_e32 v127, 0
	v_mov_b64_e32 v[130:131], s[18:19]
	v_mov_b32_e32 v126, 0
	v_mov_b32_e32 v125, 0
	v_mov_b32_e32 v124, 0
	v_mov_b32_e32 v123, 0
	v_mov_b32_e32 v122, 0
	v_mov_b32_e32 v121, 0
	v_mov_b32_e32 v120, 0
	v_mov_b32_e32 v119, 0
	v_mov_b32_e32 v118, 0
	v_mov_b32_e32 v117, 0
	v_mov_b32_e32 v116, 0
	v_mov_b32_e32 v115, 0
	v_mov_b32_e32 v114, 0
	v_mov_b32_e32 v113, 0
	v_mov_b32_e32 v112, 0
	v_mov_b32_e32 v63, 0
	v_mov_b32_e32 v62, 0
	v_mov_b32_e32 v61, 0
	v_mov_b32_e32 v60, 0
	v_mov_b32_e32 v59, 0
	v_mov_b32_e32 v58, 0
	v_mov_b32_e32 v57, 0
	v_mov_b32_e32 v56, 0
	v_mov_b32_e32 v55, 0
	v_mov_b32_e32 v54, 0
	v_mov_b32_e32 v53, 0
	v_mov_b32_e32 v52, 0
	v_mov_b32_e32 v51, 0
	v_mov_b32_e32 v50, 0
	v_mov_b32_e32 v49, 0
	v_mov_b32_e32 v48, 0
	v_mov_b32_e32 v111, 0
	v_mov_b32_e32 v110, 0
	v_mov_b32_e32 v109, 0
	v_mov_b32_e32 v108, 0
	v_mov_b32_e32 v107, 0
	v_mov_b32_e32 v106, 0
	v_mov_b32_e32 v105, 0
	v_mov_b32_e32 v104, 0
	v_mov_b32_e32 v103, 0
	v_mov_b32_e32 v102, 0
	v_mov_b32_e32 v101, 0
	v_mov_b32_e32 v100, 0
	v_mov_b32_e32 v99, 0
	v_mov_b32_e32 v98, 0
	v_mov_b32_e32 v97, 0
	v_mov_b32_e32 v96, 0
	v_mov_b32_e32 v47, 0
	v_mov_b32_e32 v46, 0
	v_mov_b32_e32 v45, 0
	v_mov_b32_e32 v44, 0
	v_mov_b32_e32 v43, 0
	v_mov_b32_e32 v42, 0
	v_mov_b32_e32 v41, 0
	v_mov_b32_e32 v40, 0
	v_mov_b32_e32 v39, 0
	v_mov_b32_e32 v38, 0
	v_mov_b32_e32 v37, 0
	v_mov_b32_e32 v36, 0
	v_mov_b32_e32 v35, 0
	v_mov_b32_e32 v34, 0
	v_mov_b32_e32 v33, 0
	v_mov_b32_e32 v32, 0
	s_xor_b64 exec, exec, s[0:1]
	s_cbranch_execz .LBB0_539
	v_readfirstlane_b32 s78, v166
	v_readfirstlane_b32 s79, v168
	v_readfirstlane_b32 s76, v186
	v_mbcnt_lo_u32_b32 v244, -1, 0
	v_mbcnt_hi_u32_b32 v244, -1, v244
	s_nop 3
	s_lshl_b32 s78, s78, 14
	s_lshl_b32 s79, s79, 13
	s_add_u32 s72, s90, s78
	s_addc_u32 s73, s91, 0
	s_add_u32 s72, s72, 0xf0f0000
	s_addc_u32 s73, s73, 0
	s_add_u32 s74, s90, s79
	s_addc_u32 s75, s91, 0
	s_add_u32 s74, s74, 0x1b108000
	s_addc_u32 s75, s75, 0
	v_lshrrev_b32_e32 v245, 2, v244
	v_lshrrev_b32_e32 v246, 4, v244
	v_xor_b32_e32 v246, v246, v244
	v_and_b32_e32 v246, 3, v246
	v_lshlrev_b32_e32 v246, 4, v246
	v_lshl_or_b32 v245, v245, 6, v246
	v_or_b32_e32 v170, v245, v186
	v_add_u32_e32 v171, 0x1000, v170
	v_add_u32_e32 v180, 0x2000, v170
	v_add_u32_e32 v181, 0x3000, v170
	v_and_b32_e32 v245, 15, v244
	v_lshrrev_b32_e32 v246, 4, v244
	v_bfe_u32 v247, v244, 2, 2
	v_xor_b32_e32 v247, v247, v246
	v_lshlrev_b32_e32 v247, 4, v247
	v_lshl_or_b32 v128, v245, 6, v247
	v_lshrrev_b32_e32 v247, 10, v186
	v_lshrrev_b32_e32 v247, 1, v247
	v_lshl_or_b32 v128, v247, 11, v128
	v_and_b32_e32 v247, 3, v244
	v_bfe_u32 v245, v244, 2, 1
	v_lshl_or_b32 v247, v245, 3, v247
	v_bfe_u32 v245, v244, 3, 1
	v_lshl_or_b32 v247, v245, 2, v247
	v_lshrrev_b32_e32 v245, 2, v247
	v_xor_b32_e32 v245, v245, v246
	v_lshlrev_b32_e32 v245, 4, v245
	v_lshl_or_b32 v167, v247, 6, v245
	v_lshrrev_b32_e32 v247, 10, v186
	v_and_b32_e32 v247, 1, v247
	v_lshl_or_b32 v167, v247, 12, v167
	v_or_b32_e32 v167, 0x4000, v167
	s_add_u32 m0, s76, 0x2000
	s_nop 0
	global_load_lds_dwordx4 v180, s[72:73]
	s_add_u32 m0, s76, 0x3000
	s_nop 0
	global_load_lds_dwordx4 v181, s[72:73]
	s_add_u32 m0, s76, 0x4000
	s_nop 0
	global_load_lds_dwordx4 v170, s[74:75]
	s_add_u32 m0, s76, 0x5000
	s_nop 0
	global_load_lds_dwordx4 v171, s[74:75]
	s_add_u32 s72, s72, 0x202000
	s_addc_u32 s73, s73, 0
	s_add_u32 s74, s74, 0x10000
	s_addc_u32 s75, s75, 0
	s_add_u32 m0, s76, 0x6000
	s_nop 0
	global_load_lds_dwordx4 v170, s[72:73]
	s_add_u32 m0, s76, 0x7000
	s_nop 0
	global_load_lds_dwordx4 v171, s[72:73]
	s_add_u32 m0, s76, 0x8000
	s_nop 0
	global_load_lds_dwordx4 v180, s[72:73]
	s_add_u32 m0, s76, 0x9000
	s_nop 0
	global_load_lds_dwordx4 v181, s[72:73]
	s_add_u32 m0, s76, 0xa000
	s_nop 0
	global_load_lds_dwordx4 v170, s[74:75]
	s_add_u32 m0, s76, 0xb000
	s_nop 0
	global_load_lds_dwordx4 v171, s[74:75]
	s_add_u32 s72, s72, 0x202000
	s_addc_u32 s73, s73, 0
	s_add_u32 s74, s74, 0x10000
	s_addc_u32 s75, s75, 0
	s_add_u32 m0, s76, 0xc000
	s_nop 0
	global_load_lds_dwordx4 v170, s[72:73]
	s_add_u32 m0, s76, 0xd000
	s_nop 0
	global_load_lds_dwordx4 v171, s[72:73]
	s_add_u32 m0, s76, 0xe000
	s_nop 0
	global_load_lds_dwordx4 v180, s[72:73]
	s_add_u32 m0, s76, 0xf000
	s_nop 0
	global_load_lds_dwordx4 v181, s[72:73]
	s_add_u32 m0, s76, 0x10000
	s_nop 0
	global_load_lds_dwordx4 v170, s[74:75]
	s_add_u32 m0, s76, 0x11000
	s_nop 0
	global_load_lds_dwordx4 v171, s[74:75]
	s_add_u32 s72, s72, 0x202000
	s_addc_u32 s73, s73, 0
	s_add_u32 s74, s74, 0x10000
	s_addc_u32 s75, s75, 0
	s_waitcnt vmcnt(12)
	s_barrier
	ds_read_b128 v[212:215], v167
	ds_read_b128 v[216:219], v167 offset:1024
	ds_read_b128 v[220:223], v167 offset:2048
	ds_read_b128 v[224:227], v167 offset:3072
	ds_read_b128 v[132:135], v128
	ds_read_b128 v[136:139], v128 offset:1024
	ds_read_b128 v[172:175], v128 offset:4096
	ds_read_b128 v[176:179], v128 offset:5120
	s_waitcnt lgkmcnt(0)
	v_mfma_f32_16x16x32_bf16 v[80:83], v[212:215], v[132:135], 0
	ds_read_b128 v[248:251], v128 offset:8192
	v_mfma_f32_16x16x32_bf16 v[84:87], v[212:215], v[136:139], 0
	ds_read_b128 v[244:247], v128 offset:9216
	v_mfma_f32_16x16x32_bf16 v[88:91], v[216:219], v[132:135], 0
	v_mfma_f32_16x16x32_bf16 v[92:95], v[216:219], v[136:139], 0
	v_mfma_f32_16x16x32_bf16 v[64:67], v[220:223], v[132:135], 0
	v_mfma_f32_16x16x32_bf16 v[68:71], v[220:223], v[136:139], 0
	v_mfma_f32_16x16x32_bf16 v[72:75], v[224:227], v[132:135], 0
	v_mfma_f32_16x16x32_bf16 v[76:79], v[224:227], v[136:139], 0
	s_waitcnt lgkmcnt(2)
	v_mfma_f32_16x16x32_bf16 v[16:19], v[212:215], v[172:175], 0
	ds_read_b128 v[132:135], v128 offset:12288
	v_mfma_f32_16x16x32_bf16 v[20:23], v[212:215], v[176:179], 0
	ds_read_b128 v[136:139], v128 offset:13312
	v_mfma_f32_16x16x32_bf16 v[24:27], v[216:219], v[172:175], 0
	v_mfma_f32_16x16x32_bf16 v[28:31], v[216:219], v[176:179], 0
	v_mfma_f32_16x16x32_bf16 v[0:3], v[220:223], v[172:175], 0
	v_mfma_f32_16x16x32_bf16 v[4:7], v[220:223], v[176:179], 0
	v_mfma_f32_16x16x32_bf16 v[8:11], v[224:227], v[172:175], 0
	v_mfma_f32_16x16x32_bf16 v[12:15], v[224:227], v[176:179], 0
	s_waitcnt lgkmcnt(0)
	s_waitcnt vmcnt(6)
	s_barrier
	ds_read_b128 v[228:231], v167 offset:24576
	ds_read_b128 v[232:235], v167 offset:25600
	v_mfma_f32_16x16x32_bf16 v[112:115], v[212:215], v[248:251], 0
	ds_read_b128 v[236:239], v167 offset:26624
	ds_read_b128 v[240:243], v167 offset:27648
	v_mfma_f32_16x16x32_bf16 v[116:119], v[212:215], v[244:247], 0
	ds_read_b128 v[172:175], v128 offset:24576
	ds_read_b128 v[176:179], v128 offset:25600
	s_add_u32 m0, s76, 0x0
	v_mfma_f32_16x16x32_bf16 v[120:123], v[216:219], v[248:251], 0
	global_load_lds_dwordx4 v170, s[72:73]
	s_add_u32 m0, s76, 0x1000
	v_mfma_f32_16x16x32_bf16 v[124:127], v[216:219], v[244:247], 0
	global_load_lds_dwordx4 v171, s[72:73]
	s_add_u32 m0, s76, 0x2000
	v_mfma_f32_16x16x32_bf16 v[96:99], v[220:223], v[248:251], 0
	global_load_lds_dwordx4 v180, s[72:73]
	v_mfma_f32_16x16x32_bf16 v[100:103], v[220:223], v[244:247], 0
	v_mfma_f32_16x16x32_bf16 v[104:107], v[224:227], v[248:251], 0
	v_mfma_f32_16x16x32_bf16 v[108:111], v[224:227], v[244:247], 0
	ds_read_b128 v[248:251], v128 offset:28672
	ds_read_b128 v[244:247], v128 offset:29696
	v_mfma_f32_16x16x32_bf16 v[48:51], v[212:215], v[132:135], 0
	s_add_u32 m0, s76, 0x3000
	v_mfma_f32_16x16x32_bf16 v[52:55], v[212:215], v[136:139], 0
	global_load_lds_dwordx4 v181, s[72:73]
	s_add_u32 m0, s76, 0x4000
	v_mfma_f32_16x16x32_bf16 v[56:59], v[216:219], v[132:135], 0
	global_load_lds_dwordx4 v170, s[74:75]
	s_add_u32 m0, s76, 0x5000
	v_mfma_f32_16x16x32_bf16 v[60:63], v[216:219], v[136:139], 0
	global_load_lds_dwordx4 v171, s[74:75]
	s_add_u32 s72, s72, 0x202000
	s_addc_u32 s73, s73, 0
	v_mfma_f32_16x16x32_bf16 v[32:35], v[220:223], v[132:135], 0
	s_add_u32 s74, s74, 0x10000
	s_addc_u32 s75, s75, 0
	v_mfma_f32_16x16x32_bf16 v[36:39], v[220:223], v[136:139], 0
	v_mfma_f32_16x16x32_bf16 v[40:43], v[224:227], v[132:135], 0
	v_mfma_f32_16x16x32_bf16 v[44:47], v[224:227], v[136:139], 0
	s_waitcnt lgkmcnt(2)
	v_mfma_f32_16x16x32_bf16 v[80:83], v[228:231], v[172:175], v[80:83]
	ds_read_b128 v[132:135], v128 offset:32768
	v_mfma_f32_16x16x32_bf16 v[84:87], v[228:231], v[176:179], v[84:87]
	ds_read_b128 v[136:139], v128 offset:33792
	v_mfma_f32_16x16x32_bf16 v[88:91], v[232:235], v[172:175], v[88:91]
	v_mfma_f32_16x16x32_bf16 v[92:95], v[232:235], v[176:179], v[92:95]
	v_mfma_f32_16x16x32_bf16 v[64:67], v[236:239], v[172:175], v[64:67]
	v_mfma_f32_16x16x32_bf16 v[68:71], v[236:239], v[176:179], v[68:71]
	v_mfma_f32_16x16x32_bf16 v[72:75], v[240:243], v[172:175], v[72:75]
	v_mfma_f32_16x16x32_bf16 v[76:79], v[240:243], v[176:179], v[76:79]
	s_waitcnt lgkmcnt(2)
	v_mfma_f32_16x16x32_bf16 v[16:19], v[228:231], v[248:251], v[16:19]
	ds_read_b128 v[172:175], v128 offset:36864
	v_mfma_f32_16x16x32_bf16 v[20:23], v[228:231], v[244:247], v[20:23]
	ds_read_b128 v[176:179], v128 offset:37888
	v_mfma_f32_16x16x32_bf16 v[24:27], v[232:235], v[248:251], v[24:27]
	v_mfma_f32_16x16x32_bf16 v[28:31], v[232:235], v[244:247], v[28:31]
	v_mfma_f32_16x16x32_bf16 v[0:3], v[236:239], v[248:251], v[0:3]
	v_mfma_f32_16x16x32_bf16 v[4:7], v[236:239], v[244:247], v[4:7]
	v_mfma_f32_16x16x32_bf16 v[8:11], v[240:243], v[248:251], v[8:11]
	v_mfma_f32_16x16x32_bf16 v[12:15], v[240:243], v[244:247], v[12:15]
	s_waitcnt lgkmcnt(0)
	s_waitcnt vmcnt(6)
	s_barrier
	ds_read_b128 v[212:215], v167 offset:49152
	ds_read_b128 v[216:219], v167 offset:50176
	v_mfma_f32_16x16x32_bf16 v[112:115], v[228:231], v[132:135], v[112:115]
	ds_read_b128 v[220:223], v167 offset:51200
	ds_read_b128 v[224:227], v167 offset:52224
	v_mfma_f32_16x16x32_bf16 v[116:119], v[228:231], v[136:139], v[116:119]
	ds_read_b128 v[248:251], v128 offset:49152
	ds_read_b128 v[244:247], v128 offset:50176
	s_add_u32 m0, s76, 0x6000
	v_mfma_f32_16x16x32_bf16 v[120:123], v[232:235], v[132:135], v[120:123]
	global_load_lds_dwordx4 v170, s[72:73]
	s_add_u32 m0, s76, 0x7000
	v_mfma_f32_16x16x32_bf16 v[124:127], v[232:235], v[136:139], v[124:127]
	global_load_lds_dwordx4 v171, s[72:73]
	s_add_u32 m0, s76, 0x8000
	v_mfma_f32_16x16x32_bf16 v[96:99], v[236:239], v[132:135], v[96:99]
	global_load_lds_dwordx4 v180, s[72:73]
	v_mfma_f32_16x16x32_bf16 v[100:103], v[236:239], v[136:139], v[100:103]
	v_mfma_f32_16x16x32_bf16 v[104:107], v[240:243], v[132:135], v[104:107]
	v_mfma_f32_16x16x32_bf16 v[108:111], v[240:243], v[136:139], v[108:111]
	ds_read_b128 v[132:135], v128 offset:53248
	ds_read_b128 v[136:139], v128 offset:54272
	v_mfma_f32_16x16x32_bf16 v[48:51], v[228:231], v[172:175], v[48:51]
	s_add_u32 m0, s76, 0x9000
	v_mfma_f32_16x16x32_bf16 v[52:55], v[228:231], v[176:179], v[52:55]
	global_load_lds_dwordx4 v181, s[72:73]
	s_add_u32 m0, s76, 0xa000
	v_mfma_f32_16x16x32_bf16 v[56:59], v[232:235], v[172:175], v[56:59]
	global_load_lds_dwordx4 v170, s[74:75]
	s_add_u32 m0, s76, 0xb000
	v_mfma_f32_16x16x32_bf16 v[60:63], v[232:235], v[176:179], v[60:63]
	global_load_lds_dwordx4 v171, s[74:75]
	s_add_u32 s72, s72, 0x202000
	s_addc_u32 s73, s73, 0
	v_mfma_f32_16x16x32_bf16 v[32:35], v[236:239], v[172:175], v[32:35]
	s_add_u32 s74, s74, 0x10000
	s_addc_u32 s75, s75, 0
	v_mfma_f32_16x16x32_bf16 v[36:39], v[236:239], v[176:179], v[36:39]
	v_mfma_f32_16x16x32_bf16 v[40:43], v[240:243], v[172:175], v[40:43]
	v_mfma_f32_16x16x32_bf16 v[44:47], v[240:243], v[176:179], v[44:47]
	s_waitcnt lgkmcnt(2)
	v_mfma_f32_16x16x32_bf16 v[80:83], v[212:215], v[248:251], v[80:83]
	ds_read_b128 v[172:175], v128 offset:57344
	v_mfma_f32_16x16x32_bf16 v[84:87], v[212:215], v[244:247], v[84:87]
	ds_read_b128 v[176:179], v128 offset:58368
	v_mfma_f32_16x16x32_bf16 v[88:91], v[216:219], v[248:251], v[88:91]
	v_mfma_f32_16x16x32_bf16 v[92:95], v[216:219], v[244:247], v[92:95]
	v_mfma_f32_16x16x32_bf16 v[64:67], v[220:223], v[248:251], v[64:67]
	v_mfma_f32_16x16x32_bf16 v[68:71], v[220:223], v[244:247], v[68:71]
	v_mfma_f32_16x16x32_bf16 v[72:75], v[224:227], v[248:251], v[72:75]
	v_mfma_f32_16x16x32_bf16 v[76:79], v[224:227], v[244:247], v[76:79]
	s_waitcnt lgkmcnt(2)
	v_mfma_f32_16x16x32_bf16 v[16:19], v[212:215], v[132:135], v[16:19]
	ds_read_b128 v[248:251], v128 offset:61440
	v_mfma_f32_16x16x32_bf16 v[20:23], v[212:215], v[136:139], v[20:23]
	ds_read_b128 v[244:247], v128 offset:62464
	v_mfma_f32_16x16x32_bf16 v[24:27], v[216:219], v[132:135], v[24:27]
	v_mfma_f32_16x16x32_bf16 v[28:31], v[216:219], v[136:139], v[28:31]
	v_mfma_f32_16x16x32_bf16 v[0:3], v[220:223], v[132:135], v[0:3]
	v_mfma_f32_16x16x32_bf16 v[4:7], v[220:223], v[136:139], v[4:7]
	v_mfma_f32_16x16x32_bf16 v[8:11], v[224:227], v[132:135], v[8:11]
	v_mfma_f32_16x16x32_bf16 v[12:15], v[224:227], v[136:139], v[12:15]
	s_waitcnt lgkmcnt(0)
	s_waitcnt vmcnt(6)
	s_barrier
	ds_read_b128 v[228:231], v167
	ds_read_b128 v[232:235], v167 offset:1024
	v_mfma_f32_16x16x32_bf16 v[112:115], v[212:215], v[172:175], v[112:115]
	ds_read_b128 v[236:239], v167 offset:2048
	ds_read_b128 v[240:243], v167 offset:3072
	v_mfma_f32_16x16x32_bf16 v[116:119], v[212:215], v[176:179], v[116:119]
	ds_read_b128 v[132:135], v128
	ds_read_b128 v[136:139], v128 offset:1024
	s_add_u32 m0, s76, 0xc000
	v_mfma_f32_16x16x32_bf16 v[120:123], v[216:219], v[172:175], v[120:123]
	global_load_lds_dwordx4 v170, s[72:73]
	s_add_u32 m0, s76, 0xd000
	v_mfma_f32_16x16x32_bf16 v[124:127], v[216:219], v[176:179], v[124:127]
	global_load_lds_dwordx4 v171, s[72:73]
	s_add_u32 m0, s76, 0xe000
	v_mfma_f32_16x16x32_bf16 v[96:99], v[220:223], v[172:175], v[96:99]
	global_load_lds_dwordx4 v180, s[72:73]
	v_mfma_f32_16x16x32_bf16 v[100:103], v[220:223], v[176:179], v[100:103]
	v_mfma_f32_16x16x32_bf16 v[104:107], v[224:227], v[172:175], v[104:107]
	v_mfma_f32_16x16x32_bf16 v[108:111], v[224:227], v[176:179], v[108:111]
	ds_read_b128 v[172:175], v128 offset:4096
	ds_read_b128 v[176:179], v128 offset:5120
	v_mfma_f32_16x16x32_bf16 v[48:51], v[212:215], v[248:251], v[48:51]
	s_add_u32 m0, s76, 0xf000
	v_mfma_f32_16x16x32_bf16 v[52:55], v[212:215], v[244:247], v[52:55]
	global_load_lds_dwordx4 v181, s[72:73]
	s_add_u32 m0, s76, 0x10000
	v_mfma_f32_16x16x32_bf16 v[56:59], v[216:219], v[248:251], v[56:59]
	global_load_lds_dwordx4 v170, s[74:75]
	s_add_u32 m0, s76, 0x11000
	v_mfma_f32_16x16x32_bf16 v[60:63], v[216:219], v[244:247], v[60:63]
	global_load_lds_dwordx4 v171, s[74:75]
	s_add_u32 s72, s72, 0x202000
	s_addc_u32 s73, s73, 0
	v_mfma_f32_16x16x32_bf16 v[32:35], v[220:223], v[248:251], v[32:35]
	s_add_u32 s74, s74, 0x10000
	s_addc_u32 s75, s75, 0
	v_mfma_f32_16x16x32_bf16 v[36:39], v[220:223], v[244:247], v[36:39]
	v_mfma_f32_16x16x32_bf16 v[40:43], v[224:227], v[248:251], v[40:43]
	v_mfma_f32_16x16x32_bf16 v[44:47], v[224:227], v[244:247], v[44:47]
	s_waitcnt lgkmcnt(2)
	v_mfma_f32_16x16x32_bf16 v[80:83], v[228:231], v[132:135], v[80:83]
	ds_read_b128 v[248:251], v128 offset:8192
	v_mfma_f32_16x16x32_bf16 v[84:87], v[228:231], v[136:139], v[84:87]
	ds_read_b128 v[244:247], v128 offset:9216
	v_mfma_f32_16x16x32_bf16 v[88:91], v[232:235], v[132:135], v[88:91]
	v_mfma_f32_16x16x32_bf16 v[92:95], v[232:235], v[136:139], v[92:95]
	v_mfma_f32_16x16x32_bf16 v[64:67], v[236:239], v[132:135], v[64:67]
	v_mfma_f32_16x16x32_bf16 v[68:71], v[236:239], v[136:139], v[68:71]
	v_mfma_f32_16x16x32_bf16 v[72:75], v[240:243], v[132:135], v[72:75]
	v_mfma_f32_16x16x32_bf16 v[76:79], v[240:243], v[136:139], v[76:79]
	s_waitcnt lgkmcnt(2)
	v_mfma_f32_16x16x32_bf16 v[16:19], v[228:231], v[172:175], v[16:19]
	ds_read_b128 v[132:135], v128 offset:12288
	v_mfma_f32_16x16x32_bf16 v[20:23], v[228:231], v[176:179], v[20:23]
	ds_read_b128 v[136:139], v128 offset:13312
	v_mfma_f32_16x16x32_bf16 v[24:27], v[232:235], v[172:175], v[24:27]
	v_mfma_f32_16x16x32_bf16 v[28:31], v[232:235], v[176:179], v[28:31]
	v_mfma_f32_16x16x32_bf16 v[0:3], v[236:239], v[172:175], v[0:3]
	v_mfma_f32_16x16x32_bf16 v[4:7], v[236:239], v[176:179], v[4:7]
	v_mfma_f32_16x16x32_bf16 v[8:11], v[240:243], v[172:175], v[8:11]
	v_mfma_f32_16x16x32_bf16 v[12:15], v[240:243], v[176:179], v[12:15]
	s_waitcnt lgkmcnt(0)
	s_waitcnt vmcnt(6)
	s_barrier
	ds_read_b128 v[212:215], v167 offset:24576
	ds_read_b128 v[216:219], v167 offset:25600
	v_mfma_f32_16x16x32_bf16 v[112:115], v[228:231], v[248:251], v[112:115]
	ds_read_b128 v[220:223], v167 offset:26624
	ds_read_b128 v[224:227], v167 offset:27648
	v_mfma_f32_16x16x32_bf16 v[116:119], v[228:231], v[244:247], v[116:119]
	ds_read_b128 v[172:175], v128 offset:24576
	ds_read_b128 v[176:179], v128 offset:25600
	s_add_u32 m0, s76, 0x0
	v_mfma_f32_16x16x32_bf16 v[120:123], v[232:235], v[248:251], v[120:123]
	global_load_lds_dwordx4 v170, s[72:73]
	s_add_u32 m0, s76, 0x1000
	v_mfma_f32_16x16x32_bf16 v[124:127], v[232:235], v[244:247], v[124:127]
	global_load_lds_dwordx4 v171, s[72:73]
	s_add_u32 m0, s76, 0x2000
	v_mfma_f32_16x16x32_bf16 v[96:99], v[236:239], v[248:251], v[96:99]
	global_load_lds_dwordx4 v180, s[72:73]
	v_mfma_f32_16x16x32_bf16 v[100:103], v[236:239], v[244:247], v[100:103]
	v_mfma_f32_16x16x32_bf16 v[104:107], v[240:243], v[248:251], v[104:107]
	v_mfma_f32_16x16x32_bf16 v[108:111], v[240:243], v[244:247], v[108:111]
	ds_read_b128 v[248:251], v128 offset:28672
	ds_read_b128 v[244:247], v128 offset:29696
	v_mfma_f32_16x16x32_bf16 v[48:51], v[228:231], v[132:135], v[48:51]
	s_add_u32 m0, s76, 0x3000
	v_mfma_f32_16x16x32_bf16 v[52:55], v[228:231], v[136:139], v[52:55]
	global_load_lds_dwordx4 v181, s[72:73]
	s_add_u32 m0, s76, 0x4000
	v_mfma_f32_16x16x32_bf16 v[56:59], v[232:235], v[132:135], v[56:59]
	global_load_lds_dwordx4 v170, s[74:75]
	s_add_u32 m0, s76, 0x5000
	v_mfma_f32_16x16x32_bf16 v[60:63], v[232:235], v[136:139], v[60:63]
	global_load_lds_dwordx4 v171, s[74:75]
	s_add_u32 s72, s72, 0x202000
	s_addc_u32 s73, s73, 0
	v_mfma_f32_16x16x32_bf16 v[32:35], v[236:239], v[132:135], v[32:35]
	s_add_u32 s74, s74, 0x10000
	s_addc_u32 s75, s75, 0
	v_mfma_f32_16x16x32_bf16 v[36:39], v[236:239], v[136:139], v[36:39]
	v_mfma_f32_16x16x32_bf16 v[40:43], v[240:243], v[132:135], v[40:43]
	v_mfma_f32_16x16x32_bf16 v[44:47], v[240:243], v[136:139], v[44:47]
	s_waitcnt lgkmcnt(2)
	v_mfma_f32_16x16x32_bf16 v[80:83], v[212:215], v[172:175], v[80:83]
	ds_read_b128 v[132:135], v128 offset:32768
	v_mfma_f32_16x16x32_bf16 v[84:87], v[212:215], v[176:179], v[84:87]
	ds_read_b128 v[136:139], v128 offset:33792
	v_mfma_f32_16x16x32_bf16 v[88:91], v[216:219], v[172:175], v[88:91]
	v_mfma_f32_16x16x32_bf16 v[92:95], v[216:219], v[176:179], v[92:95]
	v_mfma_f32_16x16x32_bf16 v[64:67], v[220:223], v[172:175], v[64:67]
	v_mfma_f32_16x16x32_bf16 v[68:71], v[220:223], v[176:179], v[68:71]
	v_mfma_f32_16x16x32_bf16 v[72:75], v[224:227], v[172:175], v[72:75]
	v_mfma_f32_16x16x32_bf16 v[76:79], v[224:227], v[176:179], v[76:79]
	s_waitcnt lgkmcnt(2)
	v_mfma_f32_16x16x32_bf16 v[16:19], v[212:215], v[248:251], v[16:19]
	ds_read_b128 v[172:175], v128 offset:36864
	v_mfma_f32_16x16x32_bf16 v[20:23], v[212:215], v[244:247], v[20:23]
	ds_read_b128 v[176:179], v128 offset:37888
	v_mfma_f32_16x16x32_bf16 v[24:27], v[216:219], v[248:251], v[24:27]
	v_mfma_f32_16x16x32_bf16 v[28:31], v[216:219], v[244:247], v[28:31]
	v_mfma_f32_16x16x32_bf16 v[0:3], v[220:223], v[248:251], v[0:3]
	v_mfma_f32_16x16x32_bf16 v[4:7], v[220:223], v[244:247], v[4:7]
	v_mfma_f32_16x16x32_bf16 v[8:11], v[224:227], v[248:251], v[8:11]
	v_mfma_f32_16x16x32_bf16 v[12:15], v[224:227], v[244:247], v[12:15]
	s_waitcnt lgkmcnt(0)
	s_waitcnt vmcnt(6)
	s_barrier
	ds_read_b128 v[228:231], v167 offset:49152
	ds_read_b128 v[232:235], v167 offset:50176
	v_mfma_f32_16x16x32_bf16 v[112:115], v[212:215], v[132:135], v[112:115]
	ds_read_b128 v[236:239], v167 offset:51200
	ds_read_b128 v[240:243], v167 offset:52224
	v_mfma_f32_16x16x32_bf16 v[116:119], v[212:215], v[136:139], v[116:119]
	ds_read_b128 v[248:251], v128 offset:49152
	ds_read_b128 v[244:247], v128 offset:50176
	s_add_u32 m0, s76, 0x6000
	v_mfma_f32_16x16x32_bf16 v[120:123], v[216:219], v[132:135], v[120:123]
	global_load_lds_dwordx4 v170, s[72:73]
	s_add_u32 m0, s76, 0x7000
	v_mfma_f32_16x16x32_bf16 v[124:127], v[216:219], v[136:139], v[124:127]
	global_load_lds_dwordx4 v171, s[72:73]
	s_add_u32 m0, s76, 0x8000
	v_mfma_f32_16x16x32_bf16 v[96:99], v[220:223], v[132:135], v[96:99]
	global_load_lds_dwordx4 v180, s[72:73]
	v_mfma_f32_16x16x32_bf16 v[100:103], v[220:223], v[136:139], v[100:103]
	v_mfma_f32_16x16x32_bf16 v[104:107], v[224:227], v[132:135], v[104:107]
	v_mfma_f32_16x16x32_bf16 v[108:111], v[224:227], v[136:139], v[108:111]
	ds_read_b128 v[132:135], v128 offset:53248
	ds_read_b128 v[136:139], v128 offset:54272
	v_mfma_f32_16x16x32_bf16 v[48:51], v[212:215], v[172:175], v[48:51]
	s_add_u32 m0, s76, 0x9000
	v_mfma_f32_16x16x32_bf16 v[52:55], v[212:215], v[176:179], v[52:55]
	global_load_lds_dwordx4 v181, s[72:73]
	s_add_u32 m0, s76, 0xa000
	v_mfma_f32_16x16x32_bf16 v[56:59], v[216:219], v[172:175], v[56:59]
	global_load_lds_dwordx4 v170, s[74:75]
	s_add_u32 m0, s76, 0xb000
	v_mfma_f32_16x16x32_bf16 v[60:63], v[216:219], v[176:179], v[60:63]
	global_load_lds_dwordx4 v171, s[74:75]
	s_add_u32 s72, s72, 0x202000
	s_addc_u32 s73, s73, 0
	v_mfma_f32_16x16x32_bf16 v[32:35], v[220:223], v[172:175], v[32:35]
	s_add_u32 s74, s74, 0x10000
	s_addc_u32 s75, s75, 0
	v_mfma_f32_16x16x32_bf16 v[36:39], v[220:223], v[176:179], v[36:39]
	v_mfma_f32_16x16x32_bf16 v[40:43], v[224:227], v[172:175], v[40:43]
	v_mfma_f32_16x16x32_bf16 v[44:47], v[224:227], v[176:179], v[44:47]
	s_waitcnt lgkmcnt(2)
	v_mfma_f32_16x16x32_bf16 v[80:83], v[228:231], v[248:251], v[80:83]
	ds_read_b128 v[172:175], v128 offset:57344
	v_mfma_f32_16x16x32_bf16 v[84:87], v[228:231], v[244:247], v[84:87]
	ds_read_b128 v[176:179], v128 offset:58368
	v_mfma_f32_16x16x32_bf16 v[88:91], v[232:235], v[248:251], v[88:91]
	v_mfma_f32_16x16x32_bf16 v[92:95], v[232:235], v[244:247], v[92:95]
	v_mfma_f32_16x16x32_bf16 v[64:67], v[236:239], v[248:251], v[64:67]
	v_mfma_f32_16x16x32_bf16 v[68:71], v[236:239], v[244:247], v[68:71]
	v_mfma_f32_16x16x32_bf16 v[72:75], v[240:243], v[248:251], v[72:75]
	v_mfma_f32_16x16x32_bf16 v[76:79], v[240:243], v[244:247], v[76:79]
	s_waitcnt lgkmcnt(2)
	v_mfma_f32_16x16x32_bf16 v[16:19], v[228:231], v[132:135], v[16:19]
	ds_read_b128 v[248:251], v128 offset:61440
	v_mfma_f32_16x16x32_bf16 v[20:23], v[228:231], v[136:139], v[20:23]
	ds_read_b128 v[244:247], v128 offset:62464
	v_mfma_f32_16x16x32_bf16 v[24:27], v[232:235], v[132:135], v[24:27]
	v_mfma_f32_16x16x32_bf16 v[28:31], v[232:235], v[136:139], v[28:31]
	v_mfma_f32_16x16x32_bf16 v[0:3], v[236:239], v[132:135], v[0:3]
	v_mfma_f32_16x16x32_bf16 v[4:7], v[236:239], v[136:139], v[4:7]
	v_mfma_f32_16x16x32_bf16 v[8:11], v[240:243], v[132:135], v[8:11]
	v_mfma_f32_16x16x32_bf16 v[12:15], v[240:243], v[136:139], v[12:15]
	s_waitcnt lgkmcnt(0)
	s_waitcnt vmcnt(6)
	s_barrier
	ds_read_b128 v[212:215], v167
	ds_read_b128 v[216:219], v167 offset:1024
	v_mfma_f32_16x16x32_bf16 v[112:115], v[228:231], v[172:175], v[112:115]
	ds_read_b128 v[220:223], v167 offset:2048
	ds_read_b128 v[224:227], v167 offset:3072
	v_mfma_f32_16x16x32_bf16 v[116:119], v[228:231], v[176:179], v[116:119]
	ds_read_b128 v[132:135], v128
	ds_read_b128 v[136:139], v128 offset:1024
	s_add_u32 m0, s76, 0xc000
	v_mfma_f32_16x16x32_bf16 v[120:123], v[232:235], v[172:175], v[120:123]
	global_load_lds_dwordx4 v170, s[72:73]
	s_add_u32 m0, s76, 0xd000
	v_mfma_f32_16x16x32_bf16 v[124:127], v[232:235], v[176:179], v[124:127]
	global_load_lds_dwordx4 v171, s[72:73]
	s_add_u32 m0, s76, 0xe000
	v_mfma_f32_16x16x32_bf16 v[96:99], v[236:239], v[172:175], v[96:99]
	global_load_lds_dwordx4 v180, s[72:73]
	v_mfma_f32_16x16x32_bf16 v[100:103], v[236:239], v[176:179], v[100:103]
	v_mfma_f32_16x16x32_bf16 v[104:107], v[240:243], v[172:175], v[104:107]
	v_mfma_f32_16x16x32_bf16 v[108:111], v[240:243], v[176:179], v[108:111]
	ds_read_b128 v[172:175], v128 offset:4096
	ds_read_b128 v[176:179], v128 offset:5120
	v_mfma_f32_16x16x32_bf16 v[48:51], v[228:231], v[248:251], v[48:51]
	s_add_u32 m0, s76, 0xf000
	v_mfma_f32_16x16x32_bf16 v[52:55], v[228:231], v[244:247], v[52:55]
	global_load_lds_dwordx4 v181, s[72:73]
	s_add_u32 m0, s76, 0x10000
	v_mfma_f32_16x16x32_bf16 v[56:59], v[232:235], v[248:251], v[56:59]
	global_load_lds_dwordx4 v170, s[74:75]
	s_add_u32 m0, s76, 0x11000
	v_mfma_f32_16x16x32_bf16 v[60:63], v[232:235], v[244:247], v[60:63]
	global_load_lds_dwordx4 v171, s[74:75]
	s_add_u32 s72, s72, 0x202000
	s_addc_u32 s73, s73, 0
	v_mfma_f32_16x16x32_bf16 v[32:35], v[236:239], v[248:251], v[32:35]
	s_add_u32 s74, s74, 0x10000
	s_addc_u32 s75, s75, 0
	v_mfma_f32_16x16x32_bf16 v[36:39], v[236:239], v[244:247], v[36:39]
	v_mfma_f32_16x16x32_bf16 v[40:43], v[240:243], v[248:251], v[40:43]
	v_mfma_f32_16x16x32_bf16 v[44:47], v[240:243], v[244:247], v[44:47]
	s_mov_b32 s77, 5
.Lgemm_p3_loop:
	s_waitcnt lgkmcnt(2)
	v_mfma_f32_16x16x32_bf16 v[80:83], v[212:215], v[132:135], v[80:83]
	ds_read_b128 v[248:251], v128 offset:8192
	v_mfma_f32_16x16x32_bf16 v[84:87], v[212:215], v[136:139], v[84:87]
	ds_read_b128 v[244:247], v128 offset:9216
	v_mfma_f32_16x16x32_bf16 v[88:91], v[216:219], v[132:135], v[88:91]
	v_mfma_f32_16x16x32_bf16 v[92:95], v[216:219], v[136:139], v[92:95]
	v_mfma_f32_16x16x32_bf16 v[64:67], v[220:223], v[132:135], v[64:67]
	v_mfma_f32_16x16x32_bf16 v[68:71], v[220:223], v[136:139], v[68:71]
	v_mfma_f32_16x16x32_bf16 v[72:75], v[224:227], v[132:135], v[72:75]
	v_mfma_f32_16x16x32_bf16 v[76:79], v[224:227], v[136:139], v[76:79]
	s_waitcnt lgkmcnt(2)
	v_mfma_f32_16x16x32_bf16 v[16:19], v[212:215], v[172:175], v[16:19]
	ds_read_b128 v[132:135], v128 offset:12288
	v_mfma_f32_16x16x32_bf16 v[20:23], v[212:215], v[176:179], v[20:23]
	ds_read_b128 v[136:139], v128 offset:13312
	v_mfma_f32_16x16x32_bf16 v[24:27], v[216:219], v[172:175], v[24:27]
	v_mfma_f32_16x16x32_bf16 v[28:31], v[216:219], v[176:179], v[28:31]
	v_mfma_f32_16x16x32_bf16 v[0:3], v[220:223], v[172:175], v[0:3]
	v_mfma_f32_16x16x32_bf16 v[4:7], v[220:223], v[176:179], v[4:7]
	v_mfma_f32_16x16x32_bf16 v[8:11], v[224:227], v[172:175], v[8:11]
	v_mfma_f32_16x16x32_bf16 v[12:15], v[224:227], v[176:179], v[12:15]
	s_waitcnt lgkmcnt(0)
	s_waitcnt vmcnt(6)
	s_barrier
	ds_read_b128 v[228:231], v167 offset:24576
	ds_read_b128 v[232:235], v167 offset:25600
	v_mfma_f32_16x16x32_bf16 v[112:115], v[212:215], v[248:251], v[112:115]
	ds_read_b128 v[236:239], v167 offset:26624
	ds_read_b128 v[240:243], v167 offset:27648
	v_mfma_f32_16x16x32_bf16 v[116:119], v[212:215], v[244:247], v[116:119]
	ds_read_b128 v[172:175], v128 offset:24576
	ds_read_b128 v[176:179], v128 offset:25600
	s_add_u32 m0, s76, 0x0
	v_mfma_f32_16x16x32_bf16 v[120:123], v[216:219], v[248:251], v[120:123]
	global_load_lds_dwordx4 v170, s[72:73]
	s_add_u32 m0, s76, 0x1000
	v_mfma_f32_16x16x32_bf16 v[124:127], v[216:219], v[244:247], v[124:127]
	global_load_lds_dwordx4 v171, s[72:73]
	s_add_u32 m0, s76, 0x2000
	v_mfma_f32_16x16x32_bf16 v[96:99], v[220:223], v[248:251], v[96:99]
	global_load_lds_dwordx4 v180, s[72:73]
	v_mfma_f32_16x16x32_bf16 v[100:103], v[220:223], v[244:247], v[100:103]
	v_mfma_f32_16x16x32_bf16 v[104:107], v[224:227], v[248:251], v[104:107]
	v_mfma_f32_16x16x32_bf16 v[108:111], v[224:227], v[244:247], v[108:111]
	ds_read_b128 v[248:251], v128 offset:28672
	ds_read_b128 v[244:247], v128 offset:29696
	v_mfma_f32_16x16x32_bf16 v[48:51], v[212:215], v[132:135], v[48:51]
	s_add_u32 m0, s76, 0x3000
	v_mfma_f32_16x16x32_bf16 v[52:55], v[212:215], v[136:139], v[52:55]
	global_load_lds_dwordx4 v181, s[72:73]
	s_add_u32 m0, s76, 0x4000
	v_mfma_f32_16x16x32_bf16 v[56:59], v[216:219], v[132:135], v[56:59]
	global_load_lds_dwordx4 v170, s[74:75]
	s_add_u32 m0, s76, 0x5000
	v_mfma_f32_16x16x32_bf16 v[60:63], v[216:219], v[136:139], v[60:63]
	global_load_lds_dwordx4 v171, s[74:75]
	s_add_u32 s72, s72, 0x202000
	s_addc_u32 s73, s73, 0
	v_mfma_f32_16x16x32_bf16 v[32:35], v[220:223], v[132:135], v[32:35]
	s_add_u32 s74, s74, 0x10000
	s_addc_u32 s75, s75, 0
	v_mfma_f32_16x16x32_bf16 v[36:39], v[220:223], v[136:139], v[36:39]
	v_mfma_f32_16x16x32_bf16 v[40:43], v[224:227], v[132:135], v[40:43]
	v_mfma_f32_16x16x32_bf16 v[44:47], v[224:227], v[136:139], v[44:47]
	s_waitcnt lgkmcnt(2)
	v_mfma_f32_16x16x32_bf16 v[80:83], v[228:231], v[172:175], v[80:83]
	ds_read_b128 v[132:135], v128 offset:32768
	v_mfma_f32_16x16x32_bf16 v[84:87], v[228:231], v[176:179], v[84:87]
	ds_read_b128 v[136:139], v128 offset:33792
	v_mfma_f32_16x16x32_bf16 v[88:91], v[232:235], v[172:175], v[88:91]
	v_mfma_f32_16x16x32_bf16 v[92:95], v[232:235], v[176:179], v[92:95]
	v_mfma_f32_16x16x32_bf16 v[64:67], v[236:239], v[172:175], v[64:67]
	v_mfma_f32_16x16x32_bf16 v[68:71], v[236:239], v[176:179], v[68:71]
	v_mfma_f32_16x16x32_bf16 v[72:75], v[240:243], v[172:175], v[72:75]
	v_mfma_f32_16x16x32_bf16 v[76:79], v[240:243], v[176:179], v[76:79]
	s_waitcnt lgkmcnt(2)
	v_mfma_f32_16x16x32_bf16 v[16:19], v[228:231], v[248:251], v[16:19]
	ds_read_b128 v[172:175], v128 offset:36864
	v_mfma_f32_16x16x32_bf16 v[20:23], v[228:231], v[244:247], v[20:23]
	ds_read_b128 v[176:179], v128 offset:37888
	v_mfma_f32_16x16x32_bf16 v[24:27], v[232:235], v[248:251], v[24:27]
	v_mfma_f32_16x16x32_bf16 v[28:31], v[232:235], v[244:247], v[28:31]
	v_mfma_f32_16x16x32_bf16 v[0:3], v[236:239], v[248:251], v[0:3]
	v_mfma_f32_16x16x32_bf16 v[4:7], v[236:239], v[244:247], v[4:7]
	v_mfma_f32_16x16x32_bf16 v[8:11], v[240:243], v[248:251], v[8:11]
	v_mfma_f32_16x16x32_bf16 v[12:15], v[240:243], v[244:247], v[12:15]
	s_waitcnt lgkmcnt(0)
	s_waitcnt vmcnt(6)
	s_barrier
	ds_read_b128 v[212:215], v167 offset:49152
	ds_read_b128 v[216:219], v167 offset:50176
	v_mfma_f32_16x16x32_bf16 v[112:115], v[228:231], v[132:135], v[112:115]
	ds_read_b128 v[220:223], v167 offset:51200
	ds_read_b128 v[224:227], v167 offset:52224
	v_mfma_f32_16x16x32_bf16 v[116:119], v[228:231], v[136:139], v[116:119]
	ds_read_b128 v[248:251], v128 offset:49152
	ds_read_b128 v[244:247], v128 offset:50176
	s_add_u32 m0, s76, 0x6000
	v_mfma_f32_16x16x32_bf16 v[120:123], v[232:235], v[132:135], v[120:123]
	global_load_lds_dwordx4 v170, s[72:73]
	s_add_u32 m0, s76, 0x7000
	v_mfma_f32_16x16x32_bf16 v[124:127], v[232:235], v[136:139], v[124:127]
	global_load_lds_dwordx4 v171, s[72:73]
	s_add_u32 m0, s76, 0x8000
	v_mfma_f32_16x16x32_bf16 v[96:99], v[236:239], v[132:135], v[96:99]
	global_load_lds_dwordx4 v180, s[72:73]
	v_mfma_f32_16x16x32_bf16 v[100:103], v[236:239], v[136:139], v[100:103]
	v_mfma_f32_16x16x32_bf16 v[104:107], v[240:243], v[132:135], v[104:107]
	v_mfma_f32_16x16x32_bf16 v[108:111], v[240:243], v[136:139], v[108:111]
	ds_read_b128 v[132:135], v128 offset:53248
	ds_read_b128 v[136:139], v128 offset:54272
	v_mfma_f32_16x16x32_bf16 v[48:51], v[228:231], v[172:175], v[48:51]
	s_add_u32 m0, s76, 0x9000
	v_mfma_f32_16x16x32_bf16 v[52:55], v[228:231], v[176:179], v[52:55]
	global_load_lds_dwordx4 v181, s[72:73]
	s_add_u32 m0, s76, 0xa000
	v_mfma_f32_16x16x32_bf16 v[56:59], v[232:235], v[172:175], v[56:59]
	global_load_lds_dwordx4 v170, s[74:75]
	s_add_u32 m0, s76, 0xb000
	v_mfma_f32_16x16x32_bf16 v[60:63], v[232:235], v[176:179], v[60:63]
	global_load_lds_dwordx4 v171, s[74:75]
	s_add_u32 s72, s72, 0x202000
	s_addc_u32 s73, s73, 0
	v_mfma_f32_16x16x32_bf16 v[32:35], v[236:239], v[172:175], v[32:35]
	s_add_u32 s74, s74, 0x10000
	s_addc_u32 s75, s75, 0
	v_mfma_f32_16x16x32_bf16 v[36:39], v[236:239], v[176:179], v[36:39]
	v_mfma_f32_16x16x32_bf16 v[40:43], v[240:243], v[172:175], v[40:43]
	v_mfma_f32_16x16x32_bf16 v[44:47], v[240:243], v[176:179], v[44:47]
	s_waitcnt lgkmcnt(2)
	v_mfma_f32_16x16x32_bf16 v[80:83], v[212:215], v[248:251], v[80:83]
	ds_read_b128 v[172:175], v128 offset:57344
	v_mfma_f32_16x16x32_bf16 v[84:87], v[212:215], v[244:247], v[84:87]
	ds_read_b128 v[176:179], v128 offset:58368
	v_mfma_f32_16x16x32_bf16 v[88:91], v[216:219], v[248:251], v[88:91]
	v_mfma_f32_16x16x32_bf16 v[92:95], v[216:219], v[244:247], v[92:95]
	v_mfma_f32_16x16x32_bf16 v[64:67], v[220:223], v[248:251], v[64:67]
	v_mfma_f32_16x16x32_bf16 v[68:71], v[220:223], v[244:247], v[68:71]
	v_mfma_f32_16x16x32_bf16 v[72:75], v[224:227], v[248:251], v[72:75]
	v_mfma_f32_16x16x32_bf16 v[76:79], v[224:227], v[244:247], v[76:79]
	s_waitcnt lgkmcnt(2)
	v_mfma_f32_16x16x32_bf16 v[16:19], v[212:215], v[132:135], v[16:19]
	ds_read_b128 v[248:251], v128 offset:61440
	v_mfma_f32_16x16x32_bf16 v[20:23], v[212:215], v[136:139], v[20:23]
	ds_read_b128 v[244:247], v128 offset:62464
	v_mfma_f32_16x16x32_bf16 v[24:27], v[216:219], v[132:135], v[24:27]
	v_mfma_f32_16x16x32_bf16 v[28:31], v[216:219], v[136:139], v[28:31]
	v_mfma_f32_16x16x32_bf16 v[0:3], v[220:223], v[132:135], v[0:3]
	v_mfma_f32_16x16x32_bf16 v[4:7], v[220:223], v[136:139], v[4:7]
	v_mfma_f32_16x16x32_bf16 v[8:11], v[224:227], v[132:135], v[8:11]
	v_mfma_f32_16x16x32_bf16 v[12:15], v[224:227], v[136:139], v[12:15]
	s_waitcnt lgkmcnt(0)
	s_waitcnt vmcnt(6)
	s_barrier
	ds_read_b128 v[228:231], v167
	ds_read_b128 v[232:235], v167 offset:1024
	v_mfma_f32_16x16x32_bf16 v[112:115], v[212:215], v[172:175], v[112:115]
	ds_read_b128 v[236:239], v167 offset:2048
	ds_read_b128 v[240:243], v167 offset:3072
	v_mfma_f32_16x16x32_bf16 v[116:119], v[212:215], v[176:179], v[116:119]
	ds_read_b128 v[132:135], v128
	ds_read_b128 v[136:139], v128 offset:1024
	s_add_u32 m0, s76, 0xc000
	v_mfma_f32_16x16x32_bf16 v[120:123], v[216:219], v[172:175], v[120:123]
	global_load_lds_dwordx4 v170, s[72:73]
	s_add_u32 m0, s76, 0xd000
	v_mfma_f32_16x16x32_bf16 v[124:127], v[216:219], v[176:179], v[124:127]
	global_load_lds_dwordx4 v171, s[72:73]
	s_add_u32 m0, s76, 0xe000
	v_mfma_f32_16x16x32_bf16 v[96:99], v[220:223], v[172:175], v[96:99]
	global_load_lds_dwordx4 v180, s[72:73]
	v_mfma_f32_16x16x32_bf16 v[100:103], v[220:223], v[176:179], v[100:103]
	v_mfma_f32_16x16x32_bf16 v[104:107], v[224:227], v[172:175], v[104:107]
	v_mfma_f32_16x16x32_bf16 v[108:111], v[224:227], v[176:179], v[108:111]
	ds_read_b128 v[172:175], v128 offset:4096
	ds_read_b128 v[176:179], v128 offset:5120
	v_mfma_f32_16x16x32_bf16 v[48:51], v[212:215], v[248:251], v[48:51]
	s_add_u32 m0, s76, 0xf000
	v_mfma_f32_16x16x32_bf16 v[52:55], v[212:215], v[244:247], v[52:55]
	global_load_lds_dwordx4 v181, s[72:73]
	s_add_u32 m0, s76, 0x10000
	v_mfma_f32_16x16x32_bf16 v[56:59], v[216:219], v[248:251], v[56:59]
	global_load_lds_dwordx4 v170, s[74:75]
	s_add_u32 m0, s76, 0x11000
	v_mfma_f32_16x16x32_bf16 v[60:63], v[216:219], v[244:247], v[60:63]
	global_load_lds_dwordx4 v171, s[74:75]
	s_add_u32 s72, s72, 0x202000
	s_addc_u32 s73, s73, 0
	v_mfma_f32_16x16x32_bf16 v[32:35], v[220:223], v[248:251], v[32:35]
	s_add_u32 s74, s74, 0x10000
	s_addc_u32 s75, s75, 0
	v_mfma_f32_16x16x32_bf16 v[36:39], v[220:223], v[244:247], v[36:39]
	v_mfma_f32_16x16x32_bf16 v[40:43], v[224:227], v[248:251], v[40:43]
	v_mfma_f32_16x16x32_bf16 v[44:47], v[224:227], v[244:247], v[44:47]
	s_waitcnt lgkmcnt(2)
	v_mfma_f32_16x16x32_bf16 v[80:83], v[228:231], v[132:135], v[80:83]
	ds_read_b128 v[248:251], v128 offset:8192
	v_mfma_f32_16x16x32_bf16 v[84:87], v[228:231], v[136:139], v[84:87]
	ds_read_b128 v[244:247], v128 offset:9216
	v_mfma_f32_16x16x32_bf16 v[88:91], v[232:235], v[132:135], v[88:91]
	v_mfma_f32_16x16x32_bf16 v[92:95], v[232:235], v[136:139], v[92:95]
	v_mfma_f32_16x16x32_bf16 v[64:67], v[236:239], v[132:135], v[64:67]
	v_mfma_f32_16x16x32_bf16 v[68:71], v[236:239], v[136:139], v[68:71]
	v_mfma_f32_16x16x32_bf16 v[72:75], v[240:243], v[132:135], v[72:75]
	v_mfma_f32_16x16x32_bf16 v[76:79], v[240:243], v[136:139], v[76:79]
	s_waitcnt lgkmcnt(2)
	v_mfma_f32_16x16x32_bf16 v[16:19], v[228:231], v[172:175], v[16:19]
	ds_read_b128 v[132:135], v128 offset:12288
	v_mfma_f32_16x16x32_bf16 v[20:23], v[228:231], v[176:179], v[20:23]
	ds_read_b128 v[136:139], v128 offset:13312
	v_mfma_f32_16x16x32_bf16 v[24:27], v[232:235], v[172:175], v[24:27]
	v_mfma_f32_16x16x32_bf16 v[28:31], v[232:235], v[176:179], v[28:31]
	v_mfma_f32_16x16x32_bf16 v[0:3], v[236:239], v[172:175], v[0:3]
	v_mfma_f32_16x16x32_bf16 v[4:7], v[236:239], v[176:179], v[4:7]
	v_mfma_f32_16x16x32_bf16 v[8:11], v[240:243], v[172:175], v[8:11]
	v_mfma_f32_16x16x32_bf16 v[12:15], v[240:243], v[176:179], v[12:15]
	s_waitcnt lgkmcnt(0)
	s_waitcnt vmcnt(6)
	s_barrier
	ds_read_b128 v[212:215], v167 offset:24576
	ds_read_b128 v[216:219], v167 offset:25600
	v_mfma_f32_16x16x32_bf16 v[112:115], v[228:231], v[248:251], v[112:115]
	ds_read_b128 v[220:223], v167 offset:26624
	ds_read_b128 v[224:227], v167 offset:27648
	v_mfma_f32_16x16x32_bf16 v[116:119], v[228:231], v[244:247], v[116:119]
	ds_read_b128 v[172:175], v128 offset:24576
	ds_read_b128 v[176:179], v128 offset:25600
	s_add_u32 m0, s76, 0x0
	v_mfma_f32_16x16x32_bf16 v[120:123], v[232:235], v[248:251], v[120:123]
	global_load_lds_dwordx4 v170, s[72:73]
	s_add_u32 m0, s76, 0x1000
	v_mfma_f32_16x16x32_bf16 v[124:127], v[232:235], v[244:247], v[124:127]
	global_load_lds_dwordx4 v171, s[72:73]
	s_add_u32 m0, s76, 0x2000
	v_mfma_f32_16x16x32_bf16 v[96:99], v[236:239], v[248:251], v[96:99]
	global_load_lds_dwordx4 v180, s[72:73]
	v_mfma_f32_16x16x32_bf16 v[100:103], v[236:239], v[244:247], v[100:103]
	v_mfma_f32_16x16x32_bf16 v[104:107], v[240:243], v[248:251], v[104:107]
	v_mfma_f32_16x16x32_bf16 v[108:111], v[240:243], v[244:247], v[108:111]
	ds_read_b128 v[248:251], v128 offset:28672
	ds_read_b128 v[244:247], v128 offset:29696
	v_mfma_f32_16x16x32_bf16 v[48:51], v[228:231], v[132:135], v[48:51]
	s_add_u32 m0, s76, 0x3000
	v_mfma_f32_16x16x32_bf16 v[52:55], v[228:231], v[136:139], v[52:55]
	global_load_lds_dwordx4 v181, s[72:73]
	s_add_u32 m0, s76, 0x4000
	v_mfma_f32_16x16x32_bf16 v[56:59], v[232:235], v[132:135], v[56:59]
	global_load_lds_dwordx4 v170, s[74:75]
	s_add_u32 m0, s76, 0x5000
	v_mfma_f32_16x16x32_bf16 v[60:63], v[232:235], v[136:139], v[60:63]
	global_load_lds_dwordx4 v171, s[74:75]
	s_add_u32 s72, s72, 0x202000
	s_addc_u32 s73, s73, 0
	v_mfma_f32_16x16x32_bf16 v[32:35], v[236:239], v[132:135], v[32:35]
	s_add_u32 s74, s74, 0x10000
	s_addc_u32 s75, s75, 0
	v_mfma_f32_16x16x32_bf16 v[36:39], v[236:239], v[136:139], v[36:39]
	v_mfma_f32_16x16x32_bf16 v[40:43], v[240:243], v[132:135], v[40:43]
	v_mfma_f32_16x16x32_bf16 v[44:47], v[240:243], v[136:139], v[44:47]
	s_waitcnt lgkmcnt(2)
	v_mfma_f32_16x16x32_bf16 v[80:83], v[212:215], v[172:175], v[80:83]
	ds_read_b128 v[132:135], v128 offset:32768
	v_mfma_f32_16x16x32_bf16 v[84:87], v[212:215], v[176:179], v[84:87]
	ds_read_b128 v[136:139], v128 offset:33792
	v_mfma_f32_16x16x32_bf16 v[88:91], v[216:219], v[172:175], v[88:91]
	v_mfma_f32_16x16x32_bf16 v[92:95], v[216:219], v[176:179], v[92:95]
	v_mfma_f32_16x16x32_bf16 v[64:67], v[220:223], v[172:175], v[64:67]
	v_mfma_f32_16x16x32_bf16 v[68:71], v[220:223], v[176:179], v[68:71]
	v_mfma_f32_16x16x32_bf16 v[72:75], v[224:227], v[172:175], v[72:75]
	v_mfma_f32_16x16x32_bf16 v[76:79], v[224:227], v[176:179], v[76:79]
	s_waitcnt lgkmcnt(2)
	v_mfma_f32_16x16x32_bf16 v[16:19], v[212:215], v[248:251], v[16:19]
	ds_read_b128 v[172:175], v128 offset:36864
	v_mfma_f32_16x16x32_bf16 v[20:23], v[212:215], v[244:247], v[20:23]
	ds_read_b128 v[176:179], v128 offset:37888
	v_mfma_f32_16x16x32_bf16 v[24:27], v[216:219], v[248:251], v[24:27]
	v_mfma_f32_16x16x32_bf16 v[28:31], v[216:219], v[244:247], v[28:31]
	v_mfma_f32_16x16x32_bf16 v[0:3], v[220:223], v[248:251], v[0:3]
	v_mfma_f32_16x16x32_bf16 v[4:7], v[220:223], v[244:247], v[4:7]
	v_mfma_f32_16x16x32_bf16 v[8:11], v[224:227], v[248:251], v[8:11]
	v_mfma_f32_16x16x32_bf16 v[12:15], v[224:227], v[244:247], v[12:15]
	s_waitcnt lgkmcnt(0)
	s_waitcnt vmcnt(6)
	s_barrier
	ds_read_b128 v[228:231], v167 offset:49152
	ds_read_b128 v[232:235], v167 offset:50176
	v_mfma_f32_16x16x32_bf16 v[112:115], v[212:215], v[132:135], v[112:115]
	ds_read_b128 v[236:239], v167 offset:51200
	ds_read_b128 v[240:243], v167 offset:52224
	v_mfma_f32_16x16x32_bf16 v[116:119], v[212:215], v[136:139], v[116:119]
	ds_read_b128 v[248:251], v128 offset:49152
	ds_read_b128 v[244:247], v128 offset:50176
	s_add_u32 m0, s76, 0x6000
	v_mfma_f32_16x16x32_bf16 v[120:123], v[216:219], v[132:135], v[120:123]
	global_load_lds_dwordx4 v170, s[72:73]
	s_add_u32 m0, s76, 0x7000
	v_mfma_f32_16x16x32_bf16 v[124:127], v[216:219], v[136:139], v[124:127]
	global_load_lds_dwordx4 v171, s[72:73]
	s_add_u32 m0, s76, 0x8000
	v_mfma_f32_16x16x32_bf16 v[96:99], v[220:223], v[132:135], v[96:99]
	global_load_lds_dwordx4 v180, s[72:73]
	v_mfma_f32_16x16x32_bf16 v[100:103], v[220:223], v[136:139], v[100:103]
	v_mfma_f32_16x16x32_bf16 v[104:107], v[224:227], v[132:135], v[104:107]
	v_mfma_f32_16x16x32_bf16 v[108:111], v[224:227], v[136:139], v[108:111]
	ds_read_b128 v[132:135], v128 offset:53248
	ds_read_b128 v[136:139], v128 offset:54272
	v_mfma_f32_16x16x32_bf16 v[48:51], v[212:215], v[172:175], v[48:51]
	s_add_u32 m0, s76, 0x9000
	v_mfma_f32_16x16x32_bf16 v[52:55], v[212:215], v[176:179], v[52:55]
	global_load_lds_dwordx4 v181, s[72:73]
	s_add_u32 m0, s76, 0xa000
	v_mfma_f32_16x16x32_bf16 v[56:59], v[216:219], v[172:175], v[56:59]
	global_load_lds_dwordx4 v170, s[74:75]
	s_add_u32 m0, s76, 0xb000
	v_mfma_f32_16x16x32_bf16 v[60:63], v[216:219], v[176:179], v[60:63]
	global_load_lds_dwordx4 v171, s[74:75]
	s_add_u32 s72, s72, 0x202000
	s_addc_u32 s73, s73, 0
	v_mfma_f32_16x16x32_bf16 v[32:35], v[220:223], v[172:175], v[32:35]
	s_add_u32 s74, s74, 0x10000
	s_addc_u32 s75, s75, 0
	v_mfma_f32_16x16x32_bf16 v[36:39], v[220:223], v[176:179], v[36:39]
	v_mfma_f32_16x16x32_bf16 v[40:43], v[224:227], v[172:175], v[40:43]
	v_mfma_f32_16x16x32_bf16 v[44:47], v[224:227], v[176:179], v[44:47]
	s_waitcnt lgkmcnt(2)
	v_mfma_f32_16x16x32_bf16 v[80:83], v[228:231], v[248:251], v[80:83]
	ds_read_b128 v[172:175], v128 offset:57344
	v_mfma_f32_16x16x32_bf16 v[84:87], v[228:231], v[244:247], v[84:87]
	ds_read_b128 v[176:179], v128 offset:58368
	v_mfma_f32_16x16x32_bf16 v[88:91], v[232:235], v[248:251], v[88:91]
	v_mfma_f32_16x16x32_bf16 v[92:95], v[232:235], v[244:247], v[92:95]
	v_mfma_f32_16x16x32_bf16 v[64:67], v[236:239], v[248:251], v[64:67]
	v_mfma_f32_16x16x32_bf16 v[68:71], v[236:239], v[244:247], v[68:71]
	v_mfma_f32_16x16x32_bf16 v[72:75], v[240:243], v[248:251], v[72:75]
	v_mfma_f32_16x16x32_bf16 v[76:79], v[240:243], v[244:247], v[76:79]
	s_waitcnt lgkmcnt(2)
	v_mfma_f32_16x16x32_bf16 v[16:19], v[228:231], v[132:135], v[16:19]
	ds_read_b128 v[248:251], v128 offset:61440
	v_mfma_f32_16x16x32_bf16 v[20:23], v[228:231], v[136:139], v[20:23]
	ds_read_b128 v[244:247], v128 offset:62464
	v_mfma_f32_16x16x32_bf16 v[24:27], v[232:235], v[132:135], v[24:27]
	v_mfma_f32_16x16x32_bf16 v[28:31], v[232:235], v[136:139], v[28:31]
	v_mfma_f32_16x16x32_bf16 v[0:3], v[236:239], v[132:135], v[0:3]
	v_mfma_f32_16x16x32_bf16 v[4:7], v[236:239], v[136:139], v[4:7]
	v_mfma_f32_16x16x32_bf16 v[8:11], v[240:243], v[132:135], v[8:11]
	v_mfma_f32_16x16x32_bf16 v[12:15], v[240:243], v[136:139], v[12:15]
	s_waitcnt lgkmcnt(0)
	s_waitcnt vmcnt(6)
	s_barrier
	ds_read_b128 v[212:215], v167
	ds_read_b128 v[216:219], v167 offset:1024
	v_mfma_f32_16x16x32_bf16 v[112:115], v[228:231], v[172:175], v[112:115]
	ds_read_b128 v[220:223], v167 offset:2048
	ds_read_b128 v[224:227], v167 offset:3072
	v_mfma_f32_16x16x32_bf16 v[116:119], v[228:231], v[176:179], v[116:119]
	ds_read_b128 v[132:135], v128
	ds_read_b128 v[136:139], v128 offset:1024
	s_add_u32 m0, s76, 0xc000
	v_mfma_f32_16x16x32_bf16 v[120:123], v[232:235], v[172:175], v[120:123]
	global_load_lds_dwordx4 v170, s[72:73]
	s_add_u32 m0, s76, 0xd000
	v_mfma_f32_16x16x32_bf16 v[124:127], v[232:235], v[176:179], v[124:127]
	global_load_lds_dwordx4 v171, s[72:73]
	s_add_u32 m0, s76, 0xe000
	v_mfma_f32_16x16x32_bf16 v[96:99], v[236:239], v[172:175], v[96:99]
	global_load_lds_dwordx4 v180, s[72:73]
	v_mfma_f32_16x16x32_bf16 v[100:103], v[236:239], v[176:179], v[100:103]
	v_mfma_f32_16x16x32_bf16 v[104:107], v[240:243], v[172:175], v[104:107]
	v_mfma_f32_16x16x32_bf16 v[108:111], v[240:243], v[176:179], v[108:111]
	ds_read_b128 v[172:175], v128 offset:4096
	ds_read_b128 v[176:179], v128 offset:5120
	v_mfma_f32_16x16x32_bf16 v[48:51], v[228:231], v[248:251], v[48:51]
	s_add_u32 m0, s76, 0xf000
	v_mfma_f32_16x16x32_bf16 v[52:55], v[228:231], v[244:247], v[52:55]
	global_load_lds_dwordx4 v181, s[72:73]
	s_add_u32 m0, s76, 0x10000
	v_mfma_f32_16x16x32_bf16 v[56:59], v[232:235], v[248:251], v[56:59]
	global_load_lds_dwordx4 v170, s[74:75]
	s_add_u32 m0, s76, 0x11000
	v_mfma_f32_16x16x32_bf16 v[60:63], v[232:235], v[244:247], v[60:63]
	global_load_lds_dwordx4 v171, s[74:75]
	s_add_u32 s72, s72, 0x202000
	s_addc_u32 s73, s73, 0
	v_mfma_f32_16x16x32_bf16 v[32:35], v[236:239], v[248:251], v[32:35]
	s_add_u32 s74, s74, 0x10000
	s_addc_u32 s75, s75, 0
	v_mfma_f32_16x16x32_bf16 v[36:39], v[236:239], v[244:247], v[36:39]
	v_mfma_f32_16x16x32_bf16 v[40:43], v[240:243], v[248:251], v[40:43]
	v_mfma_f32_16x16x32_bf16 v[44:47], v[240:243], v[244:247], v[44:47]
	s_sub_i32 s77, s77, 1
	s_cmp_lg_u32 s77, 0
	s_cbranch_scc1 .Lgemm_p3_loop
	s_waitcnt lgkmcnt(2)
	v_mfma_f32_16x16x32_bf16 v[80:83], v[212:215], v[132:135], v[80:83]
	ds_read_b128 v[248:251], v128 offset:8192
	v_mfma_f32_16x16x32_bf16 v[84:87], v[212:215], v[136:139], v[84:87]
	ds_read_b128 v[244:247], v128 offset:9216
	v_mfma_f32_16x16x32_bf16 v[88:91], v[216:219], v[132:135], v[88:91]
	v_mfma_f32_16x16x32_bf16 v[92:95], v[216:219], v[136:139], v[92:95]
	v_mfma_f32_16x16x32_bf16 v[64:67], v[220:223], v[132:135], v[64:67]
	v_mfma_f32_16x16x32_bf16 v[68:71], v[220:223], v[136:139], v[68:71]
	v_mfma_f32_16x16x32_bf16 v[72:75], v[224:227], v[132:135], v[72:75]
	v_mfma_f32_16x16x32_bf16 v[76:79], v[224:227], v[136:139], v[76:79]
	s_waitcnt lgkmcnt(2)
	v_mfma_f32_16x16x32_bf16 v[16:19], v[212:215], v[172:175], v[16:19]
	ds_read_b128 v[132:135], v128 offset:12288
	v_mfma_f32_16x16x32_bf16 v[20:23], v[212:215], v[176:179], v[20:23]
	ds_read_b128 v[136:139], v128 offset:13312
	v_mfma_f32_16x16x32_bf16 v[24:27], v[216:219], v[172:175], v[24:27]
	v_mfma_f32_16x16x32_bf16 v[28:31], v[216:219], v[176:179], v[28:31]
	v_mfma_f32_16x16x32_bf16 v[0:3], v[220:223], v[172:175], v[0:3]
	v_mfma_f32_16x16x32_bf16 v[4:7], v[220:223], v[176:179], v[4:7]
	v_mfma_f32_16x16x32_bf16 v[8:11], v[224:227], v[172:175], v[8:11]
	v_mfma_f32_16x16x32_bf16 v[12:15], v[224:227], v[176:179], v[12:15]
	s_waitcnt lgkmcnt(0)
	s_waitcnt vmcnt(6)
	s_barrier
	ds_read_b128 v[228:231], v167 offset:24576
	ds_read_b128 v[232:235], v167 offset:25600
	v_mfma_f32_16x16x32_bf16 v[112:115], v[212:215], v[248:251], v[112:115]
	ds_read_b128 v[236:239], v167 offset:26624
	ds_read_b128 v[240:243], v167 offset:27648
	v_mfma_f32_16x16x32_bf16 v[116:119], v[212:215], v[244:247], v[116:119]
	ds_read_b128 v[172:175], v128 offset:24576
	ds_read_b128 v[176:179], v128 offset:25600
	s_add_u32 m0, s76, 0x0
	v_mfma_f32_16x16x32_bf16 v[120:123], v[216:219], v[248:251], v[120:123]
	global_load_lds_dwordx4 v170, s[72:73]
	s_add_u32 m0, s76, 0x1000
	v_mfma_f32_16x16x32_bf16 v[124:127], v[216:219], v[244:247], v[124:127]
	global_load_lds_dwordx4 v171, s[72:73]
	s_add_u32 m0, s76, 0x2000
	v_mfma_f32_16x16x32_bf16 v[96:99], v[220:223], v[248:251], v[96:99]
	global_load_lds_dwordx4 v180, s[72:73]
	v_mfma_f32_16x16x32_bf16 v[100:103], v[220:223], v[244:247], v[100:103]
	v_mfma_f32_16x16x32_bf16 v[104:107], v[224:227], v[248:251], v[104:107]
	v_mfma_f32_16x16x32_bf16 v[108:111], v[224:227], v[244:247], v[108:111]
	ds_read_b128 v[248:251], v128 offset:28672
	ds_read_b128 v[244:247], v128 offset:29696
	v_mfma_f32_16x16x32_bf16 v[48:51], v[212:215], v[132:135], v[48:51]
	s_add_u32 m0, s76, 0x3000
	v_mfma_f32_16x16x32_bf16 v[52:55], v[212:215], v[136:139], v[52:55]
	global_load_lds_dwordx4 v181, s[72:73]
	s_add_u32 m0, s76, 0x4000
	v_mfma_f32_16x16x32_bf16 v[56:59], v[216:219], v[132:135], v[56:59]
	global_load_lds_dwordx4 v170, s[74:75]
	s_add_u32 m0, s76, 0x5000
	v_mfma_f32_16x16x32_bf16 v[60:63], v[216:219], v[136:139], v[60:63]
	global_load_lds_dwordx4 v171, s[74:75]
	s_add_u32 s72, s72, 0x202000
	s_addc_u32 s73, s73, 0
	v_mfma_f32_16x16x32_bf16 v[32:35], v[220:223], v[132:135], v[32:35]
	s_add_u32 s74, s74, 0x10000
	s_addc_u32 s75, s75, 0
	v_mfma_f32_16x16x32_bf16 v[36:39], v[220:223], v[136:139], v[36:39]
	v_mfma_f32_16x16x32_bf16 v[40:43], v[224:227], v[132:135], v[40:43]
	v_mfma_f32_16x16x32_bf16 v[44:47], v[224:227], v[136:139], v[44:47]
	s_waitcnt lgkmcnt(2)
	v_mfma_f32_16x16x32_bf16 v[80:83], v[228:231], v[172:175], v[80:83]
	ds_read_b128 v[132:135], v128 offset:32768
	v_mfma_f32_16x16x32_bf16 v[84:87], v[228:231], v[176:179], v[84:87]
	ds_read_b128 v[136:139], v128 offset:33792
	v_mfma_f32_16x16x32_bf16 v[88:91], v[232:235], v[172:175], v[88:91]
	v_mfma_f32_16x16x32_bf16 v[92:95], v[232:235], v[176:179], v[92:95]
	v_mfma_f32_16x16x32_bf16 v[64:67], v[236:239], v[172:175], v[64:67]
	v_mfma_f32_16x16x32_bf16 v[68:71], v[236:239], v[176:179], v[68:71]
	v_mfma_f32_16x16x32_bf16 v[72:75], v[240:243], v[172:175], v[72:75]
	v_mfma_f32_16x16x32_bf16 v[76:79], v[240:243], v[176:179], v[76:79]
	s_waitcnt lgkmcnt(2)
	v_mfma_f32_16x16x32_bf16 v[16:19], v[228:231], v[248:251], v[16:19]
	ds_read_b128 v[172:175], v128 offset:36864
	v_mfma_f32_16x16x32_bf16 v[20:23], v[228:231], v[244:247], v[20:23]
	ds_read_b128 v[176:179], v128 offset:37888
	v_mfma_f32_16x16x32_bf16 v[24:27], v[232:235], v[248:251], v[24:27]
	v_mfma_f32_16x16x32_bf16 v[28:31], v[232:235], v[244:247], v[28:31]
	v_mfma_f32_16x16x32_bf16 v[0:3], v[236:239], v[248:251], v[0:3]
	v_mfma_f32_16x16x32_bf16 v[4:7], v[236:239], v[244:247], v[4:7]
	v_mfma_f32_16x16x32_bf16 v[8:11], v[240:243], v[248:251], v[8:11]
	v_mfma_f32_16x16x32_bf16 v[12:15], v[240:243], v[244:247], v[12:15]
	s_waitcnt lgkmcnt(0)
	s_waitcnt vmcnt(6)
	s_barrier
	ds_read_b128 v[212:215], v167 offset:49152
	ds_read_b128 v[216:219], v167 offset:50176
	v_mfma_f32_16x16x32_bf16 v[112:115], v[228:231], v[132:135], v[112:115]
	ds_read_b128 v[220:223], v167 offset:51200
	ds_read_b128 v[224:227], v167 offset:52224
	v_mfma_f32_16x16x32_bf16 v[116:119], v[228:231], v[136:139], v[116:119]
	ds_read_b128 v[248:251], v128 offset:49152
	ds_read_b128 v[244:247], v128 offset:50176
	s_add_u32 m0, s76, 0x6000
	v_mfma_f32_16x16x32_bf16 v[120:123], v[232:235], v[132:135], v[120:123]
	global_load_lds_dwordx4 v170, s[72:73]
	s_add_u32 m0, s76, 0x7000
	v_mfma_f32_16x16x32_bf16 v[124:127], v[232:235], v[136:139], v[124:127]
	global_load_lds_dwordx4 v171, s[72:73]
	s_add_u32 m0, s76, 0x8000
	v_mfma_f32_16x16x32_bf16 v[96:99], v[236:239], v[132:135], v[96:99]
	global_load_lds_dwordx4 v180, s[72:73]
	v_mfma_f32_16x16x32_bf16 v[100:103], v[236:239], v[136:139], v[100:103]
	v_mfma_f32_16x16x32_bf16 v[104:107], v[240:243], v[132:135], v[104:107]
	v_mfma_f32_16x16x32_bf16 v[108:111], v[240:243], v[136:139], v[108:111]
	ds_read_b128 v[132:135], v128 offset:53248
	ds_read_b128 v[136:139], v128 offset:54272
	v_mfma_f32_16x16x32_bf16 v[48:51], v[228:231], v[172:175], v[48:51]
	s_add_u32 m0, s76, 0x9000
	v_mfma_f32_16x16x32_bf16 v[52:55], v[228:231], v[176:179], v[52:55]
	global_load_lds_dwordx4 v181, s[72:73]
	s_add_u32 m0, s76, 0xa000
	v_mfma_f32_16x16x32_bf16 v[56:59], v[232:235], v[172:175], v[56:59]
	global_load_lds_dwordx4 v170, s[74:75]
	s_add_u32 m0, s76, 0xb000
	v_mfma_f32_16x16x32_bf16 v[60:63], v[232:235], v[176:179], v[60:63]
	global_load_lds_dwordx4 v171, s[74:75]
	s_add_u32 s72, s72, 0x202000
	s_addc_u32 s73, s73, 0
	v_mfma_f32_16x16x32_bf16 v[32:35], v[236:239], v[172:175], v[32:35]
	s_add_u32 s74, s74, 0x10000
	s_addc_u32 s75, s75, 0
	v_mfma_f32_16x16x32_bf16 v[36:39], v[236:239], v[176:179], v[36:39]
	v_mfma_f32_16x16x32_bf16 v[40:43], v[240:243], v[172:175], v[40:43]
	v_mfma_f32_16x16x32_bf16 v[44:47], v[240:243], v[176:179], v[44:47]
	s_waitcnt lgkmcnt(2)
	v_mfma_f32_16x16x32_bf16 v[80:83], v[212:215], v[248:251], v[80:83]
	ds_read_b128 v[172:175], v128 offset:57344
	v_mfma_f32_16x16x32_bf16 v[84:87], v[212:215], v[244:247], v[84:87]
	ds_read_b128 v[176:179], v128 offset:58368
	v_mfma_f32_16x16x32_bf16 v[88:91], v[216:219], v[248:251], v[88:91]
	v_mfma_f32_16x16x32_bf16 v[92:95], v[216:219], v[244:247], v[92:95]
	v_mfma_f32_16x16x32_bf16 v[64:67], v[220:223], v[248:251], v[64:67]
	v_mfma_f32_16x16x32_bf16 v[68:71], v[220:223], v[244:247], v[68:71]
	v_mfma_f32_16x16x32_bf16 v[72:75], v[224:227], v[248:251], v[72:75]
	v_mfma_f32_16x16x32_bf16 v[76:79], v[224:227], v[244:247], v[76:79]
	s_waitcnt lgkmcnt(2)
	v_mfma_f32_16x16x32_bf16 v[16:19], v[212:215], v[132:135], v[16:19]
	ds_read_b128 v[248:251], v128 offset:61440
	v_mfma_f32_16x16x32_bf16 v[20:23], v[212:215], v[136:139], v[20:23]
	ds_read_b128 v[244:247], v128 offset:62464
	v_mfma_f32_16x16x32_bf16 v[24:27], v[216:219], v[132:135], v[24:27]
	v_mfma_f32_16x16x32_bf16 v[28:31], v[216:219], v[136:139], v[28:31]
	v_mfma_f32_16x16x32_bf16 v[0:3], v[220:223], v[132:135], v[0:3]
	v_mfma_f32_16x16x32_bf16 v[4:7], v[220:223], v[136:139], v[4:7]
	v_mfma_f32_16x16x32_bf16 v[8:11], v[224:227], v[132:135], v[8:11]
	v_mfma_f32_16x16x32_bf16 v[12:15], v[224:227], v[136:139], v[12:15]
	s_waitcnt lgkmcnt(0)
	s_waitcnt vmcnt(6)
	s_barrier
	ds_read_b128 v[228:231], v167
	ds_read_b128 v[232:235], v167 offset:1024
	v_mfma_f32_16x16x32_bf16 v[112:115], v[212:215], v[172:175], v[112:115]
	ds_read_b128 v[236:239], v167 offset:2048
	ds_read_b128 v[240:243], v167 offset:3072
	v_mfma_f32_16x16x32_bf16 v[116:119], v[212:215], v[176:179], v[116:119]
	ds_read_b128 v[132:135], v128
	ds_read_b128 v[136:139], v128 offset:1024
	s_add_u32 m0, s76, 0xc000
	v_mfma_f32_16x16x32_bf16 v[120:123], v[216:219], v[172:175], v[120:123]
	global_load_lds_dwordx4 v170, s[72:73]
	s_add_u32 m0, s76, 0xd000
	v_mfma_f32_16x16x32_bf16 v[124:127], v[216:219], v[176:179], v[124:127]
	global_load_lds_dwordx4 v171, s[72:73]
	s_add_u32 m0, s76, 0xe000
	v_mfma_f32_16x16x32_bf16 v[96:99], v[220:223], v[172:175], v[96:99]
	global_load_lds_dwordx4 v180, s[72:73]
	v_mfma_f32_16x16x32_bf16 v[100:103], v[220:223], v[176:179], v[100:103]
	v_mfma_f32_16x16x32_bf16 v[104:107], v[224:227], v[172:175], v[104:107]
	v_mfma_f32_16x16x32_bf16 v[108:111], v[224:227], v[176:179], v[108:111]
	ds_read_b128 v[172:175], v128 offset:4096
	ds_read_b128 v[176:179], v128 offset:5120
	v_mfma_f32_16x16x32_bf16 v[48:51], v[212:215], v[248:251], v[48:51]
	s_add_u32 m0, s76, 0xf000
	v_mfma_f32_16x16x32_bf16 v[52:55], v[212:215], v[244:247], v[52:55]
	global_load_lds_dwordx4 v181, s[72:73]
	s_add_u32 m0, s76, 0x10000
	v_mfma_f32_16x16x32_bf16 v[56:59], v[216:219], v[248:251], v[56:59]
	global_load_lds_dwordx4 v170, s[74:75]
	s_add_u32 m0, s76, 0x11000
	v_mfma_f32_16x16x32_bf16 v[60:63], v[216:219], v[244:247], v[60:63]
	global_load_lds_dwordx4 v171, s[74:75]
	s_add_u32 s72, s72, 0x202000
	s_addc_u32 s73, s73, 0
	v_mfma_f32_16x16x32_bf16 v[32:35], v[220:223], v[248:251], v[32:35]
	s_add_u32 s74, s74, 0x10000
	s_addc_u32 s75, s75, 0
	v_mfma_f32_16x16x32_bf16 v[36:39], v[220:223], v[244:247], v[36:39]
	v_mfma_f32_16x16x32_bf16 v[40:43], v[224:227], v[248:251], v[40:43]
	v_mfma_f32_16x16x32_bf16 v[44:47], v[224:227], v[244:247], v[44:47]
	s_waitcnt lgkmcnt(2)
	v_mfma_f32_16x16x32_bf16 v[80:83], v[228:231], v[132:135], v[80:83]
	ds_read_b128 v[248:251], v128 offset:8192
	v_mfma_f32_16x16x32_bf16 v[84:87], v[228:231], v[136:139], v[84:87]
	ds_read_b128 v[244:247], v128 offset:9216
	v_mfma_f32_16x16x32_bf16 v[88:91], v[232:235], v[132:135], v[88:91]
	v_mfma_f32_16x16x32_bf16 v[92:95], v[232:235], v[136:139], v[92:95]
	v_mfma_f32_16x16x32_bf16 v[64:67], v[236:239], v[132:135], v[64:67]
	v_mfma_f32_16x16x32_bf16 v[68:71], v[236:239], v[136:139], v[68:71]
	v_mfma_f32_16x16x32_bf16 v[72:75], v[240:243], v[132:135], v[72:75]
	v_mfma_f32_16x16x32_bf16 v[76:79], v[240:243], v[136:139], v[76:79]
	s_waitcnt lgkmcnt(2)
	v_mfma_f32_16x16x32_bf16 v[16:19], v[228:231], v[172:175], v[16:19]
	ds_read_b128 v[132:135], v128 offset:12288
	v_mfma_f32_16x16x32_bf16 v[20:23], v[228:231], v[176:179], v[20:23]
	ds_read_b128 v[136:139], v128 offset:13312
	v_mfma_f32_16x16x32_bf16 v[24:27], v[232:235], v[172:175], v[24:27]
	v_mfma_f32_16x16x32_bf16 v[28:31], v[232:235], v[176:179], v[28:31]
	v_mfma_f32_16x16x32_bf16 v[0:3], v[236:239], v[172:175], v[0:3]
	v_mfma_f32_16x16x32_bf16 v[4:7], v[236:239], v[176:179], v[4:7]
	v_mfma_f32_16x16x32_bf16 v[8:11], v[240:243], v[172:175], v[8:11]
	v_mfma_f32_16x16x32_bf16 v[12:15], v[240:243], v[176:179], v[12:15]
	s_waitcnt lgkmcnt(0)
	s_waitcnt vmcnt(6)
	s_barrier
	ds_read_b128 v[212:215], v167 offset:24576
	ds_read_b128 v[216:219], v167 offset:25600
	v_mfma_f32_16x16x32_bf16 v[112:115], v[228:231], v[248:251], v[112:115]
	ds_read_b128 v[220:223], v167 offset:26624
	ds_read_b128 v[224:227], v167 offset:27648
	v_mfma_f32_16x16x32_bf16 v[116:119], v[228:231], v[244:247], v[116:119]
	ds_read_b128 v[172:175], v128 offset:24576
	ds_read_b128 v[176:179], v128 offset:25600
	s_add_u32 m0, s76, 0x0
	v_mfma_f32_16x16x32_bf16 v[120:123], v[232:235], v[248:251], v[120:123]
	global_load_lds_dwordx4 v170, s[72:73]
	s_add_u32 m0, s76, 0x1000
	v_mfma_f32_16x16x32_bf16 v[124:127], v[232:235], v[244:247], v[124:127]
	global_load_lds_dwordx4 v171, s[72:73]
	s_add_u32 m0, s76, 0x2000
	v_mfma_f32_16x16x32_bf16 v[96:99], v[236:239], v[248:251], v[96:99]
	global_load_lds_dwordx4 v180, s[72:73]
	v_mfma_f32_16x16x32_bf16 v[100:103], v[236:239], v[244:247], v[100:103]
	v_mfma_f32_16x16x32_bf16 v[104:107], v[240:243], v[248:251], v[104:107]
	v_mfma_f32_16x16x32_bf16 v[108:111], v[240:243], v[244:247], v[108:111]
	ds_read_b128 v[248:251], v128 offset:28672
	ds_read_b128 v[244:247], v128 offset:29696
	v_mfma_f32_16x16x32_bf16 v[48:51], v[228:231], v[132:135], v[48:51]
	s_add_u32 m0, s76, 0x3000
	v_mfma_f32_16x16x32_bf16 v[52:55], v[228:231], v[136:139], v[52:55]
	global_load_lds_dwordx4 v181, s[72:73]
	s_add_u32 m0, s76, 0x4000
	v_mfma_f32_16x16x32_bf16 v[56:59], v[232:235], v[132:135], v[56:59]
	global_load_lds_dwordx4 v170, s[74:75]
	s_add_u32 m0, s76, 0x5000
	v_mfma_f32_16x16x32_bf16 v[60:63], v[232:235], v[136:139], v[60:63]
	global_load_lds_dwordx4 v171, s[74:75]
	s_add_u32 s72, s72, 0x202000
	s_addc_u32 s73, s73, 0
	v_mfma_f32_16x16x32_bf16 v[32:35], v[236:239], v[132:135], v[32:35]
	s_add_u32 s74, s74, 0x10000
	s_addc_u32 s75, s75, 0
	v_mfma_f32_16x16x32_bf16 v[36:39], v[236:239], v[136:139], v[36:39]
	v_mfma_f32_16x16x32_bf16 v[40:43], v[240:243], v[132:135], v[40:43]
	v_mfma_f32_16x16x32_bf16 v[44:47], v[240:243], v[136:139], v[44:47]
	s_waitcnt lgkmcnt(2)
	v_mfma_f32_16x16x32_bf16 v[80:83], v[212:215], v[172:175], v[80:83]
	ds_read_b128 v[132:135], v128 offset:32768
	v_mfma_f32_16x16x32_bf16 v[84:87], v[212:215], v[176:179], v[84:87]
	ds_read_b128 v[136:139], v128 offset:33792
	v_mfma_f32_16x16x32_bf16 v[88:91], v[216:219], v[172:175], v[88:91]
	v_mfma_f32_16x16x32_bf16 v[92:95], v[216:219], v[176:179], v[92:95]
	v_mfma_f32_16x16x32_bf16 v[64:67], v[220:223], v[172:175], v[64:67]
	v_mfma_f32_16x16x32_bf16 v[68:71], v[220:223], v[176:179], v[68:71]
	v_mfma_f32_16x16x32_bf16 v[72:75], v[224:227], v[172:175], v[72:75]
	v_mfma_f32_16x16x32_bf16 v[76:79], v[224:227], v[176:179], v[76:79]
	s_waitcnt lgkmcnt(2)
	v_mfma_f32_16x16x32_bf16 v[16:19], v[212:215], v[248:251], v[16:19]
	ds_read_b128 v[172:175], v128 offset:36864
	v_mfma_f32_16x16x32_bf16 v[20:23], v[212:215], v[244:247], v[20:23]
	ds_read_b128 v[176:179], v128 offset:37888
	v_mfma_f32_16x16x32_bf16 v[24:27], v[216:219], v[248:251], v[24:27]
	v_mfma_f32_16x16x32_bf16 v[28:31], v[216:219], v[244:247], v[28:31]
	v_mfma_f32_16x16x32_bf16 v[0:3], v[220:223], v[248:251], v[0:3]
	v_mfma_f32_16x16x32_bf16 v[4:7], v[220:223], v[244:247], v[4:7]
	v_mfma_f32_16x16x32_bf16 v[8:11], v[224:227], v[248:251], v[8:11]
	v_mfma_f32_16x16x32_bf16 v[12:15], v[224:227], v[244:247], v[12:15]
	s_waitcnt lgkmcnt(0)
	s_waitcnt vmcnt(6)
	s_barrier
	ds_read_b128 v[228:231], v167 offset:49152
	ds_read_b128 v[232:235], v167 offset:50176
	v_mfma_f32_16x16x32_bf16 v[112:115], v[212:215], v[132:135], v[112:115]
	ds_read_b128 v[236:239], v167 offset:51200
	ds_read_b128 v[240:243], v167 offset:52224
	v_mfma_f32_16x16x32_bf16 v[116:119], v[212:215], v[136:139], v[116:119]
	ds_read_b128 v[248:251], v128 offset:49152
	ds_read_b128 v[244:247], v128 offset:50176
	s_add_u32 m0, s76, 0x6000
	v_mfma_f32_16x16x32_bf16 v[120:123], v[216:219], v[132:135], v[120:123]
	global_load_lds_dwordx4 v170, s[72:73]
	s_add_u32 m0, s76, 0x7000
	v_mfma_f32_16x16x32_bf16 v[124:127], v[216:219], v[136:139], v[124:127]
	global_load_lds_dwordx4 v171, s[72:73]
	s_add_u32 m0, s76, 0x8000
	v_mfma_f32_16x16x32_bf16 v[96:99], v[220:223], v[132:135], v[96:99]
	global_load_lds_dwordx4 v180, s[72:73]
	v_mfma_f32_16x16x32_bf16 v[100:103], v[220:223], v[136:139], v[100:103]
	v_mfma_f32_16x16x32_bf16 v[104:107], v[224:227], v[132:135], v[104:107]
	v_mfma_f32_16x16x32_bf16 v[108:111], v[224:227], v[136:139], v[108:111]
	ds_read_b128 v[132:135], v128 offset:53248
	ds_read_b128 v[136:139], v128 offset:54272
	v_mfma_f32_16x16x32_bf16 v[48:51], v[212:215], v[172:175], v[48:51]
	s_add_u32 m0, s76, 0x9000
	v_mfma_f32_16x16x32_bf16 v[52:55], v[212:215], v[176:179], v[52:55]
	global_load_lds_dwordx4 v181, s[72:73]
	s_add_u32 m0, s76, 0xa000
	v_mfma_f32_16x16x32_bf16 v[56:59], v[216:219], v[172:175], v[56:59]
	global_load_lds_dwordx4 v170, s[74:75]
	s_add_u32 m0, s76, 0xb000
	v_mfma_f32_16x16x32_bf16 v[60:63], v[216:219], v[176:179], v[60:63]
	global_load_lds_dwordx4 v171, s[74:75]
	s_add_u32 s72, s72, 0x202000
	s_addc_u32 s73, s73, 0
	v_mfma_f32_16x16x32_bf16 v[32:35], v[220:223], v[172:175], v[32:35]
	s_add_u32 s74, s74, 0x10000
	s_addc_u32 s75, s75, 0
	v_mfma_f32_16x16x32_bf16 v[36:39], v[220:223], v[176:179], v[36:39]
	v_mfma_f32_16x16x32_bf16 v[40:43], v[224:227], v[172:175], v[40:43]
	v_mfma_f32_16x16x32_bf16 v[44:47], v[224:227], v[176:179], v[44:47]
	s_waitcnt lgkmcnt(2)
	v_mfma_f32_16x16x32_bf16 v[80:83], v[228:231], v[248:251], v[80:83]
	ds_read_b128 v[172:175], v128 offset:57344
	v_mfma_f32_16x16x32_bf16 v[84:87], v[228:231], v[244:247], v[84:87]
	ds_read_b128 v[176:179], v128 offset:58368
	v_mfma_f32_16x16x32_bf16 v[88:91], v[232:235], v[248:251], v[88:91]
	v_mfma_f32_16x16x32_bf16 v[92:95], v[232:235], v[244:247], v[92:95]
	v_mfma_f32_16x16x32_bf16 v[64:67], v[236:239], v[248:251], v[64:67]
	v_mfma_f32_16x16x32_bf16 v[68:71], v[236:239], v[244:247], v[68:71]
	v_mfma_f32_16x16x32_bf16 v[72:75], v[240:243], v[248:251], v[72:75]
	v_mfma_f32_16x16x32_bf16 v[76:79], v[240:243], v[244:247], v[76:79]
	s_waitcnt lgkmcnt(2)
	v_mfma_f32_16x16x32_bf16 v[16:19], v[228:231], v[132:135], v[16:19]
	ds_read_b128 v[248:251], v128 offset:61440
	v_mfma_f32_16x16x32_bf16 v[20:23], v[228:231], v[136:139], v[20:23]
	ds_read_b128 v[244:247], v128 offset:62464
	v_mfma_f32_16x16x32_bf16 v[24:27], v[232:235], v[132:135], v[24:27]
	v_mfma_f32_16x16x32_bf16 v[28:31], v[232:235], v[136:139], v[28:31]
	v_mfma_f32_16x16x32_bf16 v[0:3], v[236:239], v[132:135], v[0:3]
	v_mfma_f32_16x16x32_bf16 v[4:7], v[236:239], v[136:139], v[4:7]
	v_mfma_f32_16x16x32_bf16 v[8:11], v[240:243], v[132:135], v[8:11]
	v_mfma_f32_16x16x32_bf16 v[12:15], v[240:243], v[136:139], v[12:15]
	s_waitcnt lgkmcnt(0)
	s_waitcnt vmcnt(6)
	s_barrier
	ds_read_b128 v[212:215], v167
	ds_read_b128 v[216:219], v167 offset:1024
	v_mfma_f32_16x16x32_bf16 v[112:115], v[228:231], v[172:175], v[112:115]
	ds_read_b128 v[220:223], v167 offset:2048
	ds_read_b128 v[224:227], v167 offset:3072
	v_mfma_f32_16x16x32_bf16 v[116:119], v[228:231], v[176:179], v[116:119]
	ds_read_b128 v[132:135], v128
	ds_read_b128 v[136:139], v128 offset:1024
	v_mfma_f32_16x16x32_bf16 v[120:123], v[232:235], v[172:175], v[120:123]
	v_mfma_f32_16x16x32_bf16 v[124:127], v[232:235], v[176:179], v[124:127]
	v_mfma_f32_16x16x32_bf16 v[96:99], v[236:239], v[172:175], v[96:99]
	v_mfma_f32_16x16x32_bf16 v[100:103], v[236:239], v[176:179], v[100:103]
	v_mfma_f32_16x16x32_bf16 v[104:107], v[240:243], v[172:175], v[104:107]
	v_mfma_f32_16x16x32_bf16 v[108:111], v[240:243], v[176:179], v[108:111]
	ds_read_b128 v[172:175], v128 offset:4096
	ds_read_b128 v[176:179], v128 offset:5120
	v_mfma_f32_16x16x32_bf16 v[48:51], v[228:231], v[248:251], v[48:51]
	v_mfma_f32_16x16x32_bf16 v[52:55], v[228:231], v[244:247], v[52:55]
	v_mfma_f32_16x16x32_bf16 v[56:59], v[232:235], v[248:251], v[56:59]
	v_mfma_f32_16x16x32_bf16 v[60:63], v[232:235], v[244:247], v[60:63]
	v_mfma_f32_16x16x32_bf16 v[32:35], v[236:239], v[248:251], v[32:35]
	v_mfma_f32_16x16x32_bf16 v[36:39], v[236:239], v[244:247], v[36:39]
	v_mfma_f32_16x16x32_bf16 v[40:43], v[240:243], v[248:251], v[40:43]
	v_mfma_f32_16x16x32_bf16 v[44:47], v[240:243], v[244:247], v[44:47]
	s_waitcnt lgkmcnt(2)
	v_mfma_f32_16x16x32_bf16 v[80:83], v[212:215], v[132:135], v[80:83]
	ds_read_b128 v[248:251], v128 offset:8192
	v_mfma_f32_16x16x32_bf16 v[84:87], v[212:215], v[136:139], v[84:87]
	ds_read_b128 v[244:247], v128 offset:9216
	v_mfma_f32_16x16x32_bf16 v[88:91], v[216:219], v[132:135], v[88:91]
	v_mfma_f32_16x16x32_bf16 v[92:95], v[216:219], v[136:139], v[92:95]
	v_mfma_f32_16x16x32_bf16 v[64:67], v[220:223], v[132:135], v[64:67]
	v_mfma_f32_16x16x32_bf16 v[68:71], v[220:223], v[136:139], v[68:71]
	v_mfma_f32_16x16x32_bf16 v[72:75], v[224:227], v[132:135], v[72:75]
	v_mfma_f32_16x16x32_bf16 v[76:79], v[224:227], v[136:139], v[76:79]
	s_waitcnt lgkmcnt(2)
	v_mfma_f32_16x16x32_bf16 v[16:19], v[212:215], v[172:175], v[16:19]
	ds_read_b128 v[132:135], v128 offset:12288
	v_mfma_f32_16x16x32_bf16 v[20:23], v[212:215], v[176:179], v[20:23]
	ds_read_b128 v[136:139], v128 offset:13312
	v_mfma_f32_16x16x32_bf16 v[24:27], v[216:219], v[172:175], v[24:27]
	v_mfma_f32_16x16x32_bf16 v[28:31], v[216:219], v[176:179], v[28:31]
	v_mfma_f32_16x16x32_bf16 v[0:3], v[220:223], v[172:175], v[0:3]
	v_mfma_f32_16x16x32_bf16 v[4:7], v[220:223], v[176:179], v[4:7]
	v_mfma_f32_16x16x32_bf16 v[8:11], v[224:227], v[172:175], v[8:11]
	v_mfma_f32_16x16x32_bf16 v[12:15], v[224:227], v[176:179], v[12:15]
	s_waitcnt lgkmcnt(0)
	s_waitcnt vmcnt(0)
	s_barrier
	ds_read_b128 v[228:231], v167 offset:24576
	ds_read_b128 v[232:235], v167 offset:25600
	v_mfma_f32_16x16x32_bf16 v[112:115], v[212:215], v[248:251], v[112:115]
	ds_read_b128 v[236:239], v167 offset:26624
	ds_read_b128 v[240:243], v167 offset:27648
	v_mfma_f32_16x16x32_bf16 v[116:119], v[212:215], v[244:247], v[116:119]
	ds_read_b128 v[172:175], v128 offset:24576
	ds_read_b128 v[176:179], v128 offset:25600
	v_mfma_f32_16x16x32_bf16 v[120:123], v[216:219], v[248:251], v[120:123]
	v_mfma_f32_16x16x32_bf16 v[124:127], v[216:219], v[244:247], v[124:127]
	v_mfma_f32_16x16x32_bf16 v[96:99], v[220:223], v[248:251], v[96:99]
	v_mfma_f32_16x16x32_bf16 v[100:103], v[220:223], v[244:247], v[100:103]
	v_mfma_f32_16x16x32_bf16 v[104:107], v[224:227], v[248:251], v[104:107]
	v_mfma_f32_16x16x32_bf16 v[108:111], v[224:227], v[244:247], v[108:111]
	ds_read_b128 v[248:251], v128 offset:28672
	ds_read_b128 v[244:247], v128 offset:29696
	v_mfma_f32_16x16x32_bf16 v[48:51], v[212:215], v[132:135], v[48:51]
	v_mfma_f32_16x16x32_bf16 v[52:55], v[212:215], v[136:139], v[52:55]
	v_mfma_f32_16x16x32_bf16 v[56:59], v[216:219], v[132:135], v[56:59]
	v_mfma_f32_16x16x32_bf16 v[60:63], v[216:219], v[136:139], v[60:63]
	v_mfma_f32_16x16x32_bf16 v[32:35], v[220:223], v[132:135], v[32:35]
	v_mfma_f32_16x16x32_bf16 v[36:39], v[220:223], v[136:139], v[36:39]
	v_mfma_f32_16x16x32_bf16 v[40:43], v[224:227], v[132:135], v[40:43]
	v_mfma_f32_16x16x32_bf16 v[44:47], v[224:227], v[136:139], v[44:47]
	s_waitcnt lgkmcnt(2)
	v_mfma_f32_16x16x32_bf16 v[80:83], v[228:231], v[172:175], v[80:83]
	ds_read_b128 v[132:135], v128 offset:32768
	v_mfma_f32_16x16x32_bf16 v[84:87], v[228:231], v[176:179], v[84:87]
	ds_read_b128 v[136:139], v128 offset:33792
	v_mfma_f32_16x16x32_bf16 v[88:91], v[232:235], v[172:175], v[88:91]
	v_mfma_f32_16x16x32_bf16 v[92:95], v[232:235], v[176:179], v[92:95]
	v_mfma_f32_16x16x32_bf16 v[64:67], v[236:239], v[172:175], v[64:67]
	v_mfma_f32_16x16x32_bf16 v[68:71], v[236:239], v[176:179], v[68:71]
	v_mfma_f32_16x16x32_bf16 v[72:75], v[240:243], v[172:175], v[72:75]
	v_mfma_f32_16x16x32_bf16 v[76:79], v[240:243], v[176:179], v[76:79]
	s_waitcnt lgkmcnt(2)
	v_mfma_f32_16x16x32_bf16 v[16:19], v[228:231], v[248:251], v[16:19]
	ds_read_b128 v[172:175], v128 offset:36864
	v_mfma_f32_16x16x32_bf16 v[20:23], v[228:231], v[244:247], v[20:23]
	ds_read_b128 v[176:179], v128 offset:37888
	v_mfma_f32_16x16x32_bf16 v[24:27], v[232:235], v[248:251], v[24:27]
	v_mfma_f32_16x16x32_bf16 v[28:31], v[232:235], v[244:247], v[28:31]
	v_mfma_f32_16x16x32_bf16 v[0:3], v[236:239], v[248:251], v[0:3]
	v_mfma_f32_16x16x32_bf16 v[4:7], v[236:239], v[244:247], v[4:7]
	v_mfma_f32_16x16x32_bf16 v[8:11], v[240:243], v[248:251], v[8:11]
	v_mfma_f32_16x16x32_bf16 v[12:15], v[240:243], v[244:247], v[12:15]
	s_waitcnt lgkmcnt(0)
	v_mfma_f32_16x16x32_bf16 v[112:115], v[228:231], v[132:135], v[112:115]
	v_mfma_f32_16x16x32_bf16 v[116:119], v[228:231], v[136:139], v[116:119]
	v_mfma_f32_16x16x32_bf16 v[120:123], v[232:235], v[132:135], v[120:123]
	v_mfma_f32_16x16x32_bf16 v[124:127], v[232:235], v[136:139], v[124:127]
	v_mfma_f32_16x16x32_bf16 v[96:99], v[236:239], v[132:135], v[96:99]
	v_mfma_f32_16x16x32_bf16 v[100:103], v[236:239], v[136:139], v[100:103]
	v_mfma_f32_16x16x32_bf16 v[104:107], v[240:243], v[132:135], v[104:107]
	v_mfma_f32_16x16x32_bf16 v[108:111], v[240:243], v[136:139], v[108:111]
	v_mfma_f32_16x16x32_bf16 v[48:51], v[228:231], v[172:175], v[48:51]
	v_mfma_f32_16x16x32_bf16 v[52:55], v[228:231], v[176:179], v[52:55]
	v_mfma_f32_16x16x32_bf16 v[56:59], v[232:235], v[172:175], v[56:59]
	v_mfma_f32_16x16x32_bf16 v[60:63], v[232:235], v[176:179], v[60:63]
	v_mfma_f32_16x16x32_bf16 v[32:35], v[236:239], v[172:175], v[32:35]
	v_mfma_f32_16x16x32_bf16 v[36:39], v[236:239], v[176:179], v[36:39]
	v_mfma_f32_16x16x32_bf16 v[40:43], v[240:243], v[172:175], v[40:43]
	v_mfma_f32_16x16x32_bf16 v[44:47], v[240:243], v[176:179], v[44:47]
	s_nop 15
	s_nop 15
	v_permlane16_swap_b32_e32 v80, v84
	v_permlane16_swap_b32_e32 v81, v85
	v_permlane16_swap_b32_e32 v82, v86
	v_permlane16_swap_b32_e32 v83, v87
	v_permlane16_swap_b32_e32 v88, v92
	v_permlane16_swap_b32_e32 v89, v93
	v_permlane16_swap_b32_e32 v90, v94
	v_permlane16_swap_b32_e32 v91, v95
	v_permlane16_swap_b32_e32 v16, v20
	v_permlane16_swap_b32_e32 v17, v21
	v_permlane16_swap_b32_e32 v18, v22
	v_permlane16_swap_b32_e32 v19, v23
	v_permlane16_swap_b32_e32 v24, v28
	v_permlane16_swap_b32_e32 v25, v29
	v_permlane16_swap_b32_e32 v26, v30
	v_permlane16_swap_b32_e32 v27, v31
	v_permlane16_swap_b32_e32 v112, v116
	v_permlane16_swap_b32_e32 v113, v117
	v_permlane16_swap_b32_e32 v114, v118
	v_permlane16_swap_b32_e32 v115, v119
	v_permlane16_swap_b32_e32 v120, v124
	v_permlane16_swap_b32_e32 v121, v125
	v_permlane16_swap_b32_e32 v122, v126
	v_permlane16_swap_b32_e32 v123, v127
	v_permlane16_swap_b32_e32 v48, v52
	v_permlane16_swap_b32_e32 v49, v53
	v_permlane16_swap_b32_e32 v50, v54
	v_permlane16_swap_b32_e32 v51, v55
	v_permlane16_swap_b32_e32 v56, v60
	v_permlane16_swap_b32_e32 v57, v61
	v_permlane16_swap_b32_e32 v58, v62
	v_permlane16_swap_b32_e32 v59, v63
	v_permlane16_swap_b32_e32 v64, v68
	v_permlane16_swap_b32_e32 v65, v69
	v_permlane16_swap_b32_e32 v66, v70
	v_permlane16_swap_b32_e32 v67, v71
	v_permlane16_swap_b32_e32 v72, v76
	v_permlane16_swap_b32_e32 v73, v77
	v_permlane16_swap_b32_e32 v74, v78
	v_permlane16_swap_b32_e32 v75, v79
	v_permlane16_swap_b32_e32 v0, v4
	v_permlane16_swap_b32_e32 v1, v5
	v_permlane16_swap_b32_e32 v2, v6
	v_permlane16_swap_b32_e32 v3, v7
	v_permlane16_swap_b32_e32 v8, v12
	v_permlane16_swap_b32_e32 v9, v13
	v_permlane16_swap_b32_e32 v10, v14
	v_permlane16_swap_b32_e32 v11, v15
	v_permlane16_swap_b32_e32 v96, v100
	v_permlane16_swap_b32_e32 v97, v101
	v_permlane16_swap_b32_e32 v98, v102
	v_permlane16_swap_b32_e32 v99, v103
	v_permlane16_swap_b32_e32 v104, v108
	v_permlane16_swap_b32_e32 v105, v109
	v_permlane16_swap_b32_e32 v106, v110
	v_permlane16_swap_b32_e32 v107, v111
	v_permlane16_swap_b32_e32 v32, v36
	v_permlane16_swap_b32_e32 v33, v37
	v_permlane16_swap_b32_e32 v34, v38
	v_permlane16_swap_b32_e32 v35, v39
	v_permlane16_swap_b32_e32 v40, v44
	v_permlane16_swap_b32_e32 v41, v45
	v_permlane16_swap_b32_e32 v42, v46
	v_permlane16_swap_b32_e32 v43, v47
	s_nop 1
	v_readlane_b32 s72, v254, 13
	v_readlane_b32 s73, v254, 14
	s_nop 1
	v_mov_b64_e32 v[130:131], s[72:73]

.LBB0_630:
	s_or_saveexec_b64 s[0:1], s[0:1]
	v_mov_b32_e32 v63, 0
	v_mov_b32_e32 v62, 0
	v_mov_b32_e32 v61, 0
	v_mov_b32_e32 v60, 0
	v_mov_b32_e32 v59, 0
	v_mov_b32_e32 v58, 0
	v_mov_b32_e32 v57, 0
	v_mov_b32_e32 v56, 0
	v_mov_b32_e32 v55, 0
	v_mov_b32_e32 v54, 0
	v_mov_b32_e32 v53, 0
	v_mov_b32_e32 v52, 0
	v_mov_b32_e32 v51, 0
	v_mov_b32_e32 v50, 0
	v_mov_b32_e32 v49, 0
	v_mov_b32_e32 v48, v63
	v_mov_b32_e32 v31, 0
	v_mov_b32_e32 v30, 0
	v_mov_b32_e32 v29, 0
	v_mov_b32_e32 v28, 0
	v_mov_b32_e32 v27, 0
	v_mov_b32_e32 v26, 0
	v_mov_b32_e32 v25, 0
	v_mov_b32_e32 v24, 0
	v_mov_b32_e32 v23, 0
	v_mov_b32_e32 v22, 0
	v_mov_b32_e32 v21, 0
	v_mov_b32_e32 v20, 0
	v_mov_b32_e32 v19, 0
	v_mov_b32_e32 v18, 0
	v_mov_b32_e32 v17, 0
	v_mov_b32_e32 v16, v63
	v_mov_b32_e32 v47, 0
	v_mov_b32_e32 v46, v63
	v_mov_b32_e32 v45, 0
	v_mov_b32_e32 v44, v63
	v_mov_b32_e32 v43, 0
	v_mov_b32_e32 v42, v63
	v_mov_b32_e32 v41, 0
	v_mov_b32_e32 v40, v63
	v_mov_b32_e32 v39, 0
	v_mov_b32_e32 v38, v63
	v_mov_b32_e32 v37, 0
	v_mov_b32_e32 v36, 0
	v_mov_b32_e32 v35, 0
	v_mov_b32_e32 v34, 0
	v_mov_b32_e32 v33, 0
	v_mov_b32_e32 v32, v63
	v_mov_b32_e32 v15, 0
	v_mov_b32_e32 v14, v63
	v_mov_b32_e32 v13, 0
	v_mov_b32_e32 v12, v63
	v_mov_b32_e32 v11, 0
	v_mov_b32_e32 v10, v63
	v_mov_b32_e32 v9, 0
	v_mov_b32_e32 v8, v63
	v_mov_b32_e32 v7, 0
	v_mov_b32_e32 v6, v63
	v_mov_b32_e32 v5, 0
	v_mov_b32_e32 v4, 0
	v_mov_b32_e32 v3, 0
	v_mov_b32_e32 v2, 0
	v_mov_b32_e32 v1, 0
	v_mov_b32_e32 v0, v63
	s_xor_b64 exec, exec, s[0:1]
	s_cbranch_execz .LBB0_634
	v_readfirstlane_b32 s10, v128
	v_readfirstlane_b32 s11, v130
	v_readfirstlane_b32 s8, v226
	v_mbcnt_lo_u32_b32 v192, -1, 0
	v_mbcnt_hi_u32_b32 v192, -1, v192
	s_nop 3
	s_lshl_b32 s10, s10, 14
	s_lshl_b32 s11, s11, 13
	s_add_u32 s4, s90, s10
	s_addc_u32 s5, s91, 0
	s_add_u32 s6, s90, s11
	s_addc_u32 s7, s91, 0
	s_add_u32 s6, s6, 0x1b3c8000
	s_addc_u32 s7, s7, 0
	v_lshrrev_b32_e32 v193, 2, v192
	v_lshrrev_b32_e32 v194, 4, v192
	v_xor_b32_e32 v194, v194, v192
	v_and_b32_e32 v194, 3, v194
	v_lshlrev_b32_e32 v194, 4, v194
	v_lshl_or_b32 v193, v193, 6, v194
	v_or_b32_e32 v189, v193, v226
	v_add_u32_e32 v252, 0x1000, v189
	v_add_u32_e32 v190, 0x2000, v189
	v_add_u32_e32 v191, 0x3000, v189
	v_and_b32_e32 v193, 15, v192
	v_lshrrev_b32_e32 v194, 4, v192
	v_bfe_u32 v195, v192, 2, 2
	v_xor_b32_e32 v195, v195, v194
	v_lshlrev_b32_e32 v195, 4, v195
	v_lshl_or_b32 v129, v193, 6, v195
	v_lshrrev_b32_e32 v195, 10, v226
	v_lshrrev_b32_e32 v195, 1, v195
	v_lshl_or_b32 v129, v195, 11, v129
	v_and_b32_e32 v195, 3, v192
	v_bfe_u32 v193, v192, 2, 1
	v_lshl_or_b32 v195, v193, 3, v195
	v_bfe_u32 v193, v192, 3, 1
	v_lshl_or_b32 v195, v193, 2, v195
	v_lshrrev_b32_e32 v193, 2, v195
	v_xor_b32_e32 v193, v193, v194
	v_lshlrev_b32_e32 v193, 4, v193
	v_lshl_or_b32 v156, v195, 6, v193
	v_lshrrev_b32_e32 v195, 10, v226
	v_and_b32_e32 v195, 1, v195
	v_lshl_or_b32 v156, v195, 12, v156
	v_or_b32_e32 v156, 0x4000, v156
	s_add_u32 m0, s8, 0x2000
	s_nop 0
	global_load_lds_dwordx4 v190, s[4:5]
	s_add_u32 m0, s8, 0x3000
	s_nop 0
	global_load_lds_dwordx4 v191, s[4:5]
	s_add_u32 m0, s8, 0x4000
	s_nop 0
	global_load_lds_dwordx4 v189, s[6:7]
	s_add_u32 m0, s8, 0x5000
	s_nop 0
	global_load_lds_dwordx4 v252, s[6:7]
	s_add_u32 s4, s4, 0x202000
	s_addc_u32 s5, s5, 0
	s_add_u32 s6, s6, 0x40000
	s_addc_u32 s7, s7, 0
	s_add_u32 m0, s8, 0x6000
	s_nop 0
	global_load_lds_dwordx4 v189, s[4:5]
	s_add_u32 m0, s8, 0x7000
	s_nop 0
	global_load_lds_dwordx4 v252, s[4:5]
	s_add_u32 m0, s8, 0x8000
	s_nop 0
	global_load_lds_dwordx4 v190, s[4:5]
	s_add_u32 m0, s8, 0x9000
	s_nop 0
	global_load_lds_dwordx4 v191, s[4:5]
	s_add_u32 m0, s8, 0xa000
	s_nop 0
	global_load_lds_dwordx4 v189, s[6:7]
	s_add_u32 m0, s8, 0xb000
	s_nop 0
	global_load_lds_dwordx4 v252, s[6:7]
	s_add_u32 s4, s4, 0x202000
	s_addc_u32 s5, s5, 0
	s_add_u32 s6, s6, 0x40000
	s_addc_u32 s7, s7, 0
	s_add_u32 m0, s8, 0xc000
	s_nop 0
	global_load_lds_dwordx4 v189, s[4:5]
	s_add_u32 m0, s8, 0xd000
	s_nop 0
	global_load_lds_dwordx4 v252, s[4:5]
	s_add_u32 m0, s8, 0xe000
	s_nop 0
	global_load_lds_dwordx4 v190, s[4:5]
	s_add_u32 m0, s8, 0xf000
	s_nop 0
	global_load_lds_dwordx4 v191, s[4:5]
	s_add_u32 m0, s8, 0x10000
	s_nop 0
	global_load_lds_dwordx4 v189, s[6:7]
	s_add_u32 m0, s8, 0x11000
	s_nop 0
	global_load_lds_dwordx4 v252, s[6:7]
	s_add_u32 s4, s4, 0x202000
	s_addc_u32 s5, s5, 0
	s_add_u32 s6, s6, 0x40000
	s_addc_u32 s7, s7, 0
	s_waitcnt vmcnt(12)
	s_barrier
	ds_read_b128 v[132:135], v156
	ds_read_b128 v[136:139], v156 offset:1024
	ds_read_b128 v[140:143], v156 offset:2048
	ds_read_b128 v[180:183], v156 offset:3072
	ds_read_b128 v[248:251], v129
	ds_read_b128 v[200:203], v129 offset:1024
	ds_read_b128 v[204:207], v129 offset:4096
	ds_read_b128 v[208:211], v129 offset:5120
	s_waitcnt lgkmcnt(0)
	v_mfma_f32_16x16x32_bf16 v[112:115], v[132:135], v[248:251], 0
	ds_read_b128 v[212:215], v129 offset:8192
	v_mfma_f32_16x16x32_bf16 v[116:119], v[132:135], v[200:203], 0
	ds_read_b128 v[216:219], v129 offset:9216
	v_mfma_f32_16x16x32_bf16 v[120:123], v[136:139], v[248:251], 0
	v_mfma_f32_16x16x32_bf16 v[124:127], v[136:139], v[200:203], 0
	v_mfma_f32_16x16x32_bf16 v[96:99], v[140:143], v[248:251], 0
	v_mfma_f32_16x16x32_bf16 v[100:103], v[140:143], v[200:203], 0
	v_mfma_f32_16x16x32_bf16 v[104:107], v[180:183], v[248:251], 0
	v_mfma_f32_16x16x32_bf16 v[108:111], v[180:183], v[200:203], 0
	s_waitcnt lgkmcnt(2)
	v_mfma_f32_16x16x32_bf16 v[80:83], v[132:135], v[204:207], 0
	ds_read_b128 v[248:251], v129 offset:12288
	v_mfma_f32_16x16x32_bf16 v[84:87], v[132:135], v[208:211], 0
	ds_read_b128 v[200:203], v129 offset:13312
	v_mfma_f32_16x16x32_bf16 v[88:91], v[136:139], v[204:207], 0
	v_mfma_f32_16x16x32_bf16 v[92:95], v[136:139], v[208:211], 0
	v_mfma_f32_16x16x32_bf16 v[64:67], v[140:143], v[204:207], 0
	v_mfma_f32_16x16x32_bf16 v[68:71], v[140:143], v[208:211], 0
	v_mfma_f32_16x16x32_bf16 v[72:75], v[180:183], v[204:207], 0
	v_mfma_f32_16x16x32_bf16 v[76:79], v[180:183], v[208:211], 0
	s_waitcnt lgkmcnt(0)
	s_waitcnt vmcnt(6)
	s_barrier
	ds_read_b128 v[184:187], v156 offset:24576
	ds_read_b128 v[236:239], v156 offset:25600
	v_mfma_f32_16x16x32_bf16 v[48:51], v[132:135], v[212:215], 0
	ds_read_b128 v[240:243], v156 offset:26624
	ds_read_b128 v[244:247], v156 offset:27648
	v_mfma_f32_16x16x32_bf16 v[52:55], v[132:135], v[216:219], 0
	ds_read_b128 v[204:207], v129 offset:24576
	ds_read_b128 v[208:211], v129 offset:25600
	s_add_u32 m0, s8, 0x0
	v_mfma_f32_16x16x32_bf16 v[56:59], v[136:139], v[212:215], 0
	global_load_lds_dwordx4 v189, s[4:5]
	s_add_u32 m0, s8, 0x1000
	v_mfma_f32_16x16x32_bf16 v[60:63], v[136:139], v[216:219], 0
	global_load_lds_dwordx4 v252, s[4:5]
	s_add_u32 m0, s8, 0x2000
	v_mfma_f32_16x16x32_bf16 v[32:35], v[140:143], v[212:215], 0
	global_load_lds_dwordx4 v190, s[4:5]
	v_mfma_f32_16x16x32_bf16 v[36:39], v[140:143], v[216:219], 0
	v_mfma_f32_16x16x32_bf16 v[40:43], v[180:183], v[212:215], 0
	v_mfma_f32_16x16x32_bf16 v[44:47], v[180:183], v[216:219], 0
	ds_read_b128 v[212:215], v129 offset:28672
	ds_read_b128 v[216:219], v129 offset:29696
	v_mfma_f32_16x16x32_bf16 v[16:19], v[132:135], v[248:251], 0
	s_add_u32 m0, s8, 0x3000
	v_mfma_f32_16x16x32_bf16 v[20:23], v[132:135], v[200:203], 0
	global_load_lds_dwordx4 v191, s[4:5]
	s_add_u32 m0, s8, 0x4000
	v_mfma_f32_16x16x32_bf16 v[24:27], v[136:139], v[248:251], 0
	global_load_lds_dwordx4 v189, s[6:7]
	s_add_u32 m0, s8, 0x5000
	v_mfma_f32_16x16x32_bf16 v[28:31], v[136:139], v[200:203], 0
	global_load_lds_dwordx4 v252, s[6:7]
	s_add_u32 s4, s4, 0x202000
	s_addc_u32 s5, s5, 0
	v_mfma_f32_16x16x32_bf16 v[0:3], v[140:143], v[248:251], 0
	s_add_u32 s6, s6, 0x40000
	s_addc_u32 s7, s7, 0
	v_mfma_f32_16x16x32_bf16 v[4:7], v[140:143], v[200:203], 0
	v_mfma_f32_16x16x32_bf16 v[8:11], v[180:183], v[248:251], 0
	v_mfma_f32_16x16x32_bf16 v[12:15], v[180:183], v[200:203], 0
	s_waitcnt lgkmcnt(2)
	v_mfma_f32_16x16x32_bf16 v[112:115], v[184:187], v[204:207], v[112:115]
	ds_read_b128 v[248:251], v129 offset:32768
	v_mfma_f32_16x16x32_bf16 v[116:119], v[184:187], v[208:211], v[116:119]
	ds_read_b128 v[200:203], v129 offset:33792
	v_mfma_f32_16x16x32_bf16 v[120:123], v[236:239], v[204:207], v[120:123]
	v_mfma_f32_16x16x32_bf16 v[124:127], v[236:239], v[208:211], v[124:127]
	v_mfma_f32_16x16x32_bf16 v[96:99], v[240:243], v[204:207], v[96:99]
	v_mfma_f32_16x16x32_bf16 v[100:103], v[240:243], v[208:211], v[100:103]
	v_mfma_f32_16x16x32_bf16 v[104:107], v[244:247], v[204:207], v[104:107]
	v_mfma_f32_16x16x32_bf16 v[108:111], v[244:247], v[208:211], v[108:111]
	s_waitcnt lgkmcnt(2)
	v_mfma_f32_16x16x32_bf16 v[80:83], v[184:187], v[212:215], v[80:83]
	ds_read_b128 v[204:207], v129 offset:36864
	v_mfma_f32_16x16x32_bf16 v[84:87], v[184:187], v[216:219], v[84:87]
	ds_read_b128 v[208:211], v129 offset:37888
	v_mfma_f32_16x16x32_bf16 v[88:91], v[236:239], v[212:215], v[88:91]
	v_mfma_f32_16x16x32_bf16 v[92:95], v[236:239], v[216:219], v[92:95]
	v_mfma_f32_16x16x32_bf16 v[64:67], v[240:243], v[212:215], v[64:67]
	v_mfma_f32_16x16x32_bf16 v[68:71], v[240:243], v[216:219], v[68:71]
	v_mfma_f32_16x16x32_bf16 v[72:75], v[244:247], v[212:215], v[72:75]
	v_mfma_f32_16x16x32_bf16 v[76:79], v[244:247], v[216:219], v[76:79]
	s_waitcnt lgkmcnt(0)
	s_waitcnt vmcnt(6)
	s_barrier
	ds_read_b128 v[132:135], v156 offset:49152
	ds_read_b128 v[136:139], v156 offset:50176
	v_mfma_f32_16x16x32_bf16 v[48:51], v[184:187], v[248:251], v[48:51]
	ds_read_b128 v[140:143], v156 offset:51200
	ds_read_b128 v[180:183], v156 offset:52224
	v_mfma_f32_16x16x32_bf16 v[52:55], v[184:187], v[200:203], v[52:55]
	ds_read_b128 v[212:215], v129 offset:49152
	ds_read_b128 v[216:219], v129 offset:50176
	s_add_u32 m0, s8, 0x6000
	v_mfma_f32_16x16x32_bf16 v[56:59], v[236:239], v[248:251], v[56:59]
	global_load_lds_dwordx4 v189, s[4:5]
	s_add_u32 m0, s8, 0x7000
	v_mfma_f32_16x16x32_bf16 v[60:63], v[236:239], v[200:203], v[60:63]
	global_load_lds_dwordx4 v252, s[4:5]
	s_add_u32 m0, s8, 0x8000
	v_mfma_f32_16x16x32_bf16 v[32:35], v[240:243], v[248:251], v[32:35]
	global_load_lds_dwordx4 v190, s[4:5]
	v_mfma_f32_16x16x32_bf16 v[36:39], v[240:243], v[200:203], v[36:39]
	v_mfma_f32_16x16x32_bf16 v[40:43], v[244:247], v[248:251], v[40:43]
	v_mfma_f32_16x16x32_bf16 v[44:47], v[244:247], v[200:203], v[44:47]
	ds_read_b128 v[248:251], v129 offset:53248
	ds_read_b128 v[200:203], v129 offset:54272
	v_mfma_f32_16x16x32_bf16 v[16:19], v[184:187], v[204:207], v[16:19]
	s_add_u32 m0, s8, 0x9000
	v_mfma_f32_16x16x32_bf16 v[20:23], v[184:187], v[208:211], v[20:23]
	global_load_lds_dwordx4 v191, s[4:5]
	s_add_u32 m0, s8, 0xa000
	v_mfma_f32_16x16x32_bf16 v[24:27], v[236:239], v[204:207], v[24:27]
	global_load_lds_dwordx4 v189, s[6:7]
	s_add_u32 m0, s8, 0xb000
	v_mfma_f32_16x16x32_bf16 v[28:31], v[236:239], v[208:211], v[28:31]
	global_load_lds_dwordx4 v252, s[6:7]
	s_add_u32 s4, s4, 0x202000
	s_addc_u32 s5, s5, 0
	v_mfma_f32_16x16x32_bf16 v[0:3], v[240:243], v[204:207], v[0:3]
	s_add_u32 s6, s6, 0x40000
	s_addc_u32 s7, s7, 0
	v_mfma_f32_16x16x32_bf16 v[4:7], v[240:243], v[208:211], v[4:7]
	v_mfma_f32_16x16x32_bf16 v[8:11], v[244:247], v[204:207], v[8:11]
	v_mfma_f32_16x16x32_bf16 v[12:15], v[244:247], v[208:211], v[12:15]
	s_waitcnt lgkmcnt(2)
	v_mfma_f32_16x16x32_bf16 v[112:115], v[132:135], v[212:215], v[112:115]
	ds_read_b128 v[204:207], v129 offset:57344
	v_mfma_f32_16x16x32_bf16 v[116:119], v[132:135], v[216:219], v[116:119]
	ds_read_b128 v[208:211], v129 offset:58368
	v_mfma_f32_16x16x32_bf16 v[120:123], v[136:139], v[212:215], v[120:123]
	v_mfma_f32_16x16x32_bf16 v[124:127], v[136:139], v[216:219], v[124:127]
	v_mfma_f32_16x16x32_bf16 v[96:99], v[140:143], v[212:215], v[96:99]
	v_mfma_f32_16x16x32_bf16 v[100:103], v[140:143], v[216:219], v[100:103]
	v_mfma_f32_16x16x32_bf16 v[104:107], v[180:183], v[212:215], v[104:107]
	v_mfma_f32_16x16x32_bf16 v[108:111], v[180:183], v[216:219], v[108:111]
	s_waitcnt lgkmcnt(2)
	v_mfma_f32_16x16x32_bf16 v[80:83], v[132:135], v[248:251], v[80:83]
	ds_read_b128 v[212:215], v129 offset:61440
	v_mfma_f32_16x16x32_bf16 v[84:87], v[132:135], v[200:203], v[84:87]
	ds_read_b128 v[216:219], v129 offset:62464
	v_mfma_f32_16x16x32_bf16 v[88:91], v[136:139], v[248:251], v[88:91]
	v_mfma_f32_16x16x32_bf16 v[92:95], v[136:139], v[200:203], v[92:95]
	v_mfma_f32_16x16x32_bf16 v[64:67], v[140:143], v[248:251], v[64:67]
	v_mfma_f32_16x16x32_bf16 v[68:71], v[140:143], v[200:203], v[68:71]
	v_mfma_f32_16x16x32_bf16 v[72:75], v[180:183], v[248:251], v[72:75]
	v_mfma_f32_16x16x32_bf16 v[76:79], v[180:183], v[200:203], v[76:79]
	s_waitcnt lgkmcnt(0)
	s_waitcnt vmcnt(6)
	s_barrier
	ds_read_b128 v[184:187], v156
	ds_read_b128 v[236:239], v156 offset:1024
	v_mfma_f32_16x16x32_bf16 v[48:51], v[132:135], v[204:207], v[48:51]
	ds_read_b128 v[240:243], v156 offset:2048
	ds_read_b128 v[244:247], v156 offset:3072
	v_mfma_f32_16x16x32_bf16 v[52:55], v[132:135], v[208:211], v[52:55]
	ds_read_b128 v[248:251], v129
	ds_read_b128 v[200:203], v129 offset:1024
	s_add_u32 m0, s8, 0xc000
	v_mfma_f32_16x16x32_bf16 v[56:59], v[136:139], v[204:207], v[56:59]
	global_load_lds_dwordx4 v189, s[4:5]
	s_add_u32 m0, s8, 0xd000
	v_mfma_f32_16x16x32_bf16 v[60:63], v[136:139], v[208:211], v[60:63]
	global_load_lds_dwordx4 v252, s[4:5]
	s_add_u32 m0, s8, 0xe000
	v_mfma_f32_16x16x32_bf16 v[32:35], v[140:143], v[204:207], v[32:35]
	global_load_lds_dwordx4 v190, s[4:5]
	v_mfma_f32_16x16x32_bf16 v[36:39], v[140:143], v[208:211], v[36:39]
	v_mfma_f32_16x16x32_bf16 v[40:43], v[180:183], v[204:207], v[40:43]
	v_mfma_f32_16x16x32_bf16 v[44:47], v[180:183], v[208:211], v[44:47]
	ds_read_b128 v[204:207], v129 offset:4096
	ds_read_b128 v[208:211], v129 offset:5120
	v_mfma_f32_16x16x32_bf16 v[16:19], v[132:135], v[212:215], v[16:19]
	s_add_u32 m0, s8, 0xf000
	v_mfma_f32_16x16x32_bf16 v[20:23], v[132:135], v[216:219], v[20:23]
	global_load_lds_dwordx4 v191, s[4:5]
	s_add_u32 m0, s8, 0x10000
	v_mfma_f32_16x16x32_bf16 v[24:27], v[136:139], v[212:215], v[24:27]
	global_load_lds_dwordx4 v189, s[6:7]
	s_add_u32 m0, s8, 0x11000
	v_mfma_f32_16x16x32_bf16 v[28:31], v[136:139], v[216:219], v[28:31]
	global_load_lds_dwordx4 v252, s[6:7]
	s_add_u32 s4, s4, 0x202000
	s_addc_u32 s5, s5, 0
	v_mfma_f32_16x16x32_bf16 v[0:3], v[140:143], v[212:215], v[0:3]
	s_add_u32 s6, s6, 0x40000
	s_addc_u32 s7, s7, 0
	v_mfma_f32_16x16x32_bf16 v[4:7], v[140:143], v[216:219], v[4:7]
	v_mfma_f32_16x16x32_bf16 v[8:11], v[180:183], v[212:215], v[8:11]
	v_mfma_f32_16x16x32_bf16 v[12:15], v[180:183], v[216:219], v[12:15]
	s_waitcnt lgkmcnt(2)
	v_mfma_f32_16x16x32_bf16 v[112:115], v[184:187], v[248:251], v[112:115]
	ds_read_b128 v[212:215], v129 offset:8192
	v_mfma_f32_16x16x32_bf16 v[116:119], v[184:187], v[200:203], v[116:119]
	ds_read_b128 v[216:219], v129 offset:9216
	v_mfma_f32_16x16x32_bf16 v[120:123], v[236:239], v[248:251], v[120:123]
	v_mfma_f32_16x16x32_bf16 v[124:127], v[236:239], v[200:203], v[124:127]
	v_mfma_f32_16x16x32_bf16 v[96:99], v[240:243], v[248:251], v[96:99]
	v_mfma_f32_16x16x32_bf16 v[100:103], v[240:243], v[200:203], v[100:103]
	v_mfma_f32_16x16x32_bf16 v[104:107], v[244:247], v[248:251], v[104:107]
	v_mfma_f32_16x16x32_bf16 v[108:111], v[244:247], v[200:203], v[108:111]
	s_waitcnt lgkmcnt(2)
	v_mfma_f32_16x16x32_bf16 v[80:83], v[184:187], v[204:207], v[80:83]
	ds_read_b128 v[248:251], v129 offset:12288
	v_mfma_f32_16x16x32_bf16 v[84:87], v[184:187], v[208:211], v[84:87]
	ds_read_b128 v[200:203], v129 offset:13312
	v_mfma_f32_16x16x32_bf16 v[88:91], v[236:239], v[204:207], v[88:91]
	v_mfma_f32_16x16x32_bf16 v[92:95], v[236:239], v[208:211], v[92:95]
	v_mfma_f32_16x16x32_bf16 v[64:67], v[240:243], v[204:207], v[64:67]
	v_mfma_f32_16x16x32_bf16 v[68:71], v[240:243], v[208:211], v[68:71]
	v_mfma_f32_16x16x32_bf16 v[72:75], v[244:247], v[204:207], v[72:75]
	v_mfma_f32_16x16x32_bf16 v[76:79], v[244:247], v[208:211], v[76:79]
	s_waitcnt lgkmcnt(0)
	s_waitcnt vmcnt(6)
	s_barrier
	ds_read_b128 v[132:135], v156 offset:24576
	ds_read_b128 v[136:139], v156 offset:25600
	v_mfma_f32_16x16x32_bf16 v[48:51], v[184:187], v[212:215], v[48:51]
	ds_read_b128 v[140:143], v156 offset:26624
	ds_read_b128 v[180:183], v156 offset:27648
	v_mfma_f32_16x16x32_bf16 v[52:55], v[184:187], v[216:219], v[52:55]
	ds_read_b128 v[204:207], v129 offset:24576
	ds_read_b128 v[208:211], v129 offset:25600
	s_add_u32 m0, s8, 0x0
	v_mfma_f32_16x16x32_bf16 v[56:59], v[236:239], v[212:215], v[56:59]
	global_load_lds_dwordx4 v189, s[4:5]
	s_add_u32 m0, s8, 0x1000
	v_mfma_f32_16x16x32_bf16 v[60:63], v[236:239], v[216:219], v[60:63]
	global_load_lds_dwordx4 v252, s[4:5]
	s_add_u32 m0, s8, 0x2000
	v_mfma_f32_16x16x32_bf16 v[32:35], v[240:243], v[212:215], v[32:35]
	global_load_lds_dwordx4 v190, s[4:5]
	v_mfma_f32_16x16x32_bf16 v[36:39], v[240:243], v[216:219], v[36:39]
	v_mfma_f32_16x16x32_bf16 v[40:43], v[244:247], v[212:215], v[40:43]
	v_mfma_f32_16x16x32_bf16 v[44:47], v[244:247], v[216:219], v[44:47]
	ds_read_b128 v[212:215], v129 offset:28672
	ds_read_b128 v[216:219], v129 offset:29696
	v_mfma_f32_16x16x32_bf16 v[16:19], v[184:187], v[248:251], v[16:19]
	s_add_u32 m0, s8, 0x3000
	v_mfma_f32_16x16x32_bf16 v[20:23], v[184:187], v[200:203], v[20:23]
	global_load_lds_dwordx4 v191, s[4:5]
	s_add_u32 m0, s8, 0x4000
	v_mfma_f32_16x16x32_bf16 v[24:27], v[236:239], v[248:251], v[24:27]
	global_load_lds_dwordx4 v189, s[6:7]
	s_add_u32 m0, s8, 0x5000
	v_mfma_f32_16x16x32_bf16 v[28:31], v[236:239], v[200:203], v[28:31]
	global_load_lds_dwordx4 v252, s[6:7]
	s_add_u32 s4, s4, 0x202000
	s_addc_u32 s5, s5, 0
	v_mfma_f32_16x16x32_bf16 v[0:3], v[240:243], v[248:251], v[0:3]
	s_add_u32 s6, s6, 0x40000
	s_addc_u32 s7, s7, 0
	v_mfma_f32_16x16x32_bf16 v[4:7], v[240:243], v[200:203], v[4:7]
	v_mfma_f32_16x16x32_bf16 v[8:11], v[244:247], v[248:251], v[8:11]
	v_mfma_f32_16x16x32_bf16 v[12:15], v[244:247], v[200:203], v[12:15]
	s_waitcnt lgkmcnt(2)
	v_mfma_f32_16x16x32_bf16 v[112:115], v[132:135], v[204:207], v[112:115]
	ds_read_b128 v[248:251], v129 offset:32768
	v_mfma_f32_16x16x32_bf16 v[116:119], v[132:135], v[208:211], v[116:119]
	ds_read_b128 v[200:203], v129 offset:33792
	v_mfma_f32_16x16x32_bf16 v[120:123], v[136:139], v[204:207], v[120:123]
	v_mfma_f32_16x16x32_bf16 v[124:127], v[136:139], v[208:211], v[124:127]
	v_mfma_f32_16x16x32_bf16 v[96:99], v[140:143], v[204:207], v[96:99]
	v_mfma_f32_16x16x32_bf16 v[100:103], v[140:143], v[208:211], v[100:103]
	v_mfma_f32_16x16x32_bf16 v[104:107], v[180:183], v[204:207], v[104:107]
	v_mfma_f32_16x16x32_bf16 v[108:111], v[180:183], v[208:211], v[108:111]
	s_waitcnt lgkmcnt(2)
	v_mfma_f32_16x16x32_bf16 v[80:83], v[132:135], v[212:215], v[80:83]
	ds_read_b128 v[204:207], v129 offset:36864
	v_mfma_f32_16x16x32_bf16 v[84:87], v[132:135], v[216:219], v[84:87]
	ds_read_b128 v[208:211], v129 offset:37888
	v_mfma_f32_16x16x32_bf16 v[88:91], v[136:139], v[212:215], v[88:91]
	v_mfma_f32_16x16x32_bf16 v[92:95], v[136:139], v[216:219], v[92:95]
	v_mfma_f32_16x16x32_bf16 v[64:67], v[140:143], v[212:215], v[64:67]
	v_mfma_f32_16x16x32_bf16 v[68:71], v[140:143], v[216:219], v[68:71]
	v_mfma_f32_16x16x32_bf16 v[72:75], v[180:183], v[212:215], v[72:75]
	v_mfma_f32_16x16x32_bf16 v[76:79], v[180:183], v[216:219], v[76:79]
	s_waitcnt lgkmcnt(0)
	s_waitcnt vmcnt(6)
	s_barrier
	ds_read_b128 v[184:187], v156 offset:49152
	ds_read_b128 v[236:239], v156 offset:50176
	v_mfma_f32_16x16x32_bf16 v[48:51], v[132:135], v[248:251], v[48:51]
	ds_read_b128 v[240:243], v156 offset:51200
	ds_read_b128 v[244:247], v156 offset:52224
	v_mfma_f32_16x16x32_bf16 v[52:55], v[132:135], v[200:203], v[52:55]
	ds_read_b128 v[212:215], v129 offset:49152
	ds_read_b128 v[216:219], v129 offset:50176
	s_add_u32 m0, s8, 0x6000
	v_mfma_f32_16x16x32_bf16 v[56:59], v[136:139], v[248:251], v[56:59]
	global_load_lds_dwordx4 v189, s[4:5]
	s_add_u32 m0, s8, 0x7000
	v_mfma_f32_16x16x32_bf16 v[60:63], v[136:139], v[200:203], v[60:63]
	global_load_lds_dwordx4 v252, s[4:5]
	s_add_u32 m0, s8, 0x8000
	v_mfma_f32_16x16x32_bf16 v[32:35], v[140:143], v[248:251], v[32:35]
	global_load_lds_dwordx4 v190, s[4:5]
	v_mfma_f32_16x16x32_bf16 v[36:39], v[140:143], v[200:203], v[36:39]
	v_mfma_f32_16x16x32_bf16 v[40:43], v[180:183], v[248:251], v[40:43]
	v_mfma_f32_16x16x32_bf16 v[44:47], v[180:183], v[200:203], v[44:47]
	ds_read_b128 v[248:251], v129 offset:53248
	ds_read_b128 v[200:203], v129 offset:54272
	v_mfma_f32_16x16x32_bf16 v[16:19], v[132:135], v[204:207], v[16:19]
	s_add_u32 m0, s8, 0x9000
	v_mfma_f32_16x16x32_bf16 v[20:23], v[132:135], v[208:211], v[20:23]
	global_load_lds_dwordx4 v191, s[4:5]
	s_add_u32 m0, s8, 0xa000
	v_mfma_f32_16x16x32_bf16 v[24:27], v[136:139], v[204:207], v[24:27]
	global_load_lds_dwordx4 v189, s[6:7]
	s_add_u32 m0, s8, 0xb000
	v_mfma_f32_16x16x32_bf16 v[28:31], v[136:139], v[208:211], v[28:31]
	global_load_lds_dwordx4 v252, s[6:7]
	s_add_u32 s4, s4, 0x202000
	s_addc_u32 s5, s5, 0
	v_mfma_f32_16x16x32_bf16 v[0:3], v[140:143], v[204:207], v[0:3]
	s_add_u32 s6, s6, 0x40000
	s_addc_u32 s7, s7, 0
	v_mfma_f32_16x16x32_bf16 v[4:7], v[140:143], v[208:211], v[4:7]
	v_mfma_f32_16x16x32_bf16 v[8:11], v[180:183], v[204:207], v[8:11]
	v_mfma_f32_16x16x32_bf16 v[12:15], v[180:183], v[208:211], v[12:15]
	s_waitcnt lgkmcnt(2)
	v_mfma_f32_16x16x32_bf16 v[112:115], v[184:187], v[212:215], v[112:115]
	ds_read_b128 v[204:207], v129 offset:57344
	v_mfma_f32_16x16x32_bf16 v[116:119], v[184:187], v[216:219], v[116:119]
	ds_read_b128 v[208:211], v129 offset:58368
	v_mfma_f32_16x16x32_bf16 v[120:123], v[236:239], v[212:215], v[120:123]
	v_mfma_f32_16x16x32_bf16 v[124:127], v[236:239], v[216:219], v[124:127]
	v_mfma_f32_16x16x32_bf16 v[96:99], v[240:243], v[212:215], v[96:99]
	v_mfma_f32_16x16x32_bf16 v[100:103], v[240:243], v[216:219], v[100:103]
	v_mfma_f32_16x16x32_bf16 v[104:107], v[244:247], v[212:215], v[104:107]
	v_mfma_f32_16x16x32_bf16 v[108:111], v[244:247], v[216:219], v[108:111]
	s_waitcnt lgkmcnt(2)
	v_mfma_f32_16x16x32_bf16 v[80:83], v[184:187], v[248:251], v[80:83]
	ds_read_b128 v[212:215], v129 offset:61440
	v_mfma_f32_16x16x32_bf16 v[84:87], v[184:187], v[200:203], v[84:87]
	ds_read_b128 v[216:219], v129 offset:62464
	v_mfma_f32_16x16x32_bf16 v[88:91], v[236:239], v[248:251], v[88:91]
	v_mfma_f32_16x16x32_bf16 v[92:95], v[236:239], v[200:203], v[92:95]
	v_mfma_f32_16x16x32_bf16 v[64:67], v[240:243], v[248:251], v[64:67]
	v_mfma_f32_16x16x32_bf16 v[68:71], v[240:243], v[200:203], v[68:71]
	v_mfma_f32_16x16x32_bf16 v[72:75], v[244:247], v[248:251], v[72:75]
	v_mfma_f32_16x16x32_bf16 v[76:79], v[244:247], v[200:203], v[76:79]
	s_waitcnt lgkmcnt(0)
	s_waitcnt vmcnt(6)
	s_barrier
	ds_read_b128 v[132:135], v156
	ds_read_b128 v[136:139], v156 offset:1024
	v_mfma_f32_16x16x32_bf16 v[48:51], v[184:187], v[204:207], v[48:51]
	ds_read_b128 v[140:143], v156 offset:2048
	ds_read_b128 v[180:183], v156 offset:3072
	v_mfma_f32_16x16x32_bf16 v[52:55], v[184:187], v[208:211], v[52:55]
	ds_read_b128 v[248:251], v129
	ds_read_b128 v[200:203], v129 offset:1024
	s_add_u32 m0, s8, 0xc000
	v_mfma_f32_16x16x32_bf16 v[56:59], v[236:239], v[204:207], v[56:59]
	global_load_lds_dwordx4 v189, s[4:5]
	s_add_u32 m0, s8, 0xd000
	v_mfma_f32_16x16x32_bf16 v[60:63], v[236:239], v[208:211], v[60:63]
	global_load_lds_dwordx4 v252, s[4:5]
	s_add_u32 m0, s8, 0xe000
	v_mfma_f32_16x16x32_bf16 v[32:35], v[240:243], v[204:207], v[32:35]
	global_load_lds_dwordx4 v190, s[4:5]
	v_mfma_f32_16x16x32_bf16 v[36:39], v[240:243], v[208:211], v[36:39]
	v_mfma_f32_16x16x32_bf16 v[40:43], v[244:247], v[204:207], v[40:43]
	v_mfma_f32_16x16x32_bf16 v[44:47], v[244:247], v[208:211], v[44:47]
	ds_read_b128 v[204:207], v129 offset:4096
	ds_read_b128 v[208:211], v129 offset:5120
	v_mfma_f32_16x16x32_bf16 v[16:19], v[184:187], v[212:215], v[16:19]
	s_add_u32 m0, s8, 0xf000
	v_mfma_f32_16x16x32_bf16 v[20:23], v[184:187], v[216:219], v[20:23]
	global_load_lds_dwordx4 v191, s[4:5]
	s_add_u32 m0, s8, 0x10000
	v_mfma_f32_16x16x32_bf16 v[24:27], v[236:239], v[212:215], v[24:27]
	global_load_lds_dwordx4 v189, s[6:7]
	s_add_u32 m0, s8, 0x11000
	v_mfma_f32_16x16x32_bf16 v[28:31], v[236:239], v[216:219], v[28:31]
	global_load_lds_dwordx4 v252, s[6:7]
	s_add_u32 s4, s4, 0x202000
	s_addc_u32 s5, s5, 0
	v_mfma_f32_16x16x32_bf16 v[0:3], v[240:243], v[212:215], v[0:3]
	s_add_u32 s6, s6, 0x40000
	s_addc_u32 s7, s7, 0
	v_mfma_f32_16x16x32_bf16 v[4:7], v[240:243], v[216:219], v[4:7]
	v_mfma_f32_16x16x32_bf16 v[8:11], v[244:247], v[212:215], v[8:11]
	v_mfma_f32_16x16x32_bf16 v[12:15], v[244:247], v[216:219], v[12:15]
	s_mov_b32 s9, 3
.Lgemm_p4_loop:
	s_waitcnt lgkmcnt(2)
	v_mfma_f32_16x16x32_bf16 v[112:115], v[132:135], v[248:251], v[112:115]
	ds_read_b128 v[212:215], v129 offset:8192
	v_mfma_f32_16x16x32_bf16 v[116:119], v[132:135], v[200:203], v[116:119]
	ds_read_b128 v[216:219], v129 offset:9216
	v_mfma_f32_16x16x32_bf16 v[120:123], v[136:139], v[248:251], v[120:123]
	v_mfma_f32_16x16x32_bf16 v[124:127], v[136:139], v[200:203], v[124:127]
	v_mfma_f32_16x16x32_bf16 v[96:99], v[140:143], v[248:251], v[96:99]
	v_mfma_f32_16x16x32_bf16 v[100:103], v[140:143], v[200:203], v[100:103]
	v_mfma_f32_16x16x32_bf16 v[104:107], v[180:183], v[248:251], v[104:107]
	v_mfma_f32_16x16x32_bf16 v[108:111], v[180:183], v[200:203], v[108:111]
	s_waitcnt lgkmcnt(2)
	v_mfma_f32_16x16x32_bf16 v[80:83], v[132:135], v[204:207], v[80:83]
	ds_read_b128 v[248:251], v129 offset:12288
	v_mfma_f32_16x16x32_bf16 v[84:87], v[132:135], v[208:211], v[84:87]
	ds_read_b128 v[200:203], v129 offset:13312
	v_mfma_f32_16x16x32_bf16 v[88:91], v[136:139], v[204:207], v[88:91]
	v_mfma_f32_16x16x32_bf16 v[92:95], v[136:139], v[208:211], v[92:95]
	v_mfma_f32_16x16x32_bf16 v[64:67], v[140:143], v[204:207], v[64:67]
	v_mfma_f32_16x16x32_bf16 v[68:71], v[140:143], v[208:211], v[68:71]
	v_mfma_f32_16x16x32_bf16 v[72:75], v[180:183], v[204:207], v[72:75]
	v_mfma_f32_16x16x32_bf16 v[76:79], v[180:183], v[208:211], v[76:79]
	s_waitcnt lgkmcnt(0)
	s_waitcnt vmcnt(6)
	s_barrier
	ds_read_b128 v[184:187], v156 offset:24576
	ds_read_b128 v[236:239], v156 offset:25600
	v_mfma_f32_16x16x32_bf16 v[48:51], v[132:135], v[212:215], v[48:51]
	ds_read_b128 v[240:243], v156 offset:26624
	ds_read_b128 v[244:247], v156 offset:27648
	v_mfma_f32_16x16x32_bf16 v[52:55], v[132:135], v[216:219], v[52:55]
	ds_read_b128 v[204:207], v129 offset:24576
	ds_read_b128 v[208:211], v129 offset:25600
	s_add_u32 m0, s8, 0x0
	v_mfma_f32_16x16x32_bf16 v[56:59], v[136:139], v[212:215], v[56:59]
	global_load_lds_dwordx4 v189, s[4:5]
	s_add_u32 m0, s8, 0x1000
	v_mfma_f32_16x16x32_bf16 v[60:63], v[136:139], v[216:219], v[60:63]
	global_load_lds_dwordx4 v252, s[4:5]
	s_add_u32 m0, s8, 0x2000
	v_mfma_f32_16x16x32_bf16 v[32:35], v[140:143], v[212:215], v[32:35]
	global_load_lds_dwordx4 v190, s[4:5]
	v_mfma_f32_16x16x32_bf16 v[36:39], v[140:143], v[216:219], v[36:39]
	v_mfma_f32_16x16x32_bf16 v[40:43], v[180:183], v[212:215], v[40:43]
	v_mfma_f32_16x16x32_bf16 v[44:47], v[180:183], v[216:219], v[44:47]
	ds_read_b128 v[212:215], v129 offset:28672
	ds_read_b128 v[216:219], v129 offset:29696
	v_mfma_f32_16x16x32_bf16 v[16:19], v[132:135], v[248:251], v[16:19]
	s_add_u32 m0, s8, 0x3000
	v_mfma_f32_16x16x32_bf16 v[20:23], v[132:135], v[200:203], v[20:23]
	global_load_lds_dwordx4 v191, s[4:5]
	s_add_u32 m0, s8, 0x4000
	v_mfma_f32_16x16x32_bf16 v[24:27], v[136:139], v[248:251], v[24:27]
	global_load_lds_dwordx4 v189, s[6:7]
	s_add_u32 m0, s8, 0x5000
	v_mfma_f32_16x16x32_bf16 v[28:31], v[136:139], v[200:203], v[28:31]
	global_load_lds_dwordx4 v252, s[6:7]
	s_add_u32 s4, s4, 0x202000
	s_addc_u32 s5, s5, 0
	v_mfma_f32_16x16x32_bf16 v[0:3], v[140:143], v[248:251], v[0:3]
	s_add_u32 s6, s6, 0x40000
	s_addc_u32 s7, s7, 0
	v_mfma_f32_16x16x32_bf16 v[4:7], v[140:143], v[200:203], v[4:7]
	v_mfma_f32_16x16x32_bf16 v[8:11], v[180:183], v[248:251], v[8:11]
	v_mfma_f32_16x16x32_bf16 v[12:15], v[180:183], v[200:203], v[12:15]
	s_waitcnt lgkmcnt(2)
	v_mfma_f32_16x16x32_bf16 v[112:115], v[184:187], v[204:207], v[112:115]
	ds_read_b128 v[248:251], v129 offset:32768
	v_mfma_f32_16x16x32_bf16 v[116:119], v[184:187], v[208:211], v[116:119]
	ds_read_b128 v[200:203], v129 offset:33792
	v_mfma_f32_16x16x32_bf16 v[120:123], v[236:239], v[204:207], v[120:123]
	v_mfma_f32_16x16x32_bf16 v[124:127], v[236:239], v[208:211], v[124:127]
	v_mfma_f32_16x16x32_bf16 v[96:99], v[240:243], v[204:207], v[96:99]
	v_mfma_f32_16x16x32_bf16 v[100:103], v[240:243], v[208:211], v[100:103]
	v_mfma_f32_16x16x32_bf16 v[104:107], v[244:247], v[204:207], v[104:107]
	v_mfma_f32_16x16x32_bf16 v[108:111], v[244:247], v[208:211], v[108:111]
	s_waitcnt lgkmcnt(2)
	v_mfma_f32_16x16x32_bf16 v[80:83], v[184:187], v[212:215], v[80:83]
	ds_read_b128 v[204:207], v129 offset:36864
	v_mfma_f32_16x16x32_bf16 v[84:87], v[184:187], v[216:219], v[84:87]
	ds_read_b128 v[208:211], v129 offset:37888
	v_mfma_f32_16x16x32_bf16 v[88:91], v[236:239], v[212:215], v[88:91]
	v_mfma_f32_16x16x32_bf16 v[92:95], v[236:239], v[216:219], v[92:95]
	v_mfma_f32_16x16x32_bf16 v[64:67], v[240:243], v[212:215], v[64:67]
	v_mfma_f32_16x16x32_bf16 v[68:71], v[240:243], v[216:219], v[68:71]
	v_mfma_f32_16x16x32_bf16 v[72:75], v[244:247], v[212:215], v[72:75]
	v_mfma_f32_16x16x32_bf16 v[76:79], v[244:247], v[216:219], v[76:79]
	s_waitcnt lgkmcnt(0)
	s_waitcnt vmcnt(6)
	s_barrier
	ds_read_b128 v[132:135], v156 offset:49152
	ds_read_b128 v[136:139], v156 offset:50176
	v_mfma_f32_16x16x32_bf16 v[48:51], v[184:187], v[248:251], v[48:51]
	ds_read_b128 v[140:143], v156 offset:51200
	ds_read_b128 v[180:183], v156 offset:52224
	v_mfma_f32_16x16x32_bf16 v[52:55], v[184:187], v[200:203], v[52:55]
	ds_read_b128 v[212:215], v129 offset:49152
	ds_read_b128 v[216:219], v129 offset:50176
	s_add_u32 m0, s8, 0x6000
	v_mfma_f32_16x16x32_bf16 v[56:59], v[236:239], v[248:251], v[56:59]
	global_load_lds_dwordx4 v189, s[4:5]
	s_add_u32 m0, s8, 0x7000
	v_mfma_f32_16x16x32_bf16 v[60:63], v[236:239], v[200:203], v[60:63]
	global_load_lds_dwordx4 v252, s[4:5]
	s_add_u32 m0, s8, 0x8000
	v_mfma_f32_16x16x32_bf16 v[32:35], v[240:243], v[248:251], v[32:35]
	global_load_lds_dwordx4 v190, s[4:5]
	v_mfma_f32_16x16x32_bf16 v[36:39], v[240:243], v[200:203], v[36:39]
	v_mfma_f32_16x16x32_bf16 v[40:43], v[244:247], v[248:251], v[40:43]
	v_mfma_f32_16x16x32_bf16 v[44:47], v[244:247], v[200:203], v[44:47]
	ds_read_b128 v[248:251], v129 offset:53248
	ds_read_b128 v[200:203], v129 offset:54272
	v_mfma_f32_16x16x32_bf16 v[16:19], v[184:187], v[204:207], v[16:19]
	s_add_u32 m0, s8, 0x9000
	v_mfma_f32_16x16x32_bf16 v[20:23], v[184:187], v[208:211], v[20:23]
	global_load_lds_dwordx4 v191, s[4:5]
	s_add_u32 m0, s8, 0xa000
	v_mfma_f32_16x16x32_bf16 v[24:27], v[236:239], v[204:207], v[24:27]
	global_load_lds_dwordx4 v189, s[6:7]
	s_add_u32 m0, s8, 0xb000
	v_mfma_f32_16x16x32_bf16 v[28:31], v[236:239], v[208:211], v[28:31]
	global_load_lds_dwordx4 v252, s[6:7]
	s_add_u32 s4, s4, 0x202000
	s_addc_u32 s5, s5, 0
	v_mfma_f32_16x16x32_bf16 v[0:3], v[240:243], v[204:207], v[0:3]
	s_add_u32 s6, s6, 0x40000
	s_addc_u32 s7, s7, 0
	v_mfma_f32_16x16x32_bf16 v[4:7], v[240:243], v[208:211], v[4:7]
	v_mfma_f32_16x16x32_bf16 v[8:11], v[244:247], v[204:207], v[8:11]
	v_mfma_f32_16x16x32_bf16 v[12:15], v[244:247], v[208:211], v[12:15]
	s_waitcnt lgkmcnt(2)
	v_mfma_f32_16x16x32_bf16 v[112:115], v[132:135], v[212:215], v[112:115]
	ds_read_b128 v[204:207], v129 offset:57344
	v_mfma_f32_16x16x32_bf16 v[116:119], v[132:135], v[216:219], v[116:119]
	ds_read_b128 v[208:211], v129 offset:58368
	v_mfma_f32_16x16x32_bf16 v[120:123], v[136:139], v[212:215], v[120:123]
	v_mfma_f32_16x16x32_bf16 v[124:127], v[136:139], v[216:219], v[124:127]
	v_mfma_f32_16x16x32_bf16 v[96:99], v[140:143], v[212:215], v[96:99]
	v_mfma_f32_16x16x32_bf16 v[100:103], v[140:143], v[216:219], v[100:103]
	v_mfma_f32_16x16x32_bf16 v[104:107], v[180:183], v[212:215], v[104:107]
	v_mfma_f32_16x16x32_bf16 v[108:111], v[180:183], v[216:219], v[108:111]
	s_waitcnt lgkmcnt(2)
	v_mfma_f32_16x16x32_bf16 v[80:83], v[132:135], v[248:251], v[80:83]
	ds_read_b128 v[212:215], v129 offset:61440
	v_mfma_f32_16x16x32_bf16 v[84:87], v[132:135], v[200:203], v[84:87]
	ds_read_b128 v[216:219], v129 offset:62464
	v_mfma_f32_16x16x32_bf16 v[88:91], v[136:139], v[248:251], v[88:91]
	v_mfma_f32_16x16x32_bf16 v[92:95], v[136:139], v[200:203], v[92:95]
	v_mfma_f32_16x16x32_bf16 v[64:67], v[140:143], v[248:251], v[64:67]
	v_mfma_f32_16x16x32_bf16 v[68:71], v[140:143], v[200:203], v[68:71]
	v_mfma_f32_16x16x32_bf16 v[72:75], v[180:183], v[248:251], v[72:75]
	v_mfma_f32_16x16x32_bf16 v[76:79], v[180:183], v[200:203], v[76:79]
	s_waitcnt lgkmcnt(0)
	s_waitcnt vmcnt(6)
	s_barrier
	ds_read_b128 v[184:187], v156
	ds_read_b128 v[236:239], v156 offset:1024
	v_mfma_f32_16x16x32_bf16 v[48:51], v[132:135], v[204:207], v[48:51]
	ds_read_b128 v[240:243], v156 offset:2048
	ds_read_b128 v[244:247], v156 offset:3072
	v_mfma_f32_16x16x32_bf16 v[52:55], v[132:135], v[208:211], v[52:55]
	ds_read_b128 v[248:251], v129
	ds_read_b128 v[200:203], v129 offset:1024
	s_add_u32 m0, s8, 0xc000
	v_mfma_f32_16x16x32_bf16 v[56:59], v[136:139], v[204:207], v[56:59]
	global_load_lds_dwordx4 v189, s[4:5]
	s_add_u32 m0, s8, 0xd000
	v_mfma_f32_16x16x32_bf16 v[60:63], v[136:139], v[208:211], v[60:63]
	global_load_lds_dwordx4 v252, s[4:5]
	s_add_u32 m0, s8, 0xe000
	v_mfma_f32_16x16x32_bf16 v[32:35], v[140:143], v[204:207], v[32:35]
	global_load_lds_dwordx4 v190, s[4:5]
	v_mfma_f32_16x16x32_bf16 v[36:39], v[140:143], v[208:211], v[36:39]
	v_mfma_f32_16x16x32_bf16 v[40:43], v[180:183], v[204:207], v[40:43]
	v_mfma_f32_16x16x32_bf16 v[44:47], v[180:183], v[208:211], v[44:47]
	ds_read_b128 v[204:207], v129 offset:4096
	ds_read_b128 v[208:211], v129 offset:5120
	v_mfma_f32_16x16x32_bf16 v[16:19], v[132:135], v[212:215], v[16:19]
	s_add_u32 m0, s8, 0xf000
	v_mfma_f32_16x16x32_bf16 v[20:23], v[132:135], v[216:219], v[20:23]
	global_load_lds_dwordx4 v191, s[4:5]
	s_add_u32 m0, s8, 0x10000
	v_mfma_f32_16x16x32_bf16 v[24:27], v[136:139], v[212:215], v[24:27]
	global_load_lds_dwordx4 v189, s[6:7]
	s_add_u32 m0, s8, 0x11000
	v_mfma_f32_16x16x32_bf16 v[28:31], v[136:139], v[216:219], v[28:31]
	global_load_lds_dwordx4 v252, s[6:7]
	s_add_u32 s4, s4, 0x202000
	s_addc_u32 s5, s5, 0
	v_mfma_f32_16x16x32_bf16 v[0:3], v[140:143], v[212:215], v[0:3]
	s_add_u32 s6, s6, 0x40000
	s_addc_u32 s7, s7, 0
	v_mfma_f32_16x16x32_bf16 v[4:7], v[140:143], v[216:219], v[4:7]
	v_mfma_f32_16x16x32_bf16 v[8:11], v[180:183], v[212:215], v[8:11]
	v_mfma_f32_16x16x32_bf16 v[12:15], v[180:183], v[216:219], v[12:15]
	s_waitcnt lgkmcnt(2)
	v_mfma_f32_16x16x32_bf16 v[112:115], v[184:187], v[248:251], v[112:115]
	ds_read_b128 v[212:215], v129 offset:8192
	v_mfma_f32_16x16x32_bf16 v[116:119], v[184:187], v[200:203], v[116:119]
	ds_read_b128 v[216:219], v129 offset:9216
	v_mfma_f32_16x16x32_bf16 v[120:123], v[236:239], v[248:251], v[120:123]
	v_mfma_f32_16x16x32_bf16 v[124:127], v[236:239], v[200:203], v[124:127]
	v_mfma_f32_16x16x32_bf16 v[96:99], v[240:243], v[248:251], v[96:99]
	v_mfma_f32_16x16x32_bf16 v[100:103], v[240:243], v[200:203], v[100:103]
	v_mfma_f32_16x16x32_bf16 v[104:107], v[244:247], v[248:251], v[104:107]
	v_mfma_f32_16x16x32_bf16 v[108:111], v[244:247], v[200:203], v[108:111]
	s_waitcnt lgkmcnt(2)
	v_mfma_f32_16x16x32_bf16 v[80:83], v[184:187], v[204:207], v[80:83]
	ds_read_b128 v[248:251], v129 offset:12288
	v_mfma_f32_16x16x32_bf16 v[84:87], v[184:187], v[208:211], v[84:87]
	ds_read_b128 v[200:203], v129 offset:13312
	v_mfma_f32_16x16x32_bf16 v[88:91], v[236:239], v[204:207], v[88:91]
	v_mfma_f32_16x16x32_bf16 v[92:95], v[236:239], v[208:211], v[92:95]
	v_mfma_f32_16x16x32_bf16 v[64:67], v[240:243], v[204:207], v[64:67]
	v_mfma_f32_16x16x32_bf16 v[68:71], v[240:243], v[208:211], v[68:71]
	v_mfma_f32_16x16x32_bf16 v[72:75], v[244:247], v[204:207], v[72:75]
	v_mfma_f32_16x16x32_bf16 v[76:79], v[244:247], v[208:211], v[76:79]
	s_waitcnt lgkmcnt(0)
	s_waitcnt vmcnt(6)
	s_barrier
	ds_read_b128 v[132:135], v156 offset:24576
	ds_read_b128 v[136:139], v156 offset:25600
	v_mfma_f32_16x16x32_bf16 v[48:51], v[184:187], v[212:215], v[48:51]
	ds_read_b128 v[140:143], v156 offset:26624
	ds_read_b128 v[180:183], v156 offset:27648
	v_mfma_f32_16x16x32_bf16 v[52:55], v[184:187], v[216:219], v[52:55]
	ds_read_b128 v[204:207], v129 offset:24576
	ds_read_b128 v[208:211], v129 offset:25600
	s_add_u32 m0, s8, 0x0
	v_mfma_f32_16x16x32_bf16 v[56:59], v[236:239], v[212:215], v[56:59]
	global_load_lds_dwordx4 v189, s[4:5]
	s_add_u32 m0, s8, 0x1000
	v_mfma_f32_16x16x32_bf16 v[60:63], v[236:239], v[216:219], v[60:63]
	global_load_lds_dwordx4 v252, s[4:5]
	s_add_u32 m0, s8, 0x2000
	v_mfma_f32_16x16x32_bf16 v[32:35], v[240:243], v[212:215], v[32:35]
	global_load_lds_dwordx4 v190, s[4:5]
	v_mfma_f32_16x16x32_bf16 v[36:39], v[240:243], v[216:219], v[36:39]
	v_mfma_f32_16x16x32_bf16 v[40:43], v[244:247], v[212:215], v[40:43]
	v_mfma_f32_16x16x32_bf16 v[44:47], v[244:247], v[216:219], v[44:47]
	ds_read_b128 v[212:215], v129 offset:28672
	ds_read_b128 v[216:219], v129 offset:29696
	v_mfma_f32_16x16x32_bf16 v[16:19], v[184:187], v[248:251], v[16:19]
	s_add_u32 m0, s8, 0x3000
	v_mfma_f32_16x16x32_bf16 v[20:23], v[184:187], v[200:203], v[20:23]
	global_load_lds_dwordx4 v191, s[4:5]
	s_add_u32 m0, s8, 0x4000
	v_mfma_f32_16x16x32_bf16 v[24:27], v[236:239], v[248:251], v[24:27]
	global_load_lds_dwordx4 v189, s[6:7]
	s_add_u32 m0, s8, 0x5000
	v_mfma_f32_16x16x32_bf16 v[28:31], v[236:239], v[200:203], v[28:31]
	global_load_lds_dwordx4 v252, s[6:7]
	s_add_u32 s4, s4, 0x202000
	s_addc_u32 s5, s5, 0
	v_mfma_f32_16x16x32_bf16 v[0:3], v[240:243], v[248:251], v[0:3]
	s_add_u32 s6, s6, 0x40000
	s_addc_u32 s7, s7, 0
	v_mfma_f32_16x16x32_bf16 v[4:7], v[240:243], v[200:203], v[4:7]
	v_mfma_f32_16x16x32_bf16 v[8:11], v[244:247], v[248:251], v[8:11]
	v_mfma_f32_16x16x32_bf16 v[12:15], v[244:247], v[200:203], v[12:15]
	s_waitcnt lgkmcnt(2)
	v_mfma_f32_16x16x32_bf16 v[112:115], v[132:135], v[204:207], v[112:115]
	ds_read_b128 v[248:251], v129 offset:32768
	v_mfma_f32_16x16x32_bf16 v[116:119], v[132:135], v[208:211], v[116:119]
	ds_read_b128 v[200:203], v129 offset:33792
	v_mfma_f32_16x16x32_bf16 v[120:123], v[136:139], v[204:207], v[120:123]
	v_mfma_f32_16x16x32_bf16 v[124:127], v[136:139], v[208:211], v[124:127]
	v_mfma_f32_16x16x32_bf16 v[96:99], v[140:143], v[204:207], v[96:99]
	v_mfma_f32_16x16x32_bf16 v[100:103], v[140:143], v[208:211], v[100:103]
	v_mfma_f32_16x16x32_bf16 v[104:107], v[180:183], v[204:207], v[104:107]
	v_mfma_f32_16x16x32_bf16 v[108:111], v[180:183], v[208:211], v[108:111]
	s_waitcnt lgkmcnt(2)
	v_mfma_f32_16x16x32_bf16 v[80:83], v[132:135], v[212:215], v[80:83]
	ds_read_b128 v[204:207], v129 offset:36864
	v_mfma_f32_16x16x32_bf16 v[84:87], v[132:135], v[216:219], v[84:87]
	ds_read_b128 v[208:211], v129 offset:37888
	v_mfma_f32_16x16x32_bf16 v[88:91], v[136:139], v[212:215], v[88:91]
	v_mfma_f32_16x16x32_bf16 v[92:95], v[136:139], v[216:219], v[92:95]
	v_mfma_f32_16x16x32_bf16 v[64:67], v[140:143], v[212:215], v[64:67]
	v_mfma_f32_16x16x32_bf16 v[68:71], v[140:143], v[216:219], v[68:71]
	v_mfma_f32_16x16x32_bf16 v[72:75], v[180:183], v[212:215], v[72:75]
	v_mfma_f32_16x16x32_bf16 v[76:79], v[180:183], v[216:219], v[76:79]
	s_waitcnt lgkmcnt(0)
	s_waitcnt vmcnt(6)
	s_barrier
	ds_read_b128 v[184:187], v156 offset:49152
	ds_read_b128 v[236:239], v156 offset:50176
	v_mfma_f32_16x16x32_bf16 v[48:51], v[132:135], v[248:251], v[48:51]
	ds_read_b128 v[240:243], v156 offset:51200
	ds_read_b128 v[244:247], v156 offset:52224
	v_mfma_f32_16x16x32_bf16 v[52:55], v[132:135], v[200:203], v[52:55]
	ds_read_b128 v[212:215], v129 offset:49152
	ds_read_b128 v[216:219], v129 offset:50176
	s_add_u32 m0, s8, 0x6000
	v_mfma_f32_16x16x32_bf16 v[56:59], v[136:139], v[248:251], v[56:59]
	global_load_lds_dwordx4 v189, s[4:5]
	s_add_u32 m0, s8, 0x7000
	v_mfma_f32_16x16x32_bf16 v[60:63], v[136:139], v[200:203], v[60:63]
	global_load_lds_dwordx4 v252, s[4:5]
	s_add_u32 m0, s8, 0x8000
	v_mfma_f32_16x16x32_bf16 v[32:35], v[140:143], v[248:251], v[32:35]
	global_load_lds_dwordx4 v190, s[4:5]
	v_mfma_f32_16x16x32_bf16 v[36:39], v[140:143], v[200:203], v[36:39]
	v_mfma_f32_16x16x32_bf16 v[40:43], v[180:183], v[248:251], v[40:43]
	v_mfma_f32_16x16x32_bf16 v[44:47], v[180:183], v[200:203], v[44:47]
	ds_read_b128 v[248:251], v129 offset:53248
	ds_read_b128 v[200:203], v129 offset:54272
	v_mfma_f32_16x16x32_bf16 v[16:19], v[132:135], v[204:207], v[16:19]
	s_add_u32 m0, s8, 0x9000
	v_mfma_f32_16x16x32_bf16 v[20:23], v[132:135], v[208:211], v[20:23]
	global_load_lds_dwordx4 v191, s[4:5]
	s_add_u32 m0, s8, 0xa000
	v_mfma_f32_16x16x32_bf16 v[24:27], v[136:139], v[204:207], v[24:27]
	global_load_lds_dwordx4 v189, s[6:7]
	s_add_u32 m0, s8, 0xb000
	v_mfma_f32_16x16x32_bf16 v[28:31], v[136:139], v[208:211], v[28:31]
	global_load_lds_dwordx4 v252, s[6:7]
	s_add_u32 s4, s4, 0x202000
	s_addc_u32 s5, s5, 0
	v_mfma_f32_16x16x32_bf16 v[0:3], v[140:143], v[204:207], v[0:3]
	s_add_u32 s6, s6, 0x40000
	s_addc_u32 s7, s7, 0
	v_mfma_f32_16x16x32_bf16 v[4:7], v[140:143], v[208:211], v[4:7]
	v_mfma_f32_16x16x32_bf16 v[8:11], v[180:183], v[204:207], v[8:11]
	v_mfma_f32_16x16x32_bf16 v[12:15], v[180:183], v[208:211], v[12:15]
	s_waitcnt lgkmcnt(2)
	v_mfma_f32_16x16x32_bf16 v[112:115], v[184:187], v[212:215], v[112:115]
	ds_read_b128 v[204:207], v129 offset:57344
	v_mfma_f32_16x16x32_bf16 v[116:119], v[184:187], v[216:219], v[116:119]
	ds_read_b128 v[208:211], v129 offset:58368
	v_mfma_f32_16x16x32_bf16 v[120:123], v[236:239], v[212:215], v[120:123]
	v_mfma_f32_16x16x32_bf16 v[124:127], v[236:239], v[216:219], v[124:127]
	v_mfma_f32_16x16x32_bf16 v[96:99], v[240:243], v[212:215], v[96:99]
	v_mfma_f32_16x16x32_bf16 v[100:103], v[240:243], v[216:219], v[100:103]
	v_mfma_f32_16x16x32_bf16 v[104:107], v[244:247], v[212:215], v[104:107]
	v_mfma_f32_16x16x32_bf16 v[108:111], v[244:247], v[216:219], v[108:111]
	s_waitcnt lgkmcnt(2)
	v_mfma_f32_16x16x32_bf16 v[80:83], v[184:187], v[248:251], v[80:83]
	ds_read_b128 v[212:215], v129 offset:61440
	v_mfma_f32_16x16x32_bf16 v[84:87], v[184:187], v[200:203], v[84:87]
	ds_read_b128 v[216:219], v129 offset:62464
	v_mfma_f32_16x16x32_bf16 v[88:91], v[236:239], v[248:251], v[88:91]
	v_mfma_f32_16x16x32_bf16 v[92:95], v[236:239], v[200:203], v[92:95]
	v_mfma_f32_16x16x32_bf16 v[64:67], v[240:243], v[248:251], v[64:67]
	v_mfma_f32_16x16x32_bf16 v[68:71], v[240:243], v[200:203], v[68:71]
	v_mfma_f32_16x16x32_bf16 v[72:75], v[244:247], v[248:251], v[72:75]
	v_mfma_f32_16x16x32_bf16 v[76:79], v[244:247], v[200:203], v[76:79]
	s_waitcnt lgkmcnt(0)
	s_waitcnt vmcnt(6)
	s_barrier
	ds_read_b128 v[132:135], v156
	ds_read_b128 v[136:139], v156 offset:1024
	v_mfma_f32_16x16x32_bf16 v[48:51], v[184:187], v[204:207], v[48:51]
	ds_read_b128 v[140:143], v156 offset:2048
	ds_read_b128 v[180:183], v156 offset:3072
	v_mfma_f32_16x16x32_bf16 v[52:55], v[184:187], v[208:211], v[52:55]
	ds_read_b128 v[248:251], v129
	ds_read_b128 v[200:203], v129 offset:1024
	s_add_u32 m0, s8, 0xc000
	v_mfma_f32_16x16x32_bf16 v[56:59], v[236:239], v[204:207], v[56:59]
	global_load_lds_dwordx4 v189, s[4:5]
	s_add_u32 m0, s8, 0xd000
	v_mfma_f32_16x16x32_bf16 v[60:63], v[236:239], v[208:211], v[60:63]
	global_load_lds_dwordx4 v252, s[4:5]
	s_add_u32 m0, s8, 0xe000
	v_mfma_f32_16x16x32_bf16 v[32:35], v[240:243], v[204:207], v[32:35]
	global_load_lds_dwordx4 v190, s[4:5]
	v_mfma_f32_16x16x32_bf16 v[36:39], v[240:243], v[208:211], v[36:39]
	v_mfma_f32_16x16x32_bf16 v[40:43], v[244:247], v[204:207], v[40:43]
	v_mfma_f32_16x16x32_bf16 v[44:47], v[244:247], v[208:211], v[44:47]
	ds_read_b128 v[204:207], v129 offset:4096
	ds_read_b128 v[208:211], v129 offset:5120
	v_mfma_f32_16x16x32_bf16 v[16:19], v[184:187], v[212:215], v[16:19]
	s_add_u32 m0, s8, 0xf000
	v_mfma_f32_16x16x32_bf16 v[20:23], v[184:187], v[216:219], v[20:23]
	global_load_lds_dwordx4 v191, s[4:5]
	s_add_u32 m0, s8, 0x10000
	v_mfma_f32_16x16x32_bf16 v[24:27], v[236:239], v[212:215], v[24:27]
	global_load_lds_dwordx4 v189, s[6:7]
	s_add_u32 m0, s8, 0x11000
	v_mfma_f32_16x16x32_bf16 v[28:31], v[236:239], v[216:219], v[28:31]
	global_load_lds_dwordx4 v252, s[6:7]
	s_add_u32 s4, s4, 0x202000
	s_addc_u32 s5, s5, 0
	v_mfma_f32_16x16x32_bf16 v[0:3], v[240:243], v[212:215], v[0:3]
	s_add_u32 s6, s6, 0x40000
	s_addc_u32 s7, s7, 0
	v_mfma_f32_16x16x32_bf16 v[4:7], v[240:243], v[216:219], v[4:7]
	v_mfma_f32_16x16x32_bf16 v[8:11], v[244:247], v[212:215], v[8:11]
	v_mfma_f32_16x16x32_bf16 v[12:15], v[244:247], v[216:219], v[12:15]
	s_sub_i32 s9, s9, 1
	s_cmp_lg_u32 s9, 0
	s_cbranch_scc1 .Lgemm_p4_loop
	s_waitcnt lgkmcnt(2)
	v_mfma_f32_16x16x32_bf16 v[112:115], v[132:135], v[248:251], v[112:115]
	ds_read_b128 v[212:215], v129 offset:8192
	v_mfma_f32_16x16x32_bf16 v[116:119], v[132:135], v[200:203], v[116:119]
	ds_read_b128 v[216:219], v129 offset:9216
	v_mfma_f32_16x16x32_bf16 v[120:123], v[136:139], v[248:251], v[120:123]
	v_mfma_f32_16x16x32_bf16 v[124:127], v[136:139], v[200:203], v[124:127]
	v_mfma_f32_16x16x32_bf16 v[96:99], v[140:143], v[248:251], v[96:99]
	v_mfma_f32_16x16x32_bf16 v[100:103], v[140:143], v[200:203], v[100:103]
	v_mfma_f32_16x16x32_bf16 v[104:107], v[180:183], v[248:251], v[104:107]
	v_mfma_f32_16x16x32_bf16 v[108:111], v[180:183], v[200:203], v[108:111]
	s_waitcnt lgkmcnt(2)
	v_mfma_f32_16x16x32_bf16 v[80:83], v[132:135], v[204:207], v[80:83]
	ds_read_b128 v[248:251], v129 offset:12288
	v_mfma_f32_16x16x32_bf16 v[84:87], v[132:135], v[208:211], v[84:87]
	ds_read_b128 v[200:203], v129 offset:13312
	v_mfma_f32_16x16x32_bf16 v[88:91], v[136:139], v[204:207], v[88:91]
	v_mfma_f32_16x16x32_bf16 v[92:95], v[136:139], v[208:211], v[92:95]
	v_mfma_f32_16x16x32_bf16 v[64:67], v[140:143], v[204:207], v[64:67]
	v_mfma_f32_16x16x32_bf16 v[68:71], v[140:143], v[208:211], v[68:71]
	v_mfma_f32_16x16x32_bf16 v[72:75], v[180:183], v[204:207], v[72:75]
	v_mfma_f32_16x16x32_bf16 v[76:79], v[180:183], v[208:211], v[76:79]
	s_waitcnt lgkmcnt(0)
	s_waitcnt vmcnt(6)
	s_barrier
	ds_read_b128 v[184:187], v156 offset:24576
	ds_read_b128 v[236:239], v156 offset:25600
	v_mfma_f32_16x16x32_bf16 v[48:51], v[132:135], v[212:215], v[48:51]
	ds_read_b128 v[240:243], v156 offset:26624
	ds_read_b128 v[244:247], v156 offset:27648
	v_mfma_f32_16x16x32_bf16 v[52:55], v[132:135], v[216:219], v[52:55]
	ds_read_b128 v[204:207], v129 offset:24576
	ds_read_b128 v[208:211], v129 offset:25600
	s_add_u32 m0, s8, 0x0
	v_mfma_f32_16x16x32_bf16 v[56:59], v[136:139], v[212:215], v[56:59]
	global_load_lds_dwordx4 v189, s[4:5]
	s_add_u32 m0, s8, 0x1000
	v_mfma_f32_16x16x32_bf16 v[60:63], v[136:139], v[216:219], v[60:63]
	global_load_lds_dwordx4 v252, s[4:5]
	s_add_u32 m0, s8, 0x2000
	v_mfma_f32_16x16x32_bf16 v[32:35], v[140:143], v[212:215], v[32:35]
	global_load_lds_dwordx4 v190, s[4:5]
	v_mfma_f32_16x16x32_bf16 v[36:39], v[140:143], v[216:219], v[36:39]
	v_mfma_f32_16x16x32_bf16 v[40:43], v[180:183], v[212:215], v[40:43]
	v_mfma_f32_16x16x32_bf16 v[44:47], v[180:183], v[216:219], v[44:47]
	ds_read_b128 v[212:215], v129 offset:28672
	ds_read_b128 v[216:219], v129 offset:29696
	v_mfma_f32_16x16x32_bf16 v[16:19], v[132:135], v[248:251], v[16:19]
	s_add_u32 m0, s8, 0x3000
	v_mfma_f32_16x16x32_bf16 v[20:23], v[132:135], v[200:203], v[20:23]
	global_load_lds_dwordx4 v191, s[4:5]
	s_add_u32 m0, s8, 0x4000
	v_mfma_f32_16x16x32_bf16 v[24:27], v[136:139], v[248:251], v[24:27]
	global_load_lds_dwordx4 v189, s[6:7]
	s_add_u32 m0, s8, 0x5000
	v_mfma_f32_16x16x32_bf16 v[28:31], v[136:139], v[200:203], v[28:31]
	global_load_lds_dwordx4 v252, s[6:7]
	s_add_u32 s4, s4, 0x202000
	s_addc_u32 s5, s5, 0
	v_mfma_f32_16x16x32_bf16 v[0:3], v[140:143], v[248:251], v[0:3]
	s_add_u32 s6, s6, 0x40000
	s_addc_u32 s7, s7, 0
	v_mfma_f32_16x16x32_bf16 v[4:7], v[140:143], v[200:203], v[4:7]
	v_mfma_f32_16x16x32_bf16 v[8:11], v[180:183], v[248:251], v[8:11]
	v_mfma_f32_16x16x32_bf16 v[12:15], v[180:183], v[200:203], v[12:15]
	s_waitcnt lgkmcnt(2)
	v_mfma_f32_16x16x32_bf16 v[112:115], v[184:187], v[204:207], v[112:115]
	ds_read_b128 v[248:251], v129 offset:32768
	v_mfma_f32_16x16x32_bf16 v[116:119], v[184:187], v[208:211], v[116:119]
	ds_read_b128 v[200:203], v129 offset:33792
	v_mfma_f32_16x16x32_bf16 v[120:123], v[236:239], v[204:207], v[120:123]
	v_mfma_f32_16x16x32_bf16 v[124:127], v[236:239], v[208:211], v[124:127]
	v_mfma_f32_16x16x32_bf16 v[96:99], v[240:243], v[204:207], v[96:99]
	v_mfma_f32_16x16x32_bf16 v[100:103], v[240:243], v[208:211], v[100:103]
	v_mfma_f32_16x16x32_bf16 v[104:107], v[244:247], v[204:207], v[104:107]
	v_mfma_f32_16x16x32_bf16 v[108:111], v[244:247], v[208:211], v[108:111]
	s_waitcnt lgkmcnt(2)
	v_mfma_f32_16x16x32_bf16 v[80:83], v[184:187], v[212:215], v[80:83]
	ds_read_b128 v[204:207], v129 offset:36864
	v_mfma_f32_16x16x32_bf16 v[84:87], v[184:187], v[216:219], v[84:87]
	ds_read_b128 v[208:211], v129 offset:37888
	v_mfma_f32_16x16x32_bf16 v[88:91], v[236:239], v[212:215], v[88:91]
	v_mfma_f32_16x16x32_bf16 v[92:95], v[236:239], v[216:219], v[92:95]
	v_mfma_f32_16x16x32_bf16 v[64:67], v[240:243], v[212:215], v[64:67]
	v_mfma_f32_16x16x32_bf16 v[68:71], v[240:243], v[216:219], v[68:71]
	v_mfma_f32_16x16x32_bf16 v[72:75], v[244:247], v[212:215], v[72:75]
	v_mfma_f32_16x16x32_bf16 v[76:79], v[244:247], v[216:219], v[76:79]
	s_waitcnt lgkmcnt(0)
	s_waitcnt vmcnt(6)
	s_barrier
	ds_read_b128 v[132:135], v156 offset:49152
	ds_read_b128 v[136:139], v156 offset:50176
	v_mfma_f32_16x16x32_bf16 v[48:51], v[184:187], v[248:251], v[48:51]
	ds_read_b128 v[140:143], v156 offset:51200
	ds_read_b128 v[180:183], v156 offset:52224
	v_mfma_f32_16x16x32_bf16 v[52:55], v[184:187], v[200:203], v[52:55]
	ds_read_b128 v[212:215], v129 offset:49152
	ds_read_b128 v[216:219], v129 offset:50176
	s_add_u32 m0, s8, 0x6000
	v_mfma_f32_16x16x32_bf16 v[56:59], v[236:239], v[248:251], v[56:59]
	global_load_lds_dwordx4 v189, s[4:5]
	s_add_u32 m0, s8, 0x7000
	v_mfma_f32_16x16x32_bf16 v[60:63], v[236:239], v[200:203], v[60:63]
	global_load_lds_dwordx4 v252, s[4:5]
	s_add_u32 m0, s8, 0x8000
	v_mfma_f32_16x16x32_bf16 v[32:35], v[240:243], v[248:251], v[32:35]
	global_load_lds_dwordx4 v190, s[4:5]
	v_mfma_f32_16x16x32_bf16 v[36:39], v[240:243], v[200:203], v[36:39]
	v_mfma_f32_16x16x32_bf16 v[40:43], v[244:247], v[248:251], v[40:43]
	v_mfma_f32_16x16x32_bf16 v[44:47], v[244:247], v[200:203], v[44:47]
	ds_read_b128 v[248:251], v129 offset:53248
	ds_read_b128 v[200:203], v129 offset:54272
	v_mfma_f32_16x16x32_bf16 v[16:19], v[184:187], v[204:207], v[16:19]
	s_add_u32 m0, s8, 0x9000
	v_mfma_f32_16x16x32_bf16 v[20:23], v[184:187], v[208:211], v[20:23]
	global_load_lds_dwordx4 v191, s[4:5]
	s_add_u32 m0, s8, 0xa000
	v_mfma_f32_16x16x32_bf16 v[24:27], v[236:239], v[204:207], v[24:27]
	global_load_lds_dwordx4 v189, s[6:7]
	s_add_u32 m0, s8, 0xb000
	v_mfma_f32_16x16x32_bf16 v[28:31], v[236:239], v[208:211], v[28:31]
	global_load_lds_dwordx4 v252, s[6:7]
	s_add_u32 s4, s4, 0x202000
	s_addc_u32 s5, s5, 0
	v_mfma_f32_16x16x32_bf16 v[0:3], v[240:243], v[204:207], v[0:3]
	s_add_u32 s6, s6, 0x40000
	s_addc_u32 s7, s7, 0
	v_mfma_f32_16x16x32_bf16 v[4:7], v[240:243], v[208:211], v[4:7]
	v_mfma_f32_16x16x32_bf16 v[8:11], v[244:247], v[204:207], v[8:11]
	v_mfma_f32_16x16x32_bf16 v[12:15], v[244:247], v[208:211], v[12:15]
	s_waitcnt lgkmcnt(2)
	v_mfma_f32_16x16x32_bf16 v[112:115], v[132:135], v[212:215], v[112:115]
	ds_read_b128 v[204:207], v129 offset:57344
	v_mfma_f32_16x16x32_bf16 v[116:119], v[132:135], v[216:219], v[116:119]
	ds_read_b128 v[208:211], v129 offset:58368
	v_mfma_f32_16x16x32_bf16 v[120:123], v[136:139], v[212:215], v[120:123]
	v_mfma_f32_16x16x32_bf16 v[124:127], v[136:139], v[216:219], v[124:127]
	v_mfma_f32_16x16x32_bf16 v[96:99], v[140:143], v[212:215], v[96:99]
	v_mfma_f32_16x16x32_bf16 v[100:103], v[140:143], v[216:219], v[100:103]
	v_mfma_f32_16x16x32_bf16 v[104:107], v[180:183], v[212:215], v[104:107]
	v_mfma_f32_16x16x32_bf16 v[108:111], v[180:183], v[216:219], v[108:111]
	s_waitcnt lgkmcnt(2)
	v_mfma_f32_16x16x32_bf16 v[80:83], v[132:135], v[248:251], v[80:83]
	ds_read_b128 v[212:215], v129 offset:61440
	v_mfma_f32_16x16x32_bf16 v[84:87], v[132:135], v[200:203], v[84:87]
	ds_read_b128 v[216:219], v129 offset:62464
	v_mfma_f32_16x16x32_bf16 v[88:91], v[136:139], v[248:251], v[88:91]
	v_mfma_f32_16x16x32_bf16 v[92:95], v[136:139], v[200:203], v[92:95]
	v_mfma_f32_16x16x32_bf16 v[64:67], v[140:143], v[248:251], v[64:67]
	v_mfma_f32_16x16x32_bf16 v[68:71], v[140:143], v[200:203], v[68:71]
	v_mfma_f32_16x16x32_bf16 v[72:75], v[180:183], v[248:251], v[72:75]
	v_mfma_f32_16x16x32_bf16 v[76:79], v[180:183], v[200:203], v[76:79]
	s_waitcnt lgkmcnt(0)
	s_waitcnt vmcnt(6)
	s_barrier
	ds_read_b128 v[184:187], v156
	ds_read_b128 v[236:239], v156 offset:1024
	v_mfma_f32_16x16x32_bf16 v[48:51], v[132:135], v[204:207], v[48:51]
	ds_read_b128 v[240:243], v156 offset:2048
	ds_read_b128 v[244:247], v156 offset:3072
	v_mfma_f32_16x16x32_bf16 v[52:55], v[132:135], v[208:211], v[52:55]
	ds_read_b128 v[248:251], v129
	ds_read_b128 v[200:203], v129 offset:1024
	s_add_u32 m0, s8, 0xc000
	v_mfma_f32_16x16x32_bf16 v[56:59], v[136:139], v[204:207], v[56:59]
	global_load_lds_dwordx4 v189, s[4:5]
	s_add_u32 m0, s8, 0xd000
	v_mfma_f32_16x16x32_bf16 v[60:63], v[136:139], v[208:211], v[60:63]
	global_load_lds_dwordx4 v252, s[4:5]
	s_add_u32 m0, s8, 0xe000
	v_mfma_f32_16x16x32_bf16 v[32:35], v[140:143], v[204:207], v[32:35]
	global_load_lds_dwordx4 v190, s[4:5]
	v_mfma_f32_16x16x32_bf16 v[36:39], v[140:143], v[208:211], v[36:39]
	v_mfma_f32_16x16x32_bf16 v[40:43], v[180:183], v[204:207], v[40:43]
	v_mfma_f32_16x16x32_bf16 v[44:47], v[180:183], v[208:211], v[44:47]
	ds_read_b128 v[204:207], v129 offset:4096
	ds_read_b128 v[208:211], v129 offset:5120
	v_mfma_f32_16x16x32_bf16 v[16:19], v[132:135], v[212:215], v[16:19]
	s_add_u32 m0, s8, 0xf000
	v_mfma_f32_16x16x32_bf16 v[20:23], v[132:135], v[216:219], v[20:23]
	global_load_lds_dwordx4 v191, s[4:5]
	s_add_u32 m0, s8, 0x10000
	v_mfma_f32_16x16x32_bf16 v[24:27], v[136:139], v[212:215], v[24:27]
	global_load_lds_dwordx4 v189, s[6:7]
	s_add_u32 m0, s8, 0x11000
	v_mfma_f32_16x16x32_bf16 v[28:31], v[136:139], v[216:219], v[28:31]
	global_load_lds_dwordx4 v252, s[6:7]
	s_add_u32 s4, s4, 0x202000
	s_addc_u32 s5, s5, 0
	v_mfma_f32_16x16x32_bf16 v[0:3], v[140:143], v[212:215], v[0:3]
	s_add_u32 s6, s6, 0x40000
	s_addc_u32 s7, s7, 0
	v_mfma_f32_16x16x32_bf16 v[4:7], v[140:143], v[216:219], v[4:7]
	v_mfma_f32_16x16x32_bf16 v[8:11], v[180:183], v[212:215], v[8:11]
	v_mfma_f32_16x16x32_bf16 v[12:15], v[180:183], v[216:219], v[12:15]
	s_waitcnt lgkmcnt(2)
	v_mfma_f32_16x16x32_bf16 v[112:115], v[184:187], v[248:251], v[112:115]
	ds_read_b128 v[212:215], v129 offset:8192
	v_mfma_f32_16x16x32_bf16 v[116:119], v[184:187], v[200:203], v[116:119]
	ds_read_b128 v[216:219], v129 offset:9216
	v_mfma_f32_16x16x32_bf16 v[120:123], v[236:239], v[248:251], v[120:123]
	v_mfma_f32_16x16x32_bf16 v[124:127], v[236:239], v[200:203], v[124:127]
	v_mfma_f32_16x16x32_bf16 v[96:99], v[240:243], v[248:251], v[96:99]
	v_mfma_f32_16x16x32_bf16 v[100:103], v[240:243], v[200:203], v[100:103]
	v_mfma_f32_16x16x32_bf16 v[104:107], v[244:247], v[248:251], v[104:107]
	v_mfma_f32_16x16x32_bf16 v[108:111], v[244:247], v[200:203], v[108:111]
	s_waitcnt lgkmcnt(2)
	v_mfma_f32_16x16x32_bf16 v[80:83], v[184:187], v[204:207], v[80:83]
	ds_read_b128 v[248:251], v129 offset:12288
	v_mfma_f32_16x16x32_bf16 v[84:87], v[184:187], v[208:211], v[84:87]
	ds_read_b128 v[200:203], v129 offset:13312
	v_mfma_f32_16x16x32_bf16 v[88:91], v[236:239], v[204:207], v[88:91]
	v_mfma_f32_16x16x32_bf16 v[92:95], v[236:239], v[208:211], v[92:95]
	v_mfma_f32_16x16x32_bf16 v[64:67], v[240:243], v[204:207], v[64:67]
	v_mfma_f32_16x16x32_bf16 v[68:71], v[240:243], v[208:211], v[68:71]
	v_mfma_f32_16x16x32_bf16 v[72:75], v[244:247], v[204:207], v[72:75]
	v_mfma_f32_16x16x32_bf16 v[76:79], v[244:247], v[208:211], v[76:79]
	s_waitcnt lgkmcnt(0)
	s_waitcnt vmcnt(6)
	s_barrier
	ds_read_b128 v[132:135], v156 offset:24576
	ds_read_b128 v[136:139], v156 offset:25600
	v_mfma_f32_16x16x32_bf16 v[48:51], v[184:187], v[212:215], v[48:51]
	ds_read_b128 v[140:143], v156 offset:26624
	ds_read_b128 v[180:183], v156 offset:27648
	v_mfma_f32_16x16x32_bf16 v[52:55], v[184:187], v[216:219], v[52:55]
	ds_read_b128 v[204:207], v129 offset:24576
	ds_read_b128 v[208:211], v129 offset:25600
	s_add_u32 m0, s8, 0x0
	v_mfma_f32_16x16x32_bf16 v[56:59], v[236:239], v[212:215], v[56:59]
	global_load_lds_dwordx4 v189, s[4:5]
	s_add_u32 m0, s8, 0x1000
	v_mfma_f32_16x16x32_bf16 v[60:63], v[236:239], v[216:219], v[60:63]
	global_load_lds_dwordx4 v252, s[4:5]
	s_add_u32 m0, s8, 0x2000
	v_mfma_f32_16x16x32_bf16 v[32:35], v[240:243], v[212:215], v[32:35]
	global_load_lds_dwordx4 v190, s[4:5]
	v_mfma_f32_16x16x32_bf16 v[36:39], v[240:243], v[216:219], v[36:39]
	v_mfma_f32_16x16x32_bf16 v[40:43], v[244:247], v[212:215], v[40:43]
	v_mfma_f32_16x16x32_bf16 v[44:47], v[244:247], v[216:219], v[44:47]
	ds_read_b128 v[212:215], v129 offset:28672
	ds_read_b128 v[216:219], v129 offset:29696
	v_mfma_f32_16x16x32_bf16 v[16:19], v[184:187], v[248:251], v[16:19]
	s_add_u32 m0, s8, 0x3000
	v_mfma_f32_16x16x32_bf16 v[20:23], v[184:187], v[200:203], v[20:23]
	global_load_lds_dwordx4 v191, s[4:5]
	s_add_u32 m0, s8, 0x4000
	v_mfma_f32_16x16x32_bf16 v[24:27], v[236:239], v[248:251], v[24:27]
	global_load_lds_dwordx4 v189, s[6:7]
	s_add_u32 m0, s8, 0x5000
	v_mfma_f32_16x16x32_bf16 v[28:31], v[236:239], v[200:203], v[28:31]
	global_load_lds_dwordx4 v252, s[6:7]
	s_add_u32 s4, s4, 0x202000
	s_addc_u32 s5, s5, 0
	v_mfma_f32_16x16x32_bf16 v[0:3], v[240:243], v[248:251], v[0:3]
	s_add_u32 s6, s6, 0x40000
	s_addc_u32 s7, s7, 0
	v_mfma_f32_16x16x32_bf16 v[4:7], v[240:243], v[200:203], v[4:7]
	v_mfma_f32_16x16x32_bf16 v[8:11], v[244:247], v[248:251], v[8:11]
	v_mfma_f32_16x16x32_bf16 v[12:15], v[244:247], v[200:203], v[12:15]
	s_waitcnt lgkmcnt(2)
	v_mfma_f32_16x16x32_bf16 v[112:115], v[132:135], v[204:207], v[112:115]
	ds_read_b128 v[248:251], v129 offset:32768
	v_mfma_f32_16x16x32_bf16 v[116:119], v[132:135], v[208:211], v[116:119]
	ds_read_b128 v[200:203], v129 offset:33792
	v_mfma_f32_16x16x32_bf16 v[120:123], v[136:139], v[204:207], v[120:123]
	v_mfma_f32_16x16x32_bf16 v[124:127], v[136:139], v[208:211], v[124:127]
	v_mfma_f32_16x16x32_bf16 v[96:99], v[140:143], v[204:207], v[96:99]
	v_mfma_f32_16x16x32_bf16 v[100:103], v[140:143], v[208:211], v[100:103]
	v_mfma_f32_16x16x32_bf16 v[104:107], v[180:183], v[204:207], v[104:107]
	v_mfma_f32_16x16x32_bf16 v[108:111], v[180:183], v[208:211], v[108:111]
	s_waitcnt lgkmcnt(2)
	v_mfma_f32_16x16x32_bf16 v[80:83], v[132:135], v[212:215], v[80:83]
	ds_read_b128 v[204:207], v129 offset:36864
	v_mfma_f32_16x16x32_bf16 v[84:87], v[132:135], v[216:219], v[84:87]
	ds_read_b128 v[208:211], v129 offset:37888
	v_mfma_f32_16x16x32_bf16 v[88:91], v[136:139], v[212:215], v[88:91]
	v_mfma_f32_16x16x32_bf16 v[92:95], v[136:139], v[216:219], v[92:95]
	v_mfma_f32_16x16x32_bf16 v[64:67], v[140:143], v[212:215], v[64:67]
	v_mfma_f32_16x16x32_bf16 v[68:71], v[140:143], v[216:219], v[68:71]
	v_mfma_f32_16x16x32_bf16 v[72:75], v[180:183], v[212:215], v[72:75]
	v_mfma_f32_16x16x32_bf16 v[76:79], v[180:183], v[216:219], v[76:79]
	s_waitcnt lgkmcnt(0)
	s_waitcnt vmcnt(6)
	s_barrier
	ds_read_b128 v[184:187], v156 offset:49152
	ds_read_b128 v[236:239], v156 offset:50176
	v_mfma_f32_16x16x32_bf16 v[48:51], v[132:135], v[248:251], v[48:51]
	ds_read_b128 v[240:243], v156 offset:51200
	ds_read_b128 v[244:247], v156 offset:52224
	v_mfma_f32_16x16x32_bf16 v[52:55], v[132:135], v[200:203], v[52:55]
	ds_read_b128 v[212:215], v129 offset:49152
	ds_read_b128 v[216:219], v129 offset:50176
	s_add_u32 m0, s8, 0x6000
	v_mfma_f32_16x16x32_bf16 v[56:59], v[136:139], v[248:251], v[56:59]
	global_load_lds_dwordx4 v189, s[4:5]
	s_add_u32 m0, s8, 0x7000
	v_mfma_f32_16x16x32_bf16 v[60:63], v[136:139], v[200:203], v[60:63]
	global_load_lds_dwordx4 v252, s[4:5]
	s_add_u32 m0, s8, 0x8000
	v_mfma_f32_16x16x32_bf16 v[32:35], v[140:143], v[248:251], v[32:35]
	global_load_lds_dwordx4 v190, s[4:5]
	v_mfma_f32_16x16x32_bf16 v[36:39], v[140:143], v[200:203], v[36:39]
	v_mfma_f32_16x16x32_bf16 v[40:43], v[180:183], v[248:251], v[40:43]
	v_mfma_f32_16x16x32_bf16 v[44:47], v[180:183], v[200:203], v[44:47]
	ds_read_b128 v[248:251], v129 offset:53248
	ds_read_b128 v[200:203], v129 offset:54272
	v_mfma_f32_16x16x32_bf16 v[16:19], v[132:135], v[204:207], v[16:19]
	s_add_u32 m0, s8, 0x9000
	v_mfma_f32_16x16x32_bf16 v[20:23], v[132:135], v[208:211], v[20:23]
	global_load_lds_dwordx4 v191, s[4:5]
	s_add_u32 m0, s8, 0xa000
	v_mfma_f32_16x16x32_bf16 v[24:27], v[136:139], v[204:207], v[24:27]
	global_load_lds_dwordx4 v189, s[6:7]
	s_add_u32 m0, s8, 0xb000
	v_mfma_f32_16x16x32_bf16 v[28:31], v[136:139], v[208:211], v[28:31]
	global_load_lds_dwordx4 v252, s[6:7]
	s_add_u32 s4, s4, 0x202000
	s_addc_u32 s5, s5, 0
	v_mfma_f32_16x16x32_bf16 v[0:3], v[140:143], v[204:207], v[0:3]
	s_add_u32 s6, s6, 0x40000
	s_addc_u32 s7, s7, 0
	v_mfma_f32_16x16x32_bf16 v[4:7], v[140:143], v[208:211], v[4:7]
	v_mfma_f32_16x16x32_bf16 v[8:11], v[180:183], v[204:207], v[8:11]
	v_mfma_f32_16x16x32_bf16 v[12:15], v[180:183], v[208:211], v[12:15]
	s_waitcnt lgkmcnt(2)
	v_mfma_f32_16x16x32_bf16 v[112:115], v[184:187], v[212:215], v[112:115]
	ds_read_b128 v[204:207], v129 offset:57344
	v_mfma_f32_16x16x32_bf16 v[116:119], v[184:187], v[216:219], v[116:119]
	ds_read_b128 v[208:211], v129 offset:58368
	v_mfma_f32_16x16x32_bf16 v[120:123], v[236:239], v[212:215], v[120:123]
	v_mfma_f32_16x16x32_bf16 v[124:127], v[236:239], v[216:219], v[124:127]
	v_mfma_f32_16x16x32_bf16 v[96:99], v[240:243], v[212:215], v[96:99]
	v_mfma_f32_16x16x32_bf16 v[100:103], v[240:243], v[216:219], v[100:103]
	v_mfma_f32_16x16x32_bf16 v[104:107], v[244:247], v[212:215], v[104:107]
	v_mfma_f32_16x16x32_bf16 v[108:111], v[244:247], v[216:219], v[108:111]
	s_waitcnt lgkmcnt(2)
	v_mfma_f32_16x16x32_bf16 v[80:83], v[184:187], v[248:251], v[80:83]
	ds_read_b128 v[212:215], v129 offset:61440
	v_mfma_f32_16x16x32_bf16 v[84:87], v[184:187], v[200:203], v[84:87]
	ds_read_b128 v[216:219], v129 offset:62464
	v_mfma_f32_16x16x32_bf16 v[88:91], v[236:239], v[248:251], v[88:91]
	v_mfma_f32_16x16x32_bf16 v[92:95], v[236:239], v[200:203], v[92:95]
	v_mfma_f32_16x16x32_bf16 v[64:67], v[240:243], v[248:251], v[64:67]
	v_mfma_f32_16x16x32_bf16 v[68:71], v[240:243], v[200:203], v[68:71]
	v_mfma_f32_16x16x32_bf16 v[72:75], v[244:247], v[248:251], v[72:75]
	v_mfma_f32_16x16x32_bf16 v[76:79], v[244:247], v[200:203], v[76:79]
	s_waitcnt lgkmcnt(0)
	s_waitcnt vmcnt(6)
	s_barrier
	ds_read_b128 v[132:135], v156
	ds_read_b128 v[136:139], v156 offset:1024
	v_mfma_f32_16x16x32_bf16 v[48:51], v[184:187], v[204:207], v[48:51]
	ds_read_b128 v[140:143], v156 offset:2048
	ds_read_b128 v[180:183], v156 offset:3072
	v_mfma_f32_16x16x32_bf16 v[52:55], v[184:187], v[208:211], v[52:55]
	ds_read_b128 v[248:251], v129
	ds_read_b128 v[200:203], v129 offset:1024
	v_mfma_f32_16x16x32_bf16 v[56:59], v[236:239], v[204:207], v[56:59]
	v_mfma_f32_16x16x32_bf16 v[60:63], v[236:239], v[208:211], v[60:63]
	v_mfma_f32_16x16x32_bf16 v[32:35], v[240:243], v[204:207], v[32:35]
	v_mfma_f32_16x16x32_bf16 v[36:39], v[240:243], v[208:211], v[36:39]
	v_mfma_f32_16x16x32_bf16 v[40:43], v[244:247], v[204:207], v[40:43]
	v_mfma_f32_16x16x32_bf16 v[44:47], v[244:247], v[208:211], v[44:47]
	ds_read_b128 v[204:207], v129 offset:4096
	ds_read_b128 v[208:211], v129 offset:5120
	v_mfma_f32_16x16x32_bf16 v[16:19], v[184:187], v[212:215], v[16:19]
	v_mfma_f32_16x16x32_bf16 v[20:23], v[184:187], v[216:219], v[20:23]
	v_mfma_f32_16x16x32_bf16 v[24:27], v[236:239], v[212:215], v[24:27]
	v_mfma_f32_16x16x32_bf16 v[28:31], v[236:239], v[216:219], v[28:31]
	v_mfma_f32_16x16x32_bf16 v[0:3], v[240:243], v[212:215], v[0:3]
	v_mfma_f32_16x16x32_bf16 v[4:7], v[240:243], v[216:219], v[4:7]
	v_mfma_f32_16x16x32_bf16 v[8:11], v[244:247], v[212:215], v[8:11]
	v_mfma_f32_16x16x32_bf16 v[12:15], v[244:247], v[216:219], v[12:15]
	s_waitcnt lgkmcnt(2)
	v_mfma_f32_16x16x32_bf16 v[112:115], v[132:135], v[248:251], v[112:115]
	ds_read_b128 v[212:215], v129 offset:8192
	v_mfma_f32_16x16x32_bf16 v[116:119], v[132:135], v[200:203], v[116:119]
	ds_read_b128 v[216:219], v129 offset:9216
	v_mfma_f32_16x16x32_bf16 v[120:123], v[136:139], v[248:251], v[120:123]
	v_mfma_f32_16x16x32_bf16 v[124:127], v[136:139], v[200:203], v[124:127]
	v_mfma_f32_16x16x32_bf16 v[96:99], v[140:143], v[248:251], v[96:99]
	v_mfma_f32_16x16x32_bf16 v[100:103], v[140:143], v[200:203], v[100:103]
	v_mfma_f32_16x16x32_bf16 v[104:107], v[180:183], v[248:251], v[104:107]
	v_mfma_f32_16x16x32_bf16 v[108:111], v[180:183], v[200:203], v[108:111]
	s_waitcnt lgkmcnt(2)
	v_mfma_f32_16x16x32_bf16 v[80:83], v[132:135], v[204:207], v[80:83]
	ds_read_b128 v[248:251], v129 offset:12288
	v_mfma_f32_16x16x32_bf16 v[84:87], v[132:135], v[208:211], v[84:87]
	ds_read_b128 v[200:203], v129 offset:13312
	v_mfma_f32_16x16x32_bf16 v[88:91], v[136:139], v[204:207], v[88:91]
	v_mfma_f32_16x16x32_bf16 v[92:95], v[136:139], v[208:211], v[92:95]
	v_mfma_f32_16x16x32_bf16 v[64:67], v[140:143], v[204:207], v[64:67]
	v_mfma_f32_16x16x32_bf16 v[68:71], v[140:143], v[208:211], v[68:71]
	v_mfma_f32_16x16x32_bf16 v[72:75], v[180:183], v[204:207], v[72:75]
	v_mfma_f32_16x16x32_bf16 v[76:79], v[180:183], v[208:211], v[76:79]
	s_waitcnt lgkmcnt(0)
	s_waitcnt vmcnt(0)
	s_barrier
	ds_read_b128 v[184:187], v156 offset:24576
	ds_read_b128 v[236:239], v156 offset:25600
	v_mfma_f32_16x16x32_bf16 v[48:51], v[132:135], v[212:215], v[48:51]
	ds_read_b128 v[240:243], v156 offset:26624
	ds_read_b128 v[244:247], v156 offset:27648
	v_mfma_f32_16x16x32_bf16 v[52:55], v[132:135], v[216:219], v[52:55]
	ds_read_b128 v[204:207], v129 offset:24576
	ds_read_b128 v[208:211], v129 offset:25600
	v_mfma_f32_16x16x32_bf16 v[56:59], v[136:139], v[212:215], v[56:59]
	v_mfma_f32_16x16x32_bf16 v[60:63], v[136:139], v[216:219], v[60:63]
	v_mfma_f32_16x16x32_bf16 v[32:35], v[140:143], v[212:215], v[32:35]
	v_mfma_f32_16x16x32_bf16 v[36:39], v[140:143], v[216:219], v[36:39]
	v_mfma_f32_16x16x32_bf16 v[40:43], v[180:183], v[212:215], v[40:43]
	v_mfma_f32_16x16x32_bf16 v[44:47], v[180:183], v[216:219], v[44:47]
	ds_read_b128 v[212:215], v129 offset:28672
	ds_read_b128 v[216:219], v129 offset:29696
	v_mfma_f32_16x16x32_bf16 v[16:19], v[132:135], v[248:251], v[16:19]
	v_mfma_f32_16x16x32_bf16 v[20:23], v[132:135], v[200:203], v[20:23]
	v_mfma_f32_16x16x32_bf16 v[24:27], v[136:139], v[248:251], v[24:27]
	v_mfma_f32_16x16x32_bf16 v[28:31], v[136:139], v[200:203], v[28:31]
	v_mfma_f32_16x16x32_bf16 v[0:3], v[140:143], v[248:251], v[0:3]
	v_mfma_f32_16x16x32_bf16 v[4:7], v[140:143], v[200:203], v[4:7]
	v_mfma_f32_16x16x32_bf16 v[8:11], v[180:183], v[248:251], v[8:11]
	v_mfma_f32_16x16x32_bf16 v[12:15], v[180:183], v[200:203], v[12:15]
	s_waitcnt lgkmcnt(2)
	v_mfma_f32_16x16x32_bf16 v[112:115], v[184:187], v[204:207], v[112:115]
	ds_read_b128 v[248:251], v129 offset:32768
	v_mfma_f32_16x16x32_bf16 v[116:119], v[184:187], v[208:211], v[116:119]
	ds_read_b128 v[200:203], v129 offset:33792
	v_mfma_f32_16x16x32_bf16 v[120:123], v[236:239], v[204:207], v[120:123]
	v_mfma_f32_16x16x32_bf16 v[124:127], v[236:239], v[208:211], v[124:127]
	v_mfma_f32_16x16x32_bf16 v[96:99], v[240:243], v[204:207], v[96:99]
	v_mfma_f32_16x16x32_bf16 v[100:103], v[240:243], v[208:211], v[100:103]
	v_mfma_f32_16x16x32_bf16 v[104:107], v[244:247], v[204:207], v[104:107]
	v_mfma_f32_16x16x32_bf16 v[108:111], v[244:247], v[208:211], v[108:111]
	s_waitcnt lgkmcnt(2)
	v_mfma_f32_16x16x32_bf16 v[80:83], v[184:187], v[212:215], v[80:83]
	ds_read_b128 v[204:207], v129 offset:36864
	v_mfma_f32_16x16x32_bf16 v[84:87], v[184:187], v[216:219], v[84:87]
	ds_read_b128 v[208:211], v129 offset:37888
	v_mfma_f32_16x16x32_bf16 v[88:91], v[236:239], v[212:215], v[88:91]
	v_mfma_f32_16x16x32_bf16 v[92:95], v[236:239], v[216:219], v[92:95]
	v_mfma_f32_16x16x32_bf16 v[64:67], v[240:243], v[212:215], v[64:67]
	v_mfma_f32_16x16x32_bf16 v[68:71], v[240:243], v[216:219], v[68:71]
	v_mfma_f32_16x16x32_bf16 v[72:75], v[244:247], v[212:215], v[72:75]
	v_mfma_f32_16x16x32_bf16 v[76:79], v[244:247], v[216:219], v[76:79]
	s_waitcnt lgkmcnt(0)
	v_mfma_f32_16x16x32_bf16 v[48:51], v[184:187], v[248:251], v[48:51]
	v_mfma_f32_16x16x32_bf16 v[52:55], v[184:187], v[200:203], v[52:55]
	v_mfma_f32_16x16x32_bf16 v[56:59], v[236:239], v[248:251], v[56:59]
	v_mfma_f32_16x16x32_bf16 v[60:63], v[236:239], v[200:203], v[60:63]
	v_mfma_f32_16x16x32_bf16 v[32:35], v[240:243], v[248:251], v[32:35]
	v_mfma_f32_16x16x32_bf16 v[36:39], v[240:243], v[200:203], v[36:39]
	v_mfma_f32_16x16x32_bf16 v[40:43], v[244:247], v[248:251], v[40:43]
	v_mfma_f32_16x16x32_bf16 v[44:47], v[244:247], v[200:203], v[44:47]
	v_mfma_f32_16x16x32_bf16 v[16:19], v[184:187], v[204:207], v[16:19]
	v_mfma_f32_16x16x32_bf16 v[20:23], v[184:187], v[208:211], v[20:23]
	v_mfma_f32_16x16x32_bf16 v[24:27], v[236:239], v[204:207], v[24:27]
	v_mfma_f32_16x16x32_bf16 v[28:31], v[236:239], v[208:211], v[28:31]
	v_mfma_f32_16x16x32_bf16 v[0:3], v[240:243], v[204:207], v[0:3]
	v_mfma_f32_16x16x32_bf16 v[4:7], v[240:243], v[208:211], v[4:7]
	v_mfma_f32_16x16x32_bf16 v[8:11], v[244:247], v[204:207], v[8:11]
	v_mfma_f32_16x16x32_bf16 v[12:15], v[244:247], v[208:211], v[12:15]
	s_nop 15
	s_nop 15
	v_permlane16_swap_b32_e32 v112, v116
	v_permlane16_swap_b32_e32 v113, v117
	v_permlane16_swap_b32_e32 v114, v118
	v_permlane16_swap_b32_e32 v115, v119
	v_permlane16_swap_b32_e32 v120, v124
	v_permlane16_swap_b32_e32 v121, v125
	v_permlane16_swap_b32_e32 v122, v126
	v_permlane16_swap_b32_e32 v123, v127
	v_permlane16_swap_b32_e32 v80, v84
	v_permlane16_swap_b32_e32 v81, v85
	v_permlane16_swap_b32_e32 v82, v86
	v_permlane16_swap_b32_e32 v83, v87
	v_permlane16_swap_b32_e32 v88, v92
	v_permlane16_swap_b32_e32 v89, v93
	v_permlane16_swap_b32_e32 v90, v94
	v_permlane16_swap_b32_e32 v91, v95
	v_permlane16_swap_b32_e32 v48, v52
	v_permlane16_swap_b32_e32 v49, v53
	v_permlane16_swap_b32_e32 v50, v54
	v_permlane16_swap_b32_e32 v51, v55
	v_permlane16_swap_b32_e32 v56, v60
	v_permlane16_swap_b32_e32 v57, v61
	v_permlane16_swap_b32_e32 v58, v62
	v_permlane16_swap_b32_e32 v59, v63
	v_permlane16_swap_b32_e32 v16, v20
	v_permlane16_swap_b32_e32 v17, v21
	v_permlane16_swap_b32_e32 v18, v22
	v_permlane16_swap_b32_e32 v19, v23
	v_permlane16_swap_b32_e32 v24, v28
	v_permlane16_swap_b32_e32 v25, v29
	v_permlane16_swap_b32_e32 v26, v30
	v_permlane16_swap_b32_e32 v27, v31
	v_permlane16_swap_b32_e32 v96, v100
	v_permlane16_swap_b32_e32 v97, v101
	v_permlane16_swap_b32_e32 v98, v102
	v_permlane16_swap_b32_e32 v99, v103
	v_permlane16_swap_b32_e32 v104, v108
	v_permlane16_swap_b32_e32 v105, v109
	v_permlane16_swap_b32_e32 v106, v110
	v_permlane16_swap_b32_e32 v107, v111
	v_permlane16_swap_b32_e32 v64, v68
	v_permlane16_swap_b32_e32 v65, v69
	v_permlane16_swap_b32_e32 v66, v70
	v_permlane16_swap_b32_e32 v67, v71
	v_permlane16_swap_b32_e32 v72, v76
	v_permlane16_swap_b32_e32 v73, v77
	v_permlane16_swap_b32_e32 v74, v78
	v_permlane16_swap_b32_e32 v75, v79
	v_permlane16_swap_b32_e32 v32, v36
	v_permlane16_swap_b32_e32 v33, v37
	v_permlane16_swap_b32_e32 v34, v38
	v_permlane16_swap_b32_e32 v35, v39
	v_permlane16_swap_b32_e32 v40, v44
	v_permlane16_swap_b32_e32 v41, v45
	v_permlane16_swap_b32_e32 v42, v46
	v_permlane16_swap_b32_e32 v43, v47
	v_permlane16_swap_b32_e32 v0, v4
	v_permlane16_swap_b32_e32 v1, v5
	v_permlane16_swap_b32_e32 v2, v6
	v_permlane16_swap_b32_e32 v3, v7
	v_permlane16_swap_b32_e32 v8, v12
	v_permlane16_swap_b32_e32 v9, v13
	v_permlane16_swap_b32_e32 v10, v14
	v_permlane16_swap_b32_e32 v11, v15
	s_nop 1
	v_or_b32_e32 v190, 8, v150
	v_or_b32_e32 v191, 9, v150
	v_or_b32_e32 v192, 10, v150
	v_or_b32_e32 v193, 11, v150
	v_or_b32_e32 v194, 16, v150
	v_or_b32_e32 v195, 17, v150
	v_or_b32_e32 v200, 18, v150
	v_or_b32_e32 v201, 19, v150
	v_or_b32_e32 v202, 24, v150
	v_or_b32_e32 v203, 25, v150
	v_or_b32_e32 v204, 26, v150
	v_or_b32_e32 v205, 27, v150
	v_or_b32_e32 v206, 32, v150
	v_or_b32_e32 v207, 33, v150
	v_or_b32_e32 v208, 34, v150
	v_or_b32_e32 v209, 35, v150
	v_or_b32_e32 v210, 40, v150
	v_or_b32_e32 v211, 41, v150
	v_or_b32_e32 v212, 42, v150
	v_or_b32_e32 v213, 43, v150
	v_or_b32_e32 v214, 48, v150
	v_or_b32_e32 v215, 49, v150
	v_or_b32_e32 v216, 50, v150
	v_or_b32_e32 v217, 51, v150
	v_or_b32_e32 v218, 56, v150
	v_or_b32_e32 v219, 57, v150
	v_or_b32_e32 v220, 58, v150
	v_or_b32_e32 v221, 59, v150

.LBB0_887:
	s_or_saveexec_b64 s[0:1], s[0:1]
	v_mov_b32_e32 v127, 0
	v_mov_b32_e32 v126, 0
	v_mov_b32_e32 v125, 0
	v_mov_b32_e32 v124, 0
	v_mov_b32_e32 v123, 0
	v_mov_b32_e32 v122, 0
	v_mov_b32_e32 v121, 0
	v_mov_b32_e32 v120, 0
	v_mov_b32_e32 v119, 0
	v_mov_b32_e32 v118, 0
	v_mov_b32_e32 v117, 0
	v_mov_b32_e32 v116, 0
	v_mov_b32_e32 v115, 0
	v_mov_b32_e32 v114, 0
	v_mov_b32_e32 v113, 0
	v_mov_b32_e32 v112, 0
	v_mov_b32_e32 v63, 0
	v_mov_b32_e32 v62, 0
	v_mov_b32_e32 v61, 0
	v_mov_b32_e32 v60, 0
	v_mov_b32_e32 v59, 0
	v_mov_b32_e32 v58, 0
	v_mov_b32_e32 v57, 0
	v_mov_b32_e32 v56, 0
	v_mov_b32_e32 v55, 0
	v_mov_b32_e32 v54, 0
	v_mov_b32_e32 v53, 0
	v_mov_b32_e32 v52, 0
	v_mov_b32_e32 v51, 0
	v_mov_b32_e32 v50, 0
	v_mov_b32_e32 v49, 0
	v_mov_b32_e32 v48, 0
	v_mov_b32_e32 v111, 0
	v_mov_b32_e32 v110, 0
	v_mov_b32_e32 v109, 0
	v_mov_b32_e32 v108, 0
	v_mov_b32_e32 v107, 0
	v_mov_b32_e32 v106, 0
	v_mov_b32_e32 v105, 0
	v_mov_b32_e32 v104, 0
	v_mov_b32_e32 v103, 0
	v_mov_b32_e32 v102, 0
	v_mov_b32_e32 v101, 0
	v_mov_b32_e32 v100, 0
	v_mov_b32_e32 v99, 0
	v_mov_b32_e32 v98, 0
	v_mov_b32_e32 v97, 0
	v_mov_b32_e32 v96, 0
	v_mov_b32_e32 v47, 0
	v_mov_b32_e32 v46, 0
	v_mov_b32_e32 v45, 0
	v_mov_b32_e32 v44, 0
	v_mov_b32_e32 v43, 0
	v_mov_b32_e32 v42, 0
	v_mov_b32_e32 v41, 0
	v_mov_b32_e32 v40, 0
	v_mov_b32_e32 v39, 0
	v_mov_b32_e32 v38, 0
	v_mov_b32_e32 v37, 0
	v_mov_b32_e32 v36, 0
	v_mov_b32_e32 v35, 0
	v_mov_b32_e32 v34, 0
	v_mov_b32_e32 v33, 0
	v_mov_b32_e32 v32, 0
	s_xor_b64 exec, exec, s[0:1]
	s_cbranch_execz .LBB0_891
	v_readfirstlane_b32 s78, v148
	v_readfirstlane_b32 s79, v150
	v_readfirstlane_b32 s76, v178
	v_mbcnt_lo_u32_b32 v164, -1, 0
	v_mbcnt_hi_u32_b32 v164, -1, v164
	s_nop 3
	s_lshl_b32 s78, s78, 14
	s_lshl_b32 s79, s79, 13
	s_add_u32 s72, s90, s78
	s_addc_u32 s73, s91, 0
	s_add_u32 s74, s90, s79
	s_addc_u32 s75, s91, 0
	s_add_u32 s74, s74, 0x1bbc8000
	s_addc_u32 s75, s75, 0
	v_lshrrev_b32_e32 v165, 2, v164
	v_lshrrev_b32_e32 v166, 4, v164
	v_xor_b32_e32 v166, v166, v164
	v_and_b32_e32 v166, 3, v166
	v_lshlrev_b32_e32 v166, 4, v166
	v_lshl_or_b32 v165, v165, 6, v166
	v_or_b32_e32 v160, v165, v178
	v_add_u32_e32 v161, 0x1000, v160
	v_add_u32_e32 v162, 0x2000, v160
	v_add_u32_e32 v163, 0x3000, v160
	v_and_b32_e32 v165, 15, v164
	v_lshrrev_b32_e32 v166, 4, v164
	v_bfe_u32 v167, v164, 2, 2
	v_xor_b32_e32 v167, v167, v166
	v_lshlrev_b32_e32 v167, 4, v167
	v_lshl_or_b32 v156, v165, 6, v167
	v_lshrrev_b32_e32 v167, 10, v178
	v_lshrrev_b32_e32 v167, 1, v167
	v_lshl_or_b32 v156, v167, 11, v156
	v_and_b32_e32 v167, 3, v164
	v_bfe_u32 v165, v164, 2, 1
	v_lshl_or_b32 v167, v165, 3, v167
	v_bfe_u32 v165, v164, 3, 1
	v_lshl_or_b32 v167, v165, 2, v167
	v_lshrrev_b32_e32 v165, 2, v167
	v_xor_b32_e32 v165, v165, v166
	v_lshlrev_b32_e32 v165, 4, v165
	v_lshl_or_b32 v158, v167, 6, v165
	v_lshrrev_b32_e32 v167, 10, v178
	v_and_b32_e32 v167, 1, v167
	v_lshl_or_b32 v158, v167, 12, v158
	v_or_b32_e32 v158, 0x4000, v158
	s_add_u32 m0, s76, 0x2000
	s_nop 0
	global_load_lds_dwordx4 v162, s[72:73]
	s_add_u32 m0, s76, 0x3000
	s_nop 0
	global_load_lds_dwordx4 v163, s[72:73]
	s_add_u32 m0, s76, 0x4000
	s_nop 0
	global_load_lds_dwordx4 v160, s[74:75]
	s_add_u32 m0, s76, 0x5000
	s_nop 0
	global_load_lds_dwordx4 v161, s[74:75]
	s_add_u32 s72, s72, 0x202000
	s_addc_u32 s73, s73, 0
	s_add_u32 s74, s74, 0x10000
	s_addc_u32 s75, s75, 0
	s_add_u32 m0, s76, 0x6000
	s_nop 0
	global_load_lds_dwordx4 v160, s[72:73]
	s_add_u32 m0, s76, 0x7000
	s_nop 0
	global_load_lds_dwordx4 v161, s[72:73]
	s_add_u32 m0, s76, 0x8000
	s_nop 0
	global_load_lds_dwordx4 v162, s[72:73]
	s_add_u32 m0, s76, 0x9000
	s_nop 0
	global_load_lds_dwordx4 v163, s[72:73]
	s_add_u32 m0, s76, 0xa000
	s_nop 0
	global_load_lds_dwordx4 v160, s[74:75]
	s_add_u32 m0, s76, 0xb000
	s_nop 0
	global_load_lds_dwordx4 v161, s[74:75]
	s_add_u32 s72, s72, 0x202000
	s_addc_u32 s73, s73, 0
	s_add_u32 s74, s74, 0x10000
	s_addc_u32 s75, s75, 0
	s_add_u32 m0, s76, 0xc000
	s_nop 0
	global_load_lds_dwordx4 v160, s[72:73]
	s_add_u32 m0, s76, 0xd000
	s_nop 0
	global_load_lds_dwordx4 v161, s[72:73]
	s_add_u32 m0, s76, 0xe000
	s_nop 0
	global_load_lds_dwordx4 v162, s[72:73]
	s_add_u32 m0, s76, 0xf000
	s_nop 0
	global_load_lds_dwordx4 v163, s[72:73]
	s_add_u32 m0, s76, 0x10000
	s_nop 0
	global_load_lds_dwordx4 v160, s[74:75]
	s_add_u32 m0, s76, 0x11000
	s_nop 0
	global_load_lds_dwordx4 v161, s[74:75]
	s_add_u32 s72, s72, 0x202000
	s_addc_u32 s73, s73, 0
	s_add_u32 s74, s74, 0x10000
	s_addc_u32 s75, s75, 0
	s_waitcnt vmcnt(12)
	s_barrier
	ds_read_b128 v[200:203], v158
	ds_read_b128 v[204:207], v158 offset:1024
	ds_read_b128 v[208:211], v158 offset:2048
	ds_read_b128 v[212:215], v158 offset:3072
	ds_read_b128 v[232:235], v156
	ds_read_b128 v[236:239], v156 offset:1024
	ds_read_b128 v[240:243], v156 offset:4096
	ds_read_b128 v[152:155], v156 offset:5120
	s_waitcnt lgkmcnt(0)
	v_mfma_f32_16x16x32_bf16 v[80:83], v[200:203], v[232:235], 0
	ds_read_b128 v[244:247], v156 offset:8192
	v_mfma_f32_16x16x32_bf16 v[84:87], v[200:203], v[236:239], 0
	ds_read_b128 v[248:251], v156 offset:9216
	v_mfma_f32_16x16x32_bf16 v[88:91], v[204:207], v[232:235], 0
	v_mfma_f32_16x16x32_bf16 v[92:95], v[204:207], v[236:239], 0
	v_mfma_f32_16x16x32_bf16 v[64:67], v[208:211], v[232:235], 0
	v_mfma_f32_16x16x32_bf16 v[68:71], v[208:211], v[236:239], 0
	v_mfma_f32_16x16x32_bf16 v[72:75], v[212:215], v[232:235], 0
	v_mfma_f32_16x16x32_bf16 v[76:79], v[212:215], v[236:239], 0
	s_waitcnt lgkmcnt(2)
	v_mfma_f32_16x16x32_bf16 v[16:19], v[200:203], v[240:243], 0
	ds_read_b128 v[232:235], v156 offset:12288
	v_mfma_f32_16x16x32_bf16 v[20:23], v[200:203], v[152:155], 0
	ds_read_b128 v[236:239], v156 offset:13312
	v_mfma_f32_16x16x32_bf16 v[24:27], v[204:207], v[240:243], 0
	v_mfma_f32_16x16x32_bf16 v[28:31], v[204:207], v[152:155], 0
	v_mfma_f32_16x16x32_bf16 v[0:3], v[208:211], v[240:243], 0
	v_mfma_f32_16x16x32_bf16 v[4:7], v[208:211], v[152:155], 0
	v_mfma_f32_16x16x32_bf16 v[8:11], v[212:215], v[240:243], 0
	v_mfma_f32_16x16x32_bf16 v[12:15], v[212:215], v[152:155], 0
	s_waitcnt lgkmcnt(0)
	s_waitcnt vmcnt(6)
	s_barrier
	ds_read_b128 v[216:219], v158 offset:24576
	ds_read_b128 v[220:223], v158 offset:25600
	v_mfma_f32_16x16x32_bf16 v[112:115], v[200:203], v[244:247], 0
	ds_read_b128 v[224:227], v158 offset:26624
	ds_read_b128 v[228:231], v158 offset:27648
	v_mfma_f32_16x16x32_bf16 v[116:119], v[200:203], v[248:251], 0
	ds_read_b128 v[240:243], v156 offset:24576
	ds_read_b128 v[152:155], v156 offset:25600
	s_add_u32 m0, s76, 0x0
	v_mfma_f32_16x16x32_bf16 v[120:123], v[204:207], v[244:247], 0
	global_load_lds_dwordx4 v160, s[72:73]
	s_add_u32 m0, s76, 0x1000
	v_mfma_f32_16x16x32_bf16 v[124:127], v[204:207], v[248:251], 0
	global_load_lds_dwordx4 v161, s[72:73]
	s_add_u32 m0, s76, 0x2000
	v_mfma_f32_16x16x32_bf16 v[96:99], v[208:211], v[244:247], 0
	global_load_lds_dwordx4 v162, s[72:73]
	v_mfma_f32_16x16x32_bf16 v[100:103], v[208:211], v[248:251], 0
	v_mfma_f32_16x16x32_bf16 v[104:107], v[212:215], v[244:247], 0
	v_mfma_f32_16x16x32_bf16 v[108:111], v[212:215], v[248:251], 0
	ds_read_b128 v[244:247], v156 offset:28672
	ds_read_b128 v[248:251], v156 offset:29696
	v_mfma_f32_16x16x32_bf16 v[48:51], v[200:203], v[232:235], 0
	s_add_u32 m0, s76, 0x3000
	v_mfma_f32_16x16x32_bf16 v[52:55], v[200:203], v[236:239], 0
	global_load_lds_dwordx4 v163, s[72:73]
	s_add_u32 m0, s76, 0x4000
	v_mfma_f32_16x16x32_bf16 v[56:59], v[204:207], v[232:235], 0
	global_load_lds_dwordx4 v160, s[74:75]
	s_add_u32 m0, s76, 0x5000
	v_mfma_f32_16x16x32_bf16 v[60:63], v[204:207], v[236:239], 0
	global_load_lds_dwordx4 v161, s[74:75]
	s_add_u32 s72, s72, 0x202000
	s_addc_u32 s73, s73, 0
	v_mfma_f32_16x16x32_bf16 v[32:35], v[208:211], v[232:235], 0
	s_add_u32 s74, s74, 0x10000
	s_addc_u32 s75, s75, 0
	v_mfma_f32_16x16x32_bf16 v[36:39], v[208:211], v[236:239], 0
	v_mfma_f32_16x16x32_bf16 v[40:43], v[212:215], v[232:235], 0
	v_mfma_f32_16x16x32_bf16 v[44:47], v[212:215], v[236:239], 0
	s_waitcnt lgkmcnt(2)
	v_mfma_f32_16x16x32_bf16 v[80:83], v[216:219], v[240:243], v[80:83]
	ds_read_b128 v[232:235], v156 offset:32768
	v_mfma_f32_16x16x32_bf16 v[84:87], v[216:219], v[152:155], v[84:87]
	ds_read_b128 v[236:239], v156 offset:33792
	v_mfma_f32_16x16x32_bf16 v[88:91], v[220:223], v[240:243], v[88:91]
	v_mfma_f32_16x16x32_bf16 v[92:95], v[220:223], v[152:155], v[92:95]
	v_mfma_f32_16x16x32_bf16 v[64:67], v[224:227], v[240:243], v[64:67]
	v_mfma_f32_16x16x32_bf16 v[68:71], v[224:227], v[152:155], v[68:71]
	v_mfma_f32_16x16x32_bf16 v[72:75], v[228:231], v[240:243], v[72:75]
	v_mfma_f32_16x16x32_bf16 v[76:79], v[228:231], v[152:155], v[76:79]
	s_waitcnt lgkmcnt(2)
	v_mfma_f32_16x16x32_bf16 v[16:19], v[216:219], v[244:247], v[16:19]
	ds_read_b128 v[240:243], v156 offset:36864
	v_mfma_f32_16x16x32_bf16 v[20:23], v[216:219], v[248:251], v[20:23]
	ds_read_b128 v[152:155], v156 offset:37888
	v_mfma_f32_16x16x32_bf16 v[24:27], v[220:223], v[244:247], v[24:27]
	v_mfma_f32_16x16x32_bf16 v[28:31], v[220:223], v[248:251], v[28:31]
	v_mfma_f32_16x16x32_bf16 v[0:3], v[224:227], v[244:247], v[0:3]
	v_mfma_f32_16x16x32_bf16 v[4:7], v[224:227], v[248:251], v[4:7]
	v_mfma_f32_16x16x32_bf16 v[8:11], v[228:231], v[244:247], v[8:11]
	v_mfma_f32_16x16x32_bf16 v[12:15], v[228:231], v[248:251], v[12:15]
	s_waitcnt lgkmcnt(0)
	s_waitcnt vmcnt(6)
	s_barrier
	ds_read_b128 v[200:203], v158 offset:49152
	ds_read_b128 v[204:207], v158 offset:50176
	v_mfma_f32_16x16x32_bf16 v[112:115], v[216:219], v[232:235], v[112:115]
	ds_read_b128 v[208:211], v158 offset:51200
	ds_read_b128 v[212:215], v158 offset:52224
	v_mfma_f32_16x16x32_bf16 v[116:119], v[216:219], v[236:239], v[116:119]
	ds_read_b128 v[244:247], v156 offset:49152
	ds_read_b128 v[248:251], v156 offset:50176
	s_add_u32 m0, s76, 0x6000
	v_mfma_f32_16x16x32_bf16 v[120:123], v[220:223], v[232:235], v[120:123]
	global_load_lds_dwordx4 v160, s[72:73]
	s_add_u32 m0, s76, 0x7000
	v_mfma_f32_16x16x32_bf16 v[124:127], v[220:223], v[236:239], v[124:127]
	global_load_lds_dwordx4 v161, s[72:73]
	s_add_u32 m0, s76, 0x8000
	v_mfma_f32_16x16x32_bf16 v[96:99], v[224:227], v[232:235], v[96:99]
	global_load_lds_dwordx4 v162, s[72:73]
	v_mfma_f32_16x16x32_bf16 v[100:103], v[224:227], v[236:239], v[100:103]
	v_mfma_f32_16x16x32_bf16 v[104:107], v[228:231], v[232:235], v[104:107]
	v_mfma_f32_16x16x32_bf16 v[108:111], v[228:231], v[236:239], v[108:111]
	ds_read_b128 v[232:235], v156 offset:53248
	ds_read_b128 v[236:239], v156 offset:54272
	v_mfma_f32_16x16x32_bf16 v[48:51], v[216:219], v[240:243], v[48:51]
	s_add_u32 m0, s76, 0x9000
	v_mfma_f32_16x16x32_bf16 v[52:55], v[216:219], v[152:155], v[52:55]
	global_load_lds_dwordx4 v163, s[72:73]
	s_add_u32 m0, s76, 0xa000
	v_mfma_f32_16x16x32_bf16 v[56:59], v[220:223], v[240:243], v[56:59]
	global_load_lds_dwordx4 v160, s[74:75]
	s_add_u32 m0, s76, 0xb000
	v_mfma_f32_16x16x32_bf16 v[60:63], v[220:223], v[152:155], v[60:63]
	global_load_lds_dwordx4 v161, s[74:75]
	s_add_u32 s72, s72, 0x202000
	s_addc_u32 s73, s73, 0
	v_mfma_f32_16x16x32_bf16 v[32:35], v[224:227], v[240:243], v[32:35]
	s_add_u32 s74, s74, 0x10000
	s_addc_u32 s75, s75, 0
	v_mfma_f32_16x16x32_bf16 v[36:39], v[224:227], v[152:155], v[36:39]
	v_mfma_f32_16x16x32_bf16 v[40:43], v[228:231], v[240:243], v[40:43]
	v_mfma_f32_16x16x32_bf16 v[44:47], v[228:231], v[152:155], v[44:47]
	s_waitcnt lgkmcnt(2)
	v_mfma_f32_16x16x32_bf16 v[80:83], v[200:203], v[244:247], v[80:83]
	ds_read_b128 v[240:243], v156 offset:57344
	v_mfma_f32_16x16x32_bf16 v[84:87], v[200:203], v[248:251], v[84:87]
	ds_read_b128 v[152:155], v156 offset:58368
	v_mfma_f32_16x16x32_bf16 v[88:91], v[204:207], v[244:247], v[88:91]
	v_mfma_f32_16x16x32_bf16 v[92:95], v[204:207], v[248:251], v[92:95]
	v_mfma_f32_16x16x32_bf16 v[64:67], v[208:211], v[244:247], v[64:67]
	v_mfma_f32_16x16x32_bf16 v[68:71], v[208:211], v[248:251], v[68:71]
	v_mfma_f32_16x16x32_bf16 v[72:75], v[212:215], v[244:247], v[72:75]
	v_mfma_f32_16x16x32_bf16 v[76:79], v[212:215], v[248:251], v[76:79]
	s_waitcnt lgkmcnt(2)
	v_mfma_f32_16x16x32_bf16 v[16:19], v[200:203], v[232:235], v[16:19]
	ds_read_b128 v[244:247], v156 offset:61440
	v_mfma_f32_16x16x32_bf16 v[20:23], v[200:203], v[236:239], v[20:23]
	ds_read_b128 v[248:251], v156 offset:62464
	v_mfma_f32_16x16x32_bf16 v[24:27], v[204:207], v[232:235], v[24:27]
	v_mfma_f32_16x16x32_bf16 v[28:31], v[204:207], v[236:239], v[28:31]
	v_mfma_f32_16x16x32_bf16 v[0:3], v[208:211], v[232:235], v[0:3]
	v_mfma_f32_16x16x32_bf16 v[4:7], v[208:211], v[236:239], v[4:7]
	v_mfma_f32_16x16x32_bf16 v[8:11], v[212:215], v[232:235], v[8:11]
	v_mfma_f32_16x16x32_bf16 v[12:15], v[212:215], v[236:239], v[12:15]
	s_waitcnt lgkmcnt(0)
	s_waitcnt vmcnt(6)
	s_barrier
	ds_read_b128 v[216:219], v158
	ds_read_b128 v[220:223], v158 offset:1024
	v_mfma_f32_16x16x32_bf16 v[112:115], v[200:203], v[240:243], v[112:115]
	ds_read_b128 v[224:227], v158 offset:2048
	ds_read_b128 v[228:231], v158 offset:3072
	v_mfma_f32_16x16x32_bf16 v[116:119], v[200:203], v[152:155], v[116:119]
	ds_read_b128 v[232:235], v156
	ds_read_b128 v[236:239], v156 offset:1024
	s_add_u32 m0, s76, 0xc000
	v_mfma_f32_16x16x32_bf16 v[120:123], v[204:207], v[240:243], v[120:123]
	global_load_lds_dwordx4 v160, s[72:73]
	s_add_u32 m0, s76, 0xd000
	v_mfma_f32_16x16x32_bf16 v[124:127], v[204:207], v[152:155], v[124:127]
	global_load_lds_dwordx4 v161, s[72:73]
	s_add_u32 m0, s76, 0xe000
	v_mfma_f32_16x16x32_bf16 v[96:99], v[208:211], v[240:243], v[96:99]
	global_load_lds_dwordx4 v162, s[72:73]
	v_mfma_f32_16x16x32_bf16 v[100:103], v[208:211], v[152:155], v[100:103]
	v_mfma_f32_16x16x32_bf16 v[104:107], v[212:215], v[240:243], v[104:107]
	v_mfma_f32_16x16x32_bf16 v[108:111], v[212:215], v[152:155], v[108:111]
	ds_read_b128 v[240:243], v156 offset:4096
	ds_read_b128 v[152:155], v156 offset:5120
	v_mfma_f32_16x16x32_bf16 v[48:51], v[200:203], v[244:247], v[48:51]
	s_add_u32 m0, s76, 0xf000
	v_mfma_f32_16x16x32_bf16 v[52:55], v[200:203], v[248:251], v[52:55]
	global_load_lds_dwordx4 v163, s[72:73]
	s_add_u32 m0, s76, 0x10000
	v_mfma_f32_16x16x32_bf16 v[56:59], v[204:207], v[244:247], v[56:59]
	global_load_lds_dwordx4 v160, s[74:75]
	s_add_u32 m0, s76, 0x11000
	v_mfma_f32_16x16x32_bf16 v[60:63], v[204:207], v[248:251], v[60:63]
	global_load_lds_dwordx4 v161, s[74:75]
	s_add_u32 s72, s72, 0x202000
	s_addc_u32 s73, s73, 0
	v_mfma_f32_16x16x32_bf16 v[32:35], v[208:211], v[244:247], v[32:35]
	s_add_u32 s74, s74, 0x10000
	s_addc_u32 s75, s75, 0
	v_mfma_f32_16x16x32_bf16 v[36:39], v[208:211], v[248:251], v[36:39]
	v_mfma_f32_16x16x32_bf16 v[40:43], v[212:215], v[244:247], v[40:43]
	v_mfma_f32_16x16x32_bf16 v[44:47], v[212:215], v[248:251], v[44:47]
	s_waitcnt lgkmcnt(2)
	v_mfma_f32_16x16x32_bf16 v[80:83], v[216:219], v[232:235], v[80:83]
	ds_read_b128 v[244:247], v156 offset:8192
	v_mfma_f32_16x16x32_bf16 v[84:87], v[216:219], v[236:239], v[84:87]
	ds_read_b128 v[248:251], v156 offset:9216
	v_mfma_f32_16x16x32_bf16 v[88:91], v[220:223], v[232:235], v[88:91]
	v_mfma_f32_16x16x32_bf16 v[92:95], v[220:223], v[236:239], v[92:95]
	v_mfma_f32_16x16x32_bf16 v[64:67], v[224:227], v[232:235], v[64:67]
	v_mfma_f32_16x16x32_bf16 v[68:71], v[224:227], v[236:239], v[68:71]
	v_mfma_f32_16x16x32_bf16 v[72:75], v[228:231], v[232:235], v[72:75]
	v_mfma_f32_16x16x32_bf16 v[76:79], v[228:231], v[236:239], v[76:79]
	s_waitcnt lgkmcnt(2)
	v_mfma_f32_16x16x32_bf16 v[16:19], v[216:219], v[240:243], v[16:19]
	ds_read_b128 v[232:235], v156 offset:12288
	v_mfma_f32_16x16x32_bf16 v[20:23], v[216:219], v[152:155], v[20:23]
	ds_read_b128 v[236:239], v156 offset:13312
	v_mfma_f32_16x16x32_bf16 v[24:27], v[220:223], v[240:243], v[24:27]
	v_mfma_f32_16x16x32_bf16 v[28:31], v[220:223], v[152:155], v[28:31]
	v_mfma_f32_16x16x32_bf16 v[0:3], v[224:227], v[240:243], v[0:3]
	v_mfma_f32_16x16x32_bf16 v[4:7], v[224:227], v[152:155], v[4:7]
	v_mfma_f32_16x16x32_bf16 v[8:11], v[228:231], v[240:243], v[8:11]
	v_mfma_f32_16x16x32_bf16 v[12:15], v[228:231], v[152:155], v[12:15]
	s_waitcnt lgkmcnt(0)
	s_waitcnt vmcnt(6)
	s_barrier
	ds_read_b128 v[200:203], v158 offset:24576
	ds_read_b128 v[204:207], v158 offset:25600
	v_mfma_f32_16x16x32_bf16 v[112:115], v[216:219], v[244:247], v[112:115]
	ds_read_b128 v[208:211], v158 offset:26624
	ds_read_b128 v[212:215], v158 offset:27648
	v_mfma_f32_16x16x32_bf16 v[116:119], v[216:219], v[248:251], v[116:119]
	ds_read_b128 v[240:243], v156 offset:24576
	ds_read_b128 v[152:155], v156 offset:25600
	s_add_u32 m0, s76, 0x0
	v_mfma_f32_16x16x32_bf16 v[120:123], v[220:223], v[244:247], v[120:123]
	global_load_lds_dwordx4 v160, s[72:73]
	s_add_u32 m0, s76, 0x1000
	v_mfma_f32_16x16x32_bf16 v[124:127], v[220:223], v[248:251], v[124:127]
	global_load_lds_dwordx4 v161, s[72:73]
	s_add_u32 m0, s76, 0x2000
	v_mfma_f32_16x16x32_bf16 v[96:99], v[224:227], v[244:247], v[96:99]
	global_load_lds_dwordx4 v162, s[72:73]
	v_mfma_f32_16x16x32_bf16 v[100:103], v[224:227], v[248:251], v[100:103]
	v_mfma_f32_16x16x32_bf16 v[104:107], v[228:231], v[244:247], v[104:107]
	v_mfma_f32_16x16x32_bf16 v[108:111], v[228:231], v[248:251], v[108:111]
	ds_read_b128 v[244:247], v156 offset:28672
	ds_read_b128 v[248:251], v156 offset:29696
	v_mfma_f32_16x16x32_bf16 v[48:51], v[216:219], v[232:235], v[48:51]
	s_add_u32 m0, s76, 0x3000
	v_mfma_f32_16x16x32_bf16 v[52:55], v[216:219], v[236:239], v[52:55]
	global_load_lds_dwordx4 v163, s[72:73]
	s_add_u32 m0, s76, 0x4000
	v_mfma_f32_16x16x32_bf16 v[56:59], v[220:223], v[232:235], v[56:59]
	global_load_lds_dwordx4 v160, s[74:75]
	s_add_u32 m0, s76, 0x5000
	v_mfma_f32_16x16x32_bf16 v[60:63], v[220:223], v[236:239], v[60:63]
	global_load_lds_dwordx4 v161, s[74:75]
	s_add_u32 s72, s72, 0x202000
	s_addc_u32 s73, s73, 0
	v_mfma_f32_16x16x32_bf16 v[32:35], v[224:227], v[232:235], v[32:35]
	s_add_u32 s74, s74, 0x10000
	s_addc_u32 s75, s75, 0
	v_mfma_f32_16x16x32_bf16 v[36:39], v[224:227], v[236:239], v[36:39]
	v_mfma_f32_16x16x32_bf16 v[40:43], v[228:231], v[232:235], v[40:43]
	v_mfma_f32_16x16x32_bf16 v[44:47], v[228:231], v[236:239], v[44:47]
	s_waitcnt lgkmcnt(2)
	v_mfma_f32_16x16x32_bf16 v[80:83], v[200:203], v[240:243], v[80:83]
	ds_read_b128 v[232:235], v156 offset:32768
	v_mfma_f32_16x16x32_bf16 v[84:87], v[200:203], v[152:155], v[84:87]
	ds_read_b128 v[236:239], v156 offset:33792
	v_mfma_f32_16x16x32_bf16 v[88:91], v[204:207], v[240:243], v[88:91]
	v_mfma_f32_16x16x32_bf16 v[92:95], v[204:207], v[152:155], v[92:95]
	v_mfma_f32_16x16x32_bf16 v[64:67], v[208:211], v[240:243], v[64:67]
	v_mfma_f32_16x16x32_bf16 v[68:71], v[208:211], v[152:155], v[68:71]
	v_mfma_f32_16x16x32_bf16 v[72:75], v[212:215], v[240:243], v[72:75]
	v_mfma_f32_16x16x32_bf16 v[76:79], v[212:215], v[152:155], v[76:79]
	s_waitcnt lgkmcnt(2)
	v_mfma_f32_16x16x32_bf16 v[16:19], v[200:203], v[244:247], v[16:19]
	ds_read_b128 v[240:243], v156 offset:36864
	v_mfma_f32_16x16x32_bf16 v[20:23], v[200:203], v[248:251], v[20:23]
	ds_read_b128 v[152:155], v156 offset:37888
	v_mfma_f32_16x16x32_bf16 v[24:27], v[204:207], v[244:247], v[24:27]
	v_mfma_f32_16x16x32_bf16 v[28:31], v[204:207], v[248:251], v[28:31]
	v_mfma_f32_16x16x32_bf16 v[0:3], v[208:211], v[244:247], v[0:3]
	v_mfma_f32_16x16x32_bf16 v[4:7], v[208:211], v[248:251], v[4:7]
	v_mfma_f32_16x16x32_bf16 v[8:11], v[212:215], v[244:247], v[8:11]
	v_mfma_f32_16x16x32_bf16 v[12:15], v[212:215], v[248:251], v[12:15]
	s_waitcnt lgkmcnt(0)
	s_waitcnt vmcnt(6)
	s_barrier
	ds_read_b128 v[216:219], v158 offset:49152
	ds_read_b128 v[220:223], v158 offset:50176
	v_mfma_f32_16x16x32_bf16 v[112:115], v[200:203], v[232:235], v[112:115]
	ds_read_b128 v[224:227], v158 offset:51200
	ds_read_b128 v[228:231], v158 offset:52224
	v_mfma_f32_16x16x32_bf16 v[116:119], v[200:203], v[236:239], v[116:119]
	ds_read_b128 v[244:247], v156 offset:49152
	ds_read_b128 v[248:251], v156 offset:50176
	s_add_u32 m0, s76, 0x6000
	v_mfma_f32_16x16x32_bf16 v[120:123], v[204:207], v[232:235], v[120:123]
	global_load_lds_dwordx4 v160, s[72:73]
	s_add_u32 m0, s76, 0x7000
	v_mfma_f32_16x16x32_bf16 v[124:127], v[204:207], v[236:239], v[124:127]
	global_load_lds_dwordx4 v161, s[72:73]
	s_add_u32 m0, s76, 0x8000
	v_mfma_f32_16x16x32_bf16 v[96:99], v[208:211], v[232:235], v[96:99]
	global_load_lds_dwordx4 v162, s[72:73]
	v_mfma_f32_16x16x32_bf16 v[100:103], v[208:211], v[236:239], v[100:103]
	v_mfma_f32_16x16x32_bf16 v[104:107], v[212:215], v[232:235], v[104:107]
	v_mfma_f32_16x16x32_bf16 v[108:111], v[212:215], v[236:239], v[108:111]
	ds_read_b128 v[232:235], v156 offset:53248
	ds_read_b128 v[236:239], v156 offset:54272
	v_mfma_f32_16x16x32_bf16 v[48:51], v[200:203], v[240:243], v[48:51]
	s_add_u32 m0, s76, 0x9000
	v_mfma_f32_16x16x32_bf16 v[52:55], v[200:203], v[152:155], v[52:55]
	global_load_lds_dwordx4 v163, s[72:73]
	s_add_u32 m0, s76, 0xa000
	v_mfma_f32_16x16x32_bf16 v[56:59], v[204:207], v[240:243], v[56:59]
	global_load_lds_dwordx4 v160, s[74:75]
	s_add_u32 m0, s76, 0xb000
	v_mfma_f32_16x16x32_bf16 v[60:63], v[204:207], v[152:155], v[60:63]
	global_load_lds_dwordx4 v161, s[74:75]
	s_add_u32 s72, s72, 0x202000
	s_addc_u32 s73, s73, 0
	v_mfma_f32_16x16x32_bf16 v[32:35], v[208:211], v[240:243], v[32:35]
	s_add_u32 s74, s74, 0x10000
	s_addc_u32 s75, s75, 0
	v_mfma_f32_16x16x32_bf16 v[36:39], v[208:211], v[152:155], v[36:39]
	v_mfma_f32_16x16x32_bf16 v[40:43], v[212:215], v[240:243], v[40:43]
	v_mfma_f32_16x16x32_bf16 v[44:47], v[212:215], v[152:155], v[44:47]
	s_waitcnt lgkmcnt(2)
	v_mfma_f32_16x16x32_bf16 v[80:83], v[216:219], v[244:247], v[80:83]
	ds_read_b128 v[240:243], v156 offset:57344
	v_mfma_f32_16x16x32_bf16 v[84:87], v[216:219], v[248:251], v[84:87]
	ds_read_b128 v[152:155], v156 offset:58368
	v_mfma_f32_16x16x32_bf16 v[88:91], v[220:223], v[244:247], v[88:91]
	v_mfma_f32_16x16x32_bf16 v[92:95], v[220:223], v[248:251], v[92:95]
	v_mfma_f32_16x16x32_bf16 v[64:67], v[224:227], v[244:247], v[64:67]
	v_mfma_f32_16x16x32_bf16 v[68:71], v[224:227], v[248:251], v[68:71]
	v_mfma_f32_16x16x32_bf16 v[72:75], v[228:231], v[244:247], v[72:75]
	v_mfma_f32_16x16x32_bf16 v[76:79], v[228:231], v[248:251], v[76:79]
	s_waitcnt lgkmcnt(2)
	v_mfma_f32_16x16x32_bf16 v[16:19], v[216:219], v[232:235], v[16:19]
	ds_read_b128 v[244:247], v156 offset:61440
	v_mfma_f32_16x16x32_bf16 v[20:23], v[216:219], v[236:239], v[20:23]
	ds_read_b128 v[248:251], v156 offset:62464
	v_mfma_f32_16x16x32_bf16 v[24:27], v[220:223], v[232:235], v[24:27]
	v_mfma_f32_16x16x32_bf16 v[28:31], v[220:223], v[236:239], v[28:31]
	v_mfma_f32_16x16x32_bf16 v[0:3], v[224:227], v[232:235], v[0:3]
	v_mfma_f32_16x16x32_bf16 v[4:7], v[224:227], v[236:239], v[4:7]
	v_mfma_f32_16x16x32_bf16 v[8:11], v[228:231], v[232:235], v[8:11]
	v_mfma_f32_16x16x32_bf16 v[12:15], v[228:231], v[236:239], v[12:15]
	s_waitcnt lgkmcnt(0)
	s_waitcnt vmcnt(6)
	s_barrier
	ds_read_b128 v[200:203], v158
	ds_read_b128 v[204:207], v158 offset:1024
	v_mfma_f32_16x16x32_bf16 v[112:115], v[216:219], v[240:243], v[112:115]
	ds_read_b128 v[208:211], v158 offset:2048
	ds_read_b128 v[212:215], v158 offset:3072
	v_mfma_f32_16x16x32_bf16 v[116:119], v[216:219], v[152:155], v[116:119]
	ds_read_b128 v[232:235], v156
	ds_read_b128 v[236:239], v156 offset:1024
	s_add_u32 m0, s76, 0xc000
	v_mfma_f32_16x16x32_bf16 v[120:123], v[220:223], v[240:243], v[120:123]
	global_load_lds_dwordx4 v160, s[72:73]
	s_add_u32 m0, s76, 0xd000
	v_mfma_f32_16x16x32_bf16 v[124:127], v[220:223], v[152:155], v[124:127]
	global_load_lds_dwordx4 v161, s[72:73]
	s_add_u32 m0, s76, 0xe000
	v_mfma_f32_16x16x32_bf16 v[96:99], v[224:227], v[240:243], v[96:99]
	global_load_lds_dwordx4 v162, s[72:73]
	v_mfma_f32_16x16x32_bf16 v[100:103], v[224:227], v[152:155], v[100:103]
	v_mfma_f32_16x16x32_bf16 v[104:107], v[228:231], v[240:243], v[104:107]
	v_mfma_f32_16x16x32_bf16 v[108:111], v[228:231], v[152:155], v[108:111]
	ds_read_b128 v[240:243], v156 offset:4096
	ds_read_b128 v[152:155], v156 offset:5120
	v_mfma_f32_16x16x32_bf16 v[48:51], v[216:219], v[244:247], v[48:51]
	s_add_u32 m0, s76, 0xf000
	v_mfma_f32_16x16x32_bf16 v[52:55], v[216:219], v[248:251], v[52:55]
	global_load_lds_dwordx4 v163, s[72:73]
	s_add_u32 m0, s76, 0x10000
	v_mfma_f32_16x16x32_bf16 v[56:59], v[220:223], v[244:247], v[56:59]
	global_load_lds_dwordx4 v160, s[74:75]
	s_add_u32 m0, s76, 0x11000
	v_mfma_f32_16x16x32_bf16 v[60:63], v[220:223], v[248:251], v[60:63]
	global_load_lds_dwordx4 v161, s[74:75]
	s_add_u32 s72, s72, 0x202000
	s_addc_u32 s73, s73, 0
	v_mfma_f32_16x16x32_bf16 v[32:35], v[224:227], v[244:247], v[32:35]
	s_add_u32 s74, s74, 0x10000
	s_addc_u32 s75, s75, 0
	v_mfma_f32_16x16x32_bf16 v[36:39], v[224:227], v[248:251], v[36:39]
	v_mfma_f32_16x16x32_bf16 v[40:43], v[228:231], v[244:247], v[40:43]
	v_mfma_f32_16x16x32_bf16 v[44:47], v[228:231], v[248:251], v[44:47]
	s_mov_b32 s77, 3
.Lgemm_p6_loop:
	s_waitcnt lgkmcnt(2)
	v_mfma_f32_16x16x32_bf16 v[80:83], v[200:203], v[232:235], v[80:83]
	ds_read_b128 v[244:247], v156 offset:8192
	v_mfma_f32_16x16x32_bf16 v[84:87], v[200:203], v[236:239], v[84:87]
	ds_read_b128 v[248:251], v156 offset:9216
	v_mfma_f32_16x16x32_bf16 v[88:91], v[204:207], v[232:235], v[88:91]
	v_mfma_f32_16x16x32_bf16 v[92:95], v[204:207], v[236:239], v[92:95]
	v_mfma_f32_16x16x32_bf16 v[64:67], v[208:211], v[232:235], v[64:67]
	v_mfma_f32_16x16x32_bf16 v[68:71], v[208:211], v[236:239], v[68:71]
	v_mfma_f32_16x16x32_bf16 v[72:75], v[212:215], v[232:235], v[72:75]
	v_mfma_f32_16x16x32_bf16 v[76:79], v[212:215], v[236:239], v[76:79]
	s_waitcnt lgkmcnt(2)
	v_mfma_f32_16x16x32_bf16 v[16:19], v[200:203], v[240:243], v[16:19]
	ds_read_b128 v[232:235], v156 offset:12288
	v_mfma_f32_16x16x32_bf16 v[20:23], v[200:203], v[152:155], v[20:23]
	ds_read_b128 v[236:239], v156 offset:13312
	v_mfma_f32_16x16x32_bf16 v[24:27], v[204:207], v[240:243], v[24:27]
	v_mfma_f32_16x16x32_bf16 v[28:31], v[204:207], v[152:155], v[28:31]
	v_mfma_f32_16x16x32_bf16 v[0:3], v[208:211], v[240:243], v[0:3]
	v_mfma_f32_16x16x32_bf16 v[4:7], v[208:211], v[152:155], v[4:7]
	v_mfma_f32_16x16x32_bf16 v[8:11], v[212:215], v[240:243], v[8:11]
	v_mfma_f32_16x16x32_bf16 v[12:15], v[212:215], v[152:155], v[12:15]
	s_waitcnt lgkmcnt(0)
	s_waitcnt vmcnt(6)
	s_barrier
	ds_read_b128 v[216:219], v158 offset:24576
	ds_read_b128 v[220:223], v158 offset:25600
	v_mfma_f32_16x16x32_bf16 v[112:115], v[200:203], v[244:247], v[112:115]
	ds_read_b128 v[224:227], v158 offset:26624
	ds_read_b128 v[228:231], v158 offset:27648
	v_mfma_f32_16x16x32_bf16 v[116:119], v[200:203], v[248:251], v[116:119]
	ds_read_b128 v[240:243], v156 offset:24576
	ds_read_b128 v[152:155], v156 offset:25600
	s_add_u32 m0, s76, 0x0
	v_mfma_f32_16x16x32_bf16 v[120:123], v[204:207], v[244:247], v[120:123]
	global_load_lds_dwordx4 v160, s[72:73]
	s_add_u32 m0, s76, 0x1000
	v_mfma_f32_16x16x32_bf16 v[124:127], v[204:207], v[248:251], v[124:127]
	global_load_lds_dwordx4 v161, s[72:73]
	s_add_u32 m0, s76, 0x2000
	v_mfma_f32_16x16x32_bf16 v[96:99], v[208:211], v[244:247], v[96:99]
	global_load_lds_dwordx4 v162, s[72:73]
	v_mfma_f32_16x16x32_bf16 v[100:103], v[208:211], v[248:251], v[100:103]
	v_mfma_f32_16x16x32_bf16 v[104:107], v[212:215], v[244:247], v[104:107]
	v_mfma_f32_16x16x32_bf16 v[108:111], v[212:215], v[248:251], v[108:111]
	ds_read_b128 v[244:247], v156 offset:28672
	ds_read_b128 v[248:251], v156 offset:29696
	v_mfma_f32_16x16x32_bf16 v[48:51], v[200:203], v[232:235], v[48:51]
	s_add_u32 m0, s76, 0x3000
	v_mfma_f32_16x16x32_bf16 v[52:55], v[200:203], v[236:239], v[52:55]
	global_load_lds_dwordx4 v163, s[72:73]
	s_add_u32 m0, s76, 0x4000
	v_mfma_f32_16x16x32_bf16 v[56:59], v[204:207], v[232:235], v[56:59]
	global_load_lds_dwordx4 v160, s[74:75]
	s_add_u32 m0, s76, 0x5000
	v_mfma_f32_16x16x32_bf16 v[60:63], v[204:207], v[236:239], v[60:63]
	global_load_lds_dwordx4 v161, s[74:75]
	s_add_u32 s72, s72, 0x202000
	s_addc_u32 s73, s73, 0
	v_mfma_f32_16x16x32_bf16 v[32:35], v[208:211], v[232:235], v[32:35]
	s_add_u32 s74, s74, 0x10000
	s_addc_u32 s75, s75, 0
	v_mfma_f32_16x16x32_bf16 v[36:39], v[208:211], v[236:239], v[36:39]
	v_mfma_f32_16x16x32_bf16 v[40:43], v[212:215], v[232:235], v[40:43]
	v_mfma_f32_16x16x32_bf16 v[44:47], v[212:215], v[236:239], v[44:47]
	s_waitcnt lgkmcnt(2)
	v_mfma_f32_16x16x32_bf16 v[80:83], v[216:219], v[240:243], v[80:83]
	ds_read_b128 v[232:235], v156 offset:32768
	v_mfma_f32_16x16x32_bf16 v[84:87], v[216:219], v[152:155], v[84:87]
	ds_read_b128 v[236:239], v156 offset:33792
	v_mfma_f32_16x16x32_bf16 v[88:91], v[220:223], v[240:243], v[88:91]
	v_mfma_f32_16x16x32_bf16 v[92:95], v[220:223], v[152:155], v[92:95]
	v_mfma_f32_16x16x32_bf16 v[64:67], v[224:227], v[240:243], v[64:67]
	v_mfma_f32_16x16x32_bf16 v[68:71], v[224:227], v[152:155], v[68:71]
	v_mfma_f32_16x16x32_bf16 v[72:75], v[228:231], v[240:243], v[72:75]
	v_mfma_f32_16x16x32_bf16 v[76:79], v[228:231], v[152:155], v[76:79]
	s_waitcnt lgkmcnt(2)
	v_mfma_f32_16x16x32_bf16 v[16:19], v[216:219], v[244:247], v[16:19]
	ds_read_b128 v[240:243], v156 offset:36864
	v_mfma_f32_16x16x32_bf16 v[20:23], v[216:219], v[248:251], v[20:23]
	ds_read_b128 v[152:155], v156 offset:37888
	v_mfma_f32_16x16x32_bf16 v[24:27], v[220:223], v[244:247], v[24:27]
	v_mfma_f32_16x16x32_bf16 v[28:31], v[220:223], v[248:251], v[28:31]
	v_mfma_f32_16x16x32_bf16 v[0:3], v[224:227], v[244:247], v[0:3]
	v_mfma_f32_16x16x32_bf16 v[4:7], v[224:227], v[248:251], v[4:7]
	v_mfma_f32_16x16x32_bf16 v[8:11], v[228:231], v[244:247], v[8:11]
	v_mfma_f32_16x16x32_bf16 v[12:15], v[228:231], v[248:251], v[12:15]
	s_waitcnt lgkmcnt(0)
	s_waitcnt vmcnt(6)
	s_barrier
	ds_read_b128 v[200:203], v158 offset:49152
	ds_read_b128 v[204:207], v158 offset:50176
	v_mfma_f32_16x16x32_bf16 v[112:115], v[216:219], v[232:235], v[112:115]
	ds_read_b128 v[208:211], v158 offset:51200
	ds_read_b128 v[212:215], v158 offset:52224
	v_mfma_f32_16x16x32_bf16 v[116:119], v[216:219], v[236:239], v[116:119]
	ds_read_b128 v[244:247], v156 offset:49152
	ds_read_b128 v[248:251], v156 offset:50176
	s_add_u32 m0, s76, 0x6000
	v_mfma_f32_16x16x32_bf16 v[120:123], v[220:223], v[232:235], v[120:123]
	global_load_lds_dwordx4 v160, s[72:73]
	s_add_u32 m0, s76, 0x7000
	v_mfma_f32_16x16x32_bf16 v[124:127], v[220:223], v[236:239], v[124:127]
	global_load_lds_dwordx4 v161, s[72:73]
	s_add_u32 m0, s76, 0x8000
	v_mfma_f32_16x16x32_bf16 v[96:99], v[224:227], v[232:235], v[96:99]
	global_load_lds_dwordx4 v162, s[72:73]
	v_mfma_f32_16x16x32_bf16 v[100:103], v[224:227], v[236:239], v[100:103]
	v_mfma_f32_16x16x32_bf16 v[104:107], v[228:231], v[232:235], v[104:107]
	v_mfma_f32_16x16x32_bf16 v[108:111], v[228:231], v[236:239], v[108:111]
	ds_read_b128 v[232:235], v156 offset:53248
	ds_read_b128 v[236:239], v156 offset:54272
	v_mfma_f32_16x16x32_bf16 v[48:51], v[216:219], v[240:243], v[48:51]
	s_add_u32 m0, s76, 0x9000
	v_mfma_f32_16x16x32_bf16 v[52:55], v[216:219], v[152:155], v[52:55]
	global_load_lds_dwordx4 v163, s[72:73]
	s_add_u32 m0, s76, 0xa000
	v_mfma_f32_16x16x32_bf16 v[56:59], v[220:223], v[240:243], v[56:59]
	global_load_lds_dwordx4 v160, s[74:75]
	s_add_u32 m0, s76, 0xb000
	v_mfma_f32_16x16x32_bf16 v[60:63], v[220:223], v[152:155], v[60:63]
	global_load_lds_dwordx4 v161, s[74:75]
	s_add_u32 s72, s72, 0x202000
	s_addc_u32 s73, s73, 0
	v_mfma_f32_16x16x32_bf16 v[32:35], v[224:227], v[240:243], v[32:35]
	s_add_u32 s74, s74, 0x10000
	s_addc_u32 s75, s75, 0
	v_mfma_f32_16x16x32_bf16 v[36:39], v[224:227], v[152:155], v[36:39]
	v_mfma_f32_16x16x32_bf16 v[40:43], v[228:231], v[240:243], v[40:43]
	v_mfma_f32_16x16x32_bf16 v[44:47], v[228:231], v[152:155], v[44:47]
	s_waitcnt lgkmcnt(2)
	v_mfma_f32_16x16x32_bf16 v[80:83], v[200:203], v[244:247], v[80:83]
	ds_read_b128 v[240:243], v156 offset:57344
	v_mfma_f32_16x16x32_bf16 v[84:87], v[200:203], v[248:251], v[84:87]
	ds_read_b128 v[152:155], v156 offset:58368
	v_mfma_f32_16x16x32_bf16 v[88:91], v[204:207], v[244:247], v[88:91]
	v_mfma_f32_16x16x32_bf16 v[92:95], v[204:207], v[248:251], v[92:95]
	v_mfma_f32_16x16x32_bf16 v[64:67], v[208:211], v[244:247], v[64:67]
	v_mfma_f32_16x16x32_bf16 v[68:71], v[208:211], v[248:251], v[68:71]
	v_mfma_f32_16x16x32_bf16 v[72:75], v[212:215], v[244:247], v[72:75]
	v_mfma_f32_16x16x32_bf16 v[76:79], v[212:215], v[248:251], v[76:79]
	s_waitcnt lgkmcnt(2)
	v_mfma_f32_16x16x32_bf16 v[16:19], v[200:203], v[232:235], v[16:19]
	ds_read_b128 v[244:247], v156 offset:61440
	v_mfma_f32_16x16x32_bf16 v[20:23], v[200:203], v[236:239], v[20:23]
	ds_read_b128 v[248:251], v156 offset:62464
	v_mfma_f32_16x16x32_bf16 v[24:27], v[204:207], v[232:235], v[24:27]
	v_mfma_f32_16x16x32_bf16 v[28:31], v[204:207], v[236:239], v[28:31]
	v_mfma_f32_16x16x32_bf16 v[0:3], v[208:211], v[232:235], v[0:3]
	v_mfma_f32_16x16x32_bf16 v[4:7], v[208:211], v[236:239], v[4:7]
	v_mfma_f32_16x16x32_bf16 v[8:11], v[212:215], v[232:235], v[8:11]
	v_mfma_f32_16x16x32_bf16 v[12:15], v[212:215], v[236:239], v[12:15]
	s_waitcnt lgkmcnt(0)
	s_waitcnt vmcnt(6)
	s_barrier
	ds_read_b128 v[216:219], v158
	ds_read_b128 v[220:223], v158 offset:1024
	v_mfma_f32_16x16x32_bf16 v[112:115], v[200:203], v[240:243], v[112:115]
	ds_read_b128 v[224:227], v158 offset:2048
	ds_read_b128 v[228:231], v158 offset:3072
	v_mfma_f32_16x16x32_bf16 v[116:119], v[200:203], v[152:155], v[116:119]
	ds_read_b128 v[232:235], v156
	ds_read_b128 v[236:239], v156 offset:1024
	s_add_u32 m0, s76, 0xc000
	v_mfma_f32_16x16x32_bf16 v[120:123], v[204:207], v[240:243], v[120:123]
	global_load_lds_dwordx4 v160, s[72:73]
	s_add_u32 m0, s76, 0xd000
	v_mfma_f32_16x16x32_bf16 v[124:127], v[204:207], v[152:155], v[124:127]
	global_load_lds_dwordx4 v161, s[72:73]
	s_add_u32 m0, s76, 0xe000
	v_mfma_f32_16x16x32_bf16 v[96:99], v[208:211], v[240:243], v[96:99]
	global_load_lds_dwordx4 v162, s[72:73]
	v_mfma_f32_16x16x32_bf16 v[100:103], v[208:211], v[152:155], v[100:103]
	v_mfma_f32_16x16x32_bf16 v[104:107], v[212:215], v[240:243], v[104:107]
	v_mfma_f32_16x16x32_bf16 v[108:111], v[212:215], v[152:155], v[108:111]
	ds_read_b128 v[240:243], v156 offset:4096
	ds_read_b128 v[152:155], v156 offset:5120
	v_mfma_f32_16x16x32_bf16 v[48:51], v[200:203], v[244:247], v[48:51]
	s_add_u32 m0, s76, 0xf000
	v_mfma_f32_16x16x32_bf16 v[52:55], v[200:203], v[248:251], v[52:55]
	global_load_lds_dwordx4 v163, s[72:73]
	s_add_u32 m0, s76, 0x10000
	v_mfma_f32_16x16x32_bf16 v[56:59], v[204:207], v[244:247], v[56:59]
	global_load_lds_dwordx4 v160, s[74:75]
	s_add_u32 m0, s76, 0x11000
	v_mfma_f32_16x16x32_bf16 v[60:63], v[204:207], v[248:251], v[60:63]
	global_load_lds_dwordx4 v161, s[74:75]
	s_add_u32 s72, s72, 0x202000
	s_addc_u32 s73, s73, 0
	v_mfma_f32_16x16x32_bf16 v[32:35], v[208:211], v[244:247], v[32:35]
	s_add_u32 s74, s74, 0x10000
	s_addc_u32 s75, s75, 0
	v_mfma_f32_16x16x32_bf16 v[36:39], v[208:211], v[248:251], v[36:39]
	v_mfma_f32_16x16x32_bf16 v[40:43], v[212:215], v[244:247], v[40:43]
	v_mfma_f32_16x16x32_bf16 v[44:47], v[212:215], v[248:251], v[44:47]
	s_waitcnt lgkmcnt(2)
	v_mfma_f32_16x16x32_bf16 v[80:83], v[216:219], v[232:235], v[80:83]
	ds_read_b128 v[244:247], v156 offset:8192
	v_mfma_f32_16x16x32_bf16 v[84:87], v[216:219], v[236:239], v[84:87]
	ds_read_b128 v[248:251], v156 offset:9216
	v_mfma_f32_16x16x32_bf16 v[88:91], v[220:223], v[232:235], v[88:91]
	v_mfma_f32_16x16x32_bf16 v[92:95], v[220:223], v[236:239], v[92:95]
	v_mfma_f32_16x16x32_bf16 v[64:67], v[224:227], v[232:235], v[64:67]
	v_mfma_f32_16x16x32_bf16 v[68:71], v[224:227], v[236:239], v[68:71]
	v_mfma_f32_16x16x32_bf16 v[72:75], v[228:231], v[232:235], v[72:75]
	v_mfma_f32_16x16x32_bf16 v[76:79], v[228:231], v[236:239], v[76:79]
	s_waitcnt lgkmcnt(2)
	v_mfma_f32_16x16x32_bf16 v[16:19], v[216:219], v[240:243], v[16:19]
	ds_read_b128 v[232:235], v156 offset:12288
	v_mfma_f32_16x16x32_bf16 v[20:23], v[216:219], v[152:155], v[20:23]
	ds_read_b128 v[236:239], v156 offset:13312
	v_mfma_f32_16x16x32_bf16 v[24:27], v[220:223], v[240:243], v[24:27]
	v_mfma_f32_16x16x32_bf16 v[28:31], v[220:223], v[152:155], v[28:31]
	v_mfma_f32_16x16x32_bf16 v[0:3], v[224:227], v[240:243], v[0:3]
	v_mfma_f32_16x16x32_bf16 v[4:7], v[224:227], v[152:155], v[4:7]
	v_mfma_f32_16x16x32_bf16 v[8:11], v[228:231], v[240:243], v[8:11]
	v_mfma_f32_16x16x32_bf16 v[12:15], v[228:231], v[152:155], v[12:15]
	s_waitcnt lgkmcnt(0)
	s_waitcnt vmcnt(6)
	s_barrier
	ds_read_b128 v[200:203], v158 offset:24576
	ds_read_b128 v[204:207], v158 offset:25600
	v_mfma_f32_16x16x32_bf16 v[112:115], v[216:219], v[244:247], v[112:115]
	ds_read_b128 v[208:211], v158 offset:26624
	ds_read_b128 v[212:215], v158 offset:27648
	v_mfma_f32_16x16x32_bf16 v[116:119], v[216:219], v[248:251], v[116:119]
	ds_read_b128 v[240:243], v156 offset:24576
	ds_read_b128 v[152:155], v156 offset:25600
	s_add_u32 m0, s76, 0x0
	v_mfma_f32_16x16x32_bf16 v[120:123], v[220:223], v[244:247], v[120:123]
	global_load_lds_dwordx4 v160, s[72:73]
	s_add_u32 m0, s76, 0x1000
	v_mfma_f32_16x16x32_bf16 v[124:127], v[220:223], v[248:251], v[124:127]
	global_load_lds_dwordx4 v161, s[72:73]
	s_add_u32 m0, s76, 0x2000
	v_mfma_f32_16x16x32_bf16 v[96:99], v[224:227], v[244:247], v[96:99]
	global_load_lds_dwordx4 v162, s[72:73]
	v_mfma_f32_16x16x32_bf16 v[100:103], v[224:227], v[248:251], v[100:103]
	v_mfma_f32_16x16x32_bf16 v[104:107], v[228:231], v[244:247], v[104:107]
	v_mfma_f32_16x16x32_bf16 v[108:111], v[228:231], v[248:251], v[108:111]
	ds_read_b128 v[244:247], v156 offset:28672
	ds_read_b128 v[248:251], v156 offset:29696
	v_mfma_f32_16x16x32_bf16 v[48:51], v[216:219], v[232:235], v[48:51]
	s_add_u32 m0, s76, 0x3000
	v_mfma_f32_16x16x32_bf16 v[52:55], v[216:219], v[236:239], v[52:55]
	global_load_lds_dwordx4 v163, s[72:73]
	s_add_u32 m0, s76, 0x4000
	v_mfma_f32_16x16x32_bf16 v[56:59], v[220:223], v[232:235], v[56:59]
	global_load_lds_dwordx4 v160, s[74:75]
	s_add_u32 m0, s76, 0x5000
	v_mfma_f32_16x16x32_bf16 v[60:63], v[220:223], v[236:239], v[60:63]
	global_load_lds_dwordx4 v161, s[74:75]
	s_add_u32 s72, s72, 0x202000
	s_addc_u32 s73, s73, 0
	v_mfma_f32_16x16x32_bf16 v[32:35], v[224:227], v[232:235], v[32:35]
	s_add_u32 s74, s74, 0x10000
	s_addc_u32 s75, s75, 0
	v_mfma_f32_16x16x32_bf16 v[36:39], v[224:227], v[236:239], v[36:39]
	v_mfma_f32_16x16x32_bf16 v[40:43], v[228:231], v[232:235], v[40:43]
	v_mfma_f32_16x16x32_bf16 v[44:47], v[228:231], v[236:239], v[44:47]
	s_waitcnt lgkmcnt(2)
	v_mfma_f32_16x16x32_bf16 v[80:83], v[200:203], v[240:243], v[80:83]
	ds_read_b128 v[232:235], v156 offset:32768
	v_mfma_f32_16x16x32_bf16 v[84:87], v[200:203], v[152:155], v[84:87]
	ds_read_b128 v[236:239], v156 offset:33792
	v_mfma_f32_16x16x32_bf16 v[88:91], v[204:207], v[240:243], v[88:91]
	v_mfma_f32_16x16x32_bf16 v[92:95], v[204:207], v[152:155], v[92:95]
	v_mfma_f32_16x16x32_bf16 v[64:67], v[208:211], v[240:243], v[64:67]
	v_mfma_f32_16x16x32_bf16 v[68:71], v[208:211], v[152:155], v[68:71]
	v_mfma_f32_16x16x32_bf16 v[72:75], v[212:215], v[240:243], v[72:75]
	v_mfma_f32_16x16x32_bf16 v[76:79], v[212:215], v[152:155], v[76:79]
	s_waitcnt lgkmcnt(2)
	v_mfma_f32_16x16x32_bf16 v[16:19], v[200:203], v[244:247], v[16:19]
	ds_read_b128 v[240:243], v156 offset:36864
	v_mfma_f32_16x16x32_bf16 v[20:23], v[200:203], v[248:251], v[20:23]
	ds_read_b128 v[152:155], v156 offset:37888
	v_mfma_f32_16x16x32_bf16 v[24:27], v[204:207], v[244:247], v[24:27]
	v_mfma_f32_16x16x32_bf16 v[28:31], v[204:207], v[248:251], v[28:31]
	v_mfma_f32_16x16x32_bf16 v[0:3], v[208:211], v[244:247], v[0:3]
	v_mfma_f32_16x16x32_bf16 v[4:7], v[208:211], v[248:251], v[4:7]
	v_mfma_f32_16x16x32_bf16 v[8:11], v[212:215], v[244:247], v[8:11]
	v_mfma_f32_16x16x32_bf16 v[12:15], v[212:215], v[248:251], v[12:15]
	s_waitcnt lgkmcnt(0)
	s_waitcnt vmcnt(6)
	s_barrier
	ds_read_b128 v[216:219], v158 offset:49152
	ds_read_b128 v[220:223], v158 offset:50176
	v_mfma_f32_16x16x32_bf16 v[112:115], v[200:203], v[232:235], v[112:115]
	ds_read_b128 v[224:227], v158 offset:51200
	ds_read_b128 v[228:231], v158 offset:52224
	v_mfma_f32_16x16x32_bf16 v[116:119], v[200:203], v[236:239], v[116:119]
	ds_read_b128 v[244:247], v156 offset:49152
	ds_read_b128 v[248:251], v156 offset:50176
	s_add_u32 m0, s76, 0x6000
	v_mfma_f32_16x16x32_bf16 v[120:123], v[204:207], v[232:235], v[120:123]
	global_load_lds_dwordx4 v160, s[72:73]
	s_add_u32 m0, s76, 0x7000
	v_mfma_f32_16x16x32_bf16 v[124:127], v[204:207], v[236:239], v[124:127]
	global_load_lds_dwordx4 v161, s[72:73]
	s_add_u32 m0, s76, 0x8000
	v_mfma_f32_16x16x32_bf16 v[96:99], v[208:211], v[232:235], v[96:99]
	global_load_lds_dwordx4 v162, s[72:73]
	v_mfma_f32_16x16x32_bf16 v[100:103], v[208:211], v[236:239], v[100:103]
	v_mfma_f32_16x16x32_bf16 v[104:107], v[212:215], v[232:235], v[104:107]
	v_mfma_f32_16x16x32_bf16 v[108:111], v[212:215], v[236:239], v[108:111]
	ds_read_b128 v[232:235], v156 offset:53248
	ds_read_b128 v[236:239], v156 offset:54272
	v_mfma_f32_16x16x32_bf16 v[48:51], v[200:203], v[240:243], v[48:51]
	s_add_u32 m0, s76, 0x9000
	v_mfma_f32_16x16x32_bf16 v[52:55], v[200:203], v[152:155], v[52:55]
	global_load_lds_dwordx4 v163, s[72:73]
	s_add_u32 m0, s76, 0xa000
	v_mfma_f32_16x16x32_bf16 v[56:59], v[204:207], v[240:243], v[56:59]
	global_load_lds_dwordx4 v160, s[74:75]
	s_add_u32 m0, s76, 0xb000
	v_mfma_f32_16x16x32_bf16 v[60:63], v[204:207], v[152:155], v[60:63]
	global_load_lds_dwordx4 v161, s[74:75]
	s_add_u32 s72, s72, 0x202000
	s_addc_u32 s73, s73, 0
	v_mfma_f32_16x16x32_bf16 v[32:35], v[208:211], v[240:243], v[32:35]
	s_add_u32 s74, s74, 0x10000
	s_addc_u32 s75, s75, 0
	v_mfma_f32_16x16x32_bf16 v[36:39], v[208:211], v[152:155], v[36:39]
	v_mfma_f32_16x16x32_bf16 v[40:43], v[212:215], v[240:243], v[40:43]
	v_mfma_f32_16x16x32_bf16 v[44:47], v[212:215], v[152:155], v[44:47]
	s_waitcnt lgkmcnt(2)
	v_mfma_f32_16x16x32_bf16 v[80:83], v[216:219], v[244:247], v[80:83]
	ds_read_b128 v[240:243], v156 offset:57344
	v_mfma_f32_16x16x32_bf16 v[84:87], v[216:219], v[248:251], v[84:87]
	ds_read_b128 v[152:155], v156 offset:58368
	v_mfma_f32_16x16x32_bf16 v[88:91], v[220:223], v[244:247], v[88:91]
	v_mfma_f32_16x16x32_bf16 v[92:95], v[220:223], v[248:251], v[92:95]
	v_mfma_f32_16x16x32_bf16 v[64:67], v[224:227], v[244:247], v[64:67]
	v_mfma_f32_16x16x32_bf16 v[68:71], v[224:227], v[248:251], v[68:71]
	v_mfma_f32_16x16x32_bf16 v[72:75], v[228:231], v[244:247], v[72:75]
	v_mfma_f32_16x16x32_bf16 v[76:79], v[228:231], v[248:251], v[76:79]
	s_waitcnt lgkmcnt(2)
	v_mfma_f32_16x16x32_bf16 v[16:19], v[216:219], v[232:235], v[16:19]
	ds_read_b128 v[244:247], v156 offset:61440
	v_mfma_f32_16x16x32_bf16 v[20:23], v[216:219], v[236:239], v[20:23]
	ds_read_b128 v[248:251], v156 offset:62464
	v_mfma_f32_16x16x32_bf16 v[24:27], v[220:223], v[232:235], v[24:27]
	v_mfma_f32_16x16x32_bf16 v[28:31], v[220:223], v[236:239], v[28:31]
	v_mfma_f32_16x16x32_bf16 v[0:3], v[224:227], v[232:235], v[0:3]
	v_mfma_f32_16x16x32_bf16 v[4:7], v[224:227], v[236:239], v[4:7]
	v_mfma_f32_16x16x32_bf16 v[8:11], v[228:231], v[232:235], v[8:11]
	v_mfma_f32_16x16x32_bf16 v[12:15], v[228:231], v[236:239], v[12:15]
	s_waitcnt lgkmcnt(0)
	s_waitcnt vmcnt(6)
	s_barrier
	ds_read_b128 v[200:203], v158
	ds_read_b128 v[204:207], v158 offset:1024
	v_mfma_f32_16x16x32_bf16 v[112:115], v[216:219], v[240:243], v[112:115]
	ds_read_b128 v[208:211], v158 offset:2048
	ds_read_b128 v[212:215], v158 offset:3072
	v_mfma_f32_16x16x32_bf16 v[116:119], v[216:219], v[152:155], v[116:119]
	ds_read_b128 v[232:235], v156
	ds_read_b128 v[236:239], v156 offset:1024
	s_add_u32 m0, s76, 0xc000
	v_mfma_f32_16x16x32_bf16 v[120:123], v[220:223], v[240:243], v[120:123]
	global_load_lds_dwordx4 v160, s[72:73]
	s_add_u32 m0, s76, 0xd000
	v_mfma_f32_16x16x32_bf16 v[124:127], v[220:223], v[152:155], v[124:127]
	global_load_lds_dwordx4 v161, s[72:73]
	s_add_u32 m0, s76, 0xe000
	v_mfma_f32_16x16x32_bf16 v[96:99], v[224:227], v[240:243], v[96:99]
	global_load_lds_dwordx4 v162, s[72:73]
	v_mfma_f32_16x16x32_bf16 v[100:103], v[224:227], v[152:155], v[100:103]
	v_mfma_f32_16x16x32_bf16 v[104:107], v[228:231], v[240:243], v[104:107]
	v_mfma_f32_16x16x32_bf16 v[108:111], v[228:231], v[152:155], v[108:111]
	ds_read_b128 v[240:243], v156 offset:4096
	ds_read_b128 v[152:155], v156 offset:5120
	v_mfma_f32_16x16x32_bf16 v[48:51], v[216:219], v[244:247], v[48:51]
	s_add_u32 m0, s76, 0xf000
	v_mfma_f32_16x16x32_bf16 v[52:55], v[216:219], v[248:251], v[52:55]
	global_load_lds_dwordx4 v163, s[72:73]
	s_add_u32 m0, s76, 0x10000
	v_mfma_f32_16x16x32_bf16 v[56:59], v[220:223], v[244:247], v[56:59]
	global_load_lds_dwordx4 v160, s[74:75]
	s_add_u32 m0, s76, 0x11000
	v_mfma_f32_16x16x32_bf16 v[60:63], v[220:223], v[248:251], v[60:63]
	global_load_lds_dwordx4 v161, s[74:75]
	s_add_u32 s72, s72, 0x202000
	s_addc_u32 s73, s73, 0
	v_mfma_f32_16x16x32_bf16 v[32:35], v[224:227], v[244:247], v[32:35]
	s_add_u32 s74, s74, 0x10000
	s_addc_u32 s75, s75, 0
	v_mfma_f32_16x16x32_bf16 v[36:39], v[224:227], v[248:251], v[36:39]
	v_mfma_f32_16x16x32_bf16 v[40:43], v[228:231], v[244:247], v[40:43]
	v_mfma_f32_16x16x32_bf16 v[44:47], v[228:231], v[248:251], v[44:47]
	s_sub_i32 s77, s77, 1
	s_cmp_lg_u32 s77, 0
	s_cbranch_scc1 .Lgemm_p6_loop
	s_waitcnt lgkmcnt(2)
	v_mfma_f32_16x16x32_bf16 v[80:83], v[200:203], v[232:235], v[80:83]
	ds_read_b128 v[244:247], v156 offset:8192
	v_mfma_f32_16x16x32_bf16 v[84:87], v[200:203], v[236:239], v[84:87]
	ds_read_b128 v[248:251], v156 offset:9216
	v_mfma_f32_16x16x32_bf16 v[88:91], v[204:207], v[232:235], v[88:91]
	v_mfma_f32_16x16x32_bf16 v[92:95], v[204:207], v[236:239], v[92:95]
	v_mfma_f32_16x16x32_bf16 v[64:67], v[208:211], v[232:235], v[64:67]
	v_mfma_f32_16x16x32_bf16 v[68:71], v[208:211], v[236:239], v[68:71]
	v_mfma_f32_16x16x32_bf16 v[72:75], v[212:215], v[232:235], v[72:75]
	v_mfma_f32_16x16x32_bf16 v[76:79], v[212:215], v[236:239], v[76:79]
	s_waitcnt lgkmcnt(2)
	v_mfma_f32_16x16x32_bf16 v[16:19], v[200:203], v[240:243], v[16:19]
	ds_read_b128 v[232:235], v156 offset:12288
	v_mfma_f32_16x16x32_bf16 v[20:23], v[200:203], v[152:155], v[20:23]
	ds_read_b128 v[236:239], v156 offset:13312
	v_mfma_f32_16x16x32_bf16 v[24:27], v[204:207], v[240:243], v[24:27]
	v_mfma_f32_16x16x32_bf16 v[28:31], v[204:207], v[152:155], v[28:31]
	v_mfma_f32_16x16x32_bf16 v[0:3], v[208:211], v[240:243], v[0:3]
	v_mfma_f32_16x16x32_bf16 v[4:7], v[208:211], v[152:155], v[4:7]
	v_mfma_f32_16x16x32_bf16 v[8:11], v[212:215], v[240:243], v[8:11]
	v_mfma_f32_16x16x32_bf16 v[12:15], v[212:215], v[152:155], v[12:15]
	s_waitcnt lgkmcnt(0)
	s_waitcnt vmcnt(6)
	s_barrier
	ds_read_b128 v[216:219], v158 offset:24576
	ds_read_b128 v[220:223], v158 offset:25600
	v_mfma_f32_16x16x32_bf16 v[112:115], v[200:203], v[244:247], v[112:115]
	ds_read_b128 v[224:227], v158 offset:26624
	ds_read_b128 v[228:231], v158 offset:27648
	v_mfma_f32_16x16x32_bf16 v[116:119], v[200:203], v[248:251], v[116:119]
	ds_read_b128 v[240:243], v156 offset:24576
	ds_read_b128 v[152:155], v156 offset:25600
	s_add_u32 m0, s76, 0x0
	v_mfma_f32_16x16x32_bf16 v[120:123], v[204:207], v[244:247], v[120:123]
	global_load_lds_dwordx4 v160, s[72:73]
	s_add_u32 m0, s76, 0x1000
	v_mfma_f32_16x16x32_bf16 v[124:127], v[204:207], v[248:251], v[124:127]
	global_load_lds_dwordx4 v161, s[72:73]
	s_add_u32 m0, s76, 0x2000
	v_mfma_f32_16x16x32_bf16 v[96:99], v[208:211], v[244:247], v[96:99]
	global_load_lds_dwordx4 v162, s[72:73]
	v_mfma_f32_16x16x32_bf16 v[100:103], v[208:211], v[248:251], v[100:103]
	v_mfma_f32_16x16x32_bf16 v[104:107], v[212:215], v[244:247], v[104:107]
	v_mfma_f32_16x16x32_bf16 v[108:111], v[212:215], v[248:251], v[108:111]
	ds_read_b128 v[244:247], v156 offset:28672
	ds_read_b128 v[248:251], v156 offset:29696
	v_mfma_f32_16x16x32_bf16 v[48:51], v[200:203], v[232:235], v[48:51]
	s_add_u32 m0, s76, 0x3000
	v_mfma_f32_16x16x32_bf16 v[52:55], v[200:203], v[236:239], v[52:55]
	global_load_lds_dwordx4 v163, s[72:73]
	s_add_u32 m0, s76, 0x4000
	v_mfma_f32_16x16x32_bf16 v[56:59], v[204:207], v[232:235], v[56:59]
	global_load_lds_dwordx4 v160, s[74:75]
	s_add_u32 m0, s76, 0x5000
	v_mfma_f32_16x16x32_bf16 v[60:63], v[204:207], v[236:239], v[60:63]
	global_load_lds_dwordx4 v161, s[74:75]
	s_add_u32 s72, s72, 0x202000
	s_addc_u32 s73, s73, 0
	v_mfma_f32_16x16x32_bf16 v[32:35], v[208:211], v[232:235], v[32:35]
	s_add_u32 s74, s74, 0x10000
	s_addc_u32 s75, s75, 0
	v_mfma_f32_16x16x32_bf16 v[36:39], v[208:211], v[236:239], v[36:39]
	v_mfma_f32_16x16x32_bf16 v[40:43], v[212:215], v[232:235], v[40:43]
	v_mfma_f32_16x16x32_bf16 v[44:47], v[212:215], v[236:239], v[44:47]
	s_waitcnt lgkmcnt(2)
	v_mfma_f32_16x16x32_bf16 v[80:83], v[216:219], v[240:243], v[80:83]
	ds_read_b128 v[232:235], v156 offset:32768
	v_mfma_f32_16x16x32_bf16 v[84:87], v[216:219], v[152:155], v[84:87]
	ds_read_b128 v[236:239], v156 offset:33792
	v_mfma_f32_16x16x32_bf16 v[88:91], v[220:223], v[240:243], v[88:91]
	v_mfma_f32_16x16x32_bf16 v[92:95], v[220:223], v[152:155], v[92:95]
	v_mfma_f32_16x16x32_bf16 v[64:67], v[224:227], v[240:243], v[64:67]
	v_mfma_f32_16x16x32_bf16 v[68:71], v[224:227], v[152:155], v[68:71]
	v_mfma_f32_16x16x32_bf16 v[72:75], v[228:231], v[240:243], v[72:75]
	v_mfma_f32_16x16x32_bf16 v[76:79], v[228:231], v[152:155], v[76:79]
	s_waitcnt lgkmcnt(2)
	v_mfma_f32_16x16x32_bf16 v[16:19], v[216:219], v[244:247], v[16:19]
	ds_read_b128 v[240:243], v156 offset:36864
	v_mfma_f32_16x16x32_bf16 v[20:23], v[216:219], v[248:251], v[20:23]
	ds_read_b128 v[152:155], v156 offset:37888
	v_mfma_f32_16x16x32_bf16 v[24:27], v[220:223], v[244:247], v[24:27]
	v_mfma_f32_16x16x32_bf16 v[28:31], v[220:223], v[248:251], v[28:31]
	v_mfma_f32_16x16x32_bf16 v[0:3], v[224:227], v[244:247], v[0:3]
	v_mfma_f32_16x16x32_bf16 v[4:7], v[224:227], v[248:251], v[4:7]
	v_mfma_f32_16x16x32_bf16 v[8:11], v[228:231], v[244:247], v[8:11]
	v_mfma_f32_16x16x32_bf16 v[12:15], v[228:231], v[248:251], v[12:15]
	s_waitcnt lgkmcnt(0)
	s_waitcnt vmcnt(6)
	s_barrier
	ds_read_b128 v[200:203], v158 offset:49152
	ds_read_b128 v[204:207], v158 offset:50176
	v_mfma_f32_16x16x32_bf16 v[112:115], v[216:219], v[232:235], v[112:115]
	ds_read_b128 v[208:211], v158 offset:51200
	ds_read_b128 v[212:215], v158 offset:52224
	v_mfma_f32_16x16x32_bf16 v[116:119], v[216:219], v[236:239], v[116:119]
	ds_read_b128 v[244:247], v156 offset:49152
	ds_read_b128 v[248:251], v156 offset:50176
	s_add_u32 m0, s76, 0x6000
	v_mfma_f32_16x16x32_bf16 v[120:123], v[220:223], v[232:235], v[120:123]
	global_load_lds_dwordx4 v160, s[72:73]
	s_add_u32 m0, s76, 0x7000
	v_mfma_f32_16x16x32_bf16 v[124:127], v[220:223], v[236:239], v[124:127]
	global_load_lds_dwordx4 v161, s[72:73]
	s_add_u32 m0, s76, 0x8000
	v_mfma_f32_16x16x32_bf16 v[96:99], v[224:227], v[232:235], v[96:99]
	global_load_lds_dwordx4 v162, s[72:73]
	v_mfma_f32_16x16x32_bf16 v[100:103], v[224:227], v[236:239], v[100:103]
	v_mfma_f32_16x16x32_bf16 v[104:107], v[228:231], v[232:235], v[104:107]
	v_mfma_f32_16x16x32_bf16 v[108:111], v[228:231], v[236:239], v[108:111]
	ds_read_b128 v[232:235], v156 offset:53248
	ds_read_b128 v[236:239], v156 offset:54272
	v_mfma_f32_16x16x32_bf16 v[48:51], v[216:219], v[240:243], v[48:51]
	s_add_u32 m0, s76, 0x9000
	v_mfma_f32_16x16x32_bf16 v[52:55], v[216:219], v[152:155], v[52:55]
	global_load_lds_dwordx4 v163, s[72:73]
	s_add_u32 m0, s76, 0xa000
	v_mfma_f32_16x16x32_bf16 v[56:59], v[220:223], v[240:243], v[56:59]
	global_load_lds_dwordx4 v160, s[74:75]
	s_add_u32 m0, s76, 0xb000
	v_mfma_f32_16x16x32_bf16 v[60:63], v[220:223], v[152:155], v[60:63]
	global_load_lds_dwordx4 v161, s[74:75]
	s_add_u32 s72, s72, 0x202000
	s_addc_u32 s73, s73, 0
	v_mfma_f32_16x16x32_bf16 v[32:35], v[224:227], v[240:243], v[32:35]
	s_add_u32 s74, s74, 0x10000
	s_addc_u32 s75, s75, 0
	v_mfma_f32_16x16x32_bf16 v[36:39], v[224:227], v[152:155], v[36:39]
	v_mfma_f32_16x16x32_bf16 v[40:43], v[228:231], v[240:243], v[40:43]
	v_mfma_f32_16x16x32_bf16 v[44:47], v[228:231], v[152:155], v[44:47]
	s_waitcnt lgkmcnt(2)
	v_mfma_f32_16x16x32_bf16 v[80:83], v[200:203], v[244:247], v[80:83]
	ds_read_b128 v[240:243], v156 offset:57344
	v_mfma_f32_16x16x32_bf16 v[84:87], v[200:203], v[248:251], v[84:87]
	ds_read_b128 v[152:155], v156 offset:58368
	v_mfma_f32_16x16x32_bf16 v[88:91], v[204:207], v[244:247], v[88:91]
	v_mfma_f32_16x16x32_bf16 v[92:95], v[204:207], v[248:251], v[92:95]
	v_mfma_f32_16x16x32_bf16 v[64:67], v[208:211], v[244:247], v[64:67]
	v_mfma_f32_16x16x32_bf16 v[68:71], v[208:211], v[248:251], v[68:71]
	v_mfma_f32_16x16x32_bf16 v[72:75], v[212:215], v[244:247], v[72:75]
	v_mfma_f32_16x16x32_bf16 v[76:79], v[212:215], v[248:251], v[76:79]
	s_waitcnt lgkmcnt(2)
	v_mfma_f32_16x16x32_bf16 v[16:19], v[200:203], v[232:235], v[16:19]
	ds_read_b128 v[244:247], v156 offset:61440
	v_mfma_f32_16x16x32_bf16 v[20:23], v[200:203], v[236:239], v[20:23]
	ds_read_b128 v[248:251], v156 offset:62464
	v_mfma_f32_16x16x32_bf16 v[24:27], v[204:207], v[232:235], v[24:27]
	v_mfma_f32_16x16x32_bf16 v[28:31], v[204:207], v[236:239], v[28:31]
	v_mfma_f32_16x16x32_bf16 v[0:3], v[208:211], v[232:235], v[0:3]
	v_mfma_f32_16x16x32_bf16 v[4:7], v[208:211], v[236:239], v[4:7]
	v_mfma_f32_16x16x32_bf16 v[8:11], v[212:215], v[232:235], v[8:11]
	v_mfma_f32_16x16x32_bf16 v[12:15], v[212:215], v[236:239], v[12:15]
	s_waitcnt lgkmcnt(0)
	s_waitcnt vmcnt(6)
	s_barrier
	ds_read_b128 v[216:219], v158
	ds_read_b128 v[220:223], v158 offset:1024
	v_mfma_f32_16x16x32_bf16 v[112:115], v[200:203], v[240:243], v[112:115]
	ds_read_b128 v[224:227], v158 offset:2048
	ds_read_b128 v[228:231], v158 offset:3072
	v_mfma_f32_16x16x32_bf16 v[116:119], v[200:203], v[152:155], v[116:119]
	ds_read_b128 v[232:235], v156
	ds_read_b128 v[236:239], v156 offset:1024
	s_add_u32 m0, s76, 0xc000
	v_mfma_f32_16x16x32_bf16 v[120:123], v[204:207], v[240:243], v[120:123]
	global_load_lds_dwordx4 v160, s[72:73]
	s_add_u32 m0, s76, 0xd000
	v_mfma_f32_16x16x32_bf16 v[124:127], v[204:207], v[152:155], v[124:127]
	global_load_lds_dwordx4 v161, s[72:73]
	s_add_u32 m0, s76, 0xe000
	v_mfma_f32_16x16x32_bf16 v[96:99], v[208:211], v[240:243], v[96:99]
	global_load_lds_dwordx4 v162, s[72:73]
	v_mfma_f32_16x16x32_bf16 v[100:103], v[208:211], v[152:155], v[100:103]
	v_mfma_f32_16x16x32_bf16 v[104:107], v[212:215], v[240:243], v[104:107]
	v_mfma_f32_16x16x32_bf16 v[108:111], v[212:215], v[152:155], v[108:111]
	ds_read_b128 v[240:243], v156 offset:4096
	ds_read_b128 v[152:155], v156 offset:5120
	v_mfma_f32_16x16x32_bf16 v[48:51], v[200:203], v[244:247], v[48:51]
	s_add_u32 m0, s76, 0xf000
	v_mfma_f32_16x16x32_bf16 v[52:55], v[200:203], v[248:251], v[52:55]
	global_load_lds_dwordx4 v163, s[72:73]
	s_add_u32 m0, s76, 0x10000
	v_mfma_f32_16x16x32_bf16 v[56:59], v[204:207], v[244:247], v[56:59]
	global_load_lds_dwordx4 v160, s[74:75]
	s_add_u32 m0, s76, 0x11000
	v_mfma_f32_16x16x32_bf16 v[60:63], v[204:207], v[248:251], v[60:63]
	global_load_lds_dwordx4 v161, s[74:75]
	s_add_u32 s72, s72, 0x202000
	s_addc_u32 s73, s73, 0
	v_mfma_f32_16x16x32_bf16 v[32:35], v[208:211], v[244:247], v[32:35]
	s_add_u32 s74, s74, 0x10000
	s_addc_u32 s75, s75, 0
	v_mfma_f32_16x16x32_bf16 v[36:39], v[208:211], v[248:251], v[36:39]
	v_mfma_f32_16x16x32_bf16 v[40:43], v[212:215], v[244:247], v[40:43]
	v_mfma_f32_16x16x32_bf16 v[44:47], v[212:215], v[248:251], v[44:47]
	s_waitcnt lgkmcnt(2)
	v_mfma_f32_16x16x32_bf16 v[80:83], v[216:219], v[232:235], v[80:83]
	ds_read_b128 v[244:247], v156 offset:8192
	v_mfma_f32_16x16x32_bf16 v[84:87], v[216:219], v[236:239], v[84:87]
	ds_read_b128 v[248:251], v156 offset:9216
	v_mfma_f32_16x16x32_bf16 v[88:91], v[220:223], v[232:235], v[88:91]
	v_mfma_f32_16x16x32_bf16 v[92:95], v[220:223], v[236:239], v[92:95]
	v_mfma_f32_16x16x32_bf16 v[64:67], v[224:227], v[232:235], v[64:67]
	v_mfma_f32_16x16x32_bf16 v[68:71], v[224:227], v[236:239], v[68:71]
	v_mfma_f32_16x16x32_bf16 v[72:75], v[228:231], v[232:235], v[72:75]
	v_mfma_f32_16x16x32_bf16 v[76:79], v[228:231], v[236:239], v[76:79]
	s_waitcnt lgkmcnt(2)
	v_mfma_f32_16x16x32_bf16 v[16:19], v[216:219], v[240:243], v[16:19]
	ds_read_b128 v[232:235], v156 offset:12288
	v_mfma_f32_16x16x32_bf16 v[20:23], v[216:219], v[152:155], v[20:23]
	ds_read_b128 v[236:239], v156 offset:13312
	v_mfma_f32_16x16x32_bf16 v[24:27], v[220:223], v[240:243], v[24:27]
	v_mfma_f32_16x16x32_bf16 v[28:31], v[220:223], v[152:155], v[28:31]
	v_mfma_f32_16x16x32_bf16 v[0:3], v[224:227], v[240:243], v[0:3]
	v_mfma_f32_16x16x32_bf16 v[4:7], v[224:227], v[152:155], v[4:7]
	v_mfma_f32_16x16x32_bf16 v[8:11], v[228:231], v[240:243], v[8:11]
	v_mfma_f32_16x16x32_bf16 v[12:15], v[228:231], v[152:155], v[12:15]
	s_waitcnt lgkmcnt(0)
	s_waitcnt vmcnt(6)
	s_barrier
	ds_read_b128 v[200:203], v158 offset:24576
	ds_read_b128 v[204:207], v158 offset:25600
	v_mfma_f32_16x16x32_bf16 v[112:115], v[216:219], v[244:247], v[112:115]
	ds_read_b128 v[208:211], v158 offset:26624
	ds_read_b128 v[212:215], v158 offset:27648
	v_mfma_f32_16x16x32_bf16 v[116:119], v[216:219], v[248:251], v[116:119]
	ds_read_b128 v[240:243], v156 offset:24576
	ds_read_b128 v[152:155], v156 offset:25600
	s_add_u32 m0, s76, 0x0
	v_mfma_f32_16x16x32_bf16 v[120:123], v[220:223], v[244:247], v[120:123]
	global_load_lds_dwordx4 v160, s[72:73]
	s_add_u32 m0, s76, 0x1000
	v_mfma_f32_16x16x32_bf16 v[124:127], v[220:223], v[248:251], v[124:127]
	global_load_lds_dwordx4 v161, s[72:73]
	s_add_u32 m0, s76, 0x2000
	v_mfma_f32_16x16x32_bf16 v[96:99], v[224:227], v[244:247], v[96:99]
	global_load_lds_dwordx4 v162, s[72:73]
	v_mfma_f32_16x16x32_bf16 v[100:103], v[224:227], v[248:251], v[100:103]
	v_mfma_f32_16x16x32_bf16 v[104:107], v[228:231], v[244:247], v[104:107]
	v_mfma_f32_16x16x32_bf16 v[108:111], v[228:231], v[248:251], v[108:111]
	ds_read_b128 v[244:247], v156 offset:28672
	ds_read_b128 v[248:251], v156 offset:29696
	v_mfma_f32_16x16x32_bf16 v[48:51], v[216:219], v[232:235], v[48:51]
	s_add_u32 m0, s76, 0x3000
	v_mfma_f32_16x16x32_bf16 v[52:55], v[216:219], v[236:239], v[52:55]
	global_load_lds_dwordx4 v163, s[72:73]
	s_add_u32 m0, s76, 0x4000
	v_mfma_f32_16x16x32_bf16 v[56:59], v[220:223], v[232:235], v[56:59]
	global_load_lds_dwordx4 v160, s[74:75]
	s_add_u32 m0, s76, 0x5000
	v_mfma_f32_16x16x32_bf16 v[60:63], v[220:223], v[236:239], v[60:63]
	global_load_lds_dwordx4 v161, s[74:75]
	s_add_u32 s72, s72, 0x202000
	s_addc_u32 s73, s73, 0
	v_mfma_f32_16x16x32_bf16 v[32:35], v[224:227], v[232:235], v[32:35]
	s_add_u32 s74, s74, 0x10000
	s_addc_u32 s75, s75, 0
	v_mfma_f32_16x16x32_bf16 v[36:39], v[224:227], v[236:239], v[36:39]
	v_mfma_f32_16x16x32_bf16 v[40:43], v[228:231], v[232:235], v[40:43]
	v_mfma_f32_16x16x32_bf16 v[44:47], v[228:231], v[236:239], v[44:47]
	s_waitcnt lgkmcnt(2)
	v_mfma_f32_16x16x32_bf16 v[80:83], v[200:203], v[240:243], v[80:83]
	ds_read_b128 v[232:235], v156 offset:32768
	v_mfma_f32_16x16x32_bf16 v[84:87], v[200:203], v[152:155], v[84:87]
	ds_read_b128 v[236:239], v156 offset:33792
	v_mfma_f32_16x16x32_bf16 v[88:91], v[204:207], v[240:243], v[88:91]
	v_mfma_f32_16x16x32_bf16 v[92:95], v[204:207], v[152:155], v[92:95]
	v_mfma_f32_16x16x32_bf16 v[64:67], v[208:211], v[240:243], v[64:67]
	v_mfma_f32_16x16x32_bf16 v[68:71], v[208:211], v[152:155], v[68:71]
	v_mfma_f32_16x16x32_bf16 v[72:75], v[212:215], v[240:243], v[72:75]
	v_mfma_f32_16x16x32_bf16 v[76:79], v[212:215], v[152:155], v[76:79]
	s_waitcnt lgkmcnt(2)
	v_mfma_f32_16x16x32_bf16 v[16:19], v[200:203], v[244:247], v[16:19]
	ds_read_b128 v[240:243], v156 offset:36864
	v_mfma_f32_16x16x32_bf16 v[20:23], v[200:203], v[248:251], v[20:23]
	ds_read_b128 v[152:155], v156 offset:37888
	v_mfma_f32_16x16x32_bf16 v[24:27], v[204:207], v[244:247], v[24:27]
	v_mfma_f32_16x16x32_bf16 v[28:31], v[204:207], v[248:251], v[28:31]
	v_mfma_f32_16x16x32_bf16 v[0:3], v[208:211], v[244:247], v[0:3]
	v_mfma_f32_16x16x32_bf16 v[4:7], v[208:211], v[248:251], v[4:7]
	v_mfma_f32_16x16x32_bf16 v[8:11], v[212:215], v[244:247], v[8:11]
	v_mfma_f32_16x16x32_bf16 v[12:15], v[212:215], v[248:251], v[12:15]
	s_waitcnt lgkmcnt(0)
	s_waitcnt vmcnt(6)
	s_barrier
	ds_read_b128 v[216:219], v158 offset:49152
	ds_read_b128 v[220:223], v158 offset:50176
	v_mfma_f32_16x16x32_bf16 v[112:115], v[200:203], v[232:235], v[112:115]
	ds_read_b128 v[224:227], v158 offset:51200
	ds_read_b128 v[228:231], v158 offset:52224
	v_mfma_f32_16x16x32_bf16 v[116:119], v[200:203], v[236:239], v[116:119]
	ds_read_b128 v[244:247], v156 offset:49152
	ds_read_b128 v[248:251], v156 offset:50176
	s_add_u32 m0, s76, 0x6000
	v_mfma_f32_16x16x32_bf16 v[120:123], v[204:207], v[232:235], v[120:123]
	global_load_lds_dwordx4 v160, s[72:73]
	s_add_u32 m0, s76, 0x7000
	v_mfma_f32_16x16x32_bf16 v[124:127], v[204:207], v[236:239], v[124:127]
	global_load_lds_dwordx4 v161, s[72:73]
	s_add_u32 m0, s76, 0x8000
	v_mfma_f32_16x16x32_bf16 v[96:99], v[208:211], v[232:235], v[96:99]
	global_load_lds_dwordx4 v162, s[72:73]
	v_mfma_f32_16x16x32_bf16 v[100:103], v[208:211], v[236:239], v[100:103]
	v_mfma_f32_16x16x32_bf16 v[104:107], v[212:215], v[232:235], v[104:107]
	v_mfma_f32_16x16x32_bf16 v[108:111], v[212:215], v[236:239], v[108:111]
	ds_read_b128 v[232:235], v156 offset:53248
	ds_read_b128 v[236:239], v156 offset:54272
	v_mfma_f32_16x16x32_bf16 v[48:51], v[200:203], v[240:243], v[48:51]
	s_add_u32 m0, s76, 0x9000
	v_mfma_f32_16x16x32_bf16 v[52:55], v[200:203], v[152:155], v[52:55]
	global_load_lds_dwordx4 v163, s[72:73]
	s_add_u32 m0, s76, 0xa000
	v_mfma_f32_16x16x32_bf16 v[56:59], v[204:207], v[240:243], v[56:59]
	global_load_lds_dwordx4 v160, s[74:75]
	s_add_u32 m0, s76, 0xb000
	v_mfma_f32_16x16x32_bf16 v[60:63], v[204:207], v[152:155], v[60:63]
	global_load_lds_dwordx4 v161, s[74:75]
	s_add_u32 s72, s72, 0x202000
	s_addc_u32 s73, s73, 0
	v_mfma_f32_16x16x32_bf16 v[32:35], v[208:211], v[240:243], v[32:35]
	s_add_u32 s74, s74, 0x10000
	s_addc_u32 s75, s75, 0
	v_mfma_f32_16x16x32_bf16 v[36:39], v[208:211], v[152:155], v[36:39]
	v_mfma_f32_16x16x32_bf16 v[40:43], v[212:215], v[240:243], v[40:43]
	v_mfma_f32_16x16x32_bf16 v[44:47], v[212:215], v[152:155], v[44:47]
	s_waitcnt lgkmcnt(2)
	v_mfma_f32_16x16x32_bf16 v[80:83], v[216:219], v[244:247], v[80:83]
	ds_read_b128 v[240:243], v156 offset:57344
	v_mfma_f32_16x16x32_bf16 v[84:87], v[216:219], v[248:251], v[84:87]
	ds_read_b128 v[152:155], v156 offset:58368
	v_mfma_f32_16x16x32_bf16 v[88:91], v[220:223], v[244:247], v[88:91]
	v_mfma_f32_16x16x32_bf16 v[92:95], v[220:223], v[248:251], v[92:95]
	v_mfma_f32_16x16x32_bf16 v[64:67], v[224:227], v[244:247], v[64:67]
	v_mfma_f32_16x16x32_bf16 v[68:71], v[224:227], v[248:251], v[68:71]
	v_mfma_f32_16x16x32_bf16 v[72:75], v[228:231], v[244:247], v[72:75]
	v_mfma_f32_16x16x32_bf16 v[76:79], v[228:231], v[248:251], v[76:79]
	s_waitcnt lgkmcnt(2)
	v_mfma_f32_16x16x32_bf16 v[16:19], v[216:219], v[232:235], v[16:19]
	ds_read_b128 v[244:247], v156 offset:61440
	v_mfma_f32_16x16x32_bf16 v[20:23], v[216:219], v[236:239], v[20:23]
	ds_read_b128 v[248:251], v156 offset:62464
	v_mfma_f32_16x16x32_bf16 v[24:27], v[220:223], v[232:235], v[24:27]
	v_mfma_f32_16x16x32_bf16 v[28:31], v[220:223], v[236:239], v[28:31]
	v_mfma_f32_16x16x32_bf16 v[0:3], v[224:227], v[232:235], v[0:3]
	v_mfma_f32_16x16x32_bf16 v[4:7], v[224:227], v[236:239], v[4:7]
	v_mfma_f32_16x16x32_bf16 v[8:11], v[228:231], v[232:235], v[8:11]
	v_mfma_f32_16x16x32_bf16 v[12:15], v[228:231], v[236:239], v[12:15]
	s_waitcnt lgkmcnt(0)
	s_waitcnt vmcnt(6)
	s_barrier
	ds_read_b128 v[200:203], v158
	ds_read_b128 v[204:207], v158 offset:1024
	v_mfma_f32_16x16x32_bf16 v[112:115], v[216:219], v[240:243], v[112:115]
	ds_read_b128 v[208:211], v158 offset:2048
	ds_read_b128 v[212:215], v158 offset:3072
	v_mfma_f32_16x16x32_bf16 v[116:119], v[216:219], v[152:155], v[116:119]
	ds_read_b128 v[232:235], v156
	ds_read_b128 v[236:239], v156 offset:1024
	v_mfma_f32_16x16x32_bf16 v[120:123], v[220:223], v[240:243], v[120:123]
	v_mfma_f32_16x16x32_bf16 v[124:127], v[220:223], v[152:155], v[124:127]
	v_mfma_f32_16x16x32_bf16 v[96:99], v[224:227], v[240:243], v[96:99]
	v_mfma_f32_16x16x32_bf16 v[100:103], v[224:227], v[152:155], v[100:103]
	v_mfma_f32_16x16x32_bf16 v[104:107], v[228:231], v[240:243], v[104:107]
	v_mfma_f32_16x16x32_bf16 v[108:111], v[228:231], v[152:155], v[108:111]
	ds_read_b128 v[240:243], v156 offset:4096
	ds_read_b128 v[152:155], v156 offset:5120
	v_mfma_f32_16x16x32_bf16 v[48:51], v[216:219], v[244:247], v[48:51]
	v_mfma_f32_16x16x32_bf16 v[52:55], v[216:219], v[248:251], v[52:55]
	v_mfma_f32_16x16x32_bf16 v[56:59], v[220:223], v[244:247], v[56:59]
	v_mfma_f32_16x16x32_bf16 v[60:63], v[220:223], v[248:251], v[60:63]
	v_mfma_f32_16x16x32_bf16 v[32:35], v[224:227], v[244:247], v[32:35]
	v_mfma_f32_16x16x32_bf16 v[36:39], v[224:227], v[248:251], v[36:39]
	v_mfma_f32_16x16x32_bf16 v[40:43], v[228:231], v[244:247], v[40:43]
	v_mfma_f32_16x16x32_bf16 v[44:47], v[228:231], v[248:251], v[44:47]
	s_waitcnt lgkmcnt(2)
	v_mfma_f32_16x16x32_bf16 v[80:83], v[200:203], v[232:235], v[80:83]
	ds_read_b128 v[244:247], v156 offset:8192
	v_mfma_f32_16x16x32_bf16 v[84:87], v[200:203], v[236:239], v[84:87]
	ds_read_b128 v[248:251], v156 offset:9216
	v_mfma_f32_16x16x32_bf16 v[88:91], v[204:207], v[232:235], v[88:91]
	v_mfma_f32_16x16x32_bf16 v[92:95], v[204:207], v[236:239], v[92:95]
	v_mfma_f32_16x16x32_bf16 v[64:67], v[208:211], v[232:235], v[64:67]
	v_mfma_f32_16x16x32_bf16 v[68:71], v[208:211], v[236:239], v[68:71]
	v_mfma_f32_16x16x32_bf16 v[72:75], v[212:215], v[232:235], v[72:75]
	v_mfma_f32_16x16x32_bf16 v[76:79], v[212:215], v[236:239], v[76:79]
	s_waitcnt lgkmcnt(2)
	v_mfma_f32_16x16x32_bf16 v[16:19], v[200:203], v[240:243], v[16:19]
	ds_read_b128 v[232:235], v156 offset:12288
	v_mfma_f32_16x16x32_bf16 v[20:23], v[200:203], v[152:155], v[20:23]
	ds_read_b128 v[236:239], v156 offset:13312
	v_mfma_f32_16x16x32_bf16 v[24:27], v[204:207], v[240:243], v[24:27]
	v_mfma_f32_16x16x32_bf16 v[28:31], v[204:207], v[152:155], v[28:31]
	v_mfma_f32_16x16x32_bf16 v[0:3], v[208:211], v[240:243], v[0:3]
	v_mfma_f32_16x16x32_bf16 v[4:7], v[208:211], v[152:155], v[4:7]
	v_mfma_f32_16x16x32_bf16 v[8:11], v[212:215], v[240:243], v[8:11]
	v_mfma_f32_16x16x32_bf16 v[12:15], v[212:215], v[152:155], v[12:15]
	s_waitcnt lgkmcnt(0)
	s_waitcnt vmcnt(0)
	s_barrier
	ds_read_b128 v[216:219], v158 offset:24576
	ds_read_b128 v[220:223], v158 offset:25600
	v_mfma_f32_16x16x32_bf16 v[112:115], v[200:203], v[244:247], v[112:115]
	ds_read_b128 v[224:227], v158 offset:26624
	ds_read_b128 v[228:231], v158 offset:27648
	v_mfma_f32_16x16x32_bf16 v[116:119], v[200:203], v[248:251], v[116:119]
	ds_read_b128 v[240:243], v156 offset:24576
	ds_read_b128 v[152:155], v156 offset:25600
	v_mfma_f32_16x16x32_bf16 v[120:123], v[204:207], v[244:247], v[120:123]
	v_mfma_f32_16x16x32_bf16 v[124:127], v[204:207], v[248:251], v[124:127]
	v_mfma_f32_16x16x32_bf16 v[96:99], v[208:211], v[244:247], v[96:99]
	v_mfma_f32_16x16x32_bf16 v[100:103], v[208:211], v[248:251], v[100:103]
	v_mfma_f32_16x16x32_bf16 v[104:107], v[212:215], v[244:247], v[104:107]
	v_mfma_f32_16x16x32_bf16 v[108:111], v[212:215], v[248:251], v[108:111]
	ds_read_b128 v[244:247], v156 offset:28672
	ds_read_b128 v[248:251], v156 offset:29696
	v_mfma_f32_16x16x32_bf16 v[48:51], v[200:203], v[232:235], v[48:51]
	v_mfma_f32_16x16x32_bf16 v[52:55], v[200:203], v[236:239], v[52:55]
	v_mfma_f32_16x16x32_bf16 v[56:59], v[204:207], v[232:235], v[56:59]
	v_mfma_f32_16x16x32_bf16 v[60:63], v[204:207], v[236:239], v[60:63]
	v_mfma_f32_16x16x32_bf16 v[32:35], v[208:211], v[232:235], v[32:35]
	v_mfma_f32_16x16x32_bf16 v[36:39], v[208:211], v[236:239], v[36:39]
	v_mfma_f32_16x16x32_bf16 v[40:43], v[212:215], v[232:235], v[40:43]
	v_mfma_f32_16x16x32_bf16 v[44:47], v[212:215], v[236:239], v[44:47]
	s_waitcnt lgkmcnt(2)
	v_mfma_f32_16x16x32_bf16 v[80:83], v[216:219], v[240:243], v[80:83]
	ds_read_b128 v[232:235], v156 offset:32768
	v_mfma_f32_16x16x32_bf16 v[84:87], v[216:219], v[152:155], v[84:87]
	ds_read_b128 v[236:239], v156 offset:33792
	v_mfma_f32_16x16x32_bf16 v[88:91], v[220:223], v[240:243], v[88:91]
	v_mfma_f32_16x16x32_bf16 v[92:95], v[220:223], v[152:155], v[92:95]
	v_mfma_f32_16x16x32_bf16 v[64:67], v[224:227], v[240:243], v[64:67]
	v_mfma_f32_16x16x32_bf16 v[68:71], v[224:227], v[152:155], v[68:71]
	v_mfma_f32_16x16x32_bf16 v[72:75], v[228:231], v[240:243], v[72:75]
	v_mfma_f32_16x16x32_bf16 v[76:79], v[228:231], v[152:155], v[76:79]
	s_waitcnt lgkmcnt(2)
	v_mfma_f32_16x16x32_bf16 v[16:19], v[216:219], v[244:247], v[16:19]
	ds_read_b128 v[240:243], v156 offset:36864
	v_mfma_f32_16x16x32_bf16 v[20:23], v[216:219], v[248:251], v[20:23]
	ds_read_b128 v[152:155], v156 offset:37888
	v_mfma_f32_16x16x32_bf16 v[24:27], v[220:223], v[244:247], v[24:27]
	v_mfma_f32_16x16x32_bf16 v[28:31], v[220:223], v[248:251], v[28:31]
	v_mfma_f32_16x16x32_bf16 v[0:3], v[224:227], v[244:247], v[0:3]
	v_mfma_f32_16x16x32_bf16 v[4:7], v[224:227], v[248:251], v[4:7]
	v_mfma_f32_16x16x32_bf16 v[8:11], v[228:231], v[244:247], v[8:11]
	v_mfma_f32_16x16x32_bf16 v[12:15], v[228:231], v[248:251], v[12:15]
	s_waitcnt lgkmcnt(0)
	v_mfma_f32_16x16x32_bf16 v[112:115], v[216:219], v[232:235], v[112:115]
	v_mfma_f32_16x16x32_bf16 v[116:119], v[216:219], v[236:239], v[116:119]
	v_mfma_f32_16x16x32_bf16 v[120:123], v[220:223], v[232:235], v[120:123]
	v_mfma_f32_16x16x32_bf16 v[124:127], v[220:223], v[236:239], v[124:127]
	v_mfma_f32_16x16x32_bf16 v[96:99], v[224:227], v[232:235], v[96:99]
	v_mfma_f32_16x16x32_bf16 v[100:103], v[224:227], v[236:239], v[100:103]
	v_mfma_f32_16x16x32_bf16 v[104:107], v[228:231], v[232:235], v[104:107]
	v_mfma_f32_16x16x32_bf16 v[108:111], v[228:231], v[236:239], v[108:111]
	v_mfma_f32_16x16x32_bf16 v[48:51], v[216:219], v[240:243], v[48:51]
	v_mfma_f32_16x16x32_bf16 v[52:55], v[216:219], v[152:155], v[52:55]
	v_mfma_f32_16x16x32_bf16 v[56:59], v[220:223], v[240:243], v[56:59]
	v_mfma_f32_16x16x32_bf16 v[60:63], v[220:223], v[152:155], v[60:63]
	v_mfma_f32_16x16x32_bf16 v[32:35], v[224:227], v[240:243], v[32:35]
	v_mfma_f32_16x16x32_bf16 v[36:39], v[224:227], v[152:155], v[36:39]
	v_mfma_f32_16x16x32_bf16 v[40:43], v[228:231], v[240:243], v[40:43]
	v_mfma_f32_16x16x32_bf16 v[44:47], v[228:231], v[152:155], v[44:47]
	s_nop 15
	s_nop 15
	v_permlane16_swap_b32_e32 v80, v84
	v_permlane16_swap_b32_e32 v81, v85
	v_permlane16_swap_b32_e32 v82, v86
	v_permlane16_swap_b32_e32 v83, v87
	v_permlane16_swap_b32_e32 v88, v92
	v_permlane16_swap_b32_e32 v89, v93
	v_permlane16_swap_b32_e32 v90, v94
	v_permlane16_swap_b32_e32 v91, v95
	v_permlane16_swap_b32_e32 v16, v20
	v_permlane16_swap_b32_e32 v17, v21
	v_permlane16_swap_b32_e32 v18, v22
	v_permlane16_swap_b32_e32 v19, v23
	v_permlane16_swap_b32_e32 v24, v28
	v_permlane16_swap_b32_e32 v25, v29
	v_permlane16_swap_b32_e32 v26, v30
	v_permlane16_swap_b32_e32 v27, v31
	v_permlane16_swap_b32_e32 v112, v116
	v_permlane16_swap_b32_e32 v113, v117
	v_permlane16_swap_b32_e32 v114, v118
	v_permlane16_swap_b32_e32 v115, v119
	v_permlane16_swap_b32_e32 v120, v124
	v_permlane16_swap_b32_e32 v121, v125
	v_permlane16_swap_b32_e32 v122, v126
	v_permlane16_swap_b32_e32 v123, v127
	v_permlane16_swap_b32_e32 v48, v52
	v_permlane16_swap_b32_e32 v49, v53
	v_permlane16_swap_b32_e32 v50, v54
	v_permlane16_swap_b32_e32 v51, v55
	v_permlane16_swap_b32_e32 v56, v60
	v_permlane16_swap_b32_e32 v57, v61
	v_permlane16_swap_b32_e32 v58, v62
	v_permlane16_swap_b32_e32 v59, v63
	v_permlane16_swap_b32_e32 v64, v68
	v_permlane16_swap_b32_e32 v65, v69
	v_permlane16_swap_b32_e32 v66, v70
	v_permlane16_swap_b32_e32 v67, v71
	v_permlane16_swap_b32_e32 v72, v76
	v_permlane16_swap_b32_e32 v73, v77
	v_permlane16_swap_b32_e32 v74, v78
	v_permlane16_swap_b32_e32 v75, v79
	v_permlane16_swap_b32_e32 v0, v4
	v_permlane16_swap_b32_e32 v1, v5
	v_permlane16_swap_b32_e32 v2, v6
	v_permlane16_swap_b32_e32 v3, v7
	v_permlane16_swap_b32_e32 v8, v12
	v_permlane16_swap_b32_e32 v9, v13
	v_permlane16_swap_b32_e32 v10, v14
	v_permlane16_swap_b32_e32 v11, v15
	v_permlane16_swap_b32_e32 v96, v100
	v_permlane16_swap_b32_e32 v97, v101
	v_permlane16_swap_b32_e32 v98, v102
	v_permlane16_swap_b32_e32 v99, v103
	v_permlane16_swap_b32_e32 v104, v108
	v_permlane16_swap_b32_e32 v105, v109
	v_permlane16_swap_b32_e32 v106, v110
	v_permlane16_swap_b32_e32 v107, v111
	v_permlane16_swap_b32_e32 v32, v36
	v_permlane16_swap_b32_e32 v33, v37
	v_permlane16_swap_b32_e32 v34, v38
	v_permlane16_swap_b32_e32 v35, v39
	v_permlane16_swap_b32_e32 v40, v44
	v_permlane16_swap_b32_e32 v41, v45
	v_permlane16_swap_b32_e32 v42, v46
	v_permlane16_swap_b32_e32 v43, v47
	s_nop 1
